# HNAQP2S + residual-stream x stores without the nt hint (plain global_store_dwordx4)
# baseline (speedup 1.0000x reference)
; #define LAS __attribute__((address_space(3)))
;     __device__ __forceinline__ void operator()(const f32x4 (&acc)[2][2][4][2], const Unit& u, int wr, int wc, int fr, int fq) const {
;         const int s = u.pm >> 5, lane = fq * 16 + fr, rr = lane >> 3, pc = lane & 7;
;         const float* __restrict__ xi = xin + (size_t)u.pm * BM * DM; float* __restrict__ xo = xout + (size_t)u.pm * BM * DM; bf16_t* __restrict__ ho = Hn + (size_t)u.pm * BM * DM;
;         LAS unsigned char* st = lds_epi + (wr * 4 + wc) * 2304;
;         LAS float* sst = (LAS float*)(lds_epi + 18432 + (wr * 4 + wc) * 512);
;         const int colr = u.pn * BM + wc * 64 + 4 * pc;
;         const unsigned eb = (unsigned)((wr * 64 + rr) * DM + colr);
;         f32x4 gv[2], gsn[2];
; #pragma unroll
;         for (int bj = 0; bj < 2; ++bj) { gv[bj] = *(const f32x4*)(gate + (size_t)s * MODW + colr + bj * 32) * (0.5f * GS2);
;             if (!PLAIN) gsn[bj] = *(const f32x4*)(gnext + colr + bj * 32) * (*(const f32x4*)(scnext + (size_t)s * MODW + colr + bj * 32) + 1.0f); else gsn[bj] = gv[bj]; }
;         const unsigned wr_off = (unsigned)(fr * 144 + 16 * fq), rd_off = (unsigned)(rr * 144 + pc * 16);
;         const bool odd = (rr & 1) != 0;
;         f32x4 xb[2][2][2];
;     ...
;         ERN_LOADX(0);
; #pragma unroll
;         for (int g = 0; g < 8; ++g) { const int ai = g >> 2, m = g & 3;
;             if (g + 1 < 8) ERN_LOADX(g + 1);
;             float sq0 = 0.f, sq1 = 0.f; u32x2 hw[2][2];
; #pragma unroll
;             for (int bj = 0; bj < 2; ++bj) {
;                 *(LAS f32x4*)(st + wr_off) = acc[ai][bj][m][0]; *(LAS f32x4*)(st + wr_off + 64) = acc[ai][bj][m][1];
;                 const f32x4 a0 = *(const LAS f32x4*)(st + rd_off), a1 = *(const LAS f32x4*)(st + rd_off + 8 * 144);
;                 { const f32x4 xv = xb[g & 1][bj][0] + gv[bj] * a0; __builtin_nontemporal_store(xv, (f32x4*)((char*)xo + 4u * ERN_EOFF(g, bj, 0)));
;                   sq0 += (xv.x * xv.x + xv.y * xv.y) + (xv.z * xv.z + xv.w * xv.w);
;                   const f32x4 hv = xv * gsn[bj]; hw[bj][0].x = cvt_pk_bf16(hv.x, hv.y); hw[bj][0].y = cvt_pk_bf16(hv.z, hv.w); }
;                 { const f32x4 xv = xb[g & 1][bj][1] + gv[bj] * a1; __builtin_nontemporal_store(xv, (f32x4*)((char*)xo + 4u * ERN_EOFF(g, bj, 1)));
;                   sq1 += (xv.x * xv.x + xv.y * xv.y) + (xv.z * xv.z + xv.w * xv.w);
.LBB0_320:
	s_ashr_i32 s12, s4, 5
	s_ashr_i32 s5, s4, 31
	v_lshl_or_b32 v130, s0, 8, v192
	s_mul_i32 s14, s12, 0x12000
	s_mul_hi_i32 s0, s12, 0x12000
	s_add_u32 s12, s35, s14
	v_ashrrev_i32_e32 v131, 31, v130
	s_addc_u32 s13, s36, s0
	v_lshlrev_b64 v[132:133], 2, v[130:131]
	v_lshl_add_u64 v[134:135], s[12:13], 0, v[132:133]
	s_add_u32 s12, s37, s14
	s_addc_u32 s13, s60, s0
	v_lshl_add_u64 v[136:137], s[46:47], 0, v[132:133]
	v_lshl_add_u64 v[132:133], s[12:13], 0, v[132:133]
	s_lshl_b64 s[54:55], s[4:5], 21
	v_readlane_b32 s12, v253, 2
	v_readlane_b32 s13, v253, 3
	s_add_u32 s58, s12, s54
	v_add_u32_e32 v202, v130, v193
	s_addc_u32 s59, s13, s55
	v_lshlrev_b32_e32 v207, 2, v202
	global_load_dwordx4 v[170:173], v[136:137], off
	global_load_dwordx4 v[166:169], v[134:135], off
	global_load_dwordx4 v[174:177], v[134:135], off offset:128
	global_load_dwordx4 v[186:189], v[132:133], off
	global_load_dwordx4 v[208:211], v[132:133], off offset:128
	global_load_dwordx4 v[212:215], v207, s[58:59]
	v_add_u32_e32 v130, 0x10000, v207
	global_load_dwordx4 v[216:219], v130, s[58:59]
	global_load_dwordx4 v[220:223], v[136:137], off offset:128
	global_load_dwordx4 v[224:227], v207, s[58:59] offset:128
	v_add_u32_e32 v206, 0x10080, v207
	v_add_u32_e32 v130, 0x20000, v207
	global_load_dwordx4 v[228:231], v206, s[58:59]
	v_add_u32_e32 v154, 0x30000, v207
	v_add_u32_e32 v184, 0x20080, v207
	v_add_u32_e32 v182, 0x30080, v207
	global_load_dwordx4 v[142:145], v130, s[58:59]
	global_load_dwordx4 v[138:141], v154, s[58:59]
	global_load_dwordx4 v[134:137], v184, s[58:59]
	s_nop 0
	global_load_dwordx4 v[130:133], v182, s[58:59]
	ds_write_b128 v200, v[126:129]
	ds_write_b128 v200, v[122:125] offset:64
	v_and_b32_e32 v127, 64, v199
	ds_read_b128 v[122:125], v201
	ds_read_b128 v[232:235], v201 offset:1152
	v_xor_b32_e32 v126, 8, v199
	v_add_u32_e32 v183, 64, v127
	v_cmp_lt_i32_e32 vcc, v126, v183
	v_add_u32_e32 v185, 0x4000, v202
	s_add_u32 s56, s90, s54
	v_cndmask_b32_e32 v126, v199, v126, vcc
	v_lshlrev_b32_e32 v203, 2, v126
	v_lshlrev_b32_e32 v236, 2, v185
	s_addc_u32 s57, s91, s55
	s_lshl_b64 s[12:13], s[4:5], 20
	s_add_u32 s54, s93, s12
	v_readlane_b32 s16, v253, 6
	v_readlane_b32 s17, v253, 7
	s_addc_u32 s55, s92, s13
	v_readlane_b32 s14, v253, 4
	v_readlane_b32 s15, v253, 5
	v_readlane_b32 s18, v253, 8
	v_readlane_b32 s19, v253, 9
	v_readlane_b32 s20, v253, 10
	v_readlane_b32 s21, v253, 11
	v_readlane_b32 s22, v253, 12
	v_readlane_b32 s23, v253, 13
	v_readlane_b32 s24, v253, 14
	v_readlane_b32 s25, v253, 15
	v_readlane_b32 s26, v253, 16
	v_readlane_b32 s27, v253, 17
	s_waitcnt vmcnt(0)
	v_pk_mul_f32 v[180:181], v[166:167], 0.5 op_sel_hi:[1,0]
	v_pk_mul_f32 v[178:179], v[168:169], 0.5 op_sel_hi:[1,0]
	v_pk_add_f32 v[126:127], v[188:189], 1.0 op_sel_hi:[1,0]
	v_pk_add_f32 v[128:129], v[186:187], 1.0 op_sel_hi:[1,0]
	v_pk_mul_f32 v[166:167], v[176:177], 0.5 op_sel_hi:[1,0]
	v_pk_mul_f32 v[168:169], v[174:175], 0.5 op_sel_hi:[1,0]
	v_pk_mul_f32 v[174:175], v[172:173], v[126:127]
	v_pk_mul_f32 v[176:177], v[170:171], v[128:129]
	s_waitcnt lgkmcnt(1)
	v_pk_fma_f32 v[126:127], v[180:181], v[122:123], v[212:213]
	s_waitcnt lgkmcnt(0)
	v_pk_fma_f32 v[122:123], v[180:181], v[232:233], v[216:217]
	v_pk_fma_f32 v[128:129], v[178:179], v[124:125], v[214:215]
	v_pk_fma_f32 v[124:125], v[178:179], v[234:235], v[218:219]
	v_pk_mul_f32 v[186:187], v[176:177], v[122:123]
	global_store_dwordx4 v207, v[126:129], s[56:57]
	v_pk_mul_f32 v[170:171], v[174:175], v[128:129]
	v_pk_mul_f32 v[172:173], v[176:177], v[126:127]
	v_pk_mul_f32 v[204:205], v[174:175], v[124:125]
	v_cvt_pk_bf16_f32 v188, v172, v173
	v_cvt_pk_bf16_f32 v189, v170, v171
	global_store_dwordx4 v236, v[122:125], s[56:57]
	v_cvt_pk_bf16_f32 v186, v186, v187
	v_cvt_pk_bf16_f32 v187, v204, v205
	ds_write_b128 v200, v[118:121]
	ds_write_b128 v200, v[114:117] offset:64
	ds_read_b128 v[114:117], v201
	v_pk_add_f32 v[190:191], v[210:211], 1.0 op_sel_hi:[1,0]
	v_pk_add_f32 v[118:119], v[208:209], 1.0 op_sel_hi:[1,0]
	ds_read_b128 v[208:211], v201 offset:1152
	v_pk_mul_f32 v[170:171], v[222:223], v[190:191]
	v_pk_mul_f32 v[172:173], v[220:221], v[118:119]
	s_waitcnt lgkmcnt(1)
	v_pk_fma_f32 v[120:121], v[166:167], v[116:117], v[226:227]
	v_pk_fma_f32 v[118:119], v[168:169], v[114:115], v[224:225]
	v_pk_mul_f32 v[190:191], v[170:171], v[120:121]
	v_pk_mul_f32 v[204:205], v[172:173], v[118:119]
	global_store_dwordx4 v207, v[118:121], s[56:57] offset:128
	v_cvt_pk_bf16_f32 v204, v204, v205
	v_cvt_pk_bf16_f32 v191, v190, v191
	ds_bpermute_b32 v190, v203, v204
	ds_bpermute_b32 v191, v203, v191
	s_waitcnt lgkmcnt(2)
	v_pk_fma_f32 v[116:117], v[166:167], v[210:211], v[230:231]
	v_pk_fma_f32 v[114:115], v[168:169], v[208:209], v[228:229]
	global_store_dwordx4 v206, v[114:117], s[56:57]
	v_pk_mul_f32 v[204:205], v[172:173], v[114:115]
	v_lshlrev_b32_e32 v206, 1, v202
	v_pk_mul_f32 v[208:209], v[170:171], v[116:117]
	v_cvt_pk_bf16_f32 v204, v204, v205
	s_nop 0
	v_cvt_pk_bf16_f32 v205, v208, v209
	s_waitcnt lgkmcnt(0)
	v_add_u32_e32 v250, 0xfffff040, v206
	v_cndmask_b32_e64 v250, v206, v250, s[40:41]
	v_cndmask_b32_e64 v248, v188, v190, s[40:41]
	v_cndmask_b32_e64 v249, v189, v191, s[40:41]
	global_store_dwordx2 v250, v[248:249], s[54:55]
	v_cndmask_b32_e64 v246, v190, v188, s[40:41]
	v_cndmask_b32_e64 v247, v191, v189, s[40:41]
	s_waitcnt lgkmcnt(1)
	v_add_u32_e32 v190, 0x1040, v206
	v_cndmask_b32_e64 v190, v206, v190, s[38:39]
	global_store_dwordx2 v190, v[246:247], s[54:55]
	ds_bpermute_b32 v188, v203, v204
	ds_bpermute_b32 v189, v203, v205
	v_lshlrev_b32_e32 v190, 1, v185
	s_waitcnt lgkmcnt(0)
; #define LAS __attribute__((address_space(3)))
; #define ERN_EOFF(q, m) (eb + (unsigned)((((q) & 1) * HALF + (m) * 16) * DM + ERN_COL((q) >> 1)))
;     __device__ __forceinline__ void operator()(const f32x4 (&acc)[2][2][4][2], const Unit& u, int wr, int wc, int fr, int fq) const {
;     ...
;         for (int g = 0; g < 8; ++g) { const int ai = g >> 2, m = g & 3;
;             if (g + 1 < 8) ERN_LOADX(g + 1);
;             float sq0 = 0.f, sq1 = 0.f; u32x2 hw[2][2];
; #pragma unroll
;             for (int bj = 0; bj < 2; ++bj) {
;                 *(LAS f32x4*)(st + wr_off) = acc[ai][bj][m][0]; *(LAS f32x4*)(st + wr_off + 64) = acc[ai][bj][m][1];
;                 const f32x4 a0 = *(const LAS f32x4*)(st + rd_off), a1 = *(const LAS f32x4*)(st + rd_off + 8 * 144);
;                 { const f32x4 xv = xb[g & 1][bj][0] + gv[bj] * a0; __builtin_nontemporal_store(xv, (f32x4*)((char*)xo + 4u * ERN_EOFF(g, bj, 0)));
;                   sq0 += (xv.x * xv.x + xv.y * xv.y) + (xv.z * xv.z + xv.w * xv.w);
;                   const f32x4 hv = xv * gsn[bj]; hw[bj][0].x = cvt_pk_bf16(hv.x, hv.y); hw[bj][0].y = cvt_pk_bf16(hv.z, hv.w); }
;                 { const f32x4 xv = xb[g & 1][bj][1] + gv[bj] * a1; __builtin_nontemporal_store(xv, (f32x4*)((char*)xo + 4u * ERN_EOFF(g, bj, 1)));
;                   sq1 += (xv.x * xv.x + xv.y * xv.y) + (xv.z * xv.z + xv.w * xv.w);
;                   const f32x4 hv = xv * gsn[bj]; hw[bj][1].x = cvt_pk_bf16(hv.x, hv.y); hw[bj][1].y = cvt_pk_bf16(hv.z, hv.w); }
;             }
;             if (!NOH && !PLAIN) {
; #pragma unroll
;                 for (int rh = 0; rh < 2; ++rh) { u32x2 rv; rv.x = __shfl_xor(hw[1][rh].x, 8); rv.y = __shfl_xor(hw[1][rh].y, 8);
;                     const unsigned e0 = ERN_EOFF(g, 0, rh);
;                     const unsigned ee = odd ? (e0 - DM + 32) : e0, eo2 = odd ? e0 : (e0 + DM + 32);
;                     *(u32x2*)((char*)ho + 2u * ee) = odd ? rv : hw[0][rh];
;                     *(u32x2*)((char*)ho + 2u * eo2) = odd ? hw[0][rh] : rv; }
;             }
;             if (!PLAIN) { sq0 += __shfl_xor(sq0, 1); sq0 += __shfl_xor(sq0, 2); sq0 += __shfl_xor(sq0, 4);
;             sq1 += __shfl_xor(sq1, 1); sq1 += __shfl_xor(sq1, 2); sq1 += __shfl_xor(sq1, 4); }
;             if (!PLAIN && pc == 0) { sst[g * 16 + rr] = sq0; sst[g * 16 + 8 + rr] = sq1; }
	v_add_u32_e32 v250, 0xfffff040, v190
	v_cndmask_b32_e64 v250, v190, v250, s[40:41]
	v_cndmask_b32_e64 v248, v186, v188, s[40:41]
	v_cndmask_b32_e64 v249, v187, v189, s[40:41]
	global_store_dwordx2 v250, v[248:249], s[54:55]
	v_cndmask_b32_e64 v246, v188, v186, s[40:41]
	v_cndmask_b32_e64 v247, v189, v187, s[40:41]
	v_mul_f32_e32 v119, v119, v119
	v_mul_f32_e32 v127, v127, v127
	v_mul_f32_e32 v129, v129, v129
	v_fmac_f32_e32 v119, v118, v118
	v_mul_f32_e32 v118, v121, v121
	v_fmac_f32_e32 v129, v128, v128
	v_fmac_f32_e32 v118, v120, v120
	v_mul_f32_e32 v115, v115, v115
	v_fmac_f32_e32 v127, v126, v126
	v_add_f32_e32 v118, v119, v118
	v_fmac_f32_e32 v115, v114, v114
	v_mul_f32_e32 v114, v117, v117
	v_add_f32_e32 v117, v127, v129
	v_add_f32_e32 v117, v117, v118
	v_xor_b32_e32 v118, 1, v199
	v_cmp_lt_i32_e32 vcc, v118, v183
	v_mul_f32_e32 v123, v123, v123
	v_mul_f32_e32 v125, v125, v125
	v_cndmask_b32_e32 v118, v199, v118, vcc
	v_lshlrev_b32_e32 v204, 2, v118
	ds_bpermute_b32 v118, v204, v117
	v_fmac_f32_e32 v114, v116, v116
	v_fmac_f32_e32 v125, v124, v124
	v_fmac_f32_e32 v123, v122, v122
	v_add_f32_e32 v114, v115, v114
	s_waitcnt lgkmcnt(0)
	v_add_f32_e32 v116, v117, v118
	v_xor_b32_e32 v117, 2, v199
	v_cmp_lt_i32_e32 vcc, v117, v183
	v_add_f32_e32 v115, v123, v125
	v_add_f32_e32 v115, v115, v114
	v_cndmask_b32_e32 v117, v199, v117, vcc
	v_lshlrev_b32_e32 v205, 2, v117
	ds_bpermute_b32 v117, v205, v116
	ds_bpermute_b32 v118, v204, v115
	s_waitcnt lgkmcnt(1)
	v_add_f32_e32 v114, v116, v117
	s_waitcnt lgkmcnt(0)
	v_add_f32_e32 v117, v115, v118
	ds_bpermute_b32 v118, v205, v117
	v_xor_b32_e32 v116, 4, v199
	v_cmp_lt_i32_e32 vcc, v116, v183
	s_nop 1
	v_cndmask_b32_e32 v115, v199, v116, vcc
	v_lshlrev_b32_e32 v206, 2, v115
	s_waitcnt lgkmcnt(0)
	v_add_f32_e32 v116, v117, v118
	ds_bpermute_b32 v115, v206, v114
	ds_bpermute_b32 v117, v206, v116
	v_add_u32_e32 v118, 0x1040, v190
	v_cndmask_b32_e64 v118, v190, v118, s[38:39]
	global_store_dwordx2 v118, v[246:247], s[54:55]
	s_and_saveexec_b64 s[16:17], s[42:43]
	s_cbranch_execz .LBB0_330
	s_waitcnt lgkmcnt(1)
	v_add_f32_e32 v114, v114, v115
	s_waitcnt lgkmcnt(0)
	v_add_f32_e32 v115, v116, v117
	ds_write2_b32 v194, v114, v115 offset1:8
.LBB0_330:
	s_or_b64 exec, exec, s[16:17]
	v_add_u32_e32 v114, 0x40000, v207
	v_add_u32_e32 v190, 0x50000, v207
	v_add_u32_e32 v188, 0x40080, v207
	global_load_dwordx4 v[122:125], v190, s[58:59]
	global_load_dwordx4 v[118:121], v188, s[58:59]
	v_add_u32_e32 v186, 0x50080, v207
	global_load_dwordx4 v[126:129], v114, s[58:59]
	s_waitcnt lgkmcnt(0)
	global_load_dwordx4 v[114:117], v186, s[58:59]
	ds_write_b128 v200, v[110:113]
	ds_write_b128 v200, v[106:109] offset:64
	ds_read_b128 v[106:109], v201
	ds_read_b128 v[110:113], v201 offset:1152
	v_mov_b32_e32 v185, v155
	v_mov_b32_e32 v183, v155
	s_waitcnt lgkmcnt(1)
	v_pk_fma_f32 v[108:109], v[178:179], v[108:109], v[144:145]
	v_add_u32_e32 v144, 0x8000, v202
	v_pk_fma_f32 v[106:107], v[180:181], v[106:107], v[142:143]
	v_lshlrev_b32_e32 v142, 2, v144
	global_store_dwordx4 v142, v[106:109], s[56:57]
	v_pk_mul_f32 v[142:143], v[176:177], v[106:107]
	s_waitcnt lgkmcnt(0)
	v_pk_fma_f32 v[112:113], v[178:179], v[112:113], v[140:141]
	v_pk_fma_f32 v[110:111], v[180:181], v[110:111], v[138:139]
	v_lshl_add_u64 v[138:139], s[56:57], 0, v[154:155]
	v_pk_mul_f32 v[208:209], v[174:175], v[108:109]
	v_cvt_pk_bf16_f32 v142, v142, v143
	v_pk_mul_f32 v[140:141], v[174:175], v[112:113]
	v_cvt_pk_bf16_f32 v143, v208, v209
	global_store_dwordx4 v[138:139], v[110:113], off
	v_pk_mul_f32 v[138:139], v[176:177], v[110:111]
	s_nop 0
	v_cvt_pk_bf16_f32 v138, v138, v139
	v_cvt_pk_bf16_f32 v139, v140, v141
	ds_write_b128 v200, v[102:105]
	ds_write_b128 v200, v[98:101] offset:64
	ds_read_b128 v[98:101], v201
	ds_read_b128 v[102:105], v201 offset:1152
	s_waitcnt lgkmcnt(1)
	v_pk_fma_f32 v[98:99], v[168:169], v[98:99], v[134:135]
	v_pk_fma_f32 v[100:101], v[166:167], v[100:101], v[136:137]
	v_lshl_add_u64 v[134:135], s[56:57], 0, v[184:185]
	v_pk_mul_f32 v[136:137], v[172:173], v[98:99]
	s_waitcnt lgkmcnt(0)
	v_pk_fma_f32 v[104:105], v[166:167], v[104:105], v[132:133]
	v_pk_fma_f32 v[102:103], v[168:169], v[102:103], v[130:131]
	v_lshl_add_u64 v[130:131], s[56:57], 0, v[182:183]
	global_store_dwordx4 v[134:135], v[98:101], off
	v_pk_mul_f32 v[134:135], v[170:171], v[100:101]
	v_cvt_pk_bf16_f32 v136, v136, v137
	v_pk_mul_f32 v[132:133], v[172:173], v[102:103]
	v_cvt_pk_bf16_f32 v137, v134, v135
	global_store_dwordx4 v[130:131], v[102:105], off
	ds_bpermute_b32 v130, v203, v136
	ds_bpermute_b32 v131, v203, v137
	v_pk_mul_f32 v[134:135], v[170:171], v[104:105]
	v_cvt_pk_bf16_f32 v132, v132, v133
	s_nop 0
	v_cvt_pk_bf16_f32 v133, v134, v135
	v_lshlrev_b32_e32 v134, 1, v144
	s_waitcnt lgkmcnt(0)
	v_add_u32_e32 v250, 0xfffff040, v134
	v_cndmask_b32_e64 v250, v134, v250, s[40:41]
	v_cndmask_b32_e64 v248, v142, v130, s[40:41]
	v_cndmask_b32_e64 v249, v143, v131, s[40:41]
	global_store_dwordx2 v250, v[248:249], s[54:55]
	v_cndmask_b32_e64 v246, v130, v142, s[40:41]
	v_cndmask_b32_e64 v247, v131, v143, s[40:41]
	s_waitcnt lgkmcnt(1)
	v_add_u32_e32 v130, 0x1040, v134
	v_cndmask_b32_e64 v130, v134, v130, s[38:39]
	global_store_dwordx2 v130, v[246:247], s[54:55]
	ds_bpermute_b32 v130, v203, v132
	s_waitcnt lgkmcnt(1)
	ds_bpermute_b32 v131, v203, v133
	v_add_u32_e32 v133, 0xc000, v202
	v_lshlrev_b32_e32 v132, 1, v133
	s_waitcnt lgkmcnt(0)
	v_add_u32_e32 v250, 0xfffff040, v132
	v_cndmask_b32_e64 v250, v132, v250, s[40:41]
	v_cndmask_b32_e64 v248, v138, v130, s[40:41]
	v_cndmask_b32_e64 v249, v139, v131, s[40:41]
	global_store_dwordx2 v250, v[248:249], s[54:55]
	v_cndmask_b32_e64 v246, v130, v138, s[40:41]
	v_cndmask_b32_e64 v247, v131, v139, s[40:41]
	v_mul_f32_e32 v99, v99, v99
	v_fmac_f32_e32 v99, v98, v98
	v_mul_f32_e32 v98, v101, v101
	v_mul_f32_e32 v109, v109, v109
	v_fmac_f32_e32 v98, v100, v100
	v_mul_f32_e32 v107, v107, v107
	v_fmac_f32_e32 v109, v108, v108
	v_mul_f32_e32 v108, v111, v111
	v_mul_f32_e32 v111, v113, v113
	v_add_f32_e32 v98, v99, v98
	v_mul_f32_e32 v99, v103, v103
	v_mul_f32_e32 v100, v105, v105
	v_fmac_f32_e32 v111, v112, v112
	v_fmac_f32_e32 v99, v102, v102
	v_fmac_f32_e32 v100, v104, v104
	v_fmac_f32_e32 v107, v106, v106
	v_fmac_f32_e32 v108, v110, v110
	v_add_f32_e32 v99, v99, v100
	v_add_f32_e32 v100, v107, v109
	v_add_f32_e32 v101, v108, v111
	v_add_f32_e32 v98, v100, v98
	v_add_f32_e32 v99, v101, v99
	ds_bpermute_b32 v100, v204, v98
	ds_bpermute_b32 v101, v204, v99
	s_waitcnt lgkmcnt(1)
	v_add_f32_e32 v98, v98, v100
	s_waitcnt lgkmcnt(0)
	v_add_f32_e32 v101, v99, v101
	ds_bpermute_b32 v100, v205, v98
	ds_bpermute_b32 v102, v205, v101
	s_waitcnt lgkmcnt(1)
	v_add_f32_e32 v98, v98, v100
	s_waitcnt lgkmcnt(0)
	v_add_f32_e32 v100, v101, v102
	ds_bpermute_b32 v99, v206, v98
	ds_bpermute_b32 v101, v206, v100
	v_add_u32_e32 v102, 0x1040, v132
	v_cndmask_b32_e64 v102, v132, v102, s[38:39]
	global_store_dwordx2 v102, v[246:247], s[54:55]
	s_and_saveexec_b64 s[16:17], s[42:43]
	s_cbranch_execz .LBB0_340
; #define LAS __attribute__((address_space(3)))
; #define ERN_EOFF(q, m) (eb + (unsigned)((((q) & 1) * HALF + (m) * 16) * DM + ERN_COL((q) >> 1)))
;     __device__ __forceinline__ void operator()(const f32x4 (&acc)[2][2][4][2], const Unit& u, int wr, int wc, int fr, int fq) const {
;     ...
;         for (int g = 0; g < 8; ++g) { const int ai = g >> 2, m = g & 3;
;             if (g + 1 < 8) ERN_LOADX(g + 1);
;             float sq0 = 0.f, sq1 = 0.f; u32x2 hw[2][2];
; #pragma unroll
;             for (int bj = 0; bj < 2; ++bj) {
;                 *(LAS f32x4*)(st + wr_off) = acc[ai][bj][m][0]; *(LAS f32x4*)(st + wr_off + 64) = acc[ai][bj][m][1];
;                 const f32x4 a0 = *(const LAS f32x4*)(st + rd_off), a1 = *(const LAS f32x4*)(st + rd_off + 8 * 144);
;                 { const f32x4 xv = xb[g & 1][bj][0] + gv[bj] * a0; __builtin_nontemporal_store(xv, (f32x4*)((char*)xo + 4u * ERN_EOFF(g, bj, 0)));
;                   sq0 += (xv.x * xv.x + xv.y * xv.y) + (xv.z * xv.z + xv.w * xv.w);
;                   const f32x4 hv = xv * gsn[bj]; hw[bj][0].x = cvt_pk_bf16(hv.x, hv.y); hw[bj][0].y = cvt_pk_bf16(hv.z, hv.w); }
;                 { const f32x4 xv = xb[g & 1][bj][1] + gv[bj] * a1; __builtin_nontemporal_store(xv, (f32x4*)((char*)xo + 4u * ERN_EOFF(g, bj, 1)));
;                   sq1 += (xv.x * xv.x + xv.y * xv.y) + (xv.z * xv.z + xv.w * xv.w);
;                   const f32x4 hv = xv * gsn[bj]; hw[bj][1].x = cvt_pk_bf16(hv.x, hv.y); hw[bj][1].y = cvt_pk_bf16(hv.z, hv.w); }
;             }
;             if (!NOH && !PLAIN) {
; #pragma unroll
;                 for (int rh = 0; rh < 2; ++rh) { u32x2 rv; rv.x = __shfl_xor(hw[1][rh].x, 8); rv.y = __shfl_xor(hw[1][rh].y, 8);
;                     const unsigned e0 = ERN_EOFF(g, 0, rh);
;                     const unsigned ee = odd ? (e0 - DM + 32) : e0, eo2 = odd ? e0 : (e0 + DM + 32);
;                     *(u32x2*)((char*)ho + 2u * ee) = odd ? rv : hw[0][rh];
;                     *(u32x2*)((char*)ho + 2u * eo2) = odd ? hw[0][rh] : rv; }
;             }
;             if (!PLAIN) { sq0 += __shfl_xor(sq0, 1); sq0 += __shfl_xor(sq0, 2); sq0 += __shfl_xor(sq0, 4);
;             sq1 += __shfl_xor(sq1, 1); sq1 += __shfl_xor(sq1, 2); sq1 += __shfl_xor(sq1, 4); }
;             if (!PLAIN && pc == 0) { sst[g * 16 + rr] = sq0; sst[g * 16 + 8 + rr] = sq1; }
	s_waitcnt lgkmcnt(1)
	v_add_f32_e32 v98, v98, v99
	s_waitcnt lgkmcnt(0)
	v_add_f32_e32 v99, v100, v101
	ds_write2_b32 v194, v98, v99 offset0:16 offset1:24
.LBB0_340:
	s_or_b64 exec, exec, s[16:17]
	v_add_u32_e32 v98, 0x60000, v207
	v_add_u32_e32 v154, 0x70000, v207
	v_add_u32_e32 v132, 0x60080, v207
	global_load_dwordx4 v[106:109], v154, s[58:59]
	global_load_dwordx4 v[102:105], v132, s[58:59]
	v_add_u32_e32 v130, 0x70080, v207
	global_load_dwordx4 v[110:113], v98, s[58:59]
	s_waitcnt lgkmcnt(0)
	global_load_dwordx4 v[98:101], v130, s[58:59]
	ds_write_b128 v200, v[94:97]
	ds_write_b128 v200, v[90:93] offset:64
	ds_read_b128 v[90:93], v201
	ds_read_b128 v[94:97], v201 offset:1152
	v_mov_b32_e32 v191, v155
	v_mov_b32_e32 v189, v155
	v_mov_b32_e32 v187, v155
	s_waitcnt vmcnt(11) lgkmcnt(1)
	v_pk_fma_f32 v[92:93], v[178:179], v[92:93], v[128:129]
	v_add_u32_e32 v128, 0x10000, v202
	v_pk_fma_f32 v[90:91], v[180:181], v[90:91], v[126:127]
	v_lshlrev_b32_e32 v126, 2, v128
	global_store_dwordx4 v126, v[90:93], s[56:57]
	v_pk_mul_f32 v[126:127], v[176:177], v[90:91]
	s_waitcnt lgkmcnt(0)
	v_pk_fma_f32 v[96:97], v[178:179], v[96:97], v[124:125]
	v_pk_fma_f32 v[94:95], v[180:181], v[94:95], v[122:123]
	v_lshl_add_u64 v[122:123], s[56:57], 0, v[190:191]
	v_pk_mul_f32 v[134:135], v[174:175], v[92:93]
	v_cvt_pk_bf16_f32 v126, v126, v127
	v_pk_mul_f32 v[124:125], v[174:175], v[96:97]
	v_cvt_pk_bf16_f32 v127, v134, v135
	global_store_dwordx4 v[122:123], v[94:97], off
	v_pk_mul_f32 v[122:123], v[176:177], v[94:95]
	s_nop 0
	v_cvt_pk_bf16_f32 v122, v122, v123
	v_cvt_pk_bf16_f32 v123, v124, v125
	ds_write_b128 v200, v[86:89]
	ds_write_b128 v200, v[82:85] offset:64
	ds_read_b128 v[82:85], v201
	ds_read_b128 v[86:89], v201 offset:1152
	s_waitcnt lgkmcnt(1)
	v_pk_fma_f32 v[82:83], v[168:169], v[82:83], v[118:119]
	v_pk_fma_f32 v[84:85], v[166:167], v[84:85], v[120:121]
	v_lshl_add_u64 v[118:119], s[56:57], 0, v[188:189]
	v_pk_mul_f32 v[120:121], v[172:173], v[82:83]
	s_waitcnt vmcnt(12) lgkmcnt(0)
	v_pk_fma_f32 v[88:89], v[166:167], v[88:89], v[116:117]
	v_pk_fma_f32 v[86:87], v[168:169], v[86:87], v[114:115]
	v_lshl_add_u64 v[114:115], s[56:57], 0, v[186:187]
	global_store_dwordx4 v[118:119], v[82:85], off
	v_pk_mul_f32 v[118:119], v[170:171], v[84:85]
	v_cvt_pk_bf16_f32 v120, v120, v121
	v_pk_mul_f32 v[116:117], v[172:173], v[86:87]
	v_cvt_pk_bf16_f32 v121, v118, v119
	global_store_dwordx4 v[114:115], v[86:89], off
	ds_bpermute_b32 v114, v203, v120
	ds_bpermute_b32 v115, v203, v121
	v_pk_mul_f32 v[118:119], v[170:171], v[88:89]
	v_cvt_pk_bf16_f32 v116, v116, v117
	s_nop 0
	v_cvt_pk_bf16_f32 v117, v118, v119
	v_lshlrev_b32_e32 v118, 1, v128
	s_waitcnt lgkmcnt(0)
	v_add_u32_e32 v250, 0xfffff040, v118
	v_cndmask_b32_e64 v250, v118, v250, s[40:41]
	v_cndmask_b32_e64 v248, v126, v114, s[40:41]
	v_cndmask_b32_e64 v249, v127, v115, s[40:41]
	global_store_dwordx2 v250, v[248:249], s[54:55]
	v_cndmask_b32_e64 v246, v114, v126, s[40:41]
	v_cndmask_b32_e64 v247, v115, v127, s[40:41]
	s_waitcnt lgkmcnt(1)
	v_add_u32_e32 v114, 0x1040, v118
	v_cndmask_b32_e64 v114, v118, v114, s[38:39]
	global_store_dwordx2 v114, v[246:247], s[54:55]
	ds_bpermute_b32 v114, v203, v116
	s_waitcnt lgkmcnt(1)
	ds_bpermute_b32 v115, v203, v117
	v_add_u32_e32 v117, 0x14000, v202
	v_lshlrev_b32_e32 v116, 1, v117
	s_waitcnt lgkmcnt(0)
	v_add_u32_e32 v250, 0xfffff040, v116
	v_cndmask_b32_e64 v250, v116, v250, s[40:41]
	v_cndmask_b32_e64 v248, v122, v114, s[40:41]
	v_cndmask_b32_e64 v249, v123, v115, s[40:41]
	global_store_dwordx2 v250, v[248:249], s[54:55]
	v_cndmask_b32_e64 v246, v114, v122, s[40:41]
	v_cndmask_b32_e64 v247, v115, v123, s[40:41]
	v_mul_f32_e32 v83, v83, v83
	v_fmac_f32_e32 v83, v82, v82
	v_mul_f32_e32 v82, v85, v85
	v_mul_f32_e32 v93, v93, v93
	v_fmac_f32_e32 v82, v84, v84
	v_mul_f32_e32 v91, v91, v91
	v_fmac_f32_e32 v93, v92, v92
	v_mul_f32_e32 v92, v95, v95
	v_mul_f32_e32 v95, v97, v97
	v_add_f32_e32 v82, v83, v82
	v_mul_f32_e32 v83, v87, v87
	v_mul_f32_e32 v84, v89, v89
	v_fmac_f32_e32 v95, v96, v96
	v_fmac_f32_e32 v83, v86, v86
	v_fmac_f32_e32 v84, v88, v88
	v_fmac_f32_e32 v91, v90, v90
	v_fmac_f32_e32 v92, v94, v94
	v_add_f32_e32 v83, v83, v84
	v_add_f32_e32 v84, v91, v93
	v_add_f32_e32 v85, v92, v95
	v_add_f32_e32 v82, v84, v82
	v_add_f32_e32 v83, v85, v83
	ds_bpermute_b32 v84, v204, v82
	ds_bpermute_b32 v85, v204, v83
	s_waitcnt lgkmcnt(1)
	v_add_f32_e32 v82, v82, v84
	s_waitcnt lgkmcnt(0)
	v_add_f32_e32 v85, v83, v85
	ds_bpermute_b32 v84, v205, v82
	ds_bpermute_b32 v86, v205, v85
	s_waitcnt lgkmcnt(1)
	v_add_f32_e32 v82, v82, v84
	s_waitcnt lgkmcnt(0)
	v_add_f32_e32 v84, v85, v86
	ds_bpermute_b32 v83, v206, v82
	ds_bpermute_b32 v85, v206, v84
	v_add_u32_e32 v86, 0x1040, v116
	v_cndmask_b32_e64 v86, v116, v86, s[38:39]
	global_store_dwordx2 v86, v[246:247], s[54:55]
	s_and_saveexec_b64 s[16:17], s[42:43]
	s_cbranch_execz .LBB0_350
	s_waitcnt lgkmcnt(1)
	v_add_f32_e32 v82, v82, v83
	s_waitcnt lgkmcnt(0)
	v_add_f32_e32 v83, v84, v85
	ds_write2_b32 v194, v82, v83 offset0:32 offset1:40
; #define LAS __attribute__((address_space(3)))
; #define ERN_EOFF(q, m) (eb + (unsigned)((((q) & 1) * HALF + (m) * 16) * DM + ERN_COL((q) >> 1)))
;     __device__ __forceinline__ void operator()(const f32x4 (&acc)[2][2][4][2], const Unit& u, int wr, int wc, int fr, int fq) const {
;     ...
;         for (int g = 0; g < 8; ++g) { const int ai = g >> 2, m = g & 3;
;             if (g + 1 < 8) ERN_LOADX(g + 1);
;             float sq0 = 0.f, sq1 = 0.f; u32x2 hw[2][2];
; #pragma unroll
;             for (int bj = 0; bj < 2; ++bj) {
;                 *(LAS f32x4*)(st + wr_off) = acc[ai][bj][m][0]; *(LAS f32x4*)(st + wr_off + 64) = acc[ai][bj][m][1];
;                 const f32x4 a0 = *(const LAS f32x4*)(st + rd_off), a1 = *(const LAS f32x4*)(st + rd_off + 8 * 144);
;                 { const f32x4 xv = xb[g & 1][bj][0] + gv[bj] * a0; __builtin_nontemporal_store(xv, (f32x4*)((char*)xo + 4u * ERN_EOFF(g, bj, 0)));
;                   sq0 += (xv.x * xv.x + xv.y * xv.y) + (xv.z * xv.z + xv.w * xv.w);
;                   const f32x4 hv = xv * gsn[bj]; hw[bj][0].x = cvt_pk_bf16(hv.x, hv.y); hw[bj][0].y = cvt_pk_bf16(hv.z, hv.w); }
;                 { const f32x4 xv = xb[g & 1][bj][1] + gv[bj] * a1; __builtin_nontemporal_store(xv, (f32x4*)((char*)xo + 4u * ERN_EOFF(g, bj, 1)));
;                   sq1 += (xv.x * xv.x + xv.y * xv.y) + (xv.z * xv.z + xv.w * xv.w);
;                   const f32x4 hv = xv * gsn[bj]; hw[bj][1].x = cvt_pk_bf16(hv.x, hv.y); hw[bj][1].y = cvt_pk_bf16(hv.z, hv.w); }
;             }
;             if (!NOH && !PLAIN) {
; #pragma unroll
;                 for (int rh = 0; rh < 2; ++rh) { u32x2 rv; rv.x = __shfl_xor(hw[1][rh].x, 8); rv.y = __shfl_xor(hw[1][rh].y, 8);
;                     const unsigned e0 = ERN_EOFF(g, 0, rh);
;                     const unsigned ee = odd ? (e0 - DM + 32) : e0, eo2 = odd ? e0 : (e0 + DM + 32);
;                     *(u32x2*)((char*)ho + 2u * ee) = odd ? rv : hw[0][rh];
;                     *(u32x2*)((char*)ho + 2u * eo2) = odd ? hw[0][rh] : rv; }
;             }
;             if (!PLAIN) { sq0 += __shfl_xor(sq0, 1); sq0 += __shfl_xor(sq0, 2); sq0 += __shfl_xor(sq0, 4);
;             sq1 += __shfl_xor(sq1, 1); sq1 += __shfl_xor(sq1, 2); sq1 += __shfl_xor(sq1, 4); }
;             if (!PLAIN && pc == 0) { sst[g * 16 + rr] = sq0; sst[g * 16 + 8 + rr] = sq1; }
.LBB0_350:
	s_or_b64 exec, exec, s[16:17]
	v_add_u32_e32 v82, 0x100000, v207
	s_waitcnt lgkmcnt(1)
	v_add_u32_e32 v83, 0x110000, v207
	v_add_u32_e32 v116, 0x100080, v207
	global_load_dwordx4 v[94:97], v82, s[58:59]
	global_load_dwordx4 v[90:93], v83, s[58:59]
	v_add_u32_e32 v114, 0x110080, v207
	global_load_dwordx4 v[86:89], v116, s[58:59]
	s_waitcnt lgkmcnt(0)
	global_load_dwordx4 v[82:85], v114, s[58:59]
	ds_write_b128 v200, v[78:81]
	ds_write_b128 v200, v[74:77] offset:64
	ds_read_b128 v[74:77], v201
	ds_read_b128 v[78:81], v201 offset:1152
	v_mov_b32_e32 v133, v155
	v_mov_b32_e32 v131, v155
	s_waitcnt vmcnt(11) lgkmcnt(1)
	v_pk_fma_f32 v[76:77], v[178:179], v[76:77], v[112:113]
	v_add_u32_e32 v112, 0x18000, v202
	v_pk_fma_f32 v[74:75], v[180:181], v[74:75], v[110:111]
	v_lshlrev_b32_e32 v110, 2, v112
	global_store_dwordx4 v110, v[74:77], s[56:57]
	v_pk_mul_f32 v[110:111], v[176:177], v[74:75]
	s_waitcnt lgkmcnt(0)
	v_pk_fma_f32 v[80:81], v[178:179], v[80:81], v[108:109]
	v_pk_fma_f32 v[78:79], v[180:181], v[78:79], v[106:107]
	v_lshl_add_u64 v[106:107], s[56:57], 0, v[154:155]
	v_pk_mul_f32 v[118:119], v[174:175], v[76:77]
	v_cvt_pk_bf16_f32 v110, v110, v111
	v_pk_mul_f32 v[108:109], v[174:175], v[80:81]
	v_cvt_pk_bf16_f32 v111, v118, v119
	global_store_dwordx4 v[106:107], v[78:81], off
	v_pk_mul_f32 v[106:107], v[176:177], v[78:79]
	s_nop 0
	v_cvt_pk_bf16_f32 v106, v106, v107
	v_cvt_pk_bf16_f32 v107, v108, v109
	ds_write_b128 v200, v[70:73]
	ds_write_b128 v200, v[66:69] offset:64
	ds_read_b128 v[66:69], v201
	ds_read_b128 v[70:73], v201 offset:1152
	s_waitcnt lgkmcnt(1)
	v_pk_fma_f32 v[66:67], v[168:169], v[66:67], v[102:103]
	v_pk_fma_f32 v[68:69], v[166:167], v[68:69], v[104:105]
	v_lshl_add_u64 v[102:103], s[56:57], 0, v[132:133]
	v_pk_mul_f32 v[104:105], v[172:173], v[66:67]
	s_waitcnt vmcnt(12) lgkmcnt(0)
	v_pk_fma_f32 v[72:73], v[166:167], v[72:73], v[100:101]
	v_pk_fma_f32 v[70:71], v[168:169], v[70:71], v[98:99]
	v_lshl_add_u64 v[98:99], s[56:57], 0, v[130:131]
	global_store_dwordx4 v[102:103], v[66:69], off
	v_pk_mul_f32 v[102:103], v[170:171], v[68:69]
	v_cvt_pk_bf16_f32 v104, v104, v105
	v_pk_mul_f32 v[100:101], v[172:173], v[70:71]
	v_cvt_pk_bf16_f32 v105, v102, v103
	global_store_dwordx4 v[98:99], v[70:73], off
	ds_bpermute_b32 v98, v203, v104
	ds_bpermute_b32 v99, v203, v105
	v_pk_mul_f32 v[102:103], v[170:171], v[72:73]
	v_cvt_pk_bf16_f32 v100, v100, v101
	s_nop 0
	v_cvt_pk_bf16_f32 v101, v102, v103
	v_lshlrev_b32_e32 v102, 1, v112
	s_waitcnt lgkmcnt(0)
	v_add_u32_e32 v250, 0xfffff040, v102
	v_cndmask_b32_e64 v250, v102, v250, s[40:41]
	v_cndmask_b32_e64 v248, v110, v98, s[40:41]
	v_cndmask_b32_e64 v249, v111, v99, s[40:41]
	global_store_dwordx2 v250, v[248:249], s[54:55]
	v_cndmask_b32_e64 v246, v98, v110, s[40:41]
	v_cndmask_b32_e64 v247, v99, v111, s[40:41]
	s_waitcnt lgkmcnt(1)
	v_add_u32_e32 v98, 0x1040, v102
	v_cndmask_b32_e64 v98, v102, v98, s[38:39]
	global_store_dwordx2 v98, v[246:247], s[54:55]
	ds_bpermute_b32 v98, v203, v100
	s_waitcnt lgkmcnt(1)
	ds_bpermute_b32 v99, v203, v101
	v_add_u32_e32 v101, 0x1c000, v202
	v_lshlrev_b32_e32 v100, 1, v101
	s_waitcnt lgkmcnt(0)
	v_add_u32_e32 v250, 0xfffff040, v100
	v_cndmask_b32_e64 v250, v100, v250, s[40:41]
	v_cndmask_b32_e64 v248, v106, v98, s[40:41]
	v_cndmask_b32_e64 v249, v107, v99, s[40:41]
	global_store_dwordx2 v250, v[248:249], s[54:55]
	v_cndmask_b32_e64 v246, v98, v106, s[40:41]
	v_cndmask_b32_e64 v247, v99, v107, s[40:41]
	v_mul_f32_e32 v67, v67, v67
	v_fmac_f32_e32 v67, v66, v66
	v_mul_f32_e32 v66, v69, v69
	v_mul_f32_e32 v77, v77, v77
	v_fmac_f32_e32 v66, v68, v68
	v_mul_f32_e32 v75, v75, v75
	v_fmac_f32_e32 v77, v76, v76
	v_mul_f32_e32 v76, v79, v79
	v_mul_f32_e32 v79, v81, v81
	v_add_f32_e32 v66, v67, v66
	v_mul_f32_e32 v67, v71, v71
	v_mul_f32_e32 v68, v73, v73
	v_fmac_f32_e32 v79, v80, v80
	v_fmac_f32_e32 v67, v70, v70
	v_fmac_f32_e32 v68, v72, v72
	v_fmac_f32_e32 v75, v74, v74
	v_fmac_f32_e32 v76, v78, v78
	v_add_f32_e32 v67, v67, v68
	v_add_f32_e32 v68, v75, v77
	v_add_f32_e32 v69, v76, v79
	v_add_f32_e32 v66, v68, v66
	v_add_f32_e32 v67, v69, v67
	ds_bpermute_b32 v68, v204, v66
	ds_bpermute_b32 v69, v204, v67
	s_waitcnt lgkmcnt(1)
	v_add_f32_e32 v66, v66, v68
	s_waitcnt lgkmcnt(0)
	v_add_f32_e32 v69, v67, v69
	ds_bpermute_b32 v68, v205, v66
	ds_bpermute_b32 v70, v205, v69
	s_waitcnt lgkmcnt(1)
	v_add_f32_e32 v66, v66, v68
	s_waitcnt lgkmcnt(0)
	v_add_f32_e32 v68, v69, v70
	ds_bpermute_b32 v67, v206, v66
	ds_bpermute_b32 v69, v206, v68
	v_add_u32_e32 v70, 0x1040, v100
	v_cndmask_b32_e64 v70, v100, v70, s[38:39]
	global_store_dwordx2 v70, v[246:247], s[54:55]
	s_and_saveexec_b64 s[16:17], s[42:43]
	s_cbranch_execz .LBB0_360
	s_waitcnt lgkmcnt(1)
	v_add_f32_e32 v66, v66, v67
	s_waitcnt lgkmcnt(0)
	v_add_f32_e32 v67, v68, v69
	ds_write2_b32 v194, v66, v67 offset0:48 offset1:56
; #define LAS __attribute__((address_space(3)))
; #define ERN_EOFF(q, m) (eb + (unsigned)((((q) & 1) * HALF + (m) * 16) * DM + ERN_COL((q) >> 1)))
;     __device__ __forceinline__ void operator()(const f32x4 (&acc)[2][2][4][2], const Unit& u, int wr, int wc, int fr, int fq) const {
;     ...
;         for (int g = 0; g < 8; ++g) { const int ai = g >> 2, m = g & 3;
;             if (g + 1 < 8) ERN_LOADX(g + 1);
;             float sq0 = 0.f, sq1 = 0.f; u32x2 hw[2][2];
; #pragma unroll
;             for (int bj = 0; bj < 2; ++bj) {
;                 *(LAS f32x4*)(st + wr_off) = acc[ai][bj][m][0]; *(LAS f32x4*)(st + wr_off + 64) = acc[ai][bj][m][1];
;                 const f32x4 a0 = *(const LAS f32x4*)(st + rd_off), a1 = *(const LAS f32x4*)(st + rd_off + 8 * 144);
;                 { const f32x4 xv = xb[g & 1][bj][0] + gv[bj] * a0; __builtin_nontemporal_store(xv, (f32x4*)((char*)xo + 4u * ERN_EOFF(g, bj, 0)));
;                   sq0 += (xv.x * xv.x + xv.y * xv.y) + (xv.z * xv.z + xv.w * xv.w);
;                   const f32x4 hv = xv * gsn[bj]; hw[bj][0].x = cvt_pk_bf16(hv.x, hv.y); hw[bj][0].y = cvt_pk_bf16(hv.z, hv.w); }
;                 { const f32x4 xv = xb[g & 1][bj][1] + gv[bj] * a1; __builtin_nontemporal_store(xv, (f32x4*)((char*)xo + 4u * ERN_EOFF(g, bj, 1)));
;                   sq1 += (xv.x * xv.x + xv.y * xv.y) + (xv.z * xv.z + xv.w * xv.w);
;                   const f32x4 hv = xv * gsn[bj]; hw[bj][1].x = cvt_pk_bf16(hv.x, hv.y); hw[bj][1].y = cvt_pk_bf16(hv.z, hv.w); }
;             }
;             if (!NOH && !PLAIN) {
; #pragma unroll
;                 for (int rh = 0; rh < 2; ++rh) { u32x2 rv; rv.x = __shfl_xor(hw[1][rh].x, 8); rv.y = __shfl_xor(hw[1][rh].y, 8);
;                     const unsigned e0 = ERN_EOFF(g, 0, rh);
;                     const unsigned ee = odd ? (e0 - DM + 32) : e0, eo2 = odd ? e0 : (e0 + DM + 32);
;                     *(u32x2*)((char*)ho + 2u * ee) = odd ? rv : hw[0][rh];
;                     *(u32x2*)((char*)ho + 2u * eo2) = odd ? hw[0][rh] : rv; }
;             }
;             if (!PLAIN) { sq0 += __shfl_xor(sq0, 1); sq0 += __shfl_xor(sq0, 2); sq0 += __shfl_xor(sq0, 4);
;             sq1 += __shfl_xor(sq1, 1); sq1 += __shfl_xor(sq1, 2); sq1 += __shfl_xor(sq1, 4); }
;             if (!PLAIN && pc == 0) { sst[g * 16 + rr] = sq0; sst[g * 16 + 8 + rr] = sq1; }
.LBB0_360:
	s_or_b64 exec, exec, s[16:17]
	v_add_u32_e32 v154, 0x120000, v207
	v_add_u32_e32 v100, 0x120080, v207
	v_add_u32_e32 v102, 0x130000, v207
	global_load_dwordx4 v[78:81], v154, s[58:59]
	global_load_dwordx4 v[74:77], v102, s[58:59]
	v_add_u32_e32 v98, 0x130080, v207
	global_load_dwordx4 v[70:73], v100, s[58:59]
	s_waitcnt lgkmcnt(0)
	global_load_dwordx4 v[66:69], v98, s[58:59]
	ds_write_b128 v200, v[62:65]
	ds_write_b128 v200, v[58:61] offset:64
	ds_read_b128 v[58:61], v201
	ds_read_b128 v[62:65], v201 offset:1152
	v_mov_b32_e32 v117, v155
	v_mov_b32_e32 v115, v155
	s_waitcnt vmcnt(13) lgkmcnt(1)
	v_pk_fma_f32 v[60:61], v[178:179], v[60:61], v[96:97]
	v_add_u32_e32 v96, 0x40000, v202
	v_pk_fma_f32 v[58:59], v[180:181], v[58:59], v[94:95]
	v_lshlrev_b32_e32 v94, 2, v96
	s_waitcnt vmcnt(12) lgkmcnt(0)
	v_pk_fma_f32 v[64:65], v[178:179], v[64:65], v[92:93]
	v_add_u32_e32 v92, 0x44000, v202
	global_store_dwordx4 v94, v[58:61], s[56:57]
	v_pk_mul_f32 v[94:95], v[176:177], v[58:59]
	v_pk_fma_f32 v[62:63], v[180:181], v[62:63], v[90:91]
	v_lshlrev_b32_e32 v90, 2, v92
	v_pk_mul_f32 v[104:105], v[174:175], v[60:61]
	v_cvt_pk_bf16_f32 v94, v94, v95
	s_nop 0
	v_cvt_pk_bf16_f32 v95, v104, v105
	global_store_dwordx4 v90, v[62:65], s[56:57]
	v_pk_mul_f32 v[90:91], v[176:177], v[62:63]
	v_pk_mul_f32 v[104:105], v[174:175], v[64:65]
	v_cvt_pk_bf16_f32 v90, v90, v91
	s_nop 0
	v_cvt_pk_bf16_f32 v91, v104, v105
	ds_write_b128 v200, v[54:57]
	ds_write_b128 v200, v[50:53] offset:64
	ds_read_b128 v[50:53], v201
	ds_read_b128 v[54:57], v201 offset:1152
	s_waitcnt vmcnt(13) lgkmcnt(1)
	v_pk_fma_f32 v[50:51], v[168:169], v[50:51], v[86:87]
	v_pk_fma_f32 v[52:53], v[166:167], v[52:53], v[88:89]
	v_lshl_add_u64 v[86:87], s[56:57], 0, v[116:117]
	v_pk_mul_f32 v[88:89], v[172:173], v[50:51]
	s_waitcnt vmcnt(12) lgkmcnt(0)
	v_pk_fma_f32 v[56:57], v[166:167], v[56:57], v[84:85]
	v_pk_fma_f32 v[54:55], v[168:169], v[54:55], v[82:83]
	v_lshl_add_u64 v[82:83], s[56:57], 0, v[114:115]
	global_store_dwordx4 v[86:87], v[50:53], off
	v_pk_mul_f32 v[86:87], v[170:171], v[52:53]
	v_cvt_pk_bf16_f32 v88, v88, v89
	v_pk_mul_f32 v[84:85], v[172:173], v[54:55]
	v_cvt_pk_bf16_f32 v89, v86, v87
	global_store_dwordx4 v[82:83], v[54:57], off
	ds_bpermute_b32 v82, v203, v88
	ds_bpermute_b32 v83, v203, v89
	v_pk_mul_f32 v[86:87], v[170:171], v[56:57]
	v_cvt_pk_bf16_f32 v84, v84, v85
	s_nop 0
	v_cvt_pk_bf16_f32 v85, v86, v87
	v_lshlrev_b32_e32 v86, 1, v96
	s_waitcnt lgkmcnt(0)
	v_add_u32_e32 v250, 0xfffff040, v86
	v_cndmask_b32_e64 v250, v86, v250, s[40:41]
	v_cndmask_b32_e64 v248, v94, v82, s[40:41]
	v_cndmask_b32_e64 v249, v95, v83, s[40:41]
	global_store_dwordx2 v250, v[248:249], s[54:55]
	v_cndmask_b32_e64 v246, v82, v94, s[40:41]
	v_cndmask_b32_e64 v247, v83, v95, s[40:41]
	s_waitcnt lgkmcnt(1)
	v_add_u32_e32 v82, 0x1040, v86
	v_cndmask_b32_e64 v82, v86, v82, s[38:39]
	global_store_dwordx2 v82, v[246:247], s[54:55]
	ds_bpermute_b32 v82, v203, v84
	s_waitcnt lgkmcnt(1)
	ds_bpermute_b32 v83, v203, v85
	v_lshlrev_b32_e32 v84, 1, v92
	s_waitcnt lgkmcnt(0)
	v_add_u32_e32 v250, 0xfffff040, v84
	v_cndmask_b32_e64 v250, v84, v250, s[40:41]
	v_cndmask_b32_e64 v248, v90, v82, s[40:41]
	v_cndmask_b32_e64 v249, v91, v83, s[40:41]
	global_store_dwordx2 v250, v[248:249], s[54:55]
	v_cndmask_b32_e64 v246, v82, v90, s[40:41]
	v_cndmask_b32_e64 v247, v83, v91, s[40:41]
	v_mul_f32_e32 v51, v51, v51
	v_fmac_f32_e32 v51, v50, v50
	v_mul_f32_e32 v50, v53, v53
	v_mul_f32_e32 v61, v61, v61
	v_fmac_f32_e32 v50, v52, v52
	v_mul_f32_e32 v59, v59, v59
	v_fmac_f32_e32 v61, v60, v60
	v_mul_f32_e32 v60, v63, v63
	v_mul_f32_e32 v63, v65, v65
	v_add_f32_e32 v50, v51, v50
	v_mul_f32_e32 v51, v55, v55
	v_mul_f32_e32 v52, v57, v57
	v_fmac_f32_e32 v63, v64, v64
	v_fmac_f32_e32 v51, v54, v54
	v_fmac_f32_e32 v52, v56, v56
	v_fmac_f32_e32 v59, v58, v58
	v_fmac_f32_e32 v60, v62, v62
	v_add_f32_e32 v51, v51, v52
	v_add_f32_e32 v52, v59, v61
	v_add_f32_e32 v53, v60, v63
	v_add_f32_e32 v50, v52, v50
	v_add_f32_e32 v51, v53, v51
	ds_bpermute_b32 v52, v204, v50
	ds_bpermute_b32 v53, v204, v51
	s_waitcnt lgkmcnt(1)
	v_add_f32_e32 v50, v50, v52
	s_waitcnt lgkmcnt(0)
	v_add_f32_e32 v53, v51, v53
	ds_bpermute_b32 v52, v205, v50
	ds_bpermute_b32 v54, v205, v53
	s_waitcnt lgkmcnt(1)
	v_add_f32_e32 v50, v50, v52
	s_waitcnt lgkmcnt(0)
	v_add_f32_e32 v52, v53, v54
	ds_bpermute_b32 v51, v206, v50
	ds_bpermute_b32 v53, v206, v52
	v_add_u32_e32 v54, 0x1040, v84
	v_cndmask_b32_e64 v54, v84, v54, s[38:39]
	global_store_dwordx2 v54, v[246:247], s[54:55]
	s_and_saveexec_b64 s[16:17], s[42:43]
	s_cbranch_execz .LBB0_370
	s_waitcnt lgkmcnt(1)
	v_add_f32_e32 v50, v50, v51
	s_waitcnt lgkmcnt(0)
	v_add_f32_e32 v51, v52, v53
	ds_write2_b32 v194, v50, v51 offset0:64 offset1:72
; #define LAS __attribute__((address_space(3)))
; #define ERN_EOFF(q, m) (eb + (unsigned)((((q) & 1) * HALF + (m) * 16) * DM + ERN_COL((q) >> 1)))
;     __device__ __forceinline__ void operator()(const f32x4 (&acc)[2][2][4][2], const Unit& u, int wr, int wc, int fr, int fq) const {
;     ...
;         for (int g = 0; g < 8; ++g) { const int ai = g >> 2, m = g & 3;
;             if (g + 1 < 8) ERN_LOADX(g + 1);
;             float sq0 = 0.f, sq1 = 0.f; u32x2 hw[2][2];
; #pragma unroll
;             for (int bj = 0; bj < 2; ++bj) {
;                 *(LAS f32x4*)(st + wr_off) = acc[ai][bj][m][0]; *(LAS f32x4*)(st + wr_off + 64) = acc[ai][bj][m][1];
;                 const f32x4 a0 = *(const LAS f32x4*)(st + rd_off), a1 = *(const LAS f32x4*)(st + rd_off + 8 * 144);
;                 { const f32x4 xv = xb[g & 1][bj][0] + gv[bj] * a0; __builtin_nontemporal_store(xv, (f32x4*)((char*)xo + 4u * ERN_EOFF(g, bj, 0)));
;                   sq0 += (xv.x * xv.x + xv.y * xv.y) + (xv.z * xv.z + xv.w * xv.w);
;                   const f32x4 hv = xv * gsn[bj]; hw[bj][0].x = cvt_pk_bf16(hv.x, hv.y); hw[bj][0].y = cvt_pk_bf16(hv.z, hv.w); }
;                 { const f32x4 xv = xb[g & 1][bj][1] + gv[bj] * a1; __builtin_nontemporal_store(xv, (f32x4*)((char*)xo + 4u * ERN_EOFF(g, bj, 1)));
;                   sq1 += (xv.x * xv.x + xv.y * xv.y) + (xv.z * xv.z + xv.w * xv.w);
;                   const f32x4 hv = xv * gsn[bj]; hw[bj][1].x = cvt_pk_bf16(hv.x, hv.y); hw[bj][1].y = cvt_pk_bf16(hv.z, hv.w); }
;             }
;             if (!NOH && !PLAIN) {
; #pragma unroll
;                 for (int rh = 0; rh < 2; ++rh) { u32x2 rv; rv.x = __shfl_xor(hw[1][rh].x, 8); rv.y = __shfl_xor(hw[1][rh].y, 8);
;                     const unsigned e0 = ERN_EOFF(g, 0, rh);
;                     const unsigned ee = odd ? (e0 - DM + 32) : e0, eo2 = odd ? e0 : (e0 + DM + 32);
;                     *(u32x2*)((char*)ho + 2u * ee) = odd ? rv : hw[0][rh];
;                     *(u32x2*)((char*)ho + 2u * eo2) = odd ? hw[0][rh] : rv; }
;             }
;             if (!PLAIN) { sq0 += __shfl_xor(sq0, 1); sq0 += __shfl_xor(sq0, 2); sq0 += __shfl_xor(sq0, 4);
;             sq1 += __shfl_xor(sq1, 1); sq1 += __shfl_xor(sq1, 2); sq1 += __shfl_xor(sq1, 4); }
;             if (!PLAIN && pc == 0) { sst[g * 16 + rr] = sq0; sst[g * 16 + 8 + rr] = sq1; }
.LBB0_370:
	s_or_b64 exec, exec, s[16:17]
	v_add_u32_e32 v88, 0x140000, v207
	v_add_u32_e32 v84, 0x140080, v207
	v_add_u32_e32 v86, 0x150000, v207
	global_load_dwordx4 v[62:65], v88, s[58:59]
	global_load_dwordx4 v[58:61], v86, s[58:59]
	v_add_u32_e32 v82, 0x150080, v207
	global_load_dwordx4 v[54:57], v84, s[58:59]
	s_waitcnt lgkmcnt(0)
	global_load_dwordx4 v[50:53], v82, s[58:59]
	ds_write_b128 v200, v[46:49]
	ds_write_b128 v200, v[42:45] offset:64
	ds_read_b128 v[42:45], v201
	ds_read_b128 v[46:49], v201 offset:1152
	v_mov_b32_e32 v103, v155
	v_mov_b32_e32 v101, v155
	v_mov_b32_e32 v99, v155
	s_waitcnt vmcnt(13) lgkmcnt(1)
	v_pk_fma_f32 v[44:45], v[178:179], v[44:45], v[80:81]
	v_pk_fma_f32 v[42:43], v[180:181], v[42:43], v[78:79]
	v_lshl_add_u64 v[78:79], s[56:57], 0, v[154:155]
	global_store_dwordx4 v[78:79], v[42:45], off
	v_pk_mul_f32 v[78:79], v[176:177], v[42:43]
	s_waitcnt vmcnt(13) lgkmcnt(0)
	v_pk_fma_f32 v[48:49], v[178:179], v[48:49], v[76:77]
	v_pk_fma_f32 v[46:47], v[180:181], v[46:47], v[74:75]
	v_lshl_add_u64 v[74:75], s[56:57], 0, v[102:103]
	v_pk_mul_f32 v[80:81], v[174:175], v[44:45]
	v_cvt_pk_bf16_f32 v78, v78, v79
	v_pk_mul_f32 v[76:77], v[174:175], v[48:49]
	v_cvt_pk_bf16_f32 v79, v80, v81
	global_store_dwordx4 v[74:75], v[46:49], off
	v_pk_mul_f32 v[74:75], v[176:177], v[46:47]
	s_nop 0
	v_cvt_pk_bf16_f32 v74, v74, v75
	v_cvt_pk_bf16_f32 v75, v76, v77
	ds_write_b128 v200, v[38:41]
	ds_write_b128 v200, v[34:37] offset:64
	ds_read_b128 v[34:37], v201
	ds_read_b128 v[38:41], v201 offset:1152
	s_waitcnt vmcnt(13) lgkmcnt(1)
	v_pk_fma_f32 v[34:35], v[168:169], v[34:35], v[70:71]
	v_pk_fma_f32 v[36:37], v[166:167], v[36:37], v[72:73]
	v_lshl_add_u64 v[70:71], s[56:57], 0, v[100:101]
	v_pk_mul_f32 v[72:73], v[172:173], v[34:35]
	s_waitcnt vmcnt(12) lgkmcnt(0)
	v_pk_fma_f32 v[40:41], v[166:167], v[40:41], v[68:69]
	v_pk_fma_f32 v[38:39], v[168:169], v[38:39], v[66:67]
	v_lshl_add_u64 v[66:67], s[56:57], 0, v[98:99]
	global_store_dwordx4 v[70:71], v[34:37], off
	v_pk_mul_f32 v[70:71], v[170:171], v[36:37]
	v_cvt_pk_bf16_f32 v72, v72, v73
	v_pk_mul_f32 v[68:69], v[172:173], v[38:39]
	v_cvt_pk_bf16_f32 v73, v70, v71
	global_store_dwordx4 v[66:67], v[38:41], off
	ds_bpermute_b32 v66, v203, v72
	ds_bpermute_b32 v67, v203, v73
	v_pk_mul_f32 v[70:71], v[170:171], v[40:41]
	v_cvt_pk_bf16_f32 v68, v68, v69
	s_nop 0
	v_cvt_pk_bf16_f32 v69, v70, v71
	v_add_u32_e32 v71, 0x48000, v202
	v_lshlrev_b32_e32 v70, 1, v71
	s_waitcnt lgkmcnt(0)
	v_add_u32_e32 v250, 0xfffff040, v70
	v_cndmask_b32_e64 v250, v70, v250, s[40:41]
	v_cndmask_b32_e64 v248, v78, v66, s[40:41]
	v_cndmask_b32_e64 v249, v79, v67, s[40:41]
	global_store_dwordx2 v250, v[248:249], s[54:55]
	v_cndmask_b32_e64 v246, v66, v78, s[40:41]
	v_cndmask_b32_e64 v247, v67, v79, s[40:41]
	s_waitcnt lgkmcnt(1)
	v_add_u32_e32 v66, 0x1040, v70
	v_cndmask_b32_e64 v66, v70, v66, s[38:39]
	global_store_dwordx2 v66, v[246:247], s[54:55]
	ds_bpermute_b32 v66, v203, v68
	s_waitcnt lgkmcnt(1)
	ds_bpermute_b32 v67, v203, v69
	v_add_u32_e32 v69, 0x4c000, v202
	v_lshlrev_b32_e32 v68, 1, v69
	s_waitcnt lgkmcnt(0)
	v_add_u32_e32 v250, 0xfffff040, v68
	v_cndmask_b32_e64 v250, v68, v250, s[40:41]
	v_cndmask_b32_e64 v248, v74, v66, s[40:41]
	v_cndmask_b32_e64 v249, v75, v67, s[40:41]
	global_store_dwordx2 v250, v[248:249], s[54:55]
	v_cndmask_b32_e64 v246, v66, v74, s[40:41]
	v_cndmask_b32_e64 v247, v67, v75, s[40:41]
	v_mul_f32_e32 v35, v35, v35
	v_fmac_f32_e32 v35, v34, v34
	v_mul_f32_e32 v34, v37, v37
	v_mul_f32_e32 v45, v45, v45
	v_fmac_f32_e32 v34, v36, v36
	v_mul_f32_e32 v43, v43, v43
	v_fmac_f32_e32 v45, v44, v44
	v_mul_f32_e32 v44, v47, v47
	v_mul_f32_e32 v47, v49, v49
	v_add_f32_e32 v34, v35, v34
	v_mul_f32_e32 v35, v39, v39
	v_mul_f32_e32 v36, v41, v41
	v_fmac_f32_e32 v47, v48, v48
	v_fmac_f32_e32 v35, v38, v38
	v_fmac_f32_e32 v36, v40, v40
	v_fmac_f32_e32 v43, v42, v42
	v_fmac_f32_e32 v44, v46, v46
	v_add_f32_e32 v35, v35, v36
	v_add_f32_e32 v36, v43, v45
	v_add_f32_e32 v37, v44, v47
	v_add_f32_e32 v34, v36, v34
	v_add_f32_e32 v35, v37, v35
	ds_bpermute_b32 v36, v204, v34
	ds_bpermute_b32 v37, v204, v35
	s_waitcnt lgkmcnt(1)
	v_add_f32_e32 v34, v34, v36
	s_waitcnt lgkmcnt(0)
	v_add_f32_e32 v37, v35, v37
	ds_bpermute_b32 v36, v205, v34
	ds_bpermute_b32 v38, v205, v37
	s_waitcnt lgkmcnt(1)
	v_add_f32_e32 v34, v34, v36
	s_waitcnt lgkmcnt(0)
	v_add_f32_e32 v36, v37, v38
	ds_bpermute_b32 v35, v206, v34
	ds_bpermute_b32 v37, v206, v36
	v_add_u32_e32 v38, 0x1040, v68
	v_cndmask_b32_e64 v38, v68, v38, s[38:39]
	global_store_dwordx2 v38, v[246:247], s[54:55]
	s_and_saveexec_b64 s[16:17], s[42:43]
	s_cbranch_execz .LBB0_380
	s_waitcnt lgkmcnt(1)
	v_add_f32_e32 v34, v34, v35
	s_waitcnt lgkmcnt(0)
	v_add_f32_e32 v35, v36, v37
	ds_write2_b32 v194, v34, v35 offset0:80 offset1:88
; #define LAS __attribute__((address_space(3)))
; #define ERN_EOFF(q, m) (eb + (unsigned)((((q) & 1) * HALF + (m) * 16) * DM + ERN_COL((q) >> 1)))
;     __device__ __forceinline__ void operator()(const f32x4 (&acc)[2][2][4][2], const Unit& u, int wr, int wc, int fr, int fq) const {
;     ...
;         for (int g = 0; g < 8; ++g) { const int ai = g >> 2, m = g & 3;
;             if (g + 1 < 8) ERN_LOADX(g + 1);
;             float sq0 = 0.f, sq1 = 0.f; u32x2 hw[2][2];
; #pragma unroll
;             for (int bj = 0; bj < 2; ++bj) {
;                 *(LAS f32x4*)(st + wr_off) = acc[ai][bj][m][0]; *(LAS f32x4*)(st + wr_off + 64) = acc[ai][bj][m][1];
;                 const f32x4 a0 = *(const LAS f32x4*)(st + rd_off), a1 = *(const LAS f32x4*)(st + rd_off + 8 * 144);
;                 { const f32x4 xv = xb[g & 1][bj][0] + gv[bj] * a0; __builtin_nontemporal_store(xv, (f32x4*)((char*)xo + 4u * ERN_EOFF(g, bj, 0)));
;                   sq0 += (xv.x * xv.x + xv.y * xv.y) + (xv.z * xv.z + xv.w * xv.w);
;                   const f32x4 hv = xv * gsn[bj]; hw[bj][0].x = cvt_pk_bf16(hv.x, hv.y); hw[bj][0].y = cvt_pk_bf16(hv.z, hv.w); }
;                 { const f32x4 xv = xb[g & 1][bj][1] + gv[bj] * a1; __builtin_nontemporal_store(xv, (f32x4*)((char*)xo + 4u * ERN_EOFF(g, bj, 1)));
;                   sq1 += (xv.x * xv.x + xv.y * xv.y) + (xv.z * xv.z + xv.w * xv.w);
;                   const f32x4 hv = xv * gsn[bj]; hw[bj][1].x = cvt_pk_bf16(hv.x, hv.y); hw[bj][1].y = cvt_pk_bf16(hv.z, hv.w); }
;             }
;             if (!NOH && !PLAIN) {
; #pragma unroll
;                 for (int rh = 0; rh < 2; ++rh) { u32x2 rv; rv.x = __shfl_xor(hw[1][rh].x, 8); rv.y = __shfl_xor(hw[1][rh].y, 8);
;                     const unsigned e0 = ERN_EOFF(g, 0, rh);
;                     const unsigned ee = odd ? (e0 - DM + 32) : e0, eo2 = odd ? e0 : (e0 + DM + 32);
;                     *(u32x2*)((char*)ho + 2u * ee) = odd ? rv : hw[0][rh];
;                     *(u32x2*)((char*)ho + 2u * eo2) = odd ? hw[0][rh] : rv; }
;             }
;             if (!PLAIN) { sq0 += __shfl_xor(sq0, 1); sq0 += __shfl_xor(sq0, 2); sq0 += __shfl_xor(sq0, 4);
;             sq1 += __shfl_xor(sq1, 1); sq1 += __shfl_xor(sq1, 2); sq1 += __shfl_xor(sq1, 4); }
;             if (!PLAIN && pc == 0) { sst[g * 16 + rr] = sq0; sst[g * 16 + 8 + rr] = sq1; }
.LBB0_380:
	s_or_b64 exec, exec, s[16:17]
	v_add_u32_e32 v154, 0x160000, v207
	v_add_u32_e32 v68, 0x160080, v207
	v_add_u32_e32 v70, 0x170000, v207
	global_load_dwordx4 v[46:49], v154, s[58:59]
	global_load_dwordx4 v[42:45], v70, s[58:59]
	v_add_u32_e32 v66, 0x170080, v207
	global_load_dwordx4 v[38:41], v68, s[58:59]
	s_waitcnt lgkmcnt(0)
	global_load_dwordx4 v[34:37], v66, s[58:59]
	ds_write_b128 v200, v[30:33]
	ds_write_b128 v200, v[26:29] offset:64
	ds_read_b128 v[26:29], v201
	ds_read_b128 v[30:33], v201 offset:1152
	v_mov_b32_e32 v89, v155
	v_mov_b32_e32 v87, v155
	v_mov_b32_e32 v85, v155
	s_waitcnt vmcnt(13) lgkmcnt(1)
	v_pk_fma_f32 v[28:29], v[178:179], v[28:29], v[64:65]
	v_pk_fma_f32 v[26:27], v[180:181], v[26:27], v[62:63]
	v_lshl_add_u64 v[62:63], s[56:57], 0, v[88:89]
	global_store_dwordx4 v[62:63], v[26:29], off
	v_pk_mul_f32 v[62:63], v[176:177], v[26:27]
	s_waitcnt vmcnt(13) lgkmcnt(0)
	v_pk_fma_f32 v[32:33], v[178:179], v[32:33], v[60:61]
	v_pk_fma_f32 v[30:31], v[180:181], v[30:31], v[58:59]
	v_lshl_add_u64 v[58:59], s[56:57], 0, v[86:87]
	v_pk_mul_f32 v[64:65], v[174:175], v[28:29]
	v_cvt_pk_bf16_f32 v62, v62, v63
	v_pk_mul_f32 v[60:61], v[174:175], v[32:33]
	v_cvt_pk_bf16_f32 v63, v64, v65
	global_store_dwordx4 v[58:59], v[30:33], off
	v_pk_mul_f32 v[58:59], v[176:177], v[30:31]
	v_mov_b32_e32 v83, v155
	v_cvt_pk_bf16_f32 v58, v58, v59
	v_cvt_pk_bf16_f32 v59, v60, v61
	ds_write_b128 v200, v[22:25]
	ds_write_b128 v200, v[18:21] offset:64
	ds_read_b128 v[18:21], v201
	ds_read_b128 v[22:25], v201 offset:1152
	s_waitcnt vmcnt(13) lgkmcnt(1)
	v_pk_fma_f32 v[18:19], v[168:169], v[18:19], v[54:55]
	v_pk_fma_f32 v[20:21], v[166:167], v[20:21], v[56:57]
	v_lshl_add_u64 v[54:55], s[56:57], 0, v[84:85]
	v_pk_mul_f32 v[56:57], v[172:173], v[18:19]
	s_waitcnt vmcnt(12) lgkmcnt(0)
	v_pk_fma_f32 v[24:25], v[166:167], v[24:25], v[52:53]
	v_pk_fma_f32 v[22:23], v[168:169], v[22:23], v[50:51]
	v_lshl_add_u64 v[50:51], s[56:57], 0, v[82:83]
	global_store_dwordx4 v[54:55], v[18:21], off
	v_pk_mul_f32 v[54:55], v[170:171], v[20:21]
	v_cvt_pk_bf16_f32 v56, v56, v57
	v_pk_mul_f32 v[52:53], v[172:173], v[22:23]
	v_cvt_pk_bf16_f32 v57, v54, v55
	global_store_dwordx4 v[50:51], v[22:25], off
	ds_bpermute_b32 v50, v203, v56
	ds_bpermute_b32 v51, v203, v57
	v_pk_mul_f32 v[54:55], v[170:171], v[24:25]
	v_cvt_pk_bf16_f32 v52, v52, v53
	s_nop 0
	v_cvt_pk_bf16_f32 v53, v54, v55
	v_add_u32_e32 v55, 0x50000, v202
	v_lshlrev_b32_e32 v54, 1, v55
	s_waitcnt lgkmcnt(0)
	v_add_u32_e32 v250, 0xfffff040, v54
	v_cndmask_b32_e64 v250, v54, v250, s[40:41]
	v_cndmask_b32_e64 v248, v62, v50, s[40:41]
	v_cndmask_b32_e64 v249, v63, v51, s[40:41]
	global_store_dwordx2 v250, v[248:249], s[54:55]
	v_cndmask_b32_e64 v246, v50, v62, s[40:41]
	v_cndmask_b32_e64 v247, v51, v63, s[40:41]
	s_waitcnt lgkmcnt(1)
	v_add_u32_e32 v50, 0x1040, v54
	v_cndmask_b32_e64 v50, v54, v50, s[38:39]
	global_store_dwordx2 v50, v[246:247], s[54:55]
	ds_bpermute_b32 v50, v203, v52
	s_waitcnt lgkmcnt(1)
	ds_bpermute_b32 v51, v203, v53
	v_add_u32_e32 v53, 0x54000, v202
	v_lshlrev_b32_e32 v52, 1, v53
	s_waitcnt lgkmcnt(0)
	v_add_u32_e32 v250, 0xfffff040, v52
	v_cndmask_b32_e64 v250, v52, v250, s[40:41]
	v_cndmask_b32_e64 v248, v58, v50, s[40:41]
	v_cndmask_b32_e64 v249, v59, v51, s[40:41]
	global_store_dwordx2 v250, v[248:249], s[54:55]
	v_cndmask_b32_e64 v246, v50, v58, s[40:41]
	v_cndmask_b32_e64 v247, v51, v59, s[40:41]
	v_mul_f32_e32 v19, v19, v19
	v_fmac_f32_e32 v19, v18, v18
	v_mul_f32_e32 v18, v21, v21
	v_mul_f32_e32 v29, v29, v29
	v_fmac_f32_e32 v18, v20, v20
	v_mul_f32_e32 v27, v27, v27
	v_fmac_f32_e32 v29, v28, v28
	v_mul_f32_e32 v28, v31, v31
	v_mul_f32_e32 v31, v33, v33
	v_add_f32_e32 v18, v19, v18
	v_mul_f32_e32 v19, v23, v23
	v_mul_f32_e32 v20, v25, v25
	v_fmac_f32_e32 v31, v32, v32
	v_fmac_f32_e32 v19, v22, v22
	v_fmac_f32_e32 v20, v24, v24
	v_fmac_f32_e32 v27, v26, v26
	v_fmac_f32_e32 v28, v30, v30
	v_add_f32_e32 v19, v19, v20
	v_add_f32_e32 v20, v27, v29
	v_add_f32_e32 v21, v28, v31
	v_add_f32_e32 v18, v20, v18
	v_add_f32_e32 v19, v21, v19
	ds_bpermute_b32 v20, v204, v18
	ds_bpermute_b32 v21, v204, v19
	s_waitcnt lgkmcnt(1)
	v_add_f32_e32 v18, v18, v20
	s_waitcnt lgkmcnt(0)
	v_add_f32_e32 v21, v19, v21
	ds_bpermute_b32 v20, v205, v18
	ds_bpermute_b32 v22, v205, v21
	s_waitcnt lgkmcnt(1)
	v_add_f32_e32 v18, v18, v20
	s_waitcnt lgkmcnt(0)
	v_add_f32_e32 v20, v21, v22
	ds_bpermute_b32 v19, v206, v18
	ds_bpermute_b32 v21, v206, v20
	v_add_u32_e32 v22, 0x1040, v52
	v_cndmask_b32_e64 v22, v52, v22, s[38:39]
	global_store_dwordx2 v22, v[246:247], s[54:55]
	s_and_saveexec_b64 s[16:17], s[42:43]
	s_cbranch_execz .LBB0_390
	s_waitcnt lgkmcnt(1)
	v_add_f32_e32 v18, v18, v19
	s_waitcnt lgkmcnt(0)
	v_add_f32_e32 v19, v20, v21
	ds_write2_b32 v194, v18, v19 offset0:96 offset1:104
; #define LAS __attribute__((address_space(3)))
; #define ERN_EOFF(q, m) (eb + (unsigned)((((q) & 1) * HALF + (m) * 16) * DM + ERN_COL((q) >> 1)))
;     __device__ __forceinline__ void operator()(const f32x4 (&acc)[2][2][4][2], const Unit& u, int wr, int wc, int fr, int fq) const {
;     ...
;         for (int g = 0; g < 8; ++g) { const int ai = g >> 2, m = g & 3;
;             if (g + 1 < 8) ERN_LOADX(g + 1);
;             float sq0 = 0.f, sq1 = 0.f; u32x2 hw[2][2];
; #pragma unroll
;             for (int bj = 0; bj < 2; ++bj) {
;                 *(LAS f32x4*)(st + wr_off) = acc[ai][bj][m][0]; *(LAS f32x4*)(st + wr_off + 64) = acc[ai][bj][m][1];
;                 const f32x4 a0 = *(const LAS f32x4*)(st + rd_off), a1 = *(const LAS f32x4*)(st + rd_off + 8 * 144);
;                 { const f32x4 xv = xb[g & 1][bj][0] + gv[bj] * a0; __builtin_nontemporal_store(xv, (f32x4*)((char*)xo + 4u * ERN_EOFF(g, bj, 0)));
;                   sq0 += (xv.x * xv.x + xv.y * xv.y) + (xv.z * xv.z + xv.w * xv.w);
;                   const f32x4 hv = xv * gsn[bj]; hw[bj][0].x = cvt_pk_bf16(hv.x, hv.y); hw[bj][0].y = cvt_pk_bf16(hv.z, hv.w); }
;                 { const f32x4 xv = xb[g & 1][bj][1] + gv[bj] * a1; __builtin_nontemporal_store(xv, (f32x4*)((char*)xo + 4u * ERN_EOFF(g, bj, 1)));
;                   sq1 += (xv.x * xv.x + xv.y * xv.y) + (xv.z * xv.z + xv.w * xv.w);
;                   const f32x4 hv = xv * gsn[bj]; hw[bj][1].x = cvt_pk_bf16(hv.x, hv.y); hw[bj][1].y = cvt_pk_bf16(hv.z, hv.w); }
;             }
;             if (!NOH && !PLAIN) {
; #pragma unroll
;                 for (int rh = 0; rh < 2; ++rh) { u32x2 rv; rv.x = __shfl_xor(hw[1][rh].x, 8); rv.y = __shfl_xor(hw[1][rh].y, 8);
;                     const unsigned e0 = ERN_EOFF(g, 0, rh);
;                     const unsigned ee = odd ? (e0 - DM + 32) : e0, eo2 = odd ? e0 : (e0 + DM + 32);
;                     *(u32x2*)((char*)ho + 2u * ee) = odd ? rv : hw[0][rh];
;                     *(u32x2*)((char*)ho + 2u * eo2) = odd ? hw[0][rh] : rv; }
;             }
;             if (!PLAIN) { sq0 += __shfl_xor(sq0, 1); sq0 += __shfl_xor(sq0, 2); sq0 += __shfl_xor(sq0, 4);
;             sq1 += __shfl_xor(sq1, 1); sq1 += __shfl_xor(sq1, 2); sq1 += __shfl_xor(sq1, 4); }
;             if (!PLAIN && pc == 0) { sst[g * 16 + rr] = sq0; sst[g * 16 + 8 + rr] = sq1; }
.LBB0_390:
	s_or_b64 exec, exec, s[16:17]
	ds_write_b128 v200, v[14:17]
	ds_write_b128 v200, v[10:13] offset:64
	ds_read_b128 v[10:13], v201
	ds_read_b128 v[14:17], v201 offset:1152
	s_waitcnt lgkmcnt(5)
	v_lshl_add_u64 v[18:19], s[56:57], 0, v[154:155]
	v_mov_b32_e32 v71, v155
	v_mov_b32_e32 v69, v155
	s_waitcnt vmcnt(9) lgkmcnt(1)
	v_pk_fma_f32 v[12:13], v[178:179], v[12:13], v[48:49]
	v_pk_fma_f32 v[10:11], v[180:181], v[10:11], v[46:47]
	global_store_dwordx4 v[18:19], v[10:13], off
	v_pk_mul_f32 v[18:19], v[174:175], v[12:13]
	v_pk_mul_f32 v[20:21], v[176:177], v[10:11]
	s_waitcnt vmcnt(9) lgkmcnt(0)
	v_pk_fma_f32 v[16:17], v[178:179], v[16:17], v[44:45]
	v_cvt_pk_bf16_f32 v20, v20, v21
	v_cvt_pk_bf16_f32 v21, v18, v19
	v_pk_fma_f32 v[14:15], v[180:181], v[14:15], v[42:43]
	v_lshl_add_u64 v[18:19], s[56:57], 0, v[70:71]
	global_store_dwordx4 v[18:19], v[14:17], off
	v_pk_mul_f32 v[18:19], v[176:177], v[14:15]
	v_pk_mul_f32 v[22:23], v[174:175], v[16:17]
	v_cvt_pk_bf16_f32 v18, v18, v19
	v_mov_b32_e32 v67, v155
	v_cvt_pk_bf16_f32 v19, v22, v23
	ds_write_b128 v200, v[6:9]
	ds_write_b128 v200, v[2:5] offset:64
	ds_read_b128 v[2:5], v201
	ds_read_b128 v[6:9], v201 offset:1152
	v_lshl_add_u64 v[22:23], s[56:57], 0, v[68:69]
	s_waitcnt vmcnt(9) lgkmcnt(1)
	v_pk_fma_f32 v[4:5], v[166:167], v[4:5], v[40:41]
	v_pk_fma_f32 v[2:3], v[168:169], v[2:3], v[38:39]
	global_store_dwordx4 v[22:23], v[2:5], off
	v_pk_mul_f32 v[22:23], v[170:171], v[4:5]
	v_pk_mul_f32 v[24:25], v[172:173], v[2:3]
	s_waitcnt vmcnt(9) lgkmcnt(0)
	v_pk_fma_f32 v[8:9], v[166:167], v[8:9], v[36:37]
	v_cvt_pk_bf16_f32 v28, v24, v25
	v_cvt_pk_bf16_f32 v29, v22, v23
	v_pk_fma_f32 v[6:7], v[168:169], v[6:7], v[34:35]
	v_lshl_add_u64 v[22:23], s[56:57], 0, v[66:67]
	global_store_dwordx4 v[22:23], v[6:9], off
	ds_bpermute_b32 v22, v203, v28
	ds_bpermute_b32 v23, v203, v29
	v_pk_mul_f32 v[26:27], v[170:171], v[8:9]
	v_pk_mul_f32 v[24:25], v[172:173], v[6:7]
	s_nop 0
	v_cvt_pk_bf16_f32 v24, v24, v25
	v_cvt_pk_bf16_f32 v25, v26, v27
	v_add_u32_e32 v27, 0x58000, v202
	v_lshlrev_b32_e32 v26, 1, v27
	s_waitcnt lgkmcnt(0)
	v_add_u32_e32 v250, 0xfffff040, v26
	v_cndmask_b32_e64 v250, v26, v250, s[40:41]
	v_cndmask_b32_e64 v248, v20, v22, s[40:41]
	v_cndmask_b32_e64 v249, v21, v23, s[40:41]
	global_store_dwordx2 v250, v[248:249], s[54:55]
	v_cndmask_b32_e64 v246, v22, v20, s[40:41]
	v_cndmask_b32_e64 v247, v23, v21, s[40:41]
	s_waitcnt lgkmcnt(1)
	v_add_u32_e32 v22, 0x1040, v26
	v_cndmask_b32_e64 v22, v26, v22, s[38:39]
	global_store_dwordx2 v22, v[246:247], s[54:55]
	ds_bpermute_b32 v20, v203, v24
	ds_bpermute_b32 v21, v203, v25
	s_waitcnt lgkmcnt(2)
	v_add_u32_e32 v23, 0x5c000, v202
	v_lshlrev_b32_e32 v22, 1, v23
	s_waitcnt lgkmcnt(0)
	v_add_u32_e32 v250, 0xfffff040, v22
	v_cndmask_b32_e64 v250, v22, v250, s[40:41]
	v_cndmask_b32_e64 v248, v18, v20, s[40:41]
	v_cndmask_b32_e64 v249, v19, v21, s[40:41]
	global_store_dwordx2 v250, v[248:249], s[54:55]
	v_cndmask_b32_e64 v246, v20, v18, s[40:41]
	v_cndmask_b32_e64 v247, v21, v19, s[40:41]
	v_mul_f32_e32 v3, v3, v3
	v_fmac_f32_e32 v3, v2, v2
	v_mul_f32_e32 v2, v5, v5
	v_mul_f32_e32 v13, v13, v13
	v_fmac_f32_e32 v2, v4, v4
	v_mul_f32_e32 v11, v11, v11
	v_fmac_f32_e32 v13, v12, v12
	v_mul_f32_e32 v12, v15, v15
	v_mul_f32_e32 v15, v17, v17
	v_add_f32_e32 v2, v3, v2
	v_mul_f32_e32 v3, v7, v7
	v_mul_f32_e32 v4, v9, v9
	v_fmac_f32_e32 v15, v16, v16
	v_fmac_f32_e32 v3, v6, v6
	v_fmac_f32_e32 v4, v8, v8
	v_fmac_f32_e32 v11, v10, v10
	v_fmac_f32_e32 v12, v14, v14
	v_add_f32_e32 v3, v3, v4
	v_add_f32_e32 v4, v11, v13
	v_add_f32_e32 v5, v12, v15
	v_add_f32_e32 v2, v4, v2
	v_add_f32_e32 v3, v5, v3
	ds_bpermute_b32 v4, v204, v2
	ds_bpermute_b32 v5, v204, v3
	s_waitcnt lgkmcnt(1)
	v_add_f32_e32 v2, v2, v4
	s_waitcnt lgkmcnt(0)
	v_add_f32_e32 v5, v3, v5
	ds_bpermute_b32 v4, v205, v2
	ds_bpermute_b32 v6, v205, v5
	s_waitcnt lgkmcnt(1)
	v_add_f32_e32 v2, v2, v4
	s_waitcnt lgkmcnt(0)
	v_add_f32_e32 v4, v5, v6
	ds_bpermute_b32 v3, v206, v2
	ds_bpermute_b32 v5, v206, v4
	v_add_u32_e32 v6, 0x1040, v22
	v_cndmask_b32_e64 v6, v22, v6, s[38:39]
	global_store_dwordx2 v6, v[246:247], s[54:55]
	s_and_saveexec_b64 s[16:17], s[42:43]
	s_cbranch_execz .LBB0_400
	s_waitcnt lgkmcnt(1)
	v_add_f32_e32 v2, v2, v3
	s_waitcnt lgkmcnt(0)
	v_add_f32_e32 v3, v4, v5
	ds_write2_b32 v194, v2, v3 offset0:112 offset1:120

; #define LAS __attribute__((address_space(3)))
;     __device__ __forceinline__ void operator()(const f32x4 (&acc)[2][2][4][2], const Unit& u, int wr, int wc, int fr, int fq) const {
;         const int s = u.pm >> 5, lane = fq * 16 + fr, rr = lane >> 3, pc = lane & 7;
;         const float* __restrict__ xi = xin + (size_t)u.pm * BM * DM; float* __restrict__ xo = xout + (size_t)u.pm * BM * DM; bf16_t* __restrict__ ho = Hn + (size_t)u.pm * BM * DM;
;         LAS unsigned char* st = lds_epi + (wr * 4 + wc) * 2304;
;         LAS float* sst = (LAS float*)(lds_epi + 18432 + (wr * 4 + wc) * 512);
;         const int colr = u.pn * BM + wc * 64 + 4 * pc;
;         const unsigned eb = (unsigned)((wr * 64 + rr) * DM + colr);
;         f32x4 gv[2], gsn[2];
; #pragma unroll
;         for (int bj = 0; bj < 2; ++bj) { gv[bj] = *(const f32x4*)(gate + (size_t)s * MODW + colr + bj * 32) * (0.5f * GS2);
;             if (!PLAIN) gsn[bj] = *(const f32x4*)(gnext + colr + bj * 32) * (*(const f32x4*)(scnext + (size_t)s * MODW + colr + bj * 32) + 1.0f); else gsn[bj] = gv[bj]; }
;         const unsigned wr_off = (unsigned)(fr * 144 + 16 * fq), rd_off = (unsigned)(rr * 144 + pc * 16);
;         const bool odd = (rr & 1) != 0;
;         f32x4 xb[2][2][2];
;     ...
;         ERN_LOADX(0);
; #pragma unroll
;         for (int g = 0; g < 8; ++g) { const int ai = g >> 2, m = g & 3;
;             if (g + 1 < 8) ERN_LOADX(g + 1);
;             float sq0 = 0.f, sq1 = 0.f; u32x2 hw[2][2];
; #pragma unroll
;             for (int bj = 0; bj < 2; ++bj) {
;                 *(LAS f32x4*)(st + wr_off) = acc[ai][bj][m][0]; *(LAS f32x4*)(st + wr_off + 64) = acc[ai][bj][m][1];
;                 const f32x4 a0 = *(const LAS f32x4*)(st + rd_off), a1 = *(const LAS f32x4*)(st + rd_off + 8 * 144);
;                 { const f32x4 xv = xb[g & 1][bj][0] + gv[bj] * a0; __builtin_nontemporal_store(xv, (f32x4*)((char*)xo + 4u * ERN_EOFF(g, bj, 0)));
;                   sq0 += (xv.x * xv.x + xv.y * xv.y) + (xv.z * xv.z + xv.w * xv.w);
;                   const f32x4 hv = xv * gsn[bj]; hw[bj][0].x = cvt_pk_bf16(hv.x, hv.y); hw[bj][0].y = cvt_pk_bf16(hv.z, hv.w); }
;                 { const f32x4 xv = xb[g & 1][bj][1] + gv[bj] * a1; __builtin_nontemporal_store(xv, (f32x4*)((char*)xo + 4u * ERN_EOFF(g, bj, 1)));
;                   sq1 += (xv.x * xv.x + xv.y * xv.y) + (xv.z * xv.z + xv.w * xv.w);
.LBB0_1253:
	s_ashr_i32 s0, s92, 5
	s_ashr_i32 s93, s92, 31
	v_lshl_or_b32 v50, s46, 8, v192
	s_mul_hi_i32 s15, s0, 0x12000
	s_mul_i32 s0, s0, 0x12000
	s_add_u32 s16, s35, s0
	v_ashrrev_i32_e32 v51, 31, v50
	s_addc_u32 s17, s36, s15
	v_lshlrev_b64 v[52:53], 2, v[50:51]
	v_lshl_add_u64 v[138:139], s[16:17], 0, v[52:53]
	s_add_u32 s16, s37, s0
	s_addc_u32 s17, s52, s15
	v_lshl_add_u64 v[140:141], s[8:9], 0, v[52:53]
	v_lshl_add_u64 v[52:53], s[16:17], 0, v[52:53]
	s_lshl_b64 s[16:17], s[92:93], 21
	s_add_u32 s48, s90, s16
	v_add_u32_e32 v202, v50, v193
	s_addc_u32 s49, s91, s17
	v_lshlrev_b32_e32 v205, 2, v202
	global_load_dwordx4 v[54:57], v[138:139], off
	global_load_dwordx4 v[174:177], v[140:141], off
	global_load_dwordx4 v[178:181], v[52:53], off
	global_load_dwordx4 v[206:209], v[52:53], off offset:128
	global_load_dwordx4 v[186:189], v205, s[48:49]
	v_add_u32_e32 v50, 0x10000, v205
	global_load_dwordx4 v[210:213], v50, s[48:49]
	global_load_dwordx4 v[214:217], v[140:141], off offset:128
	s_nop 0
	global_load_dwordx4 v[50:53], v[138:139], off offset:128
	global_load_dwordx4 v[218:221], v205, s[48:49] offset:128
	v_add_u32_e32 v204, 0x10080, v205
	global_load_dwordx4 v[222:225], v204, s[48:49]
	v_add_u32_e32 v138, 0x20000, v205
	v_add_u32_e32 v162, 0x30000, v205
	v_add_u32_e32 v184, 0x20080, v205
	v_add_u32_e32 v182, 0x30080, v205
	global_load_dwordx4 v[150:153], v138, s[48:49]
	global_load_dwordx4 v[146:149], v162, s[48:49]
	global_load_dwordx4 v[142:145], v184, s[48:49]
	s_nop 0
	global_load_dwordx4 v[138:141], v182, s[48:49]
	ds_write_b128 v200, v[134:137]
	ds_write_b128 v200, v[130:133] offset:64
	v_and_b32_e32 v135, 64, v199
	ds_read_b128 v[130:133], v201
	ds_read_b128 v[226:229], v201 offset:1152
	v_xor_b32_e32 v134, 8, v199
	v_add_u32_e32 v183, 64, v135
	v_cmp_lt_i32_e32 vcc, v134, v183
	v_add_u32_e32 v185, 0x4000, v202
	v_lshlrev_b32_e32 v230, 2, v185
	v_cndmask_b32_e32 v134, v199, v134, vcc
	v_lshlrev_b32_e32 v203, 2, v134
	s_lshl_b64 s[16:17], s[92:93], 20
	v_readlane_b32 s0, v252, 41
	s_add_u32 s46, s0, s16
	v_readlane_b32 s0, v252, 42
	s_addc_u32 s47, s0, s17
	s_waitcnt vmcnt(0)
	v_pk_add_f32 v[134:135], v[180:181], 1.0 op_sel_hi:[1,0]
	v_pk_add_f32 v[136:137], v[178:179], 1.0 op_sel_hi:[1,0]
	v_pk_mul_f32 v[178:179], v[176:177], v[134:135]
	v_pk_mul_f32 v[180:181], v[174:175], v[136:137]
	s_waitcnt lgkmcnt(1)
	v_pk_fma_f32 v[134:135], v[54:55], v[130:131], v[186:187]
	s_waitcnt lgkmcnt(0)
	v_pk_fma_f32 v[130:131], v[54:55], v[226:227], v[210:211]
	v_pk_fma_f32 v[136:137], v[56:57], v[132:133], v[188:189]
	v_pk_fma_f32 v[132:133], v[56:57], v[228:229], v[212:213]
	v_pk_mul_f32 v[186:187], v[180:181], v[130:131]
	v_pk_add_f32 v[190:191], v[208:209], 1.0 op_sel_hi:[1,0]
	global_store_dwordx4 v205, v[134:137], s[48:49]
	v_pk_mul_f32 v[174:175], v[178:179], v[136:137]
	v_pk_mul_f32 v[176:177], v[180:181], v[134:135]
	v_pk_mul_f32 v[208:209], v[178:179], v[132:133]
	v_cvt_pk_bf16_f32 v188, v176, v177
	v_cvt_pk_bf16_f32 v189, v174, v175
	global_store_dwordx4 v230, v[130:133], s[48:49]
	v_cvt_pk_bf16_f32 v186, v186, v187
	v_cvt_pk_bf16_f32 v187, v208, v209
	ds_write_b128 v200, v[126:129]
	ds_write_b128 v200, v[122:125] offset:64
	ds_read_b128 v[122:125], v201
	v_pk_add_f32 v[126:127], v[206:207], 1.0 op_sel_hi:[1,0]
	ds_read_b128 v[206:209], v201 offset:1152
	v_pk_mul_f32 v[174:175], v[216:217], v[190:191]
	v_pk_mul_f32 v[176:177], v[214:215], v[126:127]
	s_waitcnt lgkmcnt(1)
	v_pk_fma_f32 v[128:129], v[52:53], v[124:125], v[220:221]
	v_pk_fma_f32 v[126:127], v[50:51], v[122:123], v[218:219]
	s_waitcnt lgkmcnt(0)
	v_pk_fma_f32 v[122:123], v[50:51], v[206:207], v[222:223]
	v_pk_mul_f32 v[190:191], v[174:175], v[128:129]
	v_pk_mul_f32 v[206:207], v[176:177], v[126:127]
	global_store_dwordx4 v205, v[126:129], s[48:49] offset:128
	v_cvt_pk_bf16_f32 v206, v206, v207
	v_cvt_pk_bf16_f32 v191, v190, v191
	ds_bpermute_b32 v190, v203, v206
	ds_bpermute_b32 v191, v203, v191
	v_pk_fma_f32 v[124:125], v[52:53], v[208:209], v[224:225]
	v_pk_mul_f32 v[206:207], v[176:177], v[122:123]
	global_store_dwordx4 v204, v[122:125], s[48:49]
	v_cvt_pk_bf16_f32 v204, v206, v207
	v_lshlrev_b32_e32 v207, 1, v202
	v_pk_mul_f32 v[208:209], v[174:175], v[124:125]
	s_nop 0
	v_cvt_pk_bf16_f32 v206, v208, v209
	s_waitcnt lgkmcnt(0)
	v_add_u32_e32 v250, 0xfffff040, v207
	v_cndmask_b32_e64 v250, v207, v250, s[40:41]
	v_cndmask_b32_e64 v248, v188, v190, s[40:41]
	v_cndmask_b32_e64 v249, v189, v191, s[40:41]
	global_store_dwordx2 v250, v[248:249], s[46:47]
	v_cndmask_b32_e64 v246, v190, v188, s[40:41]
	v_cndmask_b32_e64 v247, v191, v189, s[40:41]
	s_waitcnt lgkmcnt(1)
	v_add_u32_e32 v190, 0x1040, v207
	v_cndmask_b32_e64 v190, v207, v190, s[38:39]
	global_store_dwordx2 v190, v[246:247], s[46:47]
	ds_bpermute_b32 v188, v203, v204
	ds_bpermute_b32 v189, v203, v206
	v_lshlrev_b32_e32 v206, 1, v185
	s_and_saveexec_b64 s[16:17], s[40:41]
	v_readlane_b32 s60, v252, 4
	v_readlane_b32 s58, v252, 10
	s_xor_b64 s[16:17], exec, s[16:17]
	v_readlane_b32 s61, v252, 5
	v_readlane_b32 s59, v252, 11
	s_cbranch_execz .LBB0_1259
	v_lshlrev_b32_e32 v206, 1, v185
	v_add_u32_e32 v185, 0xfffff040, v206
	s_waitcnt lgkmcnt(0)
	global_store_dwordx2 v185, v[188:189], s[46:47]

; #define LAS __attribute__((address_space(3)))
; #define ERN_EOFF(q, m) (eb + (unsigned)((((q) & 1) * HALF + (m) * 16) * DM + ERN_COL((q) >> 1)))
;     __device__ __forceinline__ void operator()(const f32x4 (&acc)[2][2][4][2], const Unit& u, int wr, int wc, int fr, int fq) const {
;     ...
;         for (int g = 0; g < 8; ++g) { const int ai = g >> 2, m = g & 3;
;             if (g + 1 < 8) ERN_LOADX(g + 1);
;             float sq0 = 0.f, sq1 = 0.f; u32x2 hw[2][2];
; #pragma unroll
;             for (int bj = 0; bj < 2; ++bj) {
;                 *(LAS f32x4*)(st + wr_off) = acc[ai][bj][m][0]; *(LAS f32x4*)(st + wr_off + 64) = acc[ai][bj][m][1];
;                 const f32x4 a0 = *(const LAS f32x4*)(st + rd_off), a1 = *(const LAS f32x4*)(st + rd_off + 8 * 144);
;                 { const f32x4 xv = xb[g & 1][bj][0] + gv[bj] * a0; __builtin_nontemporal_store(xv, (f32x4*)((char*)xo + 4u * ERN_EOFF(g, bj, 0)));
;                   sq0 += (xv.x * xv.x + xv.y * xv.y) + (xv.z * xv.z + xv.w * xv.w);
;                   const f32x4 hv = xv * gsn[bj]; hw[bj][0].x = cvt_pk_bf16(hv.x, hv.y); hw[bj][0].y = cvt_pk_bf16(hv.z, hv.w); }
;                 { const f32x4 xv = xb[g & 1][bj][1] + gv[bj] * a1; __builtin_nontemporal_store(xv, (f32x4*)((char*)xo + 4u * ERN_EOFF(g, bj, 1)));
;                   sq1 += (xv.x * xv.x + xv.y * xv.y) + (xv.z * xv.z + xv.w * xv.w);
;                   const f32x4 hv = xv * gsn[bj]; hw[bj][1].x = cvt_pk_bf16(hv.x, hv.y); hw[bj][1].y = cvt_pk_bf16(hv.z, hv.w); }
;             }
;             if (!NOH && !PLAIN) {
; #pragma unroll
;                 for (int rh = 0; rh < 2; ++rh) { u32x2 rv; rv.x = __shfl_xor(hw[1][rh].x, 8); rv.y = __shfl_xor(hw[1][rh].y, 8);
;                     const unsigned e0 = ERN_EOFF(g, 0, rh);
;                     const unsigned ee = odd ? (e0 - DM + 32) : e0, eo2 = odd ? e0 : (e0 + DM + 32);
;                     *(u32x2*)((char*)ho + 2u * ee) = odd ? rv : hw[0][rh];
;                     *(u32x2*)((char*)ho + 2u * eo2) = odd ? hw[0][rh] : rv; }
;             }
;             if (!PLAIN) { sq0 += __shfl_xor(sq0, 1); sq0 += __shfl_xor(sq0, 2); sq0 += __shfl_xor(sq0, 4);
;             sq1 += __shfl_xor(sq1, 1); sq1 += __shfl_xor(sq1, 2); sq1 += __shfl_xor(sq1, 4); }
;             if (!PLAIN && pc == 0) { sst[g * 16 + rr] = sq0; sst[g * 16 + 8 + rr] = sq1; }
.LBB0_1263:
	s_or_b64 exec, exec, s[16:17]
	v_lshl_add_u64 v[206:207], s[48:49], 0, v[162:163]
	v_add_u32_e32 v122, 0x40000, v205
	v_add_u32_e32 v162, 0x50000, v205
	v_add_u32_e32 v186, 0x40080, v205
	global_load_dwordx4 v[130:133], v162, s[48:49]
	global_load_dwordx4 v[126:129], v186, s[48:49]
	v_add_u32_e32 v188, 0x50080, v205
	global_load_dwordx4 v[134:137], v122, s[48:49]
	s_waitcnt lgkmcnt(0)
	global_load_dwordx4 v[122:125], v188, s[48:49]
	ds_write_b128 v200, v[118:121]
	ds_write_b128 v200, v[114:117] offset:64
	ds_read_b128 v[114:117], v201
	ds_read_b128 v[118:121], v201 offset:1152
	v_mov_b32_e32 v185, v163
	v_mov_b32_e32 v183, v163
	v_lshl_add_u64 v[182:183], s[48:49], 0, v[182:183]
	s_waitcnt lgkmcnt(1)
	v_pk_fma_f32 v[116:117], v[56:57], v[116:117], v[152:153]
	v_add_u32_e32 v152, 0x8000, v202
	v_pk_fma_f32 v[114:115], v[54:55], v[114:115], v[150:151]
	v_lshlrev_b32_e32 v150, 2, v152
	s_waitcnt lgkmcnt(0)
	v_pk_fma_f32 v[118:119], v[54:55], v[118:119], v[146:147]
	global_store_dwordx4 v150, v[114:117], s[48:49]
	v_pk_mul_f32 v[150:151], v[180:181], v[114:115]
	v_pk_fma_f32 v[120:121], v[56:57], v[120:121], v[148:149]
	v_pk_mul_f32 v[146:147], v[180:181], v[118:119]
	v_pk_mul_f32 v[208:209], v[178:179], v[116:117]
	v_cvt_pk_bf16_f32 v150, v150, v151
	v_pk_mul_f32 v[148:149], v[178:179], v[120:121]
	v_cvt_pk_bf16_f32 v151, v208, v209
	global_store_dwordx4 v[206:207], v[118:121], off
	v_cvt_pk_bf16_f32 v146, v146, v147
	v_cvt_pk_bf16_f32 v147, v148, v149
	ds_write_b128 v200, v[110:113]
	ds_write_b128 v200, v[106:109] offset:64
	ds_read_b128 v[106:109], v201
	ds_read_b128 v[110:113], v201 offset:1152
	v_lshl_add_u64 v[148:149], s[48:49], 0, v[184:185]
	s_waitcnt lgkmcnt(1)
	v_pk_fma_f32 v[106:107], v[50:51], v[106:107], v[142:143]
	v_pk_fma_f32 v[108:109], v[52:53], v[108:109], v[144:145]
	v_pk_mul_f32 v[144:145], v[176:177], v[106:107]
	global_store_dwordx4 v[148:149], v[106:109], off
	v_pk_mul_f32 v[142:143], v[174:175], v[108:109]
	v_cvt_pk_bf16_f32 v144, v144, v145
	s_waitcnt lgkmcnt(0)
	v_pk_fma_f32 v[110:111], v[50:51], v[110:111], v[138:139]
	v_cvt_pk_bf16_f32 v145, v142, v143
	ds_bpermute_b32 v138, v203, v144
	ds_bpermute_b32 v139, v203, v145
	v_pk_fma_f32 v[112:113], v[52:53], v[112:113], v[140:141]
	v_pk_mul_f32 v[140:141], v[176:177], v[110:111]
	v_pk_mul_f32 v[142:143], v[174:175], v[112:113]
	global_store_dwordx4 v[182:183], v[110:113], off
	v_cvt_pk_bf16_f32 v140, v140, v141
	v_cvt_pk_bf16_f32 v141, v142, v143
	v_lshlrev_b32_e32 v142, 1, v152
	s_waitcnt lgkmcnt(0)
	v_add_u32_e32 v250, 0xfffff040, v142
	v_cndmask_b32_e64 v250, v142, v250, s[40:41]
	v_cndmask_b32_e64 v248, v150, v138, s[40:41]
	v_cndmask_b32_e64 v249, v151, v139, s[40:41]
	global_store_dwordx2 v250, v[248:249], s[46:47]
	v_cndmask_b32_e64 v246, v138, v150, s[40:41]
	v_cndmask_b32_e64 v247, v139, v151, s[40:41]
	s_waitcnt lgkmcnt(1)
	v_add_u32_e32 v138, 0x1040, v142
	v_cndmask_b32_e64 v138, v142, v138, s[38:39]
	global_store_dwordx2 v138, v[246:247], s[46:47]
	ds_bpermute_b32 v138, v203, v140
	s_waitcnt lgkmcnt(1)
	ds_bpermute_b32 v139, v203, v141
	v_add_u32_e32 v141, 0xc000, v202
	v_lshlrev_b32_e32 v140, 1, v141
	s_waitcnt lgkmcnt(0)
	v_add_u32_e32 v250, 0xfffff040, v140
	v_cndmask_b32_e64 v250, v140, v250, s[40:41]
	v_cndmask_b32_e64 v248, v146, v138, s[40:41]
	v_cndmask_b32_e64 v249, v147, v139, s[40:41]
	global_store_dwordx2 v250, v[248:249], s[46:47]
	v_cndmask_b32_e64 v246, v138, v146, s[40:41]
	v_cndmask_b32_e64 v247, v139, v147, s[40:41]
	v_mul_f32_e32 v107, v107, v107
	v_fmac_f32_e32 v107, v106, v106
	v_mul_f32_e32 v106, v109, v109
	v_mul_f32_e32 v117, v117, v117
	v_fmac_f32_e32 v106, v108, v108
	v_mul_f32_e32 v115, v115, v115
	v_fmac_f32_e32 v117, v116, v116
	v_mul_f32_e32 v116, v119, v119
	v_mul_f32_e32 v119, v121, v121
	v_add_f32_e32 v106, v107, v106
	v_mul_f32_e32 v107, v111, v111
	v_mul_f32_e32 v108, v113, v113
	v_fmac_f32_e32 v119, v120, v120
	v_fmac_f32_e32 v107, v110, v110
	v_fmac_f32_e32 v108, v112, v112
	v_fmac_f32_e32 v115, v114, v114
	v_fmac_f32_e32 v116, v118, v118
	v_add_f32_e32 v107, v107, v108
	v_add_f32_e32 v108, v115, v117
	v_add_f32_e32 v109, v116, v119
	v_add_f32_e32 v106, v108, v106
	v_add_f32_e32 v107, v109, v107
	ds_bpermute_b32 v108, v190, v106
	ds_bpermute_b32 v109, v190, v107
	s_waitcnt lgkmcnt(1)
	v_add_f32_e32 v106, v106, v108
	s_waitcnt lgkmcnt(0)
	v_add_f32_e32 v109, v107, v109
	ds_bpermute_b32 v108, v191, v106
	ds_bpermute_b32 v110, v191, v109
	s_waitcnt lgkmcnt(1)
	v_add_f32_e32 v106, v106, v108
	s_waitcnt lgkmcnt(0)
	v_add_f32_e32 v108, v109, v110
	ds_bpermute_b32 v107, v204, v106
	ds_bpermute_b32 v109, v204, v108
	v_add_u32_e32 v110, 0x1040, v140
	v_cndmask_b32_e64 v110, v140, v110, s[38:39]
	global_store_dwordx2 v110, v[246:247], s[46:47]
	s_and_saveexec_b64 s[16:17], s[42:43]
	s_cbranch_execz .LBB0_1273
	s_waitcnt lgkmcnt(1)
	v_add_f32_e32 v106, v106, v107
	s_waitcnt lgkmcnt(0)
	v_add_f32_e32 v107, v108, v109
	ds_write2_b32 v194, v106, v107 offset0:16 offset1:24
; #define LAS __attribute__((address_space(3)))
; #define ERN_EOFF(q, m) (eb + (unsigned)((((q) & 1) * HALF + (m) * 16) * DM + ERN_COL((q) >> 1)))
;     __device__ __forceinline__ void operator()(const f32x4 (&acc)[2][2][4][2], const Unit& u, int wr, int wc, int fr, int fq) const {
;     ...
;         for (int g = 0; g < 8; ++g) { const int ai = g >> 2, m = g & 3;
;             if (g + 1 < 8) ERN_LOADX(g + 1);
;             float sq0 = 0.f, sq1 = 0.f; u32x2 hw[2][2];
; #pragma unroll
;             for (int bj = 0; bj < 2; ++bj) {
;                 *(LAS f32x4*)(st + wr_off) = acc[ai][bj][m][0]; *(LAS f32x4*)(st + wr_off + 64) = acc[ai][bj][m][1];
;                 const f32x4 a0 = *(const LAS f32x4*)(st + rd_off), a1 = *(const LAS f32x4*)(st + rd_off + 8 * 144);
;                 { const f32x4 xv = xb[g & 1][bj][0] + gv[bj] * a0; __builtin_nontemporal_store(xv, (f32x4*)((char*)xo + 4u * ERN_EOFF(g, bj, 0)));
;                   sq0 += (xv.x * xv.x + xv.y * xv.y) + (xv.z * xv.z + xv.w * xv.w);
;                   const f32x4 hv = xv * gsn[bj]; hw[bj][0].x = cvt_pk_bf16(hv.x, hv.y); hw[bj][0].y = cvt_pk_bf16(hv.z, hv.w); }
;                 { const f32x4 xv = xb[g & 1][bj][1] + gv[bj] * a1; __builtin_nontemporal_store(xv, (f32x4*)((char*)xo + 4u * ERN_EOFF(g, bj, 1)));
;                   sq1 += (xv.x * xv.x + xv.y * xv.y) + (xv.z * xv.z + xv.w * xv.w);
;                   const f32x4 hv = xv * gsn[bj]; hw[bj][1].x = cvt_pk_bf16(hv.x, hv.y); hw[bj][1].y = cvt_pk_bf16(hv.z, hv.w); }
;             }
;             if (!NOH && !PLAIN) {
; #pragma unroll
;                 for (int rh = 0; rh < 2; ++rh) { u32x2 rv; rv.x = __shfl_xor(hw[1][rh].x, 8); rv.y = __shfl_xor(hw[1][rh].y, 8);
;                     const unsigned e0 = ERN_EOFF(g, 0, rh);
;                     const unsigned ee = odd ? (e0 - DM + 32) : e0, eo2 = odd ? e0 : (e0 + DM + 32);
;                     *(u32x2*)((char*)ho + 2u * ee) = odd ? rv : hw[0][rh];
;                     *(u32x2*)((char*)ho + 2u * eo2) = odd ? hw[0][rh] : rv; }
;             }
;             if (!PLAIN) { sq0 += __shfl_xor(sq0, 1); sq0 += __shfl_xor(sq0, 2); sq0 += __shfl_xor(sq0, 4);
;             sq1 += __shfl_xor(sq1, 1); sq1 += __shfl_xor(sq1, 2); sq1 += __shfl_xor(sq1, 4); }
;             if (!PLAIN && pc == 0) { sst[g * 16 + rr] = sq0; sst[g * 16 + 8 + rr] = sq1; }
.LBB0_1273:
	s_or_b64 exec, exec, s[16:17]
	v_lshl_add_u64 v[142:143], s[48:49], 0, v[162:163]
	v_add_u32_e32 v106, 0x60000, v205
	v_add_u32_e32 v162, 0x70000, v205
	v_add_u32_e32 v138, 0x60080, v205
	global_load_dwordx4 v[114:117], v162, s[48:49]
	global_load_dwordx4 v[110:113], v138, s[48:49]
	v_add_u32_e32 v140, 0x70080, v205
	global_load_dwordx4 v[118:121], v106, s[48:49]
	s_waitcnt lgkmcnt(0)
	global_load_dwordx4 v[106:109], v140, s[48:49]
	ds_write_b128 v200, v[102:105]
	ds_write_b128 v200, v[98:101] offset:64
	ds_read_b128 v[98:101], v201
	ds_read_b128 v[102:105], v201 offset:1152
	v_mov_b32_e32 v187, v163
	v_mov_b32_e32 v189, v163
	s_waitcnt vmcnt(11) lgkmcnt(1)
	v_pk_fma_f32 v[100:101], v[56:57], v[100:101], v[136:137]
	v_add_u32_e32 v136, 0x10000, v202
	v_pk_fma_f32 v[98:99], v[54:55], v[98:99], v[134:135]
	v_lshlrev_b32_e32 v134, 2, v136
	s_waitcnt lgkmcnt(0)
	v_pk_fma_f32 v[102:103], v[54:55], v[102:103], v[130:131]
	global_store_dwordx4 v134, v[98:101], s[48:49]
	v_pk_mul_f32 v[134:135], v[180:181], v[98:99]
	v_pk_fma_f32 v[104:105], v[56:57], v[104:105], v[132:133]
	v_pk_mul_f32 v[130:131], v[180:181], v[102:103]
	v_pk_mul_f32 v[144:145], v[178:179], v[100:101]
	v_cvt_pk_bf16_f32 v134, v134, v135
	v_pk_mul_f32 v[132:133], v[178:179], v[104:105]
	v_cvt_pk_bf16_f32 v135, v144, v145
	global_store_dwordx4 v[142:143], v[102:105], off
	v_cvt_pk_bf16_f32 v130, v130, v131
	v_cvt_pk_bf16_f32 v131, v132, v133
	ds_write_b128 v200, v[94:97]
	ds_write_b128 v200, v[90:93] offset:64
	ds_read_b128 v[90:93], v201
	ds_read_b128 v[94:97], v201 offset:1152
	v_lshl_add_u64 v[132:133], s[48:49], 0, v[186:187]
	v_lshl_add_u64 v[142:143], s[48:49], 0, v[188:189]
	s_waitcnt lgkmcnt(1)
	v_pk_fma_f32 v[90:91], v[50:51], v[90:91], v[126:127]
	v_pk_fma_f32 v[92:93], v[52:53], v[92:93], v[128:129]
	v_pk_mul_f32 v[128:129], v[176:177], v[90:91]
	global_store_dwordx4 v[132:133], v[90:93], off
	v_pk_mul_f32 v[126:127], v[174:175], v[92:93]
	v_cvt_pk_bf16_f32 v128, v128, v129
	s_waitcnt vmcnt(13) lgkmcnt(0)
	v_pk_fma_f32 v[94:95], v[50:51], v[94:95], v[122:123]
	v_cvt_pk_bf16_f32 v129, v126, v127
	ds_bpermute_b32 v122, v203, v128
	ds_bpermute_b32 v123, v203, v129
	v_pk_fma_f32 v[96:97], v[52:53], v[96:97], v[124:125]
	v_pk_mul_f32 v[124:125], v[176:177], v[94:95]
	v_pk_mul_f32 v[126:127], v[174:175], v[96:97]
	global_store_dwordx4 v[142:143], v[94:97], off
	v_cvt_pk_bf16_f32 v124, v124, v125
	v_cvt_pk_bf16_f32 v125, v126, v127
	v_lshlrev_b32_e32 v126, 1, v136
	s_waitcnt lgkmcnt(0)
	v_add_u32_e32 v250, 0xfffff040, v126
	v_cndmask_b32_e64 v250, v126, v250, s[40:41]
	v_cndmask_b32_e64 v248, v134, v122, s[40:41]
	v_cndmask_b32_e64 v249, v135, v123, s[40:41]
	global_store_dwordx2 v250, v[248:249], s[46:47]
	v_cndmask_b32_e64 v246, v122, v134, s[40:41]
	v_cndmask_b32_e64 v247, v123, v135, s[40:41]
	s_waitcnt lgkmcnt(1)
	v_add_u32_e32 v122, 0x1040, v126
	v_cndmask_b32_e64 v122, v126, v122, s[38:39]
	global_store_dwordx2 v122, v[246:247], s[46:47]
	ds_bpermute_b32 v122, v203, v124
	s_waitcnt lgkmcnt(1)
	ds_bpermute_b32 v123, v203, v125
	v_add_u32_e32 v125, 0x14000, v202
	v_lshlrev_b32_e32 v124, 1, v125
	s_waitcnt lgkmcnt(0)
	v_add_u32_e32 v250, 0xfffff040, v124
	v_cndmask_b32_e64 v250, v124, v250, s[40:41]
	v_cndmask_b32_e64 v248, v130, v122, s[40:41]
	v_cndmask_b32_e64 v249, v131, v123, s[40:41]
	global_store_dwordx2 v250, v[248:249], s[46:47]
	v_cndmask_b32_e64 v246, v122, v130, s[40:41]
	v_cndmask_b32_e64 v247, v123, v131, s[40:41]
	v_mul_f32_e32 v91, v91, v91
	v_fmac_f32_e32 v91, v90, v90
	v_mul_f32_e32 v90, v93, v93
	v_mul_f32_e32 v101, v101, v101
	v_fmac_f32_e32 v90, v92, v92
	v_mul_f32_e32 v99, v99, v99
	v_fmac_f32_e32 v101, v100, v100
	v_mul_f32_e32 v100, v103, v103
	v_mul_f32_e32 v103, v105, v105
	v_add_f32_e32 v90, v91, v90
	v_mul_f32_e32 v91, v95, v95
	v_mul_f32_e32 v92, v97, v97
	v_fmac_f32_e32 v103, v104, v104
	v_fmac_f32_e32 v91, v94, v94
	v_fmac_f32_e32 v92, v96, v96
	v_fmac_f32_e32 v99, v98, v98
	v_fmac_f32_e32 v100, v102, v102
	v_add_f32_e32 v91, v91, v92
	v_add_f32_e32 v92, v99, v101
	v_add_f32_e32 v93, v100, v103
	v_add_f32_e32 v90, v92, v90
	v_add_f32_e32 v91, v93, v91
	ds_bpermute_b32 v92, v190, v90
	ds_bpermute_b32 v93, v190, v91
	s_waitcnt lgkmcnt(1)
	v_add_f32_e32 v90, v90, v92
	s_waitcnt lgkmcnt(0)
	v_add_f32_e32 v93, v91, v93
	ds_bpermute_b32 v92, v191, v90
	ds_bpermute_b32 v94, v191, v93
	s_waitcnt lgkmcnt(1)
	v_add_f32_e32 v90, v90, v92
	s_waitcnt lgkmcnt(0)
	v_add_f32_e32 v92, v93, v94
	ds_bpermute_b32 v91, v204, v90
	ds_bpermute_b32 v93, v204, v92
	v_add_u32_e32 v94, 0x1040, v124
	v_cndmask_b32_e64 v94, v124, v94, s[38:39]
	global_store_dwordx2 v94, v[246:247], s[46:47]
	s_and_saveexec_b64 s[16:17], s[42:43]
	s_cbranch_execz .LBB0_1283
	s_waitcnt lgkmcnt(1)
	v_add_f32_e32 v90, v90, v91
	s_waitcnt lgkmcnt(0)
	v_add_f32_e32 v91, v92, v93
	ds_write2_b32 v194, v90, v91 offset0:32 offset1:40
; #define LAS __attribute__((address_space(3)))
; #define ERN_EOFF(q, m) (eb + (unsigned)((((q) & 1) * HALF + (m) * 16) * DM + ERN_COL((q) >> 1)))
;     __device__ __forceinline__ void operator()(const f32x4 (&acc)[2][2][4][2], const Unit& u, int wr, int wc, int fr, int fq) const {
;     ...
;         for (int g = 0; g < 8; ++g) { const int ai = g >> 2, m = g & 3;
;             if (g + 1 < 8) ERN_LOADX(g + 1);
;             float sq0 = 0.f, sq1 = 0.f; u32x2 hw[2][2];
; #pragma unroll
;             for (int bj = 0; bj < 2; ++bj) {
;                 *(LAS f32x4*)(st + wr_off) = acc[ai][bj][m][0]; *(LAS f32x4*)(st + wr_off + 64) = acc[ai][bj][m][1];
;                 const f32x4 a0 = *(const LAS f32x4*)(st + rd_off), a1 = *(const LAS f32x4*)(st + rd_off + 8 * 144);
;                 { const f32x4 xv = xb[g & 1][bj][0] + gv[bj] * a0; __builtin_nontemporal_store(xv, (f32x4*)((char*)xo + 4u * ERN_EOFF(g, bj, 0)));
;                   sq0 += (xv.x * xv.x + xv.y * xv.y) + (xv.z * xv.z + xv.w * xv.w);
;                   const f32x4 hv = xv * gsn[bj]; hw[bj][0].x = cvt_pk_bf16(hv.x, hv.y); hw[bj][0].y = cvt_pk_bf16(hv.z, hv.w); }
;                 { const f32x4 xv = xb[g & 1][bj][1] + gv[bj] * a1; __builtin_nontemporal_store(xv, (f32x4*)((char*)xo + 4u * ERN_EOFF(g, bj, 1)));
;                   sq1 += (xv.x * xv.x + xv.y * xv.y) + (xv.z * xv.z + xv.w * xv.w);
;                   const f32x4 hv = xv * gsn[bj]; hw[bj][1].x = cvt_pk_bf16(hv.x, hv.y); hw[bj][1].y = cvt_pk_bf16(hv.z, hv.w); }
;             }
;             if (!NOH && !PLAIN) {
; #pragma unroll
;                 for (int rh = 0; rh < 2; ++rh) { u32x2 rv; rv.x = __shfl_xor(hw[1][rh].x, 8); rv.y = __shfl_xor(hw[1][rh].y, 8);
;                     const unsigned e0 = ERN_EOFF(g, 0, rh);
;                     const unsigned ee = odd ? (e0 - DM + 32) : e0, eo2 = odd ? e0 : (e0 + DM + 32);
;                     *(u32x2*)((char*)ho + 2u * ee) = odd ? rv : hw[0][rh];
;                     *(u32x2*)((char*)ho + 2u * eo2) = odd ? hw[0][rh] : rv; }
;             }
;             if (!PLAIN) { sq0 += __shfl_xor(sq0, 1); sq0 += __shfl_xor(sq0, 2); sq0 += __shfl_xor(sq0, 4);
;             sq1 += __shfl_xor(sq1, 1); sq1 += __shfl_xor(sq1, 2); sq1 += __shfl_xor(sq1, 4); }
;             if (!PLAIN && pc == 0) { sst[g * 16 + rr] = sq0; sst[g * 16 + 8 + rr] = sq1; }
.LBB0_1283:
	s_or_b64 exec, exec, s[16:17]
	v_lshl_add_u64 v[124:125], s[48:49], 0, v[162:163]
	v_add_u32_e32 v90, 0x100000, v205
	s_waitcnt lgkmcnt(1)
	v_add_u32_e32 v91, 0x110000, v205
	v_add_u32_e32 v162, 0x100080, v205
	global_load_dwordx4 v[102:105], v90, s[48:49]
	global_load_dwordx4 v[98:101], v91, s[48:49]
	v_add_u32_e32 v122, 0x110080, v205
	global_load_dwordx4 v[94:97], v162, s[48:49]
	s_waitcnt lgkmcnt(0)
	global_load_dwordx4 v[90:93], v122, s[48:49]
	ds_write_b128 v200, v[86:89]
	ds_write_b128 v200, v[82:85] offset:64
	ds_read_b128 v[82:85], v201
	ds_read_b128 v[86:89], v201 offset:1152
	v_mov_b32_e32 v139, v163
	v_mov_b32_e32 v141, v163
	s_waitcnt vmcnt(11) lgkmcnt(1)
	v_pk_fma_f32 v[84:85], v[56:57], v[84:85], v[120:121]
	v_add_u32_e32 v120, 0x18000, v202
	v_pk_fma_f32 v[82:83], v[54:55], v[82:83], v[118:119]
	v_lshlrev_b32_e32 v118, 2, v120
	s_waitcnt lgkmcnt(0)
	v_pk_fma_f32 v[86:87], v[54:55], v[86:87], v[114:115]
	global_store_dwordx4 v118, v[82:85], s[48:49]
	v_pk_mul_f32 v[118:119], v[180:181], v[82:83]
	v_pk_fma_f32 v[88:89], v[56:57], v[88:89], v[116:117]
	v_pk_mul_f32 v[114:115], v[180:181], v[86:87]
	v_pk_mul_f32 v[126:127], v[178:179], v[84:85]
	v_cvt_pk_bf16_f32 v118, v118, v119
	v_pk_mul_f32 v[116:117], v[178:179], v[88:89]
	v_cvt_pk_bf16_f32 v119, v126, v127
	global_store_dwordx4 v[124:125], v[86:89], off
	v_cvt_pk_bf16_f32 v114, v114, v115
	v_cvt_pk_bf16_f32 v115, v116, v117
	ds_write_b128 v200, v[78:81]
	ds_write_b128 v200, v[74:77] offset:64
	ds_read_b128 v[74:77], v201
	ds_read_b128 v[78:81], v201 offset:1152
	v_lshl_add_u64 v[116:117], s[48:49], 0, v[138:139]
	v_lshl_add_u64 v[124:125], s[48:49], 0, v[140:141]
	s_waitcnt lgkmcnt(1)
	v_pk_fma_f32 v[74:75], v[50:51], v[74:75], v[110:111]
	v_pk_fma_f32 v[76:77], v[52:53], v[76:77], v[112:113]
	v_pk_mul_f32 v[112:113], v[176:177], v[74:75]
	global_store_dwordx4 v[116:117], v[74:77], off
	v_pk_mul_f32 v[110:111], v[174:175], v[76:77]
	v_cvt_pk_bf16_f32 v112, v112, v113
	s_waitcnt vmcnt(13) lgkmcnt(0)
	v_pk_fma_f32 v[78:79], v[50:51], v[78:79], v[106:107]
	v_cvt_pk_bf16_f32 v113, v110, v111
	ds_bpermute_b32 v106, v203, v112
	ds_bpermute_b32 v107, v203, v113
	v_pk_fma_f32 v[80:81], v[52:53], v[80:81], v[108:109]
	v_pk_mul_f32 v[108:109], v[176:177], v[78:79]
	v_pk_mul_f32 v[110:111], v[174:175], v[80:81]
	global_store_dwordx4 v[124:125], v[78:81], off
	v_cvt_pk_bf16_f32 v108, v108, v109
	v_cvt_pk_bf16_f32 v109, v110, v111
	v_lshlrev_b32_e32 v110, 1, v120
	s_waitcnt lgkmcnt(0)
	v_add_u32_e32 v250, 0xfffff040, v110
	v_cndmask_b32_e64 v250, v110, v250, s[40:41]
	v_cndmask_b32_e64 v248, v118, v106, s[40:41]
	v_cndmask_b32_e64 v249, v119, v107, s[40:41]
	global_store_dwordx2 v250, v[248:249], s[46:47]
	v_cndmask_b32_e64 v246, v106, v118, s[40:41]
	v_cndmask_b32_e64 v247, v107, v119, s[40:41]
	s_waitcnt lgkmcnt(1)
	v_add_u32_e32 v106, 0x1040, v110
	v_cndmask_b32_e64 v106, v110, v106, s[38:39]
	global_store_dwordx2 v106, v[246:247], s[46:47]
	ds_bpermute_b32 v106, v203, v108
	s_waitcnt lgkmcnt(1)
	ds_bpermute_b32 v107, v203, v109
	v_add_u32_e32 v109, 0x1c000, v202
	v_lshlrev_b32_e32 v108, 1, v109
	s_waitcnt lgkmcnt(0)
	v_add_u32_e32 v250, 0xfffff040, v108
	v_cndmask_b32_e64 v250, v108, v250, s[40:41]
	v_cndmask_b32_e64 v248, v114, v106, s[40:41]
	v_cndmask_b32_e64 v249, v115, v107, s[40:41]
	global_store_dwordx2 v250, v[248:249], s[46:47]
	v_cndmask_b32_e64 v246, v106, v114, s[40:41]
	v_cndmask_b32_e64 v247, v107, v115, s[40:41]
	v_mul_f32_e32 v75, v75, v75
	v_fmac_f32_e32 v75, v74, v74
	v_mul_f32_e32 v74, v77, v77
	v_mul_f32_e32 v85, v85, v85
	v_fmac_f32_e32 v74, v76, v76
	v_mul_f32_e32 v83, v83, v83
	v_fmac_f32_e32 v85, v84, v84
	v_mul_f32_e32 v84, v87, v87
	v_mul_f32_e32 v87, v89, v89
	v_add_f32_e32 v74, v75, v74
	v_mul_f32_e32 v75, v79, v79
	v_mul_f32_e32 v76, v81, v81
	v_fmac_f32_e32 v87, v88, v88
	v_fmac_f32_e32 v75, v78, v78
	v_fmac_f32_e32 v76, v80, v80
	v_fmac_f32_e32 v83, v82, v82
	v_fmac_f32_e32 v84, v86, v86
	v_add_f32_e32 v75, v75, v76
	v_add_f32_e32 v76, v83, v85
	v_add_f32_e32 v77, v84, v87
	v_add_f32_e32 v74, v76, v74
	v_add_f32_e32 v75, v77, v75
	ds_bpermute_b32 v76, v190, v74
	ds_bpermute_b32 v77, v190, v75
	s_waitcnt lgkmcnt(1)
	v_add_f32_e32 v74, v74, v76
	s_waitcnt lgkmcnt(0)
	v_add_f32_e32 v77, v75, v77
	ds_bpermute_b32 v76, v191, v74
	ds_bpermute_b32 v78, v191, v77
	s_waitcnt lgkmcnt(1)
	v_add_f32_e32 v74, v74, v76
	s_waitcnt lgkmcnt(0)
	v_add_f32_e32 v76, v77, v78
	ds_bpermute_b32 v75, v204, v74
	ds_bpermute_b32 v77, v204, v76
	v_add_u32_e32 v78, 0x1040, v108
	v_cndmask_b32_e64 v78, v108, v78, s[38:39]
	global_store_dwordx2 v78, v[246:247], s[46:47]
	s_and_saveexec_b64 s[16:17], s[42:43]
	s_cbranch_execz .LBB0_1293
	s_waitcnt lgkmcnt(1)
	v_add_f32_e32 v74, v74, v75
	s_waitcnt lgkmcnt(0)
	v_add_f32_e32 v75, v76, v77
	ds_write2_b32 v194, v74, v75 offset0:48 offset1:56
; #define LAS __attribute__((address_space(3)))
; #define ERN_EOFF(q, m) (eb + (unsigned)((((q) & 1) * HALF + (m) * 16) * DM + ERN_COL((q) >> 1)))
;     __device__ __forceinline__ void operator()(const f32x4 (&acc)[2][2][4][2], const Unit& u, int wr, int wc, int fr, int fq) const {
;     ...
;         for (int g = 0; g < 8; ++g) { const int ai = g >> 2, m = g & 3;
;             if (g + 1 < 8) ERN_LOADX(g + 1);
;             float sq0 = 0.f, sq1 = 0.f; u32x2 hw[2][2];
; #pragma unroll
;             for (int bj = 0; bj < 2; ++bj) {
;                 *(LAS f32x4*)(st + wr_off) = acc[ai][bj][m][0]; *(LAS f32x4*)(st + wr_off + 64) = acc[ai][bj][m][1];
;                 const f32x4 a0 = *(const LAS f32x4*)(st + rd_off), a1 = *(const LAS f32x4*)(st + rd_off + 8 * 144);
;                 { const f32x4 xv = xb[g & 1][bj][0] + gv[bj] * a0; __builtin_nontemporal_store(xv, (f32x4*)((char*)xo + 4u * ERN_EOFF(g, bj, 0)));
;                   sq0 += (xv.x * xv.x + xv.y * xv.y) + (xv.z * xv.z + xv.w * xv.w);
;                   const f32x4 hv = xv * gsn[bj]; hw[bj][0].x = cvt_pk_bf16(hv.x, hv.y); hw[bj][0].y = cvt_pk_bf16(hv.z, hv.w); }
;                 { const f32x4 xv = xb[g & 1][bj][1] + gv[bj] * a1; __builtin_nontemporal_store(xv, (f32x4*)((char*)xo + 4u * ERN_EOFF(g, bj, 1)));
;                   sq1 += (xv.x * xv.x + xv.y * xv.y) + (xv.z * xv.z + xv.w * xv.w);
;                   const f32x4 hv = xv * gsn[bj]; hw[bj][1].x = cvt_pk_bf16(hv.x, hv.y); hw[bj][1].y = cvt_pk_bf16(hv.z, hv.w); }
;             }
;             if (!NOH && !PLAIN) {
; #pragma unroll
;                 for (int rh = 0; rh < 2; ++rh) { u32x2 rv; rv.x = __shfl_xor(hw[1][rh].x, 8); rv.y = __shfl_xor(hw[1][rh].y, 8);
;                     const unsigned e0 = ERN_EOFF(g, 0, rh);
;                     const unsigned ee = odd ? (e0 - DM + 32) : e0, eo2 = odd ? e0 : (e0 + DM + 32);
;                     *(u32x2*)((char*)ho + 2u * ee) = odd ? rv : hw[0][rh];
;                     *(u32x2*)((char*)ho + 2u * eo2) = odd ? hw[0][rh] : rv; }
;             }
;             if (!PLAIN) { sq0 += __shfl_xor(sq0, 1); sq0 += __shfl_xor(sq0, 2); sq0 += __shfl_xor(sq0, 4);
;             sq1 += __shfl_xor(sq1, 1); sq1 += __shfl_xor(sq1, 2); sq1 += __shfl_xor(sq1, 4); }
;             if (!PLAIN && pc == 0) { sst[g * 16 + rr] = sq0; sst[g * 16 + 8 + rr] = sq1; }
.LBB0_1293:
	s_or_b64 exec, exec, s[16:17]
	v_lshl_add_u64 v[112:113], s[48:49], 0, v[162:163]
	v_add_u32_e32 v162, 0x120000, v205
	v_add_u32_e32 v108, 0x120080, v205
	v_add_u32_e32 v110, 0x130000, v205
	global_load_dwordx4 v[86:89], v162, s[48:49]
	global_load_dwordx4 v[82:85], v110, s[48:49]
	v_add_u32_e32 v106, 0x130080, v205
	global_load_dwordx4 v[78:81], v108, s[48:49]
	s_waitcnt lgkmcnt(0)
	global_load_dwordx4 v[74:77], v106, s[48:49]
	ds_write_b128 v200, v[70:73]
	ds_write_b128 v200, v[66:69] offset:64
	ds_read_b128 v[66:69], v201
	ds_read_b128 v[70:73], v201 offset:1152
	v_mov_b32_e32 v123, v163
	s_waitcnt vmcnt(13) lgkmcnt(1)
	v_pk_fma_f32 v[68:69], v[56:57], v[68:69], v[104:105]
	v_add_u32_e32 v104, 0x40000, v202
	v_pk_fma_f32 v[66:67], v[54:55], v[66:67], v[102:103]
	v_lshlrev_b32_e32 v102, 2, v104
	s_waitcnt vmcnt(12) lgkmcnt(0)
	v_pk_fma_f32 v[72:73], v[56:57], v[72:73], v[100:101]
	v_add_u32_e32 v100, 0x44000, v202
	global_store_dwordx4 v102, v[66:69], s[48:49]
	v_pk_mul_f32 v[102:103], v[180:181], v[66:67]
	v_pk_fma_f32 v[70:71], v[54:55], v[70:71], v[98:99]
	v_lshlrev_b32_e32 v98, 2, v100
	v_pk_mul_f32 v[114:115], v[178:179], v[68:69]
	v_cvt_pk_bf16_f32 v102, v102, v103
	s_nop 0
	v_cvt_pk_bf16_f32 v103, v114, v115
	global_store_dwordx4 v98, v[70:73], s[48:49]
	v_pk_mul_f32 v[98:99], v[180:181], v[70:71]
	v_pk_mul_f32 v[114:115], v[178:179], v[72:73]
	v_cvt_pk_bf16_f32 v98, v98, v99
	s_nop 0
	v_cvt_pk_bf16_f32 v99, v114, v115
	ds_write_b128 v200, v[62:65]
	ds_write_b128 v200, v[58:61] offset:64
	ds_read_b128 v[58:61], v201
	ds_read_b128 v[62:65], v201 offset:1152
	v_lshl_add_u64 v[114:115], s[48:49], 0, v[122:123]
	s_waitcnt vmcnt(13) lgkmcnt(1)
	v_pk_fma_f32 v[58:59], v[50:51], v[58:59], v[94:95]
	v_pk_fma_f32 v[60:61], v[52:53], v[60:61], v[96:97]
	v_pk_mul_f32 v[96:97], v[176:177], v[58:59]
	global_store_dwordx4 v[112:113], v[58:61], off
	v_pk_mul_f32 v[94:95], v[174:175], v[60:61]
	v_cvt_pk_bf16_f32 v96, v96, v97
	s_waitcnt vmcnt(13) lgkmcnt(0)
	v_pk_fma_f32 v[62:63], v[50:51], v[62:63], v[90:91]
	v_cvt_pk_bf16_f32 v97, v94, v95
	ds_bpermute_b32 v90, v203, v96
	ds_bpermute_b32 v91, v203, v97
	v_pk_fma_f32 v[64:65], v[52:53], v[64:65], v[92:93]
	v_pk_mul_f32 v[92:93], v[176:177], v[62:63]
	v_pk_mul_f32 v[94:95], v[174:175], v[64:65]
	global_store_dwordx4 v[114:115], v[62:65], off
	v_cvt_pk_bf16_f32 v92, v92, v93
	v_cvt_pk_bf16_f32 v93, v94, v95
	v_lshlrev_b32_e32 v94, 1, v104
	s_waitcnt lgkmcnt(0)
	v_add_u32_e32 v250, 0xfffff040, v94
	v_cndmask_b32_e64 v250, v94, v250, s[40:41]
	v_cndmask_b32_e64 v248, v102, v90, s[40:41]
	v_cndmask_b32_e64 v249, v103, v91, s[40:41]
	global_store_dwordx2 v250, v[248:249], s[46:47]
	v_cndmask_b32_e64 v246, v90, v102, s[40:41]
	v_cndmask_b32_e64 v247, v91, v103, s[40:41]
	s_waitcnt lgkmcnt(1)
	v_add_u32_e32 v90, 0x1040, v94
	v_cndmask_b32_e64 v90, v94, v90, s[38:39]
	global_store_dwordx2 v90, v[246:247], s[46:47]
	ds_bpermute_b32 v90, v203, v92
	s_waitcnt lgkmcnt(1)
	ds_bpermute_b32 v91, v203, v93
	v_lshlrev_b32_e32 v92, 1, v100
	s_waitcnt lgkmcnt(0)
	v_add_u32_e32 v250, 0xfffff040, v92
	v_cndmask_b32_e64 v250, v92, v250, s[40:41]
	v_cndmask_b32_e64 v248, v98, v90, s[40:41]
	v_cndmask_b32_e64 v249, v99, v91, s[40:41]
	global_store_dwordx2 v250, v[248:249], s[46:47]
	v_cndmask_b32_e64 v246, v90, v98, s[40:41]
	v_cndmask_b32_e64 v247, v91, v99, s[40:41]
	v_mul_f32_e32 v59, v59, v59
	v_fmac_f32_e32 v59, v58, v58
	v_mul_f32_e32 v58, v61, v61
	v_mul_f32_e32 v69, v69, v69
	v_fmac_f32_e32 v58, v60, v60
	v_mul_f32_e32 v67, v67, v67
	v_fmac_f32_e32 v69, v68, v68
	v_mul_f32_e32 v68, v71, v71
	v_mul_f32_e32 v71, v73, v73
	v_add_f32_e32 v58, v59, v58
	v_mul_f32_e32 v59, v63, v63
	v_mul_f32_e32 v60, v65, v65
	v_fmac_f32_e32 v71, v72, v72
	v_fmac_f32_e32 v59, v62, v62
	v_fmac_f32_e32 v60, v64, v64
	v_fmac_f32_e32 v67, v66, v66
	v_fmac_f32_e32 v68, v70, v70
	v_add_f32_e32 v59, v59, v60
	v_add_f32_e32 v60, v67, v69
	v_add_f32_e32 v61, v68, v71
	v_add_f32_e32 v58, v60, v58
	v_add_f32_e32 v59, v61, v59
	ds_bpermute_b32 v60, v190, v58
	ds_bpermute_b32 v61, v190, v59
	s_waitcnt lgkmcnt(1)
	v_add_f32_e32 v58, v58, v60
	s_waitcnt lgkmcnt(0)
	v_add_f32_e32 v61, v59, v61
	ds_bpermute_b32 v60, v191, v58
	ds_bpermute_b32 v62, v191, v61
	s_waitcnt lgkmcnt(1)
	v_add_f32_e32 v58, v58, v60
	s_waitcnt lgkmcnt(0)
	v_add_f32_e32 v60, v61, v62
	ds_bpermute_b32 v59, v204, v58
	ds_bpermute_b32 v61, v204, v60
	v_add_u32_e32 v62, 0x1040, v92
	v_cndmask_b32_e64 v62, v92, v62, s[38:39]
	global_store_dwordx2 v62, v[246:247], s[46:47]
	s_and_saveexec_b64 s[16:17], s[42:43]
	s_cbranch_execz .LBB0_1303
	s_waitcnt lgkmcnt(1)
	v_add_f32_e32 v58, v58, v59
	s_waitcnt lgkmcnt(0)
	v_add_f32_e32 v59, v60, v61
	ds_write2_b32 v194, v58, v59 offset0:64 offset1:72
; #define LAS __attribute__((address_space(3)))
; #define ERN_EOFF(q, m) (eb + (unsigned)((((q) & 1) * HALF + (m) * 16) * DM + ERN_COL((q) >> 1)))
;     __device__ __forceinline__ void operator()(const f32x4 (&acc)[2][2][4][2], const Unit& u, int wr, int wc, int fr, int fq) const {
;     ...
;         for (int g = 0; g < 8; ++g) { const int ai = g >> 2, m = g & 3;
;             if (g + 1 < 8) ERN_LOADX(g + 1);
;             float sq0 = 0.f, sq1 = 0.f; u32x2 hw[2][2];
; #pragma unroll
;             for (int bj = 0; bj < 2; ++bj) {
;                 *(LAS f32x4*)(st + wr_off) = acc[ai][bj][m][0]; *(LAS f32x4*)(st + wr_off + 64) = acc[ai][bj][m][1];
;                 const f32x4 a0 = *(const LAS f32x4*)(st + rd_off), a1 = *(const LAS f32x4*)(st + rd_off + 8 * 144);
;                 { const f32x4 xv = xb[g & 1][bj][0] + gv[bj] * a0; __builtin_nontemporal_store(xv, (f32x4*)((char*)xo + 4u * ERN_EOFF(g, bj, 0)));
;                   sq0 += (xv.x * xv.x + xv.y * xv.y) + (xv.z * xv.z + xv.w * xv.w);
;                   const f32x4 hv = xv * gsn[bj]; hw[bj][0].x = cvt_pk_bf16(hv.x, hv.y); hw[bj][0].y = cvt_pk_bf16(hv.z, hv.w); }
;                 { const f32x4 xv = xb[g & 1][bj][1] + gv[bj] * a1; __builtin_nontemporal_store(xv, (f32x4*)((char*)xo + 4u * ERN_EOFF(g, bj, 1)));
;                   sq1 += (xv.x * xv.x + xv.y * xv.y) + (xv.z * xv.z + xv.w * xv.w);
;                   const f32x4 hv = xv * gsn[bj]; hw[bj][1].x = cvt_pk_bf16(hv.x, hv.y); hw[bj][1].y = cvt_pk_bf16(hv.z, hv.w); }
;             }
;             if (!NOH && !PLAIN) {
; #pragma unroll
;                 for (int rh = 0; rh < 2; ++rh) { u32x2 rv; rv.x = __shfl_xor(hw[1][rh].x, 8); rv.y = __shfl_xor(hw[1][rh].y, 8);
;                     const unsigned e0 = ERN_EOFF(g, 0, rh);
;                     const unsigned ee = odd ? (e0 - DM + 32) : e0, eo2 = odd ? e0 : (e0 + DM + 32);
;                     *(u32x2*)((char*)ho + 2u * ee) = odd ? rv : hw[0][rh];
;                     *(u32x2*)((char*)ho + 2u * eo2) = odd ? hw[0][rh] : rv; }
;             }
;             if (!PLAIN) { sq0 += __shfl_xor(sq0, 1); sq0 += __shfl_xor(sq0, 2); sq0 += __shfl_xor(sq0, 4);
;             sq1 += __shfl_xor(sq1, 1); sq1 += __shfl_xor(sq1, 2); sq1 += __shfl_xor(sq1, 4); }
;             if (!PLAIN && pc == 0) { sst[g * 16 + rr] = sq0; sst[g * 16 + 8 + rr] = sq1; }
.LBB0_1303:
	s_or_b64 exec, exec, s[16:17]
	v_lshl_add_u64 v[96:97], s[48:49], 0, v[162:163]
	v_add_u32_e32 v162, 0x140000, v205
	v_add_u32_e32 v92, 0x140080, v205
	v_add_u32_e32 v94, 0x150000, v205
	global_load_dwordx4 v[70:73], v162, s[48:49]
	global_load_dwordx4 v[66:69], v94, s[48:49]
	v_add_u32_e32 v90, 0x150080, v205
	global_load_dwordx4 v[62:65], v92, s[48:49]
	s_waitcnt lgkmcnt(0)
	global_load_dwordx4 v[58:61], v90, s[48:49]
	ds_write_b128 v200, v[46:49]
	ds_write_b128 v200, v[42:45] offset:64
	ds_read_b128 v[42:45], v201
	ds_read_b128 v[46:49], v201 offset:1152
	v_mov_b32_e32 v111, v163
	v_lshl_add_u64 v[98:99], s[48:49], 0, v[110:111]
	v_mov_b32_e32 v109, v163
	s_waitcnt vmcnt(13) lgkmcnt(1)
	v_pk_fma_f32 v[42:43], v[54:55], v[42:43], v[86:87]
	s_waitcnt vmcnt(12) lgkmcnt(0)
	v_pk_fma_f32 v[46:47], v[54:55], v[46:47], v[82:83]
	v_pk_fma_f32 v[44:45], v[56:57], v[44:45], v[88:89]
	v_pk_mul_f32 v[86:87], v[180:181], v[42:43]
	v_pk_fma_f32 v[48:49], v[56:57], v[48:49], v[84:85]
	v_pk_mul_f32 v[82:83], v[180:181], v[46:47]
	global_store_dwordx4 v[96:97], v[42:45], off
	v_pk_mul_f32 v[88:89], v[178:179], v[44:45]
	v_cvt_pk_bf16_f32 v86, v86, v87
	v_pk_mul_f32 v[84:85], v[178:179], v[48:49]
	v_cvt_pk_bf16_f32 v87, v88, v89
	global_store_dwordx4 v[98:99], v[46:49], off
	v_cvt_pk_bf16_f32 v82, v82, v83
	v_cvt_pk_bf16_f32 v83, v84, v85
	ds_write_b128 v200, v[38:41]
	ds_write_b128 v200, v[34:37] offset:64
	ds_read_b128 v[34:37], v201
	ds_read_b128 v[38:41], v201 offset:1152
	v_lshl_add_u64 v[84:85], s[48:49], 0, v[108:109]
	v_mov_b32_e32 v107, v163
	v_lshl_add_u64 v[88:89], s[48:49], 0, v[106:107]
	s_waitcnt vmcnt(13) lgkmcnt(1)
	v_pk_fma_f32 v[34:35], v[50:51], v[34:35], v[78:79]
	v_pk_fma_f32 v[36:37], v[52:53], v[36:37], v[80:81]
	v_pk_mul_f32 v[80:81], v[176:177], v[34:35]
	global_store_dwordx4 v[84:85], v[34:37], off
	v_pk_mul_f32 v[78:79], v[174:175], v[36:37]
	v_cvt_pk_bf16_f32 v80, v80, v81
	s_waitcnt vmcnt(13) lgkmcnt(0)
	v_pk_fma_f32 v[38:39], v[50:51], v[38:39], v[74:75]
	v_cvt_pk_bf16_f32 v81, v78, v79
	ds_bpermute_b32 v74, v203, v80
	ds_bpermute_b32 v75, v203, v81
	v_pk_fma_f32 v[40:41], v[52:53], v[40:41], v[76:77]
	v_pk_mul_f32 v[76:77], v[176:177], v[38:39]
	v_pk_mul_f32 v[78:79], v[174:175], v[40:41]
	global_store_dwordx4 v[88:89], v[38:41], off
	v_cvt_pk_bf16_f32 v76, v76, v77
	v_cvt_pk_bf16_f32 v77, v78, v79
	v_add_u32_e32 v79, 0x48000, v202
	v_lshlrev_b32_e32 v78, 1, v79
	s_waitcnt lgkmcnt(0)
	v_add_u32_e32 v250, 0xfffff040, v78
	v_cndmask_b32_e64 v250, v78, v250, s[40:41]
	v_cndmask_b32_e64 v248, v86, v74, s[40:41]
	v_cndmask_b32_e64 v249, v87, v75, s[40:41]
	global_store_dwordx2 v250, v[248:249], s[46:47]
	v_cndmask_b32_e64 v246, v74, v86, s[40:41]
	v_cndmask_b32_e64 v247, v75, v87, s[40:41]
	s_waitcnt lgkmcnt(1)
	v_add_u32_e32 v74, 0x1040, v78
	v_cndmask_b32_e64 v74, v78, v74, s[38:39]
	global_store_dwordx2 v74, v[246:247], s[46:47]
	ds_bpermute_b32 v74, v203, v76
	s_waitcnt lgkmcnt(1)
	ds_bpermute_b32 v75, v203, v77
	v_add_u32_e32 v77, 0x4c000, v202
	v_lshlrev_b32_e32 v76, 1, v77
	s_waitcnt lgkmcnt(0)
	v_add_u32_e32 v250, 0xfffff040, v76
	v_cndmask_b32_e64 v250, v76, v250, s[40:41]
	v_cndmask_b32_e64 v248, v82, v74, s[40:41]
	v_cndmask_b32_e64 v249, v83, v75, s[40:41]
	global_store_dwordx2 v250, v[248:249], s[46:47]
	v_cndmask_b32_e64 v246, v74, v82, s[40:41]
	v_cndmask_b32_e64 v247, v75, v83, s[40:41]
	v_mul_f32_e32 v35, v35, v35
	v_fmac_f32_e32 v35, v34, v34
	v_mul_f32_e32 v34, v37, v37
	v_mul_f32_e32 v45, v45, v45
	v_fmac_f32_e32 v34, v36, v36
	v_mul_f32_e32 v43, v43, v43
	v_fmac_f32_e32 v45, v44, v44
	v_mul_f32_e32 v44, v47, v47
	v_mul_f32_e32 v47, v49, v49
	v_add_f32_e32 v34, v35, v34
	v_mul_f32_e32 v35, v39, v39
	v_mul_f32_e32 v36, v41, v41
	v_fmac_f32_e32 v47, v48, v48
	v_fmac_f32_e32 v35, v38, v38
	v_fmac_f32_e32 v36, v40, v40
	v_fmac_f32_e32 v43, v42, v42
	v_fmac_f32_e32 v44, v46, v46
	v_add_f32_e32 v35, v35, v36
	v_add_f32_e32 v36, v43, v45
	v_add_f32_e32 v37, v44, v47
	v_add_f32_e32 v34, v36, v34
	v_add_f32_e32 v35, v37, v35
	ds_bpermute_b32 v36, v190, v34
	ds_bpermute_b32 v37, v190, v35
	s_waitcnt lgkmcnt(1)
	v_add_f32_e32 v34, v34, v36
	s_waitcnt lgkmcnt(0)
	v_add_f32_e32 v37, v35, v37
	ds_bpermute_b32 v36, v191, v34
	ds_bpermute_b32 v38, v191, v37
	s_waitcnt lgkmcnt(1)
	v_add_f32_e32 v34, v34, v36
	s_waitcnt lgkmcnt(0)
	v_add_f32_e32 v36, v37, v38
	ds_bpermute_b32 v35, v204, v34
	ds_bpermute_b32 v37, v204, v36
	v_add_u32_e32 v38, 0x1040, v76
	v_cndmask_b32_e64 v38, v76, v38, s[38:39]
	global_store_dwordx2 v38, v[246:247], s[46:47]
	s_and_saveexec_b64 s[16:17], s[42:43]
	s_cbranch_execz .LBB0_1313
	s_waitcnt lgkmcnt(1)
	v_add_f32_e32 v34, v34, v35
	s_waitcnt lgkmcnt(0)
	v_add_f32_e32 v35, v36, v37
	ds_write2_b32 v194, v34, v35 offset0:80 offset1:88
; #define LAS __attribute__((address_space(3)))
; #define ERN_EOFF(q, m) (eb + (unsigned)((((q) & 1) * HALF + (m) * 16) * DM + ERN_COL((q) >> 1)))
;     __device__ __forceinline__ void operator()(const f32x4 (&acc)[2][2][4][2], const Unit& u, int wr, int wc, int fr, int fq) const {
;     ...
;         for (int g = 0; g < 8; ++g) { const int ai = g >> 2, m = g & 3;
;             if (g + 1 < 8) ERN_LOADX(g + 1);
;             float sq0 = 0.f, sq1 = 0.f; u32x2 hw[2][2];
; #pragma unroll
;             for (int bj = 0; bj < 2; ++bj) {
;                 *(LAS f32x4*)(st + wr_off) = acc[ai][bj][m][0]; *(LAS f32x4*)(st + wr_off + 64) = acc[ai][bj][m][1];
;                 const f32x4 a0 = *(const LAS f32x4*)(st + rd_off), a1 = *(const LAS f32x4*)(st + rd_off + 8 * 144);
;                 { const f32x4 xv = xb[g & 1][bj][0] + gv[bj] * a0; __builtin_nontemporal_store(xv, (f32x4*)((char*)xo + 4u * ERN_EOFF(g, bj, 0)));
;                   sq0 += (xv.x * xv.x + xv.y * xv.y) + (xv.z * xv.z + xv.w * xv.w);
;                   const f32x4 hv = xv * gsn[bj]; hw[bj][0].x = cvt_pk_bf16(hv.x, hv.y); hw[bj][0].y = cvt_pk_bf16(hv.z, hv.w); }
;                 { const f32x4 xv = xb[g & 1][bj][1] + gv[bj] * a1; __builtin_nontemporal_store(xv, (f32x4*)((char*)xo + 4u * ERN_EOFF(g, bj, 1)));
;                   sq1 += (xv.x * xv.x + xv.y * xv.y) + (xv.z * xv.z + xv.w * xv.w);
;                   const f32x4 hv = xv * gsn[bj]; hw[bj][1].x = cvt_pk_bf16(hv.x, hv.y); hw[bj][1].y = cvt_pk_bf16(hv.z, hv.w); }
;             }
;             if (!NOH && !PLAIN) {
; #pragma unroll
;                 for (int rh = 0; rh < 2; ++rh) { u32x2 rv; rv.x = __shfl_xor(hw[1][rh].x, 8); rv.y = __shfl_xor(hw[1][rh].y, 8);
;                     const unsigned e0 = ERN_EOFF(g, 0, rh);
;                     const unsigned ee = odd ? (e0 - DM + 32) : e0, eo2 = odd ? e0 : (e0 + DM + 32);
;                     *(u32x2*)((char*)ho + 2u * ee) = odd ? rv : hw[0][rh];
;                     *(u32x2*)((char*)ho + 2u * eo2) = odd ? hw[0][rh] : rv; }
;             }
;             if (!PLAIN) { sq0 += __shfl_xor(sq0, 1); sq0 += __shfl_xor(sq0, 2); sq0 += __shfl_xor(sq0, 4);
;             sq1 += __shfl_xor(sq1, 1); sq1 += __shfl_xor(sq1, 2); sq1 += __shfl_xor(sq1, 4); }
;             if (!PLAIN && pc == 0) { sst[g * 16 + rr] = sq0; sst[g * 16 + 8 + rr] = sq1; }
.LBB0_1313:
	s_or_b64 exec, exec, s[16:17]
	v_lshl_add_u64 v[80:81], s[48:49], 0, v[162:163]
	v_add_u32_e32 v162, 0x160000, v205
	v_add_u32_e32 v76, 0x160080, v205
	v_add_u32_e32 v78, 0x170000, v205
	global_load_dwordx4 v[46:49], v162, s[48:49]
	global_load_dwordx4 v[42:45], v78, s[48:49]
	v_add_u32_e32 v74, 0x170080, v205
	global_load_dwordx4 v[38:41], v76, s[48:49]
	s_waitcnt lgkmcnt(0)
	global_load_dwordx4 v[34:37], v74, s[48:49]
	ds_write_b128 v200, v[30:33]
	ds_write_b128 v200, v[26:29] offset:64
	ds_read_b128 v[26:29], v201
	ds_read_b128 v[30:33], v201 offset:1152
	v_mov_b32_e32 v95, v163
	v_lshl_add_u64 v[82:83], s[48:49], 0, v[94:95]
	v_mov_b32_e32 v93, v163
	s_waitcnt vmcnt(13) lgkmcnt(1)
	v_pk_fma_f32 v[26:27], v[54:55], v[26:27], v[70:71]
	s_waitcnt vmcnt(12) lgkmcnt(0)
	v_pk_fma_f32 v[30:31], v[54:55], v[30:31], v[66:67]
	v_pk_fma_f32 v[28:29], v[56:57], v[28:29], v[72:73]
	v_pk_mul_f32 v[70:71], v[180:181], v[26:27]
	v_pk_fma_f32 v[32:33], v[56:57], v[32:33], v[68:69]
	v_pk_mul_f32 v[66:67], v[180:181], v[30:31]
	global_store_dwordx4 v[80:81], v[26:29], off
	v_pk_mul_f32 v[72:73], v[178:179], v[28:29]
	v_cvt_pk_bf16_f32 v70, v70, v71
	v_pk_mul_f32 v[68:69], v[178:179], v[32:33]
	v_cvt_pk_bf16_f32 v71, v72, v73
	global_store_dwordx4 v[82:83], v[30:33], off
	v_cvt_pk_bf16_f32 v66, v66, v67
	v_cvt_pk_bf16_f32 v67, v68, v69
	ds_write_b128 v200, v[22:25]
	ds_write_b128 v200, v[18:21] offset:64
	ds_read_b128 v[18:21], v201
	ds_read_b128 v[22:25], v201 offset:1152
	v_lshl_add_u64 v[68:69], s[48:49], 0, v[92:93]
	v_mov_b32_e32 v91, v163
	v_lshl_add_u64 v[72:73], s[48:49], 0, v[90:91]
	s_waitcnt vmcnt(13) lgkmcnt(1)
	v_pk_fma_f32 v[18:19], v[50:51], v[18:19], v[62:63]
	v_pk_fma_f32 v[20:21], v[52:53], v[20:21], v[64:65]
	v_pk_mul_f32 v[64:65], v[176:177], v[18:19]
	global_store_dwordx4 v[68:69], v[18:21], off
	v_pk_mul_f32 v[62:63], v[174:175], v[20:21]
	v_cvt_pk_bf16_f32 v64, v64, v65
	s_waitcnt vmcnt(13) lgkmcnt(0)
	v_pk_fma_f32 v[22:23], v[50:51], v[22:23], v[58:59]
	v_cvt_pk_bf16_f32 v65, v62, v63
	ds_bpermute_b32 v58, v203, v64
	ds_bpermute_b32 v59, v203, v65
	v_pk_fma_f32 v[24:25], v[52:53], v[24:25], v[60:61]
	v_pk_mul_f32 v[60:61], v[176:177], v[22:23]
	v_pk_mul_f32 v[62:63], v[174:175], v[24:25]
	global_store_dwordx4 v[72:73], v[22:25], off
	v_cvt_pk_bf16_f32 v60, v60, v61
	v_cvt_pk_bf16_f32 v61, v62, v63
	v_add_u32_e32 v63, 0x50000, v202
	v_lshlrev_b32_e32 v62, 1, v63
	s_waitcnt lgkmcnt(0)
	v_add_u32_e32 v250, 0xfffff040, v62
	v_cndmask_b32_e64 v250, v62, v250, s[40:41]
	v_cndmask_b32_e64 v248, v70, v58, s[40:41]
	v_cndmask_b32_e64 v249, v71, v59, s[40:41]
	global_store_dwordx2 v250, v[248:249], s[46:47]
	v_cndmask_b32_e64 v246, v58, v70, s[40:41]
	v_cndmask_b32_e64 v247, v59, v71, s[40:41]
	s_waitcnt lgkmcnt(1)
	v_add_u32_e32 v58, 0x1040, v62
	v_cndmask_b32_e64 v58, v62, v58, s[38:39]
	global_store_dwordx2 v58, v[246:247], s[46:47]
	ds_bpermute_b32 v58, v203, v60
	s_waitcnt lgkmcnt(1)
	ds_bpermute_b32 v59, v203, v61
	v_add_u32_e32 v61, 0x54000, v202
	v_lshlrev_b32_e32 v60, 1, v61
	s_waitcnt lgkmcnt(0)
	v_add_u32_e32 v250, 0xfffff040, v60
	v_cndmask_b32_e64 v250, v60, v250, s[40:41]
	v_cndmask_b32_e64 v248, v66, v58, s[40:41]
	v_cndmask_b32_e64 v249, v67, v59, s[40:41]
	global_store_dwordx2 v250, v[248:249], s[46:47]
	v_cndmask_b32_e64 v246, v58, v66, s[40:41]
	v_cndmask_b32_e64 v247, v59, v67, s[40:41]
	v_mul_f32_e32 v19, v19, v19
	v_fmac_f32_e32 v19, v18, v18
	v_mul_f32_e32 v18, v21, v21
	v_mul_f32_e32 v29, v29, v29
	v_fmac_f32_e32 v18, v20, v20
	v_mul_f32_e32 v27, v27, v27
	v_fmac_f32_e32 v29, v28, v28
	v_mul_f32_e32 v28, v31, v31
	v_mul_f32_e32 v31, v33, v33
	v_add_f32_e32 v18, v19, v18
	v_mul_f32_e32 v19, v23, v23
	v_mul_f32_e32 v20, v25, v25
	v_fmac_f32_e32 v31, v32, v32
	v_fmac_f32_e32 v19, v22, v22
	v_fmac_f32_e32 v20, v24, v24
	v_fmac_f32_e32 v27, v26, v26
	v_fmac_f32_e32 v28, v30, v30
	v_add_f32_e32 v19, v19, v20
	v_add_f32_e32 v20, v27, v29
	v_add_f32_e32 v21, v28, v31
	v_add_f32_e32 v18, v20, v18
	v_add_f32_e32 v19, v21, v19
	ds_bpermute_b32 v20, v190, v18
	ds_bpermute_b32 v21, v190, v19
	s_waitcnt lgkmcnt(1)
	v_add_f32_e32 v18, v18, v20
	s_waitcnt lgkmcnt(0)
	v_add_f32_e32 v21, v19, v21
	ds_bpermute_b32 v20, v191, v18
	ds_bpermute_b32 v22, v191, v21
	s_waitcnt lgkmcnt(1)
	v_add_f32_e32 v18, v18, v20
	s_waitcnt lgkmcnt(0)
	v_add_f32_e32 v20, v21, v22
	ds_bpermute_b32 v19, v204, v18
	ds_bpermute_b32 v21, v204, v20
	v_add_u32_e32 v22, 0x1040, v60
	v_cndmask_b32_e64 v22, v60, v22, s[38:39]
	global_store_dwordx2 v22, v[246:247], s[46:47]
	s_and_saveexec_b64 s[16:17], s[42:43]
	s_cbranch_execz .LBB0_1323
	s_waitcnt lgkmcnt(1)
	v_add_f32_e32 v18, v18, v19
	s_waitcnt lgkmcnt(0)
	v_add_f32_e32 v19, v20, v21
	ds_write2_b32 v194, v18, v19 offset0:96 offset1:104
; #define LAS __attribute__((address_space(3)))
; #define ERN_EOFF(q, m) (eb + (unsigned)((((q) & 1) * HALF + (m) * 16) * DM + ERN_COL((q) >> 1)))
;     __device__ __forceinline__ void operator()(const f32x4 (&acc)[2][2][4][2], const Unit& u, int wr, int wc, int fr, int fq) const {
;     ...
;         for (int g = 0; g < 8; ++g) { const int ai = g >> 2, m = g & 3;
;             if (g + 1 < 8) ERN_LOADX(g + 1);
;             float sq0 = 0.f, sq1 = 0.f; u32x2 hw[2][2];
; #pragma unroll
;             for (int bj = 0; bj < 2; ++bj) {
;                 *(LAS f32x4*)(st + wr_off) = acc[ai][bj][m][0]; *(LAS f32x4*)(st + wr_off + 64) = acc[ai][bj][m][1];
;                 const f32x4 a0 = *(const LAS f32x4*)(st + rd_off), a1 = *(const LAS f32x4*)(st + rd_off + 8 * 144);
;                 { const f32x4 xv = xb[g & 1][bj][0] + gv[bj] * a0; __builtin_nontemporal_store(xv, (f32x4*)((char*)xo + 4u * ERN_EOFF(g, bj, 0)));
;                   sq0 += (xv.x * xv.x + xv.y * xv.y) + (xv.z * xv.z + xv.w * xv.w);
;                   const f32x4 hv = xv * gsn[bj]; hw[bj][0].x = cvt_pk_bf16(hv.x, hv.y); hw[bj][0].y = cvt_pk_bf16(hv.z, hv.w); }
;                 { const f32x4 xv = xb[g & 1][bj][1] + gv[bj] * a1; __builtin_nontemporal_store(xv, (f32x4*)((char*)xo + 4u * ERN_EOFF(g, bj, 1)));
;                   sq1 += (xv.x * xv.x + xv.y * xv.y) + (xv.z * xv.z + xv.w * xv.w);
;                   const f32x4 hv = xv * gsn[bj]; hw[bj][1].x = cvt_pk_bf16(hv.x, hv.y); hw[bj][1].y = cvt_pk_bf16(hv.z, hv.w); }
;             }
;             if (!NOH && !PLAIN) {
; #pragma unroll
;                 for (int rh = 0; rh < 2; ++rh) { u32x2 rv; rv.x = __shfl_xor(hw[1][rh].x, 8); rv.y = __shfl_xor(hw[1][rh].y, 8);
;                     const unsigned e0 = ERN_EOFF(g, 0, rh);
;                     const unsigned ee = odd ? (e0 - DM + 32) : e0, eo2 = odd ? e0 : (e0 + DM + 32);
;                     *(u32x2*)((char*)ho + 2u * ee) = odd ? rv : hw[0][rh];
;                     *(u32x2*)((char*)ho + 2u * eo2) = odd ? hw[0][rh] : rv; }
;             }
;             if (!PLAIN) { sq0 += __shfl_xor(sq0, 1); sq0 += __shfl_xor(sq0, 2); sq0 += __shfl_xor(sq0, 4);
;             sq1 += __shfl_xor(sq1, 1); sq1 += __shfl_xor(sq1, 2); sq1 += __shfl_xor(sq1, 4); }
;             if (!PLAIN && pc == 0) { sst[g * 16 + rr] = sq0; sst[g * 16 + 8 + rr] = sq1; }
.LBB0_1323:
	s_or_b64 exec, exec, s[16:17]
	ds_write_b128 v200, v[14:17]
	ds_write_b128 v200, v[10:13] offset:64
	ds_read_b128 v[10:13], v201
	ds_read_b128 v[14:17], v201 offset:1152
	s_waitcnt lgkmcnt(5)
	v_lshl_add_u64 v[18:19], s[48:49], 0, v[162:163]
	v_mov_b32_e32 v79, v163
	v_lshl_add_u64 v[22:23], s[48:49], 0, v[78:79]
	s_waitcnt vmcnt(9) lgkmcnt(1)
	v_pk_fma_f32 v[12:13], v[56:57], v[12:13], v[48:49]
	v_pk_fma_f32 v[10:11], v[54:55], v[10:11], v[46:47]
	global_store_dwordx4 v[18:19], v[10:13], off
	v_pk_mul_f32 v[18:19], v[178:179], v[12:13]
	v_pk_mul_f32 v[20:21], v[180:181], v[10:11]
	s_waitcnt vmcnt(9) lgkmcnt(0)
	v_pk_fma_f32 v[14:15], v[54:55], v[14:15], v[42:43]
	v_cvt_pk_bf16_f32 v20, v20, v21
	v_cvt_pk_bf16_f32 v21, v18, v19
	v_pk_fma_f32 v[16:17], v[56:57], v[16:17], v[44:45]
	v_pk_mul_f32 v[18:19], v[180:181], v[14:15]
	global_store_dwordx4 v[22:23], v[14:17], off
	v_pk_mul_f32 v[22:23], v[178:179], v[16:17]
	v_cvt_pk_bf16_f32 v18, v18, v19
	v_mov_b32_e32 v77, v163
	v_cvt_pk_bf16_f32 v19, v22, v23
	ds_write_b128 v200, v[6:9]
	ds_write_b128 v200, v[2:5] offset:64
	ds_read_b128 v[2:5], v201
	ds_read_b128 v[6:9], v201 offset:1152
	v_lshl_add_u64 v[22:23], s[48:49], 0, v[76:77]
	v_mov_b32_e32 v75, v163
	v_lshl_add_u64 v[24:25], s[48:49], 0, v[74:75]
	s_waitcnt vmcnt(9) lgkmcnt(1)
	v_pk_fma_f32 v[4:5], v[52:53], v[4:5], v[40:41]
	v_pk_fma_f32 v[2:3], v[50:51], v[2:3], v[38:39]
	global_store_dwordx4 v[22:23], v[2:5], off
	v_pk_mul_f32 v[22:23], v[174:175], v[4:5]
	v_pk_mul_f32 v[26:27], v[176:177], v[2:3]
	s_waitcnt vmcnt(9) lgkmcnt(0)
	v_pk_fma_f32 v[8:9], v[52:53], v[8:9], v[36:37]
	v_cvt_pk_bf16_f32 v28, v26, v27
	v_cvt_pk_bf16_f32 v23, v22, v23
	ds_bpermute_b32 v22, v203, v28
	ds_bpermute_b32 v23, v203, v23
	v_pk_fma_f32 v[6:7], v[50:51], v[6:7], v[34:35]
	global_store_dwordx4 v[24:25], v[6:9], off
	v_pk_mul_f32 v[26:27], v[174:175], v[8:9]
	v_pk_mul_f32 v[24:25], v[176:177], v[6:7]
	s_nop 0
	v_cvt_pk_bf16_f32 v24, v24, v25
	v_cvt_pk_bf16_f32 v25, v26, v27
	v_add_u32_e32 v27, 0x58000, v202
	v_lshlrev_b32_e32 v26, 1, v27
	s_waitcnt lgkmcnt(0)
	v_add_u32_e32 v250, 0xfffff040, v26
	v_cndmask_b32_e64 v250, v26, v250, s[40:41]
	v_cndmask_b32_e64 v248, v20, v22, s[40:41]
	v_cndmask_b32_e64 v249, v21, v23, s[40:41]
	global_store_dwordx2 v250, v[248:249], s[46:47]
	v_cndmask_b32_e64 v246, v22, v20, s[40:41]
	v_cndmask_b32_e64 v247, v23, v21, s[40:41]
	s_waitcnt lgkmcnt(1)
	v_add_u32_e32 v22, 0x1040, v26
	v_cndmask_b32_e64 v22, v26, v22, s[38:39]
	global_store_dwordx2 v22, v[246:247], s[46:47]
	ds_bpermute_b32 v20, v203, v24
	ds_bpermute_b32 v21, v203, v25
	s_waitcnt lgkmcnt(2)
	v_add_u32_e32 v23, 0x5c000, v202
	v_lshlrev_b32_e32 v22, 1, v23
	s_waitcnt lgkmcnt(0)
	v_add_u32_e32 v250, 0xfffff040, v22
	v_cndmask_b32_e64 v250, v22, v250, s[40:41]
	v_cndmask_b32_e64 v248, v18, v20, s[40:41]
	v_cndmask_b32_e64 v249, v19, v21, s[40:41]
	global_store_dwordx2 v250, v[248:249], s[46:47]
	v_cndmask_b32_e64 v246, v20, v18, s[40:41]
	v_cndmask_b32_e64 v247, v21, v19, s[40:41]
	v_mul_f32_e32 v3, v3, v3
	v_fmac_f32_e32 v3, v2, v2
	v_mul_f32_e32 v2, v5, v5
	v_mul_f32_e32 v13, v13, v13
	v_fmac_f32_e32 v2, v4, v4
	v_mul_f32_e32 v11, v11, v11
	v_fmac_f32_e32 v13, v12, v12
	v_mul_f32_e32 v12, v15, v15
	v_mul_f32_e32 v15, v17, v17
	v_add_f32_e32 v2, v3, v2
	v_mul_f32_e32 v3, v7, v7
	v_mul_f32_e32 v4, v9, v9
	v_fmac_f32_e32 v15, v16, v16
	v_fmac_f32_e32 v3, v6, v6
	v_fmac_f32_e32 v4, v8, v8
	v_fmac_f32_e32 v11, v10, v10
	v_fmac_f32_e32 v12, v14, v14
	v_add_f32_e32 v3, v3, v4
	v_add_f32_e32 v4, v11, v13
	v_add_f32_e32 v5, v12, v15
	v_add_f32_e32 v2, v4, v2
	v_add_f32_e32 v3, v5, v3
	ds_bpermute_b32 v4, v190, v2
	ds_bpermute_b32 v5, v190, v3
	s_waitcnt lgkmcnt(1)
	v_add_f32_e32 v2, v2, v4
	s_waitcnt lgkmcnt(0)
	v_add_f32_e32 v5, v3, v5
	ds_bpermute_b32 v4, v191, v2
	ds_bpermute_b32 v6, v191, v5
	s_waitcnt lgkmcnt(1)
	v_add_f32_e32 v2, v2, v4
	s_waitcnt lgkmcnt(0)
	v_add_f32_e32 v4, v5, v6
	ds_bpermute_b32 v3, v204, v2
	ds_bpermute_b32 v5, v204, v4
	v_add_u32_e32 v6, 0x1040, v22
	v_cndmask_b32_e64 v6, v22, v6, s[38:39]
	global_store_dwordx2 v6, v[246:247], s[46:47]
	s_and_saveexec_b64 s[16:17], s[42:43]
	s_cbranch_execz .LBB0_1333
	s_waitcnt lgkmcnt(1)
	v_add_f32_e32 v2, v2, v3
	s_waitcnt lgkmcnt(0)
	v_add_f32_e32 v3, v4, v5
	ds_write2_b32 v194, v2, v3 offset0:112 offset1:120

; #define LAS __attribute__((address_space(3)))
;     __device__ __forceinline__ void operator()(const f32x4 (&acc)[2][2][4][2], const Unit& u, int wr, int wc, int fr, int fq) const {
;         const int s = u.pm >> 5, lane = fq * 16 + fr, rr = lane >> 3, pc = lane & 7;
;         const float* __restrict__ xi = xin + (size_t)u.pm * BM * DM; float* __restrict__ xo = xout + (size_t)u.pm * BM * DM; bf16_t* __restrict__ ho = Hn + (size_t)u.pm * BM * DM;
;         LAS unsigned char* st = lds_epi + (wr * 4 + wc) * 2304;
;         LAS float* sst = (LAS float*)(lds_epi + 18432 + (wr * 4 + wc) * 512);
;         const int colr = u.pn * BM + wc * 64 + 4 * pc;
;         const unsigned eb = (unsigned)((wr * 64 + rr) * DM + colr);
;         f32x4 gv[2], gsn[2];
; #pragma unroll
;         for (int bj = 0; bj < 2; ++bj) { gv[bj] = *(const f32x4*)(gate + (size_t)s * MODW + colr + bj * 32) * (0.5f * GS2);
;             if (!PLAIN) gsn[bj] = *(const f32x4*)(gnext + colr + bj * 32) * (*(const f32x4*)(scnext + (size_t)s * MODW + colr + bj * 32) + 1.0f); else gsn[bj] = gv[bj]; }
;         const unsigned wr_off = (unsigned)(fr * 144 + 16 * fq), rd_off = (unsigned)(rr * 144 + pc * 16);
;         const bool odd = (rr & 1) != 0;
;         f32x4 xb[2][2][2];
;     ...
;         ERN_LOADX(0);
; #pragma unroll
;         for (int g = 0; g < 8; ++g) { const int ai = g >> 2, m = g & 3;
;             if (g + 1 < 8) ERN_LOADX(g + 1);
;             float sq0 = 0.f, sq1 = 0.f; u32x2 hw[2][2];
; #pragma unroll
;             for (int bj = 0; bj < 2; ++bj) {
;                 *(LAS f32x4*)(st + wr_off) = acc[ai][bj][m][0]; *(LAS f32x4*)(st + wr_off + 64) = acc[ai][bj][m][1];
;                 const f32x4 a0 = *(const LAS f32x4*)(st + rd_off), a1 = *(const LAS f32x4*)(st + rd_off + 8 * 144);
;                 { const f32x4 xv = xb[g & 1][bj][0] + gv[bj] * a0; __builtin_nontemporal_store(xv, (f32x4*)((char*)xo + 4u * ERN_EOFF(g, bj, 0)));
;                   sq0 += (xv.x * xv.x + xv.y * xv.y) + (xv.z * xv.z + xv.w * xv.w);
;                   const f32x4 hv = xv * gsn[bj]; hw[bj][0].x = cvt_pk_bf16(hv.x, hv.y); hw[bj][0].y = cvt_pk_bf16(hv.z, hv.w); }
;                 { const f32x4 xv = xb[g & 1][bj][1] + gv[bj] * a1; __builtin_nontemporal_store(xv, (f32x4*)((char*)xo + 4u * ERN_EOFF(g, bj, 1)));
;                   sq1 += (xv.x * xv.x + xv.y * xv.y) + (xv.z * xv.z + xv.w * xv.w);
.LBB0_1598:
	s_ashr_i32 s16, s8, 5
	s_ashr_i32 s9, s8, 31
	v_lshl_or_b32 v130, s0, 8, v192
	s_mul_i32 s20, s16, 0x12000
	s_mul_hi_i32 s0, s16, 0x12000
	s_add_u32 s16, s37, s20
	v_ashrrev_i32_e32 v131, 31, v130
	s_addc_u32 s17, s48, s0
	v_lshlrev_b64 v[132:133], 2, v[130:131]
	v_lshl_add_u64 v[134:135], s[16:17], 0, v[132:133]
	s_add_u32 s16, s26, s20
	s_addc_u32 s17, s27, s0
	v_lshl_add_u64 v[136:137], s[4:5], 0, v[132:133]
	v_lshl_add_u64 v[132:133], s[16:17], 0, v[132:133]
	s_lshl_b64 s[16:17], s[8:9], 21
	s_add_u32 s22, s90, s16
	v_add_u32_e32 v202, v130, v193
	s_addc_u32 s23, s91, s17
	v_lshlrev_b32_e32 v205, 2, v202
	global_load_dwordx4 v[170:173], v[136:137], off
	global_load_dwordx4 v[166:169], v[134:135], off
	global_load_dwordx4 v[186:189], v[134:135], off offset:128
	global_load_dwordx4 v[206:209], v[132:133], off
	global_load_dwordx4 v[210:213], v[132:133], off offset:128
	global_load_dwordx4 v[214:217], v205, s[22:23]
	v_add_u32_e32 v130, 0x10000, v205
	global_load_dwordx4 v[218:221], v130, s[22:23]
	global_load_dwordx4 v[222:225], v[136:137], off offset:128
	global_load_dwordx4 v[226:229], v205, s[22:23] offset:128
	v_add_u32_e32 v204, 0x10080, v205
	global_load_dwordx4 v[230:233], v204, s[22:23]
	v_add_u32_e32 v130, 0x20000, v205
	v_add_u32_e32 v154, 0x30000, v205
	v_add_u32_e32 v184, 0x20080, v205
	v_add_u32_e32 v182, 0x30080, v205
	global_load_dwordx4 v[142:145], v130, s[22:23]
	global_load_dwordx4 v[138:141], v154, s[22:23]
	global_load_dwordx4 v[134:137], v184, s[22:23]
	s_nop 0
	global_load_dwordx4 v[130:133], v182, s[22:23]
	ds_write_b128 v200, v[126:129]
	ds_write_b128 v200, v[122:125] offset:64
	v_and_b32_e32 v127, 64, v199
	ds_read_b128 v[122:125], v201
	ds_read_b128 v[234:237], v201 offset:1152
	v_xor_b32_e32 v126, 8, v199
	v_add_u32_e32 v183, 64, v127
	v_cmp_lt_i32_e32 vcc, v126, v183
	v_add_u32_e32 v185, 0x4000, v202
	v_lshlrev_b32_e32 v238, 2, v185
	v_cndmask_b32_e32 v126, v199, v126, vcc
	v_lshlrev_b32_e32 v203, 2, v126
	s_lshl_b64 s[16:17], s[8:9], 20
	s_add_u32 s20, s93, s16
	s_addc_u32 s21, s92, s17
	s_waitcnt vmcnt(0)
	v_pk_mul_f32 v[180:181], v[166:167], 0.5 op_sel_hi:[1,0]
	v_pk_mul_f32 v[176:177], v[168:169], 0.5 op_sel_hi:[1,0]
	v_pk_add_f32 v[126:127], v[208:209], 1.0 op_sel_hi:[1,0]
	v_pk_add_f32 v[128:129], v[206:207], 1.0 op_sel_hi:[1,0]
	v_pk_mul_f32 v[174:175], v[172:173], v[126:127]
	v_pk_mul_f32 v[178:179], v[170:171], v[128:129]
	s_waitcnt lgkmcnt(1)
	v_pk_fma_f32 v[126:127], v[180:181], v[122:123], v[214:215]
	s_waitcnt lgkmcnt(0)
	v_pk_fma_f32 v[122:123], v[180:181], v[234:235], v[218:219]
	v_pk_mul_f32 v[168:169], v[186:187], 0.5 op_sel_hi:[1,0]
	v_pk_fma_f32 v[128:129], v[176:177], v[124:125], v[216:217]
	v_pk_fma_f32 v[124:125], v[176:177], v[236:237], v[220:221]
	v_pk_mul_f32 v[186:187], v[178:179], v[122:123]
	v_pk_mul_f32 v[166:167], v[188:189], 0.5 op_sel_hi:[1,0]
	global_store_dwordx4 v205, v[126:129], s[22:23]
	v_pk_mul_f32 v[170:171], v[174:175], v[128:129]
	v_pk_mul_f32 v[172:173], v[178:179], v[126:127]
	v_pk_mul_f32 v[206:207], v[174:175], v[124:125]
	v_cvt_pk_bf16_f32 v188, v172, v173
	v_cvt_pk_bf16_f32 v189, v170, v171
	global_store_dwordx4 v238, v[122:125], s[22:23]
	v_cvt_pk_bf16_f32 v186, v186, v187
	v_cvt_pk_bf16_f32 v187, v206, v207
	ds_write_b128 v200, v[118:121]
	ds_write_b128 v200, v[114:117] offset:64
	ds_read_b128 v[114:117], v201
	ds_read_b128 v[206:209], v201 offset:1152
	v_pk_add_f32 v[190:191], v[212:213], 1.0 op_sel_hi:[1,0]
	v_pk_add_f32 v[118:119], v[210:211], 1.0 op_sel_hi:[1,0]
	v_pk_mul_f32 v[170:171], v[224:225], v[190:191]
	v_pk_mul_f32 v[172:173], v[222:223], v[118:119]
	s_waitcnt lgkmcnt(1)
	v_pk_fma_f32 v[120:121], v[166:167], v[116:117], v[228:229]
	v_pk_fma_f32 v[118:119], v[168:169], v[114:115], v[226:227]
	s_waitcnt lgkmcnt(0)
	v_pk_fma_f32 v[114:115], v[168:169], v[206:207], v[230:231]
	v_pk_mul_f32 v[190:191], v[170:171], v[120:121]
	v_pk_mul_f32 v[206:207], v[172:173], v[118:119]
	global_store_dwordx4 v205, v[118:121], s[22:23] offset:128
	v_cvt_pk_bf16_f32 v206, v206, v207
	v_cvt_pk_bf16_f32 v191, v190, v191
	ds_bpermute_b32 v190, v203, v206
	ds_bpermute_b32 v191, v203, v191
	v_pk_fma_f32 v[116:117], v[166:167], v[208:209], v[232:233]
	v_pk_mul_f32 v[206:207], v[172:173], v[114:115]
	global_store_dwordx4 v204, v[114:117], s[22:23]
	v_cvt_pk_bf16_f32 v204, v206, v207
	v_lshlrev_b32_e32 v207, 1, v202
	v_pk_mul_f32 v[208:209], v[170:171], v[116:117]
	s_nop 0
	v_cvt_pk_bf16_f32 v206, v208, v209
	s_waitcnt lgkmcnt(0)
	v_add_u32_e32 v250, 0xfffff040, v207
	v_cndmask_b32_e64 v250, v207, v250, s[40:41]
	v_cndmask_b32_e64 v248, v188, v190, s[40:41]
	v_cndmask_b32_e64 v249, v189, v191, s[40:41]
	global_store_dwordx2 v250, v[248:249], s[20:21]
	v_cndmask_b32_e64 v246, v190, v188, s[40:41]
	v_cndmask_b32_e64 v247, v191, v189, s[40:41]
	s_waitcnt lgkmcnt(1)
	v_add_u32_e32 v190, 0x1040, v207
	v_cndmask_b32_e64 v190, v207, v190, s[38:39]
	global_store_dwordx2 v190, v[246:247], s[20:21]
	ds_bpermute_b32 v188, v203, v204
	ds_bpermute_b32 v189, v203, v206
	v_lshlrev_b32_e32 v206, 1, v185
	s_waitcnt lgkmcnt(0)
; #define LAS __attribute__((address_space(3)))
; #define ERN_EOFF(q, m) (eb + (unsigned)((((q) & 1) * HALF + (m) * 16) * DM + ERN_COL((q) >> 1)))
;     __device__ __forceinline__ void operator()(const f32x4 (&acc)[2][2][4][2], const Unit& u, int wr, int wc, int fr, int fq) const {
;     ...
;         for (int g = 0; g < 8; ++g) { const int ai = g >> 2, m = g & 3;
;             if (g + 1 < 8) ERN_LOADX(g + 1);
;             float sq0 = 0.f, sq1 = 0.f; u32x2 hw[2][2];
; #pragma unroll
;             for (int bj = 0; bj < 2; ++bj) {
;                 *(LAS f32x4*)(st + wr_off) = acc[ai][bj][m][0]; *(LAS f32x4*)(st + wr_off + 64) = acc[ai][bj][m][1];
;                 const f32x4 a0 = *(const LAS f32x4*)(st + rd_off), a1 = *(const LAS f32x4*)(st + rd_off + 8 * 144);
;                 { const f32x4 xv = xb[g & 1][bj][0] + gv[bj] * a0; __builtin_nontemporal_store(xv, (f32x4*)((char*)xo + 4u * ERN_EOFF(g, bj, 0)));
;                   sq0 += (xv.x * xv.x + xv.y * xv.y) + (xv.z * xv.z + xv.w * xv.w);
;                   const f32x4 hv = xv * gsn[bj]; hw[bj][0].x = cvt_pk_bf16(hv.x, hv.y); hw[bj][0].y = cvt_pk_bf16(hv.z, hv.w); }
;                 { const f32x4 xv = xb[g & 1][bj][1] + gv[bj] * a1; __builtin_nontemporal_store(xv, (f32x4*)((char*)xo + 4u * ERN_EOFF(g, bj, 1)));
;                   sq1 += (xv.x * xv.x + xv.y * xv.y) + (xv.z * xv.z + xv.w * xv.w);
;                   const f32x4 hv = xv * gsn[bj]; hw[bj][1].x = cvt_pk_bf16(hv.x, hv.y); hw[bj][1].y = cvt_pk_bf16(hv.z, hv.w); }
;             }
;             if (!NOH && !PLAIN) {
; #pragma unroll
;                 for (int rh = 0; rh < 2; ++rh) { u32x2 rv; rv.x = __shfl_xor(hw[1][rh].x, 8); rv.y = __shfl_xor(hw[1][rh].y, 8);
;                     const unsigned e0 = ERN_EOFF(g, 0, rh);
;                     const unsigned ee = odd ? (e0 - DM + 32) : e0, eo2 = odd ? e0 : (e0 + DM + 32);
;                     *(u32x2*)((char*)ho + 2u * ee) = odd ? rv : hw[0][rh];
;                     *(u32x2*)((char*)ho + 2u * eo2) = odd ? hw[0][rh] : rv; }
;             }
;             if (!PLAIN) { sq0 += __shfl_xor(sq0, 1); sq0 += __shfl_xor(sq0, 2); sq0 += __shfl_xor(sq0, 4);
;             sq1 += __shfl_xor(sq1, 1); sq1 += __shfl_xor(sq1, 2); sq1 += __shfl_xor(sq1, 4); }
;             if (!PLAIN && pc == 0) { sst[g * 16 + rr] = sq0; sst[g * 16 + 8 + rr] = sq1; }
	v_add_u32_e32 v250, 0xfffff040, v206
	v_cndmask_b32_e64 v250, v206, v250, s[40:41]
	v_cndmask_b32_e64 v248, v186, v188, s[40:41]
	v_cndmask_b32_e64 v249, v187, v189, s[40:41]
	global_store_dwordx2 v250, v[248:249], s[20:21]
	v_cndmask_b32_e64 v246, v188, v186, s[40:41]
	v_cndmask_b32_e64 v247, v189, v187, s[40:41]
	v_mul_f32_e32 v119, v119, v119
	v_mul_f32_e32 v127, v127, v127
	v_mul_f32_e32 v129, v129, v129
	v_fmac_f32_e32 v119, v118, v118
	v_mul_f32_e32 v118, v121, v121
	v_fmac_f32_e32 v129, v128, v128
	v_fmac_f32_e32 v118, v120, v120
	v_mul_f32_e32 v115, v115, v115
	v_fmac_f32_e32 v127, v126, v126
	v_add_f32_e32 v118, v119, v118
	v_fmac_f32_e32 v115, v114, v114
	v_mul_f32_e32 v114, v117, v117
	v_add_f32_e32 v117, v127, v129
	v_add_f32_e32 v117, v117, v118
	v_xor_b32_e32 v118, 1, v199
	v_cmp_lt_i32_e32 vcc, v118, v183
	v_mul_f32_e32 v123, v123, v123
	v_mul_f32_e32 v125, v125, v125
	v_cndmask_b32_e32 v118, v199, v118, vcc
	v_lshlrev_b32_e32 v190, 2, v118
	ds_bpermute_b32 v118, v190, v117
	v_fmac_f32_e32 v114, v116, v116
	v_fmac_f32_e32 v125, v124, v124
	v_fmac_f32_e32 v123, v122, v122
	v_add_f32_e32 v114, v115, v114
	s_waitcnt lgkmcnt(0)
	v_add_f32_e32 v116, v117, v118
	v_xor_b32_e32 v117, 2, v199
	v_cmp_lt_i32_e32 vcc, v117, v183
	v_add_f32_e32 v115, v123, v125
	v_add_f32_e32 v115, v115, v114
	v_cndmask_b32_e32 v117, v199, v117, vcc
	v_lshlrev_b32_e32 v191, 2, v117
	ds_bpermute_b32 v117, v191, v116
	ds_bpermute_b32 v118, v190, v115
	s_waitcnt lgkmcnt(1)
	v_add_f32_e32 v114, v116, v117
	s_waitcnt lgkmcnt(0)
	v_add_f32_e32 v117, v115, v118
	ds_bpermute_b32 v118, v191, v117
	v_xor_b32_e32 v116, 4, v199
	v_cmp_lt_i32_e32 vcc, v116, v183
	s_nop 1
	v_cndmask_b32_e32 v115, v199, v116, vcc
	v_lshlrev_b32_e32 v204, 2, v115
	s_waitcnt lgkmcnt(0)
	v_add_f32_e32 v116, v117, v118
	ds_bpermute_b32 v115, v204, v114
	ds_bpermute_b32 v117, v204, v116
	v_add_u32_e32 v118, 0x1040, v206
	v_cndmask_b32_e64 v118, v206, v118, s[38:39]
	global_store_dwordx2 v118, v[246:247], s[20:21]
	s_and_saveexec_b64 s[16:17], s[42:43]
	s_cbranch_execz .LBB0_1608
	s_waitcnt lgkmcnt(1)
	v_add_f32_e32 v114, v114, v115
	s_waitcnt lgkmcnt(0)
	v_add_f32_e32 v115, v116, v117
	ds_write2_b32 v194, v114, v115 offset1:8
.LBB0_1608:
	s_or_b64 exec, exec, s[16:17]
	v_lshl_add_u64 v[206:207], s[22:23], 0, v[154:155]
	v_add_u32_e32 v114, 0x40000, v205
	v_add_u32_e32 v154, 0x50000, v205
	v_add_u32_e32 v186, 0x40080, v205
	global_load_dwordx4 v[122:125], v154, s[22:23]
	global_load_dwordx4 v[118:121], v186, s[22:23]
	v_add_u32_e32 v188, 0x50080, v205
	global_load_dwordx4 v[126:129], v114, s[22:23]
	s_waitcnt lgkmcnt(0)
	global_load_dwordx4 v[114:117], v188, s[22:23]
	ds_write_b128 v200, v[110:113]
	ds_write_b128 v200, v[106:109] offset:64
	ds_read_b128 v[106:109], v201
	ds_read_b128 v[110:113], v201 offset:1152
	v_mov_b32_e32 v185, v155
	v_mov_b32_e32 v183, v155
	v_lshl_add_u64 v[182:183], s[22:23], 0, v[182:183]
	s_waitcnt lgkmcnt(1)
	v_pk_fma_f32 v[108:109], v[176:177], v[108:109], v[144:145]
	v_add_u32_e32 v144, 0x8000, v202
	v_pk_fma_f32 v[106:107], v[180:181], v[106:107], v[142:143]
	v_lshlrev_b32_e32 v142, 2, v144
	s_waitcnt lgkmcnt(0)
	v_pk_fma_f32 v[110:111], v[180:181], v[110:111], v[138:139]
	global_store_dwordx4 v142, v[106:109], s[22:23]
	v_pk_mul_f32 v[142:143], v[178:179], v[106:107]
	v_pk_fma_f32 v[112:113], v[176:177], v[112:113], v[140:141]
	v_pk_mul_f32 v[138:139], v[178:179], v[110:111]
	v_pk_mul_f32 v[208:209], v[174:175], v[108:109]
	v_cvt_pk_bf16_f32 v142, v142, v143
	v_pk_mul_f32 v[140:141], v[174:175], v[112:113]
	v_cvt_pk_bf16_f32 v143, v208, v209
	global_store_dwordx4 v[206:207], v[110:113], off
	v_cvt_pk_bf16_f32 v138, v138, v139
	v_cvt_pk_bf16_f32 v139, v140, v141
	ds_write_b128 v200, v[102:105]
	ds_write_b128 v200, v[98:101] offset:64
	ds_read_b128 v[98:101], v201
	ds_read_b128 v[102:105], v201 offset:1152
	v_lshl_add_u64 v[140:141], s[22:23], 0, v[184:185]
	s_waitcnt lgkmcnt(1)
	v_pk_fma_f32 v[98:99], v[168:169], v[98:99], v[134:135]
	v_pk_fma_f32 v[100:101], v[166:167], v[100:101], v[136:137]
	v_pk_mul_f32 v[136:137], v[172:173], v[98:99]
	global_store_dwordx4 v[140:141], v[98:101], off
	v_pk_mul_f32 v[134:135], v[170:171], v[100:101]
	v_cvt_pk_bf16_f32 v136, v136, v137
	s_waitcnt lgkmcnt(0)
	v_pk_fma_f32 v[102:103], v[168:169], v[102:103], v[130:131]
	v_cvt_pk_bf16_f32 v137, v134, v135
	ds_bpermute_b32 v130, v203, v136
	ds_bpermute_b32 v131, v203, v137
	v_pk_fma_f32 v[104:105], v[166:167], v[104:105], v[132:133]
	v_pk_mul_f32 v[132:133], v[172:173], v[102:103]
	v_pk_mul_f32 v[134:135], v[170:171], v[104:105]
	global_store_dwordx4 v[182:183], v[102:105], off
	v_cvt_pk_bf16_f32 v132, v132, v133
	v_cvt_pk_bf16_f32 v133, v134, v135
	v_lshlrev_b32_e32 v134, 1, v144
	s_waitcnt lgkmcnt(0)
	v_add_u32_e32 v250, 0xfffff040, v134
	v_cndmask_b32_e64 v250, v134, v250, s[40:41]
	v_cndmask_b32_e64 v248, v142, v130, s[40:41]
	v_cndmask_b32_e64 v249, v143, v131, s[40:41]
	global_store_dwordx2 v250, v[248:249], s[20:21]
	v_cndmask_b32_e64 v246, v130, v142, s[40:41]
	v_cndmask_b32_e64 v247, v131, v143, s[40:41]
	s_waitcnt lgkmcnt(1)
	v_add_u32_e32 v130, 0x1040, v134
	v_cndmask_b32_e64 v130, v134, v130, s[38:39]
	global_store_dwordx2 v130, v[246:247], s[20:21]
	ds_bpermute_b32 v130, v203, v132
	s_waitcnt lgkmcnt(1)
	ds_bpermute_b32 v131, v203, v133
	v_add_u32_e32 v133, 0xc000, v202
	v_lshlrev_b32_e32 v132, 1, v133
	s_waitcnt lgkmcnt(0)
	v_add_u32_e32 v250, 0xfffff040, v132
	v_cndmask_b32_e64 v250, v132, v250, s[40:41]
	v_cndmask_b32_e64 v248, v138, v130, s[40:41]
	v_cndmask_b32_e64 v249, v139, v131, s[40:41]
	global_store_dwordx2 v250, v[248:249], s[20:21]
	v_cndmask_b32_e64 v246, v130, v138, s[40:41]
	v_cndmask_b32_e64 v247, v131, v139, s[40:41]
	v_mul_f32_e32 v99, v99, v99
	v_fmac_f32_e32 v99, v98, v98
	v_mul_f32_e32 v98, v101, v101
	v_mul_f32_e32 v109, v109, v109
	v_fmac_f32_e32 v98, v100, v100
	v_mul_f32_e32 v107, v107, v107
	v_fmac_f32_e32 v109, v108, v108
	v_mul_f32_e32 v108, v111, v111
	v_mul_f32_e32 v111, v113, v113
	v_add_f32_e32 v98, v99, v98
	v_mul_f32_e32 v99, v103, v103
	v_mul_f32_e32 v100, v105, v105
	v_fmac_f32_e32 v111, v112, v112
	v_fmac_f32_e32 v99, v102, v102
	v_fmac_f32_e32 v100, v104, v104
	v_fmac_f32_e32 v107, v106, v106
	v_fmac_f32_e32 v108, v110, v110
	v_add_f32_e32 v99, v99, v100
	v_add_f32_e32 v100, v107, v109
	v_add_f32_e32 v101, v108, v111
	v_add_f32_e32 v98, v100, v98
	v_add_f32_e32 v99, v101, v99
	ds_bpermute_b32 v100, v190, v98
	ds_bpermute_b32 v101, v190, v99
	s_waitcnt lgkmcnt(1)
	v_add_f32_e32 v98, v98, v100
	s_waitcnt lgkmcnt(0)
	v_add_f32_e32 v101, v99, v101
	ds_bpermute_b32 v100, v191, v98
	ds_bpermute_b32 v102, v191, v101
	s_waitcnt lgkmcnt(1)
	v_add_f32_e32 v98, v98, v100
	s_waitcnt lgkmcnt(0)
	v_add_f32_e32 v100, v101, v102
	ds_bpermute_b32 v99, v204, v98
	ds_bpermute_b32 v101, v204, v100
	v_add_u32_e32 v102, 0x1040, v132
	v_cndmask_b32_e64 v102, v132, v102, s[38:39]
	global_store_dwordx2 v102, v[246:247], s[20:21]
	s_and_saveexec_b64 s[16:17], s[42:43]
	s_cbranch_execz .LBB0_1618
; #define LAS __attribute__((address_space(3)))
; #define ERN_EOFF(q, m) (eb + (unsigned)((((q) & 1) * HALF + (m) * 16) * DM + ERN_COL((q) >> 1)))
;     __device__ __forceinline__ void operator()(const f32x4 (&acc)[2][2][4][2], const Unit& u, int wr, int wc, int fr, int fq) const {
;     ...
;         for (int g = 0; g < 8; ++g) { const int ai = g >> 2, m = g & 3;
;             if (g + 1 < 8) ERN_LOADX(g + 1);
;             float sq0 = 0.f, sq1 = 0.f; u32x2 hw[2][2];
; #pragma unroll
;             for (int bj = 0; bj < 2; ++bj) {
;                 *(LAS f32x4*)(st + wr_off) = acc[ai][bj][m][0]; *(LAS f32x4*)(st + wr_off + 64) = acc[ai][bj][m][1];
;                 const f32x4 a0 = *(const LAS f32x4*)(st + rd_off), a1 = *(const LAS f32x4*)(st + rd_off + 8 * 144);
;                 { const f32x4 xv = xb[g & 1][bj][0] + gv[bj] * a0; __builtin_nontemporal_store(xv, (f32x4*)((char*)xo + 4u * ERN_EOFF(g, bj, 0)));
;                   sq0 += (xv.x * xv.x + xv.y * xv.y) + (xv.z * xv.z + xv.w * xv.w);
;                   const f32x4 hv = xv * gsn[bj]; hw[bj][0].x = cvt_pk_bf16(hv.x, hv.y); hw[bj][0].y = cvt_pk_bf16(hv.z, hv.w); }
;                 { const f32x4 xv = xb[g & 1][bj][1] + gv[bj] * a1; __builtin_nontemporal_store(xv, (f32x4*)((char*)xo + 4u * ERN_EOFF(g, bj, 1)));
;                   sq1 += (xv.x * xv.x + xv.y * xv.y) + (xv.z * xv.z + xv.w * xv.w);
;                   const f32x4 hv = xv * gsn[bj]; hw[bj][1].x = cvt_pk_bf16(hv.x, hv.y); hw[bj][1].y = cvt_pk_bf16(hv.z, hv.w); }
;             }
;             if (!NOH && !PLAIN) {
; #pragma unroll
;                 for (int rh = 0; rh < 2; ++rh) { u32x2 rv; rv.x = __shfl_xor(hw[1][rh].x, 8); rv.y = __shfl_xor(hw[1][rh].y, 8);
;                     const unsigned e0 = ERN_EOFF(g, 0, rh);
;                     const unsigned ee = odd ? (e0 - DM + 32) : e0, eo2 = odd ? e0 : (e0 + DM + 32);
;                     *(u32x2*)((char*)ho + 2u * ee) = odd ? rv : hw[0][rh];
;                     *(u32x2*)((char*)ho + 2u * eo2) = odd ? hw[0][rh] : rv; }
;             }
;             if (!PLAIN) { sq0 += __shfl_xor(sq0, 1); sq0 += __shfl_xor(sq0, 2); sq0 += __shfl_xor(sq0, 4);
;             sq1 += __shfl_xor(sq1, 1); sq1 += __shfl_xor(sq1, 2); sq1 += __shfl_xor(sq1, 4); }
;             if (!PLAIN && pc == 0) { sst[g * 16 + rr] = sq0; sst[g * 16 + 8 + rr] = sq1; }
	s_waitcnt lgkmcnt(1)
	v_add_f32_e32 v98, v98, v99
	s_waitcnt lgkmcnt(0)
	v_add_f32_e32 v99, v100, v101
	ds_write2_b32 v194, v98, v99 offset0:16 offset1:24
.LBB0_1618:
	s_or_b64 exec, exec, s[16:17]
	v_lshl_add_u64 v[134:135], s[22:23], 0, v[154:155]
	v_add_u32_e32 v98, 0x60000, v205
	v_add_u32_e32 v154, 0x70000, v205
	v_add_u32_e32 v130, 0x60080, v205
	global_load_dwordx4 v[106:109], v154, s[22:23]
	global_load_dwordx4 v[102:105], v130, s[22:23]
	v_add_u32_e32 v132, 0x70080, v205
	global_load_dwordx4 v[110:113], v98, s[22:23]
	s_waitcnt lgkmcnt(0)
	global_load_dwordx4 v[98:101], v132, s[22:23]
	ds_write_b128 v200, v[94:97]
	ds_write_b128 v200, v[90:93] offset:64
	ds_read_b128 v[90:93], v201
	ds_read_b128 v[94:97], v201 offset:1152
	v_mov_b32_e32 v187, v155
	v_mov_b32_e32 v189, v155
	s_waitcnt vmcnt(11) lgkmcnt(1)
	v_pk_fma_f32 v[92:93], v[176:177], v[92:93], v[128:129]
	v_add_u32_e32 v128, 0x10000, v202
	v_pk_fma_f32 v[90:91], v[180:181], v[90:91], v[126:127]
	v_lshlrev_b32_e32 v126, 2, v128
	s_waitcnt lgkmcnt(0)
	v_pk_fma_f32 v[94:95], v[180:181], v[94:95], v[122:123]
	global_store_dwordx4 v126, v[90:93], s[22:23]
	v_pk_mul_f32 v[126:127], v[178:179], v[90:91]
	v_pk_fma_f32 v[96:97], v[176:177], v[96:97], v[124:125]
	v_pk_mul_f32 v[122:123], v[178:179], v[94:95]
	v_pk_mul_f32 v[136:137], v[174:175], v[92:93]
	v_cvt_pk_bf16_f32 v126, v126, v127
	v_pk_mul_f32 v[124:125], v[174:175], v[96:97]
	v_cvt_pk_bf16_f32 v127, v136, v137
	global_store_dwordx4 v[134:135], v[94:97], off
	v_cvt_pk_bf16_f32 v122, v122, v123
	v_cvt_pk_bf16_f32 v123, v124, v125
	ds_write_b128 v200, v[86:89]
	ds_write_b128 v200, v[82:85] offset:64
	ds_read_b128 v[82:85], v201
	ds_read_b128 v[86:89], v201 offset:1152
	v_lshl_add_u64 v[124:125], s[22:23], 0, v[186:187]
	v_lshl_add_u64 v[134:135], s[22:23], 0, v[188:189]
	s_waitcnt lgkmcnt(1)
	v_pk_fma_f32 v[82:83], v[168:169], v[82:83], v[118:119]
	v_pk_fma_f32 v[84:85], v[166:167], v[84:85], v[120:121]
	v_pk_mul_f32 v[120:121], v[172:173], v[82:83]
	global_store_dwordx4 v[124:125], v[82:85], off
	v_pk_mul_f32 v[118:119], v[170:171], v[84:85]
	v_cvt_pk_bf16_f32 v120, v120, v121
	s_waitcnt vmcnt(13) lgkmcnt(0)
	v_pk_fma_f32 v[86:87], v[168:169], v[86:87], v[114:115]
	v_cvt_pk_bf16_f32 v121, v118, v119
	ds_bpermute_b32 v114, v203, v120
	ds_bpermute_b32 v115, v203, v121
	v_pk_fma_f32 v[88:89], v[166:167], v[88:89], v[116:117]
	v_pk_mul_f32 v[116:117], v[172:173], v[86:87]
	v_pk_mul_f32 v[118:119], v[170:171], v[88:89]
	global_store_dwordx4 v[134:135], v[86:89], off
	v_cvt_pk_bf16_f32 v116, v116, v117
	v_cvt_pk_bf16_f32 v117, v118, v119
	v_lshlrev_b32_e32 v118, 1, v128
	s_waitcnt lgkmcnt(0)
	v_add_u32_e32 v250, 0xfffff040, v118
	v_cndmask_b32_e64 v250, v118, v250, s[40:41]
	v_cndmask_b32_e64 v248, v126, v114, s[40:41]
	v_cndmask_b32_e64 v249, v127, v115, s[40:41]
	global_store_dwordx2 v250, v[248:249], s[20:21]
	v_cndmask_b32_e64 v246, v114, v126, s[40:41]
	v_cndmask_b32_e64 v247, v115, v127, s[40:41]
	s_waitcnt lgkmcnt(1)
	v_add_u32_e32 v114, 0x1040, v118
	v_cndmask_b32_e64 v114, v118, v114, s[38:39]
	global_store_dwordx2 v114, v[246:247], s[20:21]
	ds_bpermute_b32 v114, v203, v116
	s_waitcnt lgkmcnt(1)
	ds_bpermute_b32 v115, v203, v117
	v_add_u32_e32 v117, 0x14000, v202
	v_lshlrev_b32_e32 v116, 1, v117
	s_waitcnt lgkmcnt(0)
	v_add_u32_e32 v250, 0xfffff040, v116
	v_cndmask_b32_e64 v250, v116, v250, s[40:41]
	v_cndmask_b32_e64 v248, v122, v114, s[40:41]
	v_cndmask_b32_e64 v249, v123, v115, s[40:41]
	global_store_dwordx2 v250, v[248:249], s[20:21]
	v_cndmask_b32_e64 v246, v114, v122, s[40:41]
	v_cndmask_b32_e64 v247, v115, v123, s[40:41]
	v_mul_f32_e32 v83, v83, v83
	v_fmac_f32_e32 v83, v82, v82
	v_mul_f32_e32 v82, v85, v85
	v_mul_f32_e32 v93, v93, v93
	v_fmac_f32_e32 v82, v84, v84
	v_mul_f32_e32 v91, v91, v91
	v_fmac_f32_e32 v93, v92, v92
	v_mul_f32_e32 v92, v95, v95
	v_mul_f32_e32 v95, v97, v97
	v_add_f32_e32 v82, v83, v82
	v_mul_f32_e32 v83, v87, v87
	v_mul_f32_e32 v84, v89, v89
	v_fmac_f32_e32 v95, v96, v96
	v_fmac_f32_e32 v83, v86, v86
	v_fmac_f32_e32 v84, v88, v88
	v_fmac_f32_e32 v91, v90, v90
	v_fmac_f32_e32 v92, v94, v94
	v_add_f32_e32 v83, v83, v84
	v_add_f32_e32 v84, v91, v93
	v_add_f32_e32 v85, v92, v95
	v_add_f32_e32 v82, v84, v82
	v_add_f32_e32 v83, v85, v83
	ds_bpermute_b32 v84, v190, v82
	ds_bpermute_b32 v85, v190, v83
	s_waitcnt lgkmcnt(1)
	v_add_f32_e32 v82, v82, v84
	s_waitcnt lgkmcnt(0)
	v_add_f32_e32 v85, v83, v85
	ds_bpermute_b32 v84, v191, v82
	ds_bpermute_b32 v86, v191, v85
	s_waitcnt lgkmcnt(1)
	v_add_f32_e32 v82, v82, v84
	s_waitcnt lgkmcnt(0)
	v_add_f32_e32 v84, v85, v86
	ds_bpermute_b32 v83, v204, v82
	ds_bpermute_b32 v85, v204, v84
	v_add_u32_e32 v86, 0x1040, v116
	v_cndmask_b32_e64 v86, v116, v86, s[38:39]
	global_store_dwordx2 v86, v[246:247], s[20:21]
	s_and_saveexec_b64 s[16:17], s[42:43]
	s_cbranch_execz .LBB0_1628
	s_waitcnt lgkmcnt(1)
	v_add_f32_e32 v82, v82, v83
	s_waitcnt lgkmcnt(0)
	v_add_f32_e32 v83, v84, v85
	ds_write2_b32 v194, v82, v83 offset0:32 offset1:40
; #define LAS __attribute__((address_space(3)))
; #define ERN_EOFF(q, m) (eb + (unsigned)((((q) & 1) * HALF + (m) * 16) * DM + ERN_COL((q) >> 1)))
;     __device__ __forceinline__ void operator()(const f32x4 (&acc)[2][2][4][2], const Unit& u, int wr, int wc, int fr, int fq) const {
;     ...
;         for (int g = 0; g < 8; ++g) { const int ai = g >> 2, m = g & 3;
;             if (g + 1 < 8) ERN_LOADX(g + 1);
;             float sq0 = 0.f, sq1 = 0.f; u32x2 hw[2][2];
; #pragma unroll
;             for (int bj = 0; bj < 2; ++bj) {
;                 *(LAS f32x4*)(st + wr_off) = acc[ai][bj][m][0]; *(LAS f32x4*)(st + wr_off + 64) = acc[ai][bj][m][1];
;                 const f32x4 a0 = *(const LAS f32x4*)(st + rd_off), a1 = *(const LAS f32x4*)(st + rd_off + 8 * 144);
;                 { const f32x4 xv = xb[g & 1][bj][0] + gv[bj] * a0; __builtin_nontemporal_store(xv, (f32x4*)((char*)xo + 4u * ERN_EOFF(g, bj, 0)));
;                   sq0 += (xv.x * xv.x + xv.y * xv.y) + (xv.z * xv.z + xv.w * xv.w);
;                   const f32x4 hv = xv * gsn[bj]; hw[bj][0].x = cvt_pk_bf16(hv.x, hv.y); hw[bj][0].y = cvt_pk_bf16(hv.z, hv.w); }
;                 { const f32x4 xv = xb[g & 1][bj][1] + gv[bj] * a1; __builtin_nontemporal_store(xv, (f32x4*)((char*)xo + 4u * ERN_EOFF(g, bj, 1)));
;                   sq1 += (xv.x * xv.x + xv.y * xv.y) + (xv.z * xv.z + xv.w * xv.w);
;                   const f32x4 hv = xv * gsn[bj]; hw[bj][1].x = cvt_pk_bf16(hv.x, hv.y); hw[bj][1].y = cvt_pk_bf16(hv.z, hv.w); }
;             }
;             if (!NOH && !PLAIN) {
; #pragma unroll
;                 for (int rh = 0; rh < 2; ++rh) { u32x2 rv; rv.x = __shfl_xor(hw[1][rh].x, 8); rv.y = __shfl_xor(hw[1][rh].y, 8);
;                     const unsigned e0 = ERN_EOFF(g, 0, rh);
;                     const unsigned ee = odd ? (e0 - DM + 32) : e0, eo2 = odd ? e0 : (e0 + DM + 32);
;                     *(u32x2*)((char*)ho + 2u * ee) = odd ? rv : hw[0][rh];
;                     *(u32x2*)((char*)ho + 2u * eo2) = odd ? hw[0][rh] : rv; }
;             }
;             if (!PLAIN) { sq0 += __shfl_xor(sq0, 1); sq0 += __shfl_xor(sq0, 2); sq0 += __shfl_xor(sq0, 4);
;             sq1 += __shfl_xor(sq1, 1); sq1 += __shfl_xor(sq1, 2); sq1 += __shfl_xor(sq1, 4); }
;             if (!PLAIN && pc == 0) { sst[g * 16 + rr] = sq0; sst[g * 16 + 8 + rr] = sq1; }
.LBB0_1628:
	s_or_b64 exec, exec, s[16:17]
	v_lshl_add_u64 v[116:117], s[22:23], 0, v[154:155]
	v_add_u32_e32 v82, 0x100000, v205
	s_waitcnt lgkmcnt(1)
	v_add_u32_e32 v83, 0x110000, v205
	v_add_u32_e32 v154, 0x100080, v205
	global_load_dwordx4 v[94:97], v82, s[22:23]
	global_load_dwordx4 v[90:93], v83, s[22:23]
	v_add_u32_e32 v114, 0x110080, v205
	global_load_dwordx4 v[86:89], v154, s[22:23]
	s_waitcnt lgkmcnt(0)
	global_load_dwordx4 v[82:85], v114, s[22:23]
	ds_write_b128 v200, v[78:81]
	ds_write_b128 v200, v[74:77] offset:64
	ds_read_b128 v[74:77], v201
	ds_read_b128 v[78:81], v201 offset:1152
	v_mov_b32_e32 v131, v155
	v_mov_b32_e32 v133, v155
	s_waitcnt vmcnt(11) lgkmcnt(1)
	v_pk_fma_f32 v[76:77], v[176:177], v[76:77], v[112:113]
	v_add_u32_e32 v112, 0x18000, v202
	v_pk_fma_f32 v[74:75], v[180:181], v[74:75], v[110:111]
	v_lshlrev_b32_e32 v110, 2, v112
	s_waitcnt lgkmcnt(0)
	v_pk_fma_f32 v[78:79], v[180:181], v[78:79], v[106:107]
	global_store_dwordx4 v110, v[74:77], s[22:23]
	v_pk_mul_f32 v[110:111], v[178:179], v[74:75]
	v_pk_fma_f32 v[80:81], v[176:177], v[80:81], v[108:109]
	v_pk_mul_f32 v[106:107], v[178:179], v[78:79]
	v_pk_mul_f32 v[118:119], v[174:175], v[76:77]
	v_cvt_pk_bf16_f32 v110, v110, v111
	v_pk_mul_f32 v[108:109], v[174:175], v[80:81]
	v_cvt_pk_bf16_f32 v111, v118, v119
	global_store_dwordx4 v[116:117], v[78:81], off
	v_cvt_pk_bf16_f32 v106, v106, v107
	v_cvt_pk_bf16_f32 v107, v108, v109
	ds_write_b128 v200, v[70:73]
	ds_write_b128 v200, v[66:69] offset:64
	ds_read_b128 v[66:69], v201
	ds_read_b128 v[70:73], v201 offset:1152
	v_lshl_add_u64 v[108:109], s[22:23], 0, v[130:131]
	v_lshl_add_u64 v[116:117], s[22:23], 0, v[132:133]
	s_waitcnt lgkmcnt(1)
	v_pk_fma_f32 v[66:67], v[168:169], v[66:67], v[102:103]
	v_pk_fma_f32 v[68:69], v[166:167], v[68:69], v[104:105]
	v_pk_mul_f32 v[104:105], v[172:173], v[66:67]
	global_store_dwordx4 v[108:109], v[66:69], off
	v_pk_mul_f32 v[102:103], v[170:171], v[68:69]
	v_cvt_pk_bf16_f32 v104, v104, v105
	s_waitcnt vmcnt(13) lgkmcnt(0)
	v_pk_fma_f32 v[70:71], v[168:169], v[70:71], v[98:99]
	v_cvt_pk_bf16_f32 v105, v102, v103
	ds_bpermute_b32 v98, v203, v104
	ds_bpermute_b32 v99, v203, v105
	v_pk_fma_f32 v[72:73], v[166:167], v[72:73], v[100:101]
	v_pk_mul_f32 v[100:101], v[172:173], v[70:71]
	v_pk_mul_f32 v[102:103], v[170:171], v[72:73]
	global_store_dwordx4 v[116:117], v[70:73], off
	v_cvt_pk_bf16_f32 v100, v100, v101
	v_cvt_pk_bf16_f32 v101, v102, v103
	v_lshlrev_b32_e32 v102, 1, v112
	s_waitcnt lgkmcnt(0)
	v_add_u32_e32 v250, 0xfffff040, v102
	v_cndmask_b32_e64 v250, v102, v250, s[40:41]
	v_cndmask_b32_e64 v248, v110, v98, s[40:41]
	v_cndmask_b32_e64 v249, v111, v99, s[40:41]
	global_store_dwordx2 v250, v[248:249], s[20:21]
	v_cndmask_b32_e64 v246, v98, v110, s[40:41]
	v_cndmask_b32_e64 v247, v99, v111, s[40:41]
	s_waitcnt lgkmcnt(1)
	v_add_u32_e32 v98, 0x1040, v102
	v_cndmask_b32_e64 v98, v102, v98, s[38:39]
	global_store_dwordx2 v98, v[246:247], s[20:21]
	ds_bpermute_b32 v98, v203, v100
	s_waitcnt lgkmcnt(1)
	ds_bpermute_b32 v99, v203, v101
	v_add_u32_e32 v101, 0x1c000, v202
	v_lshlrev_b32_e32 v100, 1, v101
	s_waitcnt lgkmcnt(0)
	v_add_u32_e32 v250, 0xfffff040, v100
	v_cndmask_b32_e64 v250, v100, v250, s[40:41]
	v_cndmask_b32_e64 v248, v106, v98, s[40:41]
	v_cndmask_b32_e64 v249, v107, v99, s[40:41]
	global_store_dwordx2 v250, v[248:249], s[20:21]
	v_cndmask_b32_e64 v246, v98, v106, s[40:41]
	v_cndmask_b32_e64 v247, v99, v107, s[40:41]
	v_mul_f32_e32 v67, v67, v67
	v_fmac_f32_e32 v67, v66, v66
	v_mul_f32_e32 v66, v69, v69
	v_mul_f32_e32 v77, v77, v77
	v_fmac_f32_e32 v66, v68, v68
	v_mul_f32_e32 v75, v75, v75
	v_fmac_f32_e32 v77, v76, v76
	v_mul_f32_e32 v76, v79, v79
	v_mul_f32_e32 v79, v81, v81
	v_add_f32_e32 v66, v67, v66
	v_mul_f32_e32 v67, v71, v71
	v_mul_f32_e32 v68, v73, v73
	v_fmac_f32_e32 v79, v80, v80
	v_fmac_f32_e32 v67, v70, v70
	v_fmac_f32_e32 v68, v72, v72
	v_fmac_f32_e32 v75, v74, v74
	v_fmac_f32_e32 v76, v78, v78
	v_add_f32_e32 v67, v67, v68
	v_add_f32_e32 v68, v75, v77
	v_add_f32_e32 v69, v76, v79
	v_add_f32_e32 v66, v68, v66
	v_add_f32_e32 v67, v69, v67
	ds_bpermute_b32 v68, v190, v66
	ds_bpermute_b32 v69, v190, v67
	s_waitcnt lgkmcnt(1)
	v_add_f32_e32 v66, v66, v68
	s_waitcnt lgkmcnt(0)
	v_add_f32_e32 v69, v67, v69
	ds_bpermute_b32 v68, v191, v66
	ds_bpermute_b32 v70, v191, v69
	s_waitcnt lgkmcnt(1)
	v_add_f32_e32 v66, v66, v68
	s_waitcnt lgkmcnt(0)
	v_add_f32_e32 v68, v69, v70
	ds_bpermute_b32 v67, v204, v66
	ds_bpermute_b32 v69, v204, v68
	v_add_u32_e32 v70, 0x1040, v100
	v_cndmask_b32_e64 v70, v100, v70, s[38:39]
	global_store_dwordx2 v70, v[246:247], s[20:21]
	s_and_saveexec_b64 s[16:17], s[42:43]
	s_cbranch_execz .LBB0_1638
	s_waitcnt lgkmcnt(1)
	v_add_f32_e32 v66, v66, v67
	s_waitcnt lgkmcnt(0)
	v_add_f32_e32 v67, v68, v69
	ds_write2_b32 v194, v66, v67 offset0:48 offset1:56
; #define LAS __attribute__((address_space(3)))
; #define ERN_EOFF(q, m) (eb + (unsigned)((((q) & 1) * HALF + (m) * 16) * DM + ERN_COL((q) >> 1)))
;     __device__ __forceinline__ void operator()(const f32x4 (&acc)[2][2][4][2], const Unit& u, int wr, int wc, int fr, int fq) const {
;     ...
;         for (int g = 0; g < 8; ++g) { const int ai = g >> 2, m = g & 3;
;             if (g + 1 < 8) ERN_LOADX(g + 1);
;             float sq0 = 0.f, sq1 = 0.f; u32x2 hw[2][2];
; #pragma unroll
;             for (int bj = 0; bj < 2; ++bj) {
;                 *(LAS f32x4*)(st + wr_off) = acc[ai][bj][m][0]; *(LAS f32x4*)(st + wr_off + 64) = acc[ai][bj][m][1];
;                 const f32x4 a0 = *(const LAS f32x4*)(st + rd_off), a1 = *(const LAS f32x4*)(st + rd_off + 8 * 144);
;                 { const f32x4 xv = xb[g & 1][bj][0] + gv[bj] * a0; __builtin_nontemporal_store(xv, (f32x4*)((char*)xo + 4u * ERN_EOFF(g, bj, 0)));
;                   sq0 += (xv.x * xv.x + xv.y * xv.y) + (xv.z * xv.z + xv.w * xv.w);
;                   const f32x4 hv = xv * gsn[bj]; hw[bj][0].x = cvt_pk_bf16(hv.x, hv.y); hw[bj][0].y = cvt_pk_bf16(hv.z, hv.w); }
;                 { const f32x4 xv = xb[g & 1][bj][1] + gv[bj] * a1; __builtin_nontemporal_store(xv, (f32x4*)((char*)xo + 4u * ERN_EOFF(g, bj, 1)));
;                   sq1 += (xv.x * xv.x + xv.y * xv.y) + (xv.z * xv.z + xv.w * xv.w);
;                   const f32x4 hv = xv * gsn[bj]; hw[bj][1].x = cvt_pk_bf16(hv.x, hv.y); hw[bj][1].y = cvt_pk_bf16(hv.z, hv.w); }
;             }
;             if (!NOH && !PLAIN) {
; #pragma unroll
;                 for (int rh = 0; rh < 2; ++rh) { u32x2 rv; rv.x = __shfl_xor(hw[1][rh].x, 8); rv.y = __shfl_xor(hw[1][rh].y, 8);
;                     const unsigned e0 = ERN_EOFF(g, 0, rh);
;                     const unsigned ee = odd ? (e0 - DM + 32) : e0, eo2 = odd ? e0 : (e0 + DM + 32);
;                     *(u32x2*)((char*)ho + 2u * ee) = odd ? rv : hw[0][rh];
;                     *(u32x2*)((char*)ho + 2u * eo2) = odd ? hw[0][rh] : rv; }
;             }
;             if (!PLAIN) { sq0 += __shfl_xor(sq0, 1); sq0 += __shfl_xor(sq0, 2); sq0 += __shfl_xor(sq0, 4);
;             sq1 += __shfl_xor(sq1, 1); sq1 += __shfl_xor(sq1, 2); sq1 += __shfl_xor(sq1, 4); }
;             if (!PLAIN && pc == 0) { sst[g * 16 + rr] = sq0; sst[g * 16 + 8 + rr] = sq1; }
.LBB0_1638:
	s_or_b64 exec, exec, s[16:17]
	v_lshl_add_u64 v[104:105], s[22:23], 0, v[154:155]
	v_add_u32_e32 v154, 0x120000, v205
	v_add_u32_e32 v100, 0x120080, v205
	v_add_u32_e32 v102, 0x130000, v205
	global_load_dwordx4 v[78:81], v154, s[22:23]
	global_load_dwordx4 v[74:77], v102, s[22:23]
	v_add_u32_e32 v98, 0x130080, v205
	global_load_dwordx4 v[70:73], v100, s[22:23]
	s_waitcnt lgkmcnt(0)
	global_load_dwordx4 v[66:69], v98, s[22:23]
	ds_write_b128 v200, v[62:65]
	ds_write_b128 v200, v[58:61] offset:64
	ds_read_b128 v[58:61], v201
	ds_read_b128 v[62:65], v201 offset:1152
	v_mov_b32_e32 v115, v155
	s_waitcnt vmcnt(13) lgkmcnt(1)
	v_pk_fma_f32 v[60:61], v[176:177], v[60:61], v[96:97]
	v_add_u32_e32 v96, 0x40000, v202
	v_pk_fma_f32 v[58:59], v[180:181], v[58:59], v[94:95]
	v_lshlrev_b32_e32 v94, 2, v96
	s_waitcnt vmcnt(12) lgkmcnt(0)
	v_pk_fma_f32 v[64:65], v[176:177], v[64:65], v[92:93]
	v_add_u32_e32 v92, 0x44000, v202
	global_store_dwordx4 v94, v[58:61], s[22:23]
	v_pk_mul_f32 v[94:95], v[178:179], v[58:59]
	v_pk_fma_f32 v[62:63], v[180:181], v[62:63], v[90:91]
	v_lshlrev_b32_e32 v90, 2, v92
	v_pk_mul_f32 v[106:107], v[174:175], v[60:61]
	v_cvt_pk_bf16_f32 v94, v94, v95
	s_nop 0
	v_cvt_pk_bf16_f32 v95, v106, v107
	global_store_dwordx4 v90, v[62:65], s[22:23]
	v_pk_mul_f32 v[90:91], v[178:179], v[62:63]
	v_pk_mul_f32 v[106:107], v[174:175], v[64:65]
	v_cvt_pk_bf16_f32 v90, v90, v91
	s_nop 0
	v_cvt_pk_bf16_f32 v91, v106, v107
	ds_write_b128 v200, v[54:57]
	ds_write_b128 v200, v[50:53] offset:64
	ds_read_b128 v[50:53], v201
	ds_read_b128 v[54:57], v201 offset:1152
	v_lshl_add_u64 v[106:107], s[22:23], 0, v[114:115]
	s_waitcnt vmcnt(13) lgkmcnt(1)
	v_pk_fma_f32 v[50:51], v[168:169], v[50:51], v[86:87]
	v_pk_fma_f32 v[52:53], v[166:167], v[52:53], v[88:89]
	v_pk_mul_f32 v[88:89], v[172:173], v[50:51]
	global_store_dwordx4 v[104:105], v[50:53], off
	v_pk_mul_f32 v[86:87], v[170:171], v[52:53]
	v_cvt_pk_bf16_f32 v88, v88, v89
	s_waitcnt vmcnt(13) lgkmcnt(0)
	v_pk_fma_f32 v[54:55], v[168:169], v[54:55], v[82:83]
	v_cvt_pk_bf16_f32 v89, v86, v87
	ds_bpermute_b32 v82, v203, v88
	ds_bpermute_b32 v83, v203, v89
	v_pk_fma_f32 v[56:57], v[166:167], v[56:57], v[84:85]
	v_pk_mul_f32 v[84:85], v[172:173], v[54:55]
	v_pk_mul_f32 v[86:87], v[170:171], v[56:57]
	global_store_dwordx4 v[106:107], v[54:57], off
	v_cvt_pk_bf16_f32 v84, v84, v85
	v_cvt_pk_bf16_f32 v85, v86, v87
	v_lshlrev_b32_e32 v86, 1, v96
	s_waitcnt lgkmcnt(0)
	v_add_u32_e32 v250, 0xfffff040, v86
	v_cndmask_b32_e64 v250, v86, v250, s[40:41]
	v_cndmask_b32_e64 v248, v94, v82, s[40:41]
	v_cndmask_b32_e64 v249, v95, v83, s[40:41]
	global_store_dwordx2 v250, v[248:249], s[20:21]
	v_cndmask_b32_e64 v246, v82, v94, s[40:41]
	v_cndmask_b32_e64 v247, v83, v95, s[40:41]
	s_waitcnt lgkmcnt(1)
	v_add_u32_e32 v82, 0x1040, v86
	v_cndmask_b32_e64 v82, v86, v82, s[38:39]
	global_store_dwordx2 v82, v[246:247], s[20:21]
	ds_bpermute_b32 v82, v203, v84
	s_waitcnt lgkmcnt(1)
	ds_bpermute_b32 v83, v203, v85
	v_lshlrev_b32_e32 v84, 1, v92
	s_waitcnt lgkmcnt(0)
	v_add_u32_e32 v250, 0xfffff040, v84
	v_cndmask_b32_e64 v250, v84, v250, s[40:41]
	v_cndmask_b32_e64 v248, v90, v82, s[40:41]
	v_cndmask_b32_e64 v249, v91, v83, s[40:41]
	global_store_dwordx2 v250, v[248:249], s[20:21]
	v_cndmask_b32_e64 v246, v82, v90, s[40:41]
	v_cndmask_b32_e64 v247, v83, v91, s[40:41]
	v_mul_f32_e32 v51, v51, v51
	v_fmac_f32_e32 v51, v50, v50
	v_mul_f32_e32 v50, v53, v53
	v_mul_f32_e32 v61, v61, v61
	v_fmac_f32_e32 v50, v52, v52
	v_mul_f32_e32 v59, v59, v59
	v_fmac_f32_e32 v61, v60, v60
	v_mul_f32_e32 v60, v63, v63
	v_mul_f32_e32 v63, v65, v65
	v_add_f32_e32 v50, v51, v50
	v_mul_f32_e32 v51, v55, v55
	v_mul_f32_e32 v52, v57, v57
	v_fmac_f32_e32 v63, v64, v64
	v_fmac_f32_e32 v51, v54, v54
	v_fmac_f32_e32 v52, v56, v56
	v_fmac_f32_e32 v59, v58, v58
	v_fmac_f32_e32 v60, v62, v62
	v_add_f32_e32 v51, v51, v52
	v_add_f32_e32 v52, v59, v61
	v_add_f32_e32 v53, v60, v63
	v_add_f32_e32 v50, v52, v50
	v_add_f32_e32 v51, v53, v51
	ds_bpermute_b32 v52, v190, v50
	ds_bpermute_b32 v53, v190, v51
	s_waitcnt lgkmcnt(1)
	v_add_f32_e32 v50, v50, v52
	s_waitcnt lgkmcnt(0)
	v_add_f32_e32 v53, v51, v53
	ds_bpermute_b32 v52, v191, v50
	ds_bpermute_b32 v54, v191, v53
	s_waitcnt lgkmcnt(1)
	v_add_f32_e32 v50, v50, v52
	s_waitcnt lgkmcnt(0)
	v_add_f32_e32 v52, v53, v54
	ds_bpermute_b32 v51, v204, v50
	ds_bpermute_b32 v53, v204, v52
	v_add_u32_e32 v54, 0x1040, v84
	v_cndmask_b32_e64 v54, v84, v54, s[38:39]
	global_store_dwordx2 v54, v[246:247], s[20:21]
	s_and_saveexec_b64 s[16:17], s[42:43]
	s_cbranch_execz .LBB0_1648
	s_waitcnt lgkmcnt(1)
	v_add_f32_e32 v50, v50, v51
	s_waitcnt lgkmcnt(0)
	v_add_f32_e32 v51, v52, v53
	ds_write2_b32 v194, v50, v51 offset0:64 offset1:72
; #define LAS __attribute__((address_space(3)))
; #define ERN_EOFF(q, m) (eb + (unsigned)((((q) & 1) * HALF + (m) * 16) * DM + ERN_COL((q) >> 1)))
;     __device__ __forceinline__ void operator()(const f32x4 (&acc)[2][2][4][2], const Unit& u, int wr, int wc, int fr, int fq) const {
;     ...
;         for (int g = 0; g < 8; ++g) { const int ai = g >> 2, m = g & 3;
;             if (g + 1 < 8) ERN_LOADX(g + 1);
;             float sq0 = 0.f, sq1 = 0.f; u32x2 hw[2][2];
; #pragma unroll
;             for (int bj = 0; bj < 2; ++bj) {
;                 *(LAS f32x4*)(st + wr_off) = acc[ai][bj][m][0]; *(LAS f32x4*)(st + wr_off + 64) = acc[ai][bj][m][1];
;                 const f32x4 a0 = *(const LAS f32x4*)(st + rd_off), a1 = *(const LAS f32x4*)(st + rd_off + 8 * 144);
;                 { const f32x4 xv = xb[g & 1][bj][0] + gv[bj] * a0; __builtin_nontemporal_store(xv, (f32x4*)((char*)xo + 4u * ERN_EOFF(g, bj, 0)));
;                   sq0 += (xv.x * xv.x + xv.y * xv.y) + (xv.z * xv.z + xv.w * xv.w);
;                   const f32x4 hv = xv * gsn[bj]; hw[bj][0].x = cvt_pk_bf16(hv.x, hv.y); hw[bj][0].y = cvt_pk_bf16(hv.z, hv.w); }
;                 { const f32x4 xv = xb[g & 1][bj][1] + gv[bj] * a1; __builtin_nontemporal_store(xv, (f32x4*)((char*)xo + 4u * ERN_EOFF(g, bj, 1)));
;                   sq1 += (xv.x * xv.x + xv.y * xv.y) + (xv.z * xv.z + xv.w * xv.w);
;                   const f32x4 hv = xv * gsn[bj]; hw[bj][1].x = cvt_pk_bf16(hv.x, hv.y); hw[bj][1].y = cvt_pk_bf16(hv.z, hv.w); }
;             }
;             if (!NOH && !PLAIN) {
; #pragma unroll
;                 for (int rh = 0; rh < 2; ++rh) { u32x2 rv; rv.x = __shfl_xor(hw[1][rh].x, 8); rv.y = __shfl_xor(hw[1][rh].y, 8);
;                     const unsigned e0 = ERN_EOFF(g, 0, rh);
;                     const unsigned ee = odd ? (e0 - DM + 32) : e0, eo2 = odd ? e0 : (e0 + DM + 32);
;                     *(u32x2*)((char*)ho + 2u * ee) = odd ? rv : hw[0][rh];
;                     *(u32x2*)((char*)ho + 2u * eo2) = odd ? hw[0][rh] : rv; }
;             }
;             if (!PLAIN) { sq0 += __shfl_xor(sq0, 1); sq0 += __shfl_xor(sq0, 2); sq0 += __shfl_xor(sq0, 4);
;             sq1 += __shfl_xor(sq1, 1); sq1 += __shfl_xor(sq1, 2); sq1 += __shfl_xor(sq1, 4); }
;             if (!PLAIN && pc == 0) { sst[g * 16 + rr] = sq0; sst[g * 16 + 8 + rr] = sq1; }
.LBB0_1648:
	s_or_b64 exec, exec, s[16:17]
	v_lshl_add_u64 v[88:89], s[22:23], 0, v[154:155]
	v_add_u32_e32 v154, 0x140000, v205
	v_add_u32_e32 v84, 0x140080, v205
	v_add_u32_e32 v86, 0x150000, v205
	global_load_dwordx4 v[62:65], v154, s[22:23]
	global_load_dwordx4 v[58:61], v86, s[22:23]
	v_add_u32_e32 v82, 0x150080, v205
	global_load_dwordx4 v[54:57], v84, s[22:23]
	s_waitcnt lgkmcnt(0)
	global_load_dwordx4 v[50:53], v82, s[22:23]
	ds_write_b128 v200, v[46:49]
	ds_write_b128 v200, v[42:45] offset:64
	ds_read_b128 v[42:45], v201
	ds_read_b128 v[46:49], v201 offset:1152
	v_mov_b32_e32 v103, v155
	v_lshl_add_u64 v[90:91], s[22:23], 0, v[102:103]
	v_mov_b32_e32 v101, v155
	s_waitcnt vmcnt(13) lgkmcnt(1)
	v_pk_fma_f32 v[42:43], v[180:181], v[42:43], v[78:79]
	s_waitcnt vmcnt(12) lgkmcnt(0)
	v_pk_fma_f32 v[46:47], v[180:181], v[46:47], v[74:75]
	v_pk_fma_f32 v[44:45], v[176:177], v[44:45], v[80:81]
	v_pk_mul_f32 v[78:79], v[178:179], v[42:43]
	v_pk_fma_f32 v[48:49], v[176:177], v[48:49], v[76:77]
	v_pk_mul_f32 v[74:75], v[178:179], v[46:47]
	global_store_dwordx4 v[88:89], v[42:45], off
	v_pk_mul_f32 v[80:81], v[174:175], v[44:45]
	v_cvt_pk_bf16_f32 v78, v78, v79
	v_pk_mul_f32 v[76:77], v[174:175], v[48:49]
	v_cvt_pk_bf16_f32 v79, v80, v81
	global_store_dwordx4 v[90:91], v[46:49], off
	v_cvt_pk_bf16_f32 v74, v74, v75
	v_cvt_pk_bf16_f32 v75, v76, v77
	ds_write_b128 v200, v[38:41]
	ds_write_b128 v200, v[34:37] offset:64
	ds_read_b128 v[34:37], v201
	ds_read_b128 v[38:41], v201 offset:1152
	v_lshl_add_u64 v[76:77], s[22:23], 0, v[100:101]
	v_mov_b32_e32 v99, v155
	v_lshl_add_u64 v[80:81], s[22:23], 0, v[98:99]
	s_waitcnt vmcnt(13) lgkmcnt(1)
	v_pk_fma_f32 v[34:35], v[168:169], v[34:35], v[70:71]
	v_pk_fma_f32 v[36:37], v[166:167], v[36:37], v[72:73]
	v_pk_mul_f32 v[72:73], v[172:173], v[34:35]
	global_store_dwordx4 v[76:77], v[34:37], off
	v_pk_mul_f32 v[70:71], v[170:171], v[36:37]
	v_cvt_pk_bf16_f32 v72, v72, v73
	s_waitcnt vmcnt(13) lgkmcnt(0)
	v_pk_fma_f32 v[38:39], v[168:169], v[38:39], v[66:67]
	v_cvt_pk_bf16_f32 v73, v70, v71
	ds_bpermute_b32 v66, v203, v72
	ds_bpermute_b32 v67, v203, v73
	v_pk_fma_f32 v[40:41], v[166:167], v[40:41], v[68:69]
	v_pk_mul_f32 v[68:69], v[172:173], v[38:39]
	v_pk_mul_f32 v[70:71], v[170:171], v[40:41]
	global_store_dwordx4 v[80:81], v[38:41], off
	v_cvt_pk_bf16_f32 v68, v68, v69
	v_cvt_pk_bf16_f32 v69, v70, v71
	v_add_u32_e32 v71, 0x48000, v202
	v_lshlrev_b32_e32 v70, 1, v71
	s_waitcnt lgkmcnt(0)
	v_add_u32_e32 v250, 0xfffff040, v70
	v_cndmask_b32_e64 v250, v70, v250, s[40:41]
	v_cndmask_b32_e64 v248, v78, v66, s[40:41]
	v_cndmask_b32_e64 v249, v79, v67, s[40:41]
	global_store_dwordx2 v250, v[248:249], s[20:21]
	v_cndmask_b32_e64 v246, v66, v78, s[40:41]
	v_cndmask_b32_e64 v247, v67, v79, s[40:41]
	s_waitcnt lgkmcnt(1)
	v_add_u32_e32 v66, 0x1040, v70
	v_cndmask_b32_e64 v66, v70, v66, s[38:39]
	global_store_dwordx2 v66, v[246:247], s[20:21]
	ds_bpermute_b32 v66, v203, v68
	s_waitcnt lgkmcnt(1)
	ds_bpermute_b32 v67, v203, v69
	v_add_u32_e32 v69, 0x4c000, v202
	v_lshlrev_b32_e32 v68, 1, v69
	s_waitcnt lgkmcnt(0)
	v_add_u32_e32 v250, 0xfffff040, v68
	v_cndmask_b32_e64 v250, v68, v250, s[40:41]
	v_cndmask_b32_e64 v248, v74, v66, s[40:41]
	v_cndmask_b32_e64 v249, v75, v67, s[40:41]
	global_store_dwordx2 v250, v[248:249], s[20:21]
	v_cndmask_b32_e64 v246, v66, v74, s[40:41]
	v_cndmask_b32_e64 v247, v67, v75, s[40:41]
	v_mul_f32_e32 v35, v35, v35
	v_fmac_f32_e32 v35, v34, v34
	v_mul_f32_e32 v34, v37, v37
	v_mul_f32_e32 v45, v45, v45
	v_fmac_f32_e32 v34, v36, v36
	v_mul_f32_e32 v43, v43, v43
	v_fmac_f32_e32 v45, v44, v44
	v_mul_f32_e32 v44, v47, v47
	v_mul_f32_e32 v47, v49, v49
	v_add_f32_e32 v34, v35, v34
	v_mul_f32_e32 v35, v39, v39
	v_mul_f32_e32 v36, v41, v41
	v_fmac_f32_e32 v47, v48, v48
	v_fmac_f32_e32 v35, v38, v38
	v_fmac_f32_e32 v36, v40, v40
	v_fmac_f32_e32 v43, v42, v42
	v_fmac_f32_e32 v44, v46, v46
	v_add_f32_e32 v35, v35, v36
	v_add_f32_e32 v36, v43, v45
	v_add_f32_e32 v37, v44, v47
	v_add_f32_e32 v34, v36, v34
	v_add_f32_e32 v35, v37, v35
	ds_bpermute_b32 v36, v190, v34
	ds_bpermute_b32 v37, v190, v35
	s_waitcnt lgkmcnt(1)
	v_add_f32_e32 v34, v34, v36
	s_waitcnt lgkmcnt(0)
	v_add_f32_e32 v37, v35, v37
	ds_bpermute_b32 v36, v191, v34
	ds_bpermute_b32 v38, v191, v37
	s_waitcnt lgkmcnt(1)
	v_add_f32_e32 v34, v34, v36
	s_waitcnt lgkmcnt(0)
	v_add_f32_e32 v36, v37, v38
	ds_bpermute_b32 v35, v204, v34
	ds_bpermute_b32 v37, v204, v36
	v_add_u32_e32 v38, 0x1040, v68
	v_cndmask_b32_e64 v38, v68, v38, s[38:39]
	global_store_dwordx2 v38, v[246:247], s[20:21]
	s_and_saveexec_b64 s[16:17], s[42:43]
	s_cbranch_execz .LBB0_1658
	s_waitcnt lgkmcnt(1)
	v_add_f32_e32 v34, v34, v35
	s_waitcnt lgkmcnt(0)
	v_add_f32_e32 v35, v36, v37
	ds_write2_b32 v194, v34, v35 offset0:80 offset1:88
; #define LAS __attribute__((address_space(3)))
; #define ERN_EOFF(q, m) (eb + (unsigned)((((q) & 1) * HALF + (m) * 16) * DM + ERN_COL((q) >> 1)))
;     __device__ __forceinline__ void operator()(const f32x4 (&acc)[2][2][4][2], const Unit& u, int wr, int wc, int fr, int fq) const {
;     ...
;         for (int g = 0; g < 8; ++g) { const int ai = g >> 2, m = g & 3;
;             if (g + 1 < 8) ERN_LOADX(g + 1);
;             float sq0 = 0.f, sq1 = 0.f; u32x2 hw[2][2];
; #pragma unroll
;             for (int bj = 0; bj < 2; ++bj) {
;                 *(LAS f32x4*)(st + wr_off) = acc[ai][bj][m][0]; *(LAS f32x4*)(st + wr_off + 64) = acc[ai][bj][m][1];
;                 const f32x4 a0 = *(const LAS f32x4*)(st + rd_off), a1 = *(const LAS f32x4*)(st + rd_off + 8 * 144);
;                 { const f32x4 xv = xb[g & 1][bj][0] + gv[bj] * a0; __builtin_nontemporal_store(xv, (f32x4*)((char*)xo + 4u * ERN_EOFF(g, bj, 0)));
;                   sq0 += (xv.x * xv.x + xv.y * xv.y) + (xv.z * xv.z + xv.w * xv.w);
;                   const f32x4 hv = xv * gsn[bj]; hw[bj][0].x = cvt_pk_bf16(hv.x, hv.y); hw[bj][0].y = cvt_pk_bf16(hv.z, hv.w); }
;                 { const f32x4 xv = xb[g & 1][bj][1] + gv[bj] * a1; __builtin_nontemporal_store(xv, (f32x4*)((char*)xo + 4u * ERN_EOFF(g, bj, 1)));
;                   sq1 += (xv.x * xv.x + xv.y * xv.y) + (xv.z * xv.z + xv.w * xv.w);
;                   const f32x4 hv = xv * gsn[bj]; hw[bj][1].x = cvt_pk_bf16(hv.x, hv.y); hw[bj][1].y = cvt_pk_bf16(hv.z, hv.w); }
;             }
;             if (!NOH && !PLAIN) {
; #pragma unroll
;                 for (int rh = 0; rh < 2; ++rh) { u32x2 rv; rv.x = __shfl_xor(hw[1][rh].x, 8); rv.y = __shfl_xor(hw[1][rh].y, 8);
;                     const unsigned e0 = ERN_EOFF(g, 0, rh);
;                     const unsigned ee = odd ? (e0 - DM + 32) : e0, eo2 = odd ? e0 : (e0 + DM + 32);
;                     *(u32x2*)((char*)ho + 2u * ee) = odd ? rv : hw[0][rh];
;                     *(u32x2*)((char*)ho + 2u * eo2) = odd ? hw[0][rh] : rv; }
;             }
;             if (!PLAIN) { sq0 += __shfl_xor(sq0, 1); sq0 += __shfl_xor(sq0, 2); sq0 += __shfl_xor(sq0, 4);
;             sq1 += __shfl_xor(sq1, 1); sq1 += __shfl_xor(sq1, 2); sq1 += __shfl_xor(sq1, 4); }
;             if (!PLAIN && pc == 0) { sst[g * 16 + rr] = sq0; sst[g * 16 + 8 + rr] = sq1; }
.LBB0_1658:
	s_or_b64 exec, exec, s[16:17]
	v_lshl_add_u64 v[72:73], s[22:23], 0, v[154:155]
	v_add_u32_e32 v154, 0x160000, v205
	v_add_u32_e32 v68, 0x160080, v205
	v_add_u32_e32 v70, 0x170000, v205
	global_load_dwordx4 v[46:49], v154, s[22:23]
	global_load_dwordx4 v[42:45], v70, s[22:23]
	v_add_u32_e32 v66, 0x170080, v205
	global_load_dwordx4 v[38:41], v68, s[22:23]
	s_waitcnt lgkmcnt(0)
	global_load_dwordx4 v[34:37], v66, s[22:23]
	ds_write_b128 v200, v[30:33]
	ds_write_b128 v200, v[26:29] offset:64
	ds_read_b128 v[26:29], v201
	ds_read_b128 v[30:33], v201 offset:1152
	v_mov_b32_e32 v87, v155
	v_lshl_add_u64 v[74:75], s[22:23], 0, v[86:87]
	v_mov_b32_e32 v85, v155
	s_waitcnt vmcnt(13) lgkmcnt(1)
	v_pk_fma_f32 v[26:27], v[180:181], v[26:27], v[62:63]
	s_waitcnt vmcnt(12) lgkmcnt(0)
	v_pk_fma_f32 v[30:31], v[180:181], v[30:31], v[58:59]
	v_pk_fma_f32 v[28:29], v[176:177], v[28:29], v[64:65]
	v_pk_mul_f32 v[62:63], v[178:179], v[26:27]
	v_pk_fma_f32 v[32:33], v[176:177], v[32:33], v[60:61]
	v_pk_mul_f32 v[58:59], v[178:179], v[30:31]
	global_store_dwordx4 v[72:73], v[26:29], off
	v_pk_mul_f32 v[64:65], v[174:175], v[28:29]
	v_cvt_pk_bf16_f32 v62, v62, v63
	v_pk_mul_f32 v[60:61], v[174:175], v[32:33]
	v_cvt_pk_bf16_f32 v63, v64, v65
	global_store_dwordx4 v[74:75], v[30:33], off
	v_cvt_pk_bf16_f32 v58, v58, v59
	v_cvt_pk_bf16_f32 v59, v60, v61
	ds_write_b128 v200, v[22:25]
	ds_write_b128 v200, v[18:21] offset:64
	ds_read_b128 v[18:21], v201
	ds_read_b128 v[22:25], v201 offset:1152
	v_lshl_add_u64 v[60:61], s[22:23], 0, v[84:85]
	v_mov_b32_e32 v83, v155
	v_lshl_add_u64 v[64:65], s[22:23], 0, v[82:83]
	s_waitcnt vmcnt(13) lgkmcnt(1)
	v_pk_fma_f32 v[18:19], v[168:169], v[18:19], v[54:55]
	v_pk_fma_f32 v[20:21], v[166:167], v[20:21], v[56:57]
	v_pk_mul_f32 v[56:57], v[172:173], v[18:19]
	global_store_dwordx4 v[60:61], v[18:21], off
	v_pk_mul_f32 v[54:55], v[170:171], v[20:21]
	v_cvt_pk_bf16_f32 v56, v56, v57
	s_waitcnt vmcnt(13) lgkmcnt(0)
	v_pk_fma_f32 v[22:23], v[168:169], v[22:23], v[50:51]
	v_cvt_pk_bf16_f32 v57, v54, v55
	ds_bpermute_b32 v50, v203, v56
	ds_bpermute_b32 v51, v203, v57
	v_pk_fma_f32 v[24:25], v[166:167], v[24:25], v[52:53]
	v_pk_mul_f32 v[52:53], v[172:173], v[22:23]
	v_pk_mul_f32 v[54:55], v[170:171], v[24:25]
	global_store_dwordx4 v[64:65], v[22:25], off
	v_cvt_pk_bf16_f32 v52, v52, v53
	v_cvt_pk_bf16_f32 v53, v54, v55
	v_add_u32_e32 v55, 0x50000, v202
	v_lshlrev_b32_e32 v54, 1, v55
	s_waitcnt lgkmcnt(0)
	v_add_u32_e32 v250, 0xfffff040, v54
	v_cndmask_b32_e64 v250, v54, v250, s[40:41]
	v_cndmask_b32_e64 v248, v62, v50, s[40:41]
	v_cndmask_b32_e64 v249, v63, v51, s[40:41]
	global_store_dwordx2 v250, v[248:249], s[20:21]
	v_cndmask_b32_e64 v246, v50, v62, s[40:41]
	v_cndmask_b32_e64 v247, v51, v63, s[40:41]
	s_waitcnt lgkmcnt(1)
	v_add_u32_e32 v50, 0x1040, v54
	v_cndmask_b32_e64 v50, v54, v50, s[38:39]
	global_store_dwordx2 v50, v[246:247], s[20:21]
	ds_bpermute_b32 v50, v203, v52
	s_waitcnt lgkmcnt(1)
	ds_bpermute_b32 v51, v203, v53
	v_add_u32_e32 v53, 0x54000, v202
	v_lshlrev_b32_e32 v52, 1, v53
	s_waitcnt lgkmcnt(0)
	v_add_u32_e32 v250, 0xfffff040, v52
	v_cndmask_b32_e64 v250, v52, v250, s[40:41]
	v_cndmask_b32_e64 v248, v58, v50, s[40:41]
	v_cndmask_b32_e64 v249, v59, v51, s[40:41]
	global_store_dwordx2 v250, v[248:249], s[20:21]
	v_cndmask_b32_e64 v246, v50, v58, s[40:41]
	v_cndmask_b32_e64 v247, v51, v59, s[40:41]
	v_mul_f32_e32 v19, v19, v19
	v_fmac_f32_e32 v19, v18, v18
	v_mul_f32_e32 v18, v21, v21
	v_mul_f32_e32 v29, v29, v29
	v_fmac_f32_e32 v18, v20, v20
	v_mul_f32_e32 v27, v27, v27
	v_fmac_f32_e32 v29, v28, v28
	v_mul_f32_e32 v28, v31, v31
	v_mul_f32_e32 v31, v33, v33
	v_add_f32_e32 v18, v19, v18
	v_mul_f32_e32 v19, v23, v23
	v_mul_f32_e32 v20, v25, v25
	v_fmac_f32_e32 v31, v32, v32
	v_fmac_f32_e32 v19, v22, v22
	v_fmac_f32_e32 v20, v24, v24
	v_fmac_f32_e32 v27, v26, v26
	v_fmac_f32_e32 v28, v30, v30
	v_add_f32_e32 v19, v19, v20
	v_add_f32_e32 v20, v27, v29
	v_add_f32_e32 v21, v28, v31
	v_add_f32_e32 v18, v20, v18
	v_add_f32_e32 v19, v21, v19
	ds_bpermute_b32 v20, v190, v18
	ds_bpermute_b32 v21, v190, v19
	s_waitcnt lgkmcnt(1)
	v_add_f32_e32 v18, v18, v20
	s_waitcnt lgkmcnt(0)
	v_add_f32_e32 v21, v19, v21
	ds_bpermute_b32 v20, v191, v18
	ds_bpermute_b32 v22, v191, v21
	s_waitcnt lgkmcnt(1)
	v_add_f32_e32 v18, v18, v20
	s_waitcnt lgkmcnt(0)
	v_add_f32_e32 v20, v21, v22
	ds_bpermute_b32 v19, v204, v18
	ds_bpermute_b32 v21, v204, v20
	v_add_u32_e32 v22, 0x1040, v52
	v_cndmask_b32_e64 v22, v52, v22, s[38:39]
	global_store_dwordx2 v22, v[246:247], s[20:21]
	s_and_saveexec_b64 s[16:17], s[42:43]
	s_cbranch_execz .LBB0_1668
	s_waitcnt lgkmcnt(1)
	v_add_f32_e32 v18, v18, v19
	s_waitcnt lgkmcnt(0)
	v_add_f32_e32 v19, v20, v21
	ds_write2_b32 v194, v18, v19 offset0:96 offset1:104
; #define LAS __attribute__((address_space(3)))
; #define ERN_EOFF(q, m) (eb + (unsigned)((((q) & 1) * HALF + (m) * 16) * DM + ERN_COL((q) >> 1)))
;     __device__ __forceinline__ void operator()(const f32x4 (&acc)[2][2][4][2], const Unit& u, int wr, int wc, int fr, int fq) const {
;     ...
;         for (int g = 0; g < 8; ++g) { const int ai = g >> 2, m = g & 3;
;             if (g + 1 < 8) ERN_LOADX(g + 1);
;             float sq0 = 0.f, sq1 = 0.f; u32x2 hw[2][2];
; #pragma unroll
;             for (int bj = 0; bj < 2; ++bj) {
;                 *(LAS f32x4*)(st + wr_off) = acc[ai][bj][m][0]; *(LAS f32x4*)(st + wr_off + 64) = acc[ai][bj][m][1];
;                 const f32x4 a0 = *(const LAS f32x4*)(st + rd_off), a1 = *(const LAS f32x4*)(st + rd_off + 8 * 144);
;                 { const f32x4 xv = xb[g & 1][bj][0] + gv[bj] * a0; __builtin_nontemporal_store(xv, (f32x4*)((char*)xo + 4u * ERN_EOFF(g, bj, 0)));
;                   sq0 += (xv.x * xv.x + xv.y * xv.y) + (xv.z * xv.z + xv.w * xv.w);
;                   const f32x4 hv = xv * gsn[bj]; hw[bj][0].x = cvt_pk_bf16(hv.x, hv.y); hw[bj][0].y = cvt_pk_bf16(hv.z, hv.w); }
;                 { const f32x4 xv = xb[g & 1][bj][1] + gv[bj] * a1; __builtin_nontemporal_store(xv, (f32x4*)((char*)xo + 4u * ERN_EOFF(g, bj, 1)));
;                   sq1 += (xv.x * xv.x + xv.y * xv.y) + (xv.z * xv.z + xv.w * xv.w);
;                   const f32x4 hv = xv * gsn[bj]; hw[bj][1].x = cvt_pk_bf16(hv.x, hv.y); hw[bj][1].y = cvt_pk_bf16(hv.z, hv.w); }
;             }
;             if (!NOH && !PLAIN) {
; #pragma unroll
;                 for (int rh = 0; rh < 2; ++rh) { u32x2 rv; rv.x = __shfl_xor(hw[1][rh].x, 8); rv.y = __shfl_xor(hw[1][rh].y, 8);
;                     const unsigned e0 = ERN_EOFF(g, 0, rh);
;                     const unsigned ee = odd ? (e0 - DM + 32) : e0, eo2 = odd ? e0 : (e0 + DM + 32);
;                     *(u32x2*)((char*)ho + 2u * ee) = odd ? rv : hw[0][rh];
;                     *(u32x2*)((char*)ho + 2u * eo2) = odd ? hw[0][rh] : rv; }
;             }
;             if (!PLAIN) { sq0 += __shfl_xor(sq0, 1); sq0 += __shfl_xor(sq0, 2); sq0 += __shfl_xor(sq0, 4);
;             sq1 += __shfl_xor(sq1, 1); sq1 += __shfl_xor(sq1, 2); sq1 += __shfl_xor(sq1, 4); }
;             if (!PLAIN && pc == 0) { sst[g * 16 + rr] = sq0; sst[g * 16 + 8 + rr] = sq1; }
.LBB0_1668:
	s_or_b64 exec, exec, s[16:17]
	ds_write_b128 v200, v[14:17]
	ds_write_b128 v200, v[10:13] offset:64
	ds_read_b128 v[10:13], v201
	ds_read_b128 v[14:17], v201 offset:1152
	s_waitcnt lgkmcnt(5)
	v_lshl_add_u64 v[18:19], s[22:23], 0, v[154:155]
	v_mov_b32_e32 v71, v155
	v_lshl_add_u64 v[22:23], s[22:23], 0, v[70:71]
	s_waitcnt vmcnt(9) lgkmcnt(1)
	v_pk_fma_f32 v[12:13], v[176:177], v[12:13], v[48:49]
	v_pk_fma_f32 v[10:11], v[180:181], v[10:11], v[46:47]
	global_store_dwordx4 v[18:19], v[10:13], off
	v_pk_mul_f32 v[18:19], v[174:175], v[12:13]
	v_pk_mul_f32 v[20:21], v[178:179], v[10:11]
	s_waitcnt vmcnt(9) lgkmcnt(0)
	v_pk_fma_f32 v[14:15], v[180:181], v[14:15], v[42:43]
	v_cvt_pk_bf16_f32 v20, v20, v21
	v_cvt_pk_bf16_f32 v21, v18, v19
	v_pk_fma_f32 v[16:17], v[176:177], v[16:17], v[44:45]
	v_pk_mul_f32 v[18:19], v[178:179], v[14:15]
	global_store_dwordx4 v[22:23], v[14:17], off
	v_pk_mul_f32 v[22:23], v[174:175], v[16:17]
	v_cvt_pk_bf16_f32 v18, v18, v19
	v_mov_b32_e32 v69, v155
	v_cvt_pk_bf16_f32 v19, v22, v23
	ds_write_b128 v200, v[6:9]
	ds_write_b128 v200, v[2:5] offset:64
	ds_read_b128 v[2:5], v201
	ds_read_b128 v[6:9], v201 offset:1152
	v_lshl_add_u64 v[22:23], s[22:23], 0, v[68:69]
	v_mov_b32_e32 v67, v155
	v_lshl_add_u64 v[24:25], s[22:23], 0, v[66:67]
	s_waitcnt vmcnt(9) lgkmcnt(1)
	v_pk_fma_f32 v[4:5], v[166:167], v[4:5], v[40:41]
	v_pk_fma_f32 v[2:3], v[168:169], v[2:3], v[38:39]
	global_store_dwordx4 v[22:23], v[2:5], off
	v_pk_mul_f32 v[22:23], v[170:171], v[4:5]
	v_pk_mul_f32 v[26:27], v[172:173], v[2:3]
	s_waitcnt vmcnt(9) lgkmcnt(0)
	v_pk_fma_f32 v[8:9], v[166:167], v[8:9], v[36:37]
	v_cvt_pk_bf16_f32 v28, v26, v27
	v_cvt_pk_bf16_f32 v23, v22, v23
	ds_bpermute_b32 v22, v203, v28
	ds_bpermute_b32 v23, v203, v23
	v_pk_fma_f32 v[6:7], v[168:169], v[6:7], v[34:35]
	global_store_dwordx4 v[24:25], v[6:9], off
	v_pk_mul_f32 v[26:27], v[170:171], v[8:9]
	v_pk_mul_f32 v[24:25], v[172:173], v[6:7]
	s_nop 0
	v_cvt_pk_bf16_f32 v24, v24, v25
	v_cvt_pk_bf16_f32 v25, v26, v27
	v_add_u32_e32 v27, 0x58000, v202
	v_lshlrev_b32_e32 v26, 1, v27
	s_waitcnt lgkmcnt(0)
	v_add_u32_e32 v250, 0xfffff040, v26
	v_cndmask_b32_e64 v250, v26, v250, s[40:41]
	v_cndmask_b32_e64 v248, v20, v22, s[40:41]
	v_cndmask_b32_e64 v249, v21, v23, s[40:41]
	global_store_dwordx2 v250, v[248:249], s[20:21]
	v_cndmask_b32_e64 v246, v22, v20, s[40:41]
	v_cndmask_b32_e64 v247, v23, v21, s[40:41]
	s_waitcnt lgkmcnt(1)
	v_add_u32_e32 v22, 0x1040, v26
	v_cndmask_b32_e64 v22, v26, v22, s[38:39]
	global_store_dwordx2 v22, v[246:247], s[20:21]
	ds_bpermute_b32 v20, v203, v24
	ds_bpermute_b32 v21, v203, v25
	s_waitcnt lgkmcnt(2)
	v_add_u32_e32 v23, 0x5c000, v202
	v_lshlrev_b32_e32 v22, 1, v23
	s_waitcnt lgkmcnt(0)
	v_add_u32_e32 v250, 0xfffff040, v22
	v_cndmask_b32_e64 v250, v22, v250, s[40:41]
	v_cndmask_b32_e64 v248, v18, v20, s[40:41]
	v_cndmask_b32_e64 v249, v19, v21, s[40:41]
	global_store_dwordx2 v250, v[248:249], s[20:21]
	v_cndmask_b32_e64 v246, v20, v18, s[40:41]
	v_cndmask_b32_e64 v247, v21, v19, s[40:41]
	v_mul_f32_e32 v3, v3, v3
	v_fmac_f32_e32 v3, v2, v2
	v_mul_f32_e32 v2, v5, v5
	v_mul_f32_e32 v13, v13, v13
	v_fmac_f32_e32 v2, v4, v4
	v_mul_f32_e32 v11, v11, v11
	v_fmac_f32_e32 v13, v12, v12
	v_mul_f32_e32 v12, v15, v15
	v_mul_f32_e32 v15, v17, v17
	v_add_f32_e32 v2, v3, v2
	v_mul_f32_e32 v3, v7, v7
	v_mul_f32_e32 v4, v9, v9
	v_fmac_f32_e32 v15, v16, v16
	v_fmac_f32_e32 v3, v6, v6
	v_fmac_f32_e32 v4, v8, v8
	v_fmac_f32_e32 v11, v10, v10
	v_fmac_f32_e32 v12, v14, v14
	v_add_f32_e32 v3, v3, v4
	v_add_f32_e32 v4, v11, v13
	v_add_f32_e32 v5, v12, v15
	v_add_f32_e32 v2, v4, v2
	v_add_f32_e32 v3, v5, v3
	ds_bpermute_b32 v4, v190, v2
	ds_bpermute_b32 v5, v190, v3
	s_waitcnt lgkmcnt(1)
	v_add_f32_e32 v2, v2, v4
	s_waitcnt lgkmcnt(0)
	v_add_f32_e32 v5, v3, v5
	ds_bpermute_b32 v4, v191, v2
	ds_bpermute_b32 v6, v191, v5
	s_waitcnt lgkmcnt(1)
	v_add_f32_e32 v2, v2, v4
	s_waitcnt lgkmcnt(0)
	v_add_f32_e32 v4, v5, v6
	ds_bpermute_b32 v3, v204, v2
	ds_bpermute_b32 v5, v204, v4
	v_add_u32_e32 v6, 0x1040, v22
	v_cndmask_b32_e64 v6, v22, v6, s[38:39]
	global_store_dwordx2 v6, v[246:247], s[20:21]
	s_and_saveexec_b64 s[16:17], s[42:43]
	s_cbranch_execz .LBB0_1678
	s_waitcnt lgkmcnt(1)
	v_add_f32_e32 v2, v2, v3
	s_waitcnt lgkmcnt(0)
	v_add_f32_e32 v3, v4, v5
	ds_write2_b32 v194, v2, v3 offset0:112 offset1:120

; #define LAS __attribute__((address_space(3)))
;     __device__ __forceinline__ void operator()(const f32x4 (&acc)[2][2][4][2], const Unit& u, int wr, int wc, int fr, int fq) const {
;         const int s = u.pm >> 5, lane = fq * 16 + fr, rr = lane >> 3, pc = lane & 7;
;         const float* __restrict__ xi = xin + (size_t)u.pm * BM * DM; float* __restrict__ xo = xout + (size_t)u.pm * BM * DM; bf16_t* __restrict__ ho = Hn + (size_t)u.pm * BM * DM;
;         LAS unsigned char* st = lds_epi + (wr * 4 + wc) * 2304;
;         LAS float* sst = (LAS float*)(lds_epi + 18432 + (wr * 4 + wc) * 512);
;         const int colr = u.pn * BM + wc * 64 + 4 * pc;
;         const unsigned eb = (unsigned)((wr * 64 + rr) * DM + colr);
;         f32x4 gv[2], gsn[2];
; #pragma unroll
;         for (int bj = 0; bj < 2; ++bj) { gv[bj] = *(const f32x4*)(gate + (size_t)s * MODW + colr + bj * 32) * (0.5f * GS2);
;             if (!PLAIN) gsn[bj] = *(const f32x4*)(gnext + colr + bj * 32) * (*(const f32x4*)(scnext + (size_t)s * MODW + colr + bj * 32) + 1.0f); else gsn[bj] = gv[bj]; }
;         const unsigned wr_off = (unsigned)(fr * 144 + 16 * fq), rd_off = (unsigned)(rr * 144 + pc * 16);
;         const bool odd = (rr & 1) != 0;
;         f32x4 xb[2][2][2];
;     ...
;         ERN_LOADX(0);
; #pragma unroll
;         for (int g = 0; g < 8; ++g) { const int ai = g >> 2, m = g & 3;
;             if (g + 1 < 8) ERN_LOADX(g + 1);
;             float sq0 = 0.f, sq1 = 0.f; u32x2 hw[2][2];
; #pragma unroll
;             for (int bj = 0; bj < 2; ++bj) {
;                 *(LAS f32x4*)(st + wr_off) = acc[ai][bj][m][0]; *(LAS f32x4*)(st + wr_off + 64) = acc[ai][bj][m][1];
;                 const f32x4 a0 = *(const LAS f32x4*)(st + rd_off), a1 = *(const LAS f32x4*)(st + rd_off + 8 * 144);
;                 { const f32x4 xv = xb[g & 1][bj][0] + gv[bj] * a0; __builtin_nontemporal_store(xv, (f32x4*)((char*)xo + 4u * ERN_EOFF(g, bj, 0)));
;                   sq0 += (xv.x * xv.x + xv.y * xv.y) + (xv.z * xv.z + xv.w * xv.w);
;                   const f32x4 hv = xv * gsn[bj]; hw[bj][0].x = cvt_pk_bf16(hv.x, hv.y); hw[bj][0].y = cvt_pk_bf16(hv.z, hv.w); }
;                 { const f32x4 xv = xb[g & 1][bj][1] + gv[bj] * a1; __builtin_nontemporal_store(xv, (f32x4*)((char*)xo + 4u * ERN_EOFF(g, bj, 1)));
;                   sq1 += (xv.x * xv.x + xv.y * xv.y) + (xv.z * xv.z + xv.w * xv.w);
.LBB0_1929:
	s_ashr_i32 s18, s4, 5
	s_ashr_i32 s5, s4, 31
	v_lshl_or_b32 v130, s0, 8, v192
	s_mul_i32 s20, s18, 0x12000
	s_mul_hi_i32 s0, s18, 0x12000
	s_add_u32 s18, s33, s20
	v_ashrrev_i32_e32 v131, 31, v130
	s_addc_u32 s19, s34, s0
	v_lshlrev_b64 v[132:133], 2, v[130:131]
	v_lshl_add_u64 v[134:135], s[18:19], 0, v[132:133]
	s_add_u32 s18, s35, s20
	s_addc_u32 s19, s36, s0
	v_lshl_add_u64 v[136:137], s[10:11], 0, v[132:133]
	v_lshl_add_u64 v[132:133], s[18:19], 0, v[132:133]
	s_lshl_b64 s[18:19], s[4:5], 21
	s_add_u32 s20, s90, s18
	v_add_u32_e32 v202, v130, v193
	s_addc_u32 s21, s91, s19
	v_lshlrev_b32_e32 v205, 2, v202
	global_load_dwordx4 v[170:173], v[136:137], off
	global_load_dwordx4 v[166:169], v[134:135], off
	global_load_dwordx4 v[186:189], v[134:135], off offset:128
	global_load_dwordx4 v[206:209], v[132:133], off
	global_load_dwordx4 v[210:213], v[132:133], off offset:128
	global_load_dwordx4 v[214:217], v205, s[20:21]
	v_add_u32_e32 v130, 0x10000, v205
	global_load_dwordx4 v[218:221], v130, s[20:21]
	global_load_dwordx4 v[222:225], v[136:137], off offset:128
	global_load_dwordx4 v[226:229], v205, s[20:21] offset:128
	v_add_u32_e32 v204, 0x10080, v205
	global_load_dwordx4 v[230:233], v204, s[20:21]
	v_add_u32_e32 v130, 0x20000, v205
	v_add_u32_e32 v154, 0x30000, v205
	v_add_u32_e32 v184, 0x20080, v205
	v_add_u32_e32 v182, 0x30080, v205
	global_load_dwordx4 v[142:145], v130, s[20:21]
	global_load_dwordx4 v[138:141], v154, s[20:21]
	global_load_dwordx4 v[134:137], v184, s[20:21]
	s_nop 0
	global_load_dwordx4 v[130:133], v182, s[20:21]
	ds_write_b128 v200, v[126:129]
	ds_write_b128 v200, v[122:125] offset:64
	v_and_b32_e32 v127, 64, v199
	ds_read_b128 v[122:125], v201
	ds_read_b128 v[234:237], v201 offset:1152
	v_xor_b32_e32 v126, 8, v199
	v_add_u32_e32 v183, 64, v127
	v_cmp_lt_i32_e32 vcc, v126, v183
	v_add_u32_e32 v185, 0x4000, v202
	v_lshlrev_b32_e32 v238, 2, v185
	v_cndmask_b32_e32 v126, v199, v126, vcc
	v_lshlrev_b32_e32 v203, 2, v126
	s_lshl_b64 s[18:19], s[4:5], 20
	s_add_u32 s18, s93, s18
	s_addc_u32 s19, s92, s19
	s_waitcnt vmcnt(0)
	v_pk_mul_f32 v[180:181], v[166:167], 0.5 op_sel_hi:[1,0]
	v_pk_mul_f32 v[176:177], v[168:169], 0.5 op_sel_hi:[1,0]
	v_pk_add_f32 v[126:127], v[208:209], 1.0 op_sel_hi:[1,0]
	v_pk_add_f32 v[128:129], v[206:207], 1.0 op_sel_hi:[1,0]
	v_pk_mul_f32 v[174:175], v[172:173], v[126:127]
	v_pk_mul_f32 v[178:179], v[170:171], v[128:129]
	s_waitcnt lgkmcnt(1)
	v_pk_fma_f32 v[126:127], v[180:181], v[122:123], v[214:215]
	s_waitcnt lgkmcnt(0)
	v_pk_fma_f32 v[122:123], v[180:181], v[234:235], v[218:219]
	v_pk_mul_f32 v[168:169], v[186:187], 0.5 op_sel_hi:[1,0]
	v_pk_fma_f32 v[128:129], v[176:177], v[124:125], v[216:217]
	v_pk_fma_f32 v[124:125], v[176:177], v[236:237], v[220:221]
	v_pk_mul_f32 v[186:187], v[178:179], v[122:123]
	v_pk_mul_f32 v[166:167], v[188:189], 0.5 op_sel_hi:[1,0]
	global_store_dwordx4 v205, v[126:129], s[20:21]
	v_pk_mul_f32 v[170:171], v[174:175], v[128:129]
	v_pk_mul_f32 v[172:173], v[178:179], v[126:127]
	v_pk_mul_f32 v[206:207], v[174:175], v[124:125]
	v_cvt_pk_bf16_f32 v188, v172, v173
	v_cvt_pk_bf16_f32 v189, v170, v171
	global_store_dwordx4 v238, v[122:125], s[20:21]
	v_cvt_pk_bf16_f32 v186, v186, v187
	v_cvt_pk_bf16_f32 v187, v206, v207
	ds_write_b128 v200, v[118:121]
	ds_write_b128 v200, v[114:117] offset:64
	ds_read_b128 v[114:117], v201
	ds_read_b128 v[206:209], v201 offset:1152
	v_pk_add_f32 v[190:191], v[212:213], 1.0 op_sel_hi:[1,0]
	v_pk_add_f32 v[118:119], v[210:211], 1.0 op_sel_hi:[1,0]
	v_pk_mul_f32 v[170:171], v[224:225], v[190:191]
	v_pk_mul_f32 v[172:173], v[222:223], v[118:119]
	s_waitcnt lgkmcnt(1)
	v_pk_fma_f32 v[120:121], v[166:167], v[116:117], v[228:229]
	v_pk_fma_f32 v[118:119], v[168:169], v[114:115], v[226:227]
	s_waitcnt lgkmcnt(0)
	v_pk_fma_f32 v[114:115], v[168:169], v[206:207], v[230:231]
	v_pk_mul_f32 v[190:191], v[170:171], v[120:121]
	v_pk_mul_f32 v[206:207], v[172:173], v[118:119]
	global_store_dwordx4 v205, v[118:121], s[20:21] offset:128
	v_cvt_pk_bf16_f32 v206, v206, v207
	v_cvt_pk_bf16_f32 v191, v190, v191
	ds_bpermute_b32 v190, v203, v206
	ds_bpermute_b32 v191, v203, v191
	v_pk_fma_f32 v[116:117], v[166:167], v[208:209], v[232:233]
	v_pk_mul_f32 v[206:207], v[172:173], v[114:115]
	global_store_dwordx4 v204, v[114:117], s[20:21]
	v_cvt_pk_bf16_f32 v204, v206, v207
	v_lshlrev_b32_e32 v207, 1, v202
	v_pk_mul_f32 v[208:209], v[170:171], v[116:117]
	s_nop 0
	v_cvt_pk_bf16_f32 v206, v208, v209
	s_waitcnt lgkmcnt(0)
	v_add_u32_e32 v250, 0xfffff040, v207
	v_cndmask_b32_e64 v250, v207, v250, s[40:41]
	v_cndmask_b32_e64 v248, v188, v190, s[40:41]
	v_cndmask_b32_e64 v249, v189, v191, s[40:41]
	global_store_dwordx2 v250, v[248:249], s[18:19]
	v_cndmask_b32_e64 v246, v190, v188, s[40:41]
	v_cndmask_b32_e64 v247, v191, v189, s[40:41]
	s_waitcnt lgkmcnt(1)
	v_add_u32_e32 v190, 0x1040, v207
	v_cndmask_b32_e64 v190, v207, v190, s[38:39]
	global_store_dwordx2 v190, v[246:247], s[18:19]
	ds_bpermute_b32 v188, v203, v204
	ds_bpermute_b32 v189, v203, v206
	v_lshlrev_b32_e32 v206, 1, v185
	s_waitcnt lgkmcnt(0)
; #define LAS __attribute__((address_space(3)))
; #define ERN_EOFF(q, m) (eb + (unsigned)((((q) & 1) * HALF + (m) * 16) * DM + ERN_COL((q) >> 1)))
;     __device__ __forceinline__ void operator()(const f32x4 (&acc)[2][2][4][2], const Unit& u, int wr, int wc, int fr, int fq) const {
;     ...
;         for (int g = 0; g < 8; ++g) { const int ai = g >> 2, m = g & 3;
;             if (g + 1 < 8) ERN_LOADX(g + 1);
;             float sq0 = 0.f, sq1 = 0.f; u32x2 hw[2][2];
; #pragma unroll
;             for (int bj = 0; bj < 2; ++bj) {
;                 *(LAS f32x4*)(st + wr_off) = acc[ai][bj][m][0]; *(LAS f32x4*)(st + wr_off + 64) = acc[ai][bj][m][1];
;                 const f32x4 a0 = *(const LAS f32x4*)(st + rd_off), a1 = *(const LAS f32x4*)(st + rd_off + 8 * 144);
;                 { const f32x4 xv = xb[g & 1][bj][0] + gv[bj] * a0; __builtin_nontemporal_store(xv, (f32x4*)((char*)xo + 4u * ERN_EOFF(g, bj, 0)));
;                   sq0 += (xv.x * xv.x + xv.y * xv.y) + (xv.z * xv.z + xv.w * xv.w);
;                   const f32x4 hv = xv * gsn[bj]; hw[bj][0].x = cvt_pk_bf16(hv.x, hv.y); hw[bj][0].y = cvt_pk_bf16(hv.z, hv.w); }
;                 { const f32x4 xv = xb[g & 1][bj][1] + gv[bj] * a1; __builtin_nontemporal_store(xv, (f32x4*)((char*)xo + 4u * ERN_EOFF(g, bj, 1)));
;                   sq1 += (xv.x * xv.x + xv.y * xv.y) + (xv.z * xv.z + xv.w * xv.w);
;                   const f32x4 hv = xv * gsn[bj]; hw[bj][1].x = cvt_pk_bf16(hv.x, hv.y); hw[bj][1].y = cvt_pk_bf16(hv.z, hv.w); }
;             }
;             if (!NOH && !PLAIN) {
; #pragma unroll
;                 for (int rh = 0; rh < 2; ++rh) { u32x2 rv; rv.x = __shfl_xor(hw[1][rh].x, 8); rv.y = __shfl_xor(hw[1][rh].y, 8);
;                     const unsigned e0 = ERN_EOFF(g, 0, rh);
;                     const unsigned ee = odd ? (e0 - DM + 32) : e0, eo2 = odd ? e0 : (e0 + DM + 32);
;                     *(u32x2*)((char*)ho + 2u * ee) = odd ? rv : hw[0][rh];
;                     *(u32x2*)((char*)ho + 2u * eo2) = odd ? hw[0][rh] : rv; }
;             }
;             if (!PLAIN) { sq0 += __shfl_xor(sq0, 1); sq0 += __shfl_xor(sq0, 2); sq0 += __shfl_xor(sq0, 4);
;             sq1 += __shfl_xor(sq1, 1); sq1 += __shfl_xor(sq1, 2); sq1 += __shfl_xor(sq1, 4); }
;             if (!PLAIN && pc == 0) { sst[g * 16 + rr] = sq0; sst[g * 16 + 8 + rr] = sq1; }
	v_add_u32_e32 v250, 0xfffff040, v206
	v_cndmask_b32_e64 v250, v206, v250, s[40:41]
	v_cndmask_b32_e64 v248, v186, v188, s[40:41]
	v_cndmask_b32_e64 v249, v187, v189, s[40:41]
	global_store_dwordx2 v250, v[248:249], s[18:19]
	v_cndmask_b32_e64 v246, v188, v186, s[40:41]
	v_cndmask_b32_e64 v247, v189, v187, s[40:41]
	v_mul_f32_e32 v119, v119, v119
	v_mul_f32_e32 v127, v127, v127
	v_mul_f32_e32 v129, v129, v129
	v_fmac_f32_e32 v119, v118, v118
	v_mul_f32_e32 v118, v121, v121
	v_fmac_f32_e32 v129, v128, v128
	v_fmac_f32_e32 v118, v120, v120
	v_mul_f32_e32 v115, v115, v115
	v_fmac_f32_e32 v127, v126, v126
	v_add_f32_e32 v118, v119, v118
	v_fmac_f32_e32 v115, v114, v114
	v_mul_f32_e32 v114, v117, v117
	v_add_f32_e32 v117, v127, v129
	v_add_f32_e32 v117, v117, v118
	v_xor_b32_e32 v118, 1, v199
	v_cmp_lt_i32_e32 vcc, v118, v183
	v_mul_f32_e32 v123, v123, v123
	v_mul_f32_e32 v125, v125, v125
	v_cndmask_b32_e32 v118, v199, v118, vcc
	v_lshlrev_b32_e32 v190, 2, v118
	ds_bpermute_b32 v118, v190, v117
	v_fmac_f32_e32 v114, v116, v116
	v_fmac_f32_e32 v125, v124, v124
	v_fmac_f32_e32 v123, v122, v122
	v_add_f32_e32 v114, v115, v114
	s_waitcnt lgkmcnt(0)
	v_add_f32_e32 v116, v117, v118
	v_xor_b32_e32 v117, 2, v199
	v_cmp_lt_i32_e32 vcc, v117, v183
	v_add_f32_e32 v115, v123, v125
	v_add_f32_e32 v115, v115, v114
	v_cndmask_b32_e32 v117, v199, v117, vcc
	v_lshlrev_b32_e32 v191, 2, v117
	ds_bpermute_b32 v117, v191, v116
	ds_bpermute_b32 v118, v190, v115
	s_waitcnt lgkmcnt(1)
	v_add_f32_e32 v114, v116, v117
	s_waitcnt lgkmcnt(0)
	v_add_f32_e32 v117, v115, v118
	ds_bpermute_b32 v118, v191, v117
	v_xor_b32_e32 v116, 4, v199
	v_cmp_lt_i32_e32 vcc, v116, v183
	s_nop 1
	v_cndmask_b32_e32 v115, v199, v116, vcc
	v_lshlrev_b32_e32 v204, 2, v115
	s_waitcnt lgkmcnt(0)
	v_add_f32_e32 v116, v117, v118
	ds_bpermute_b32 v115, v204, v114
	ds_bpermute_b32 v117, v204, v116
	v_add_u32_e32 v118, 0x1040, v206
	v_cndmask_b32_e64 v118, v206, v118, s[38:39]
	global_store_dwordx2 v118, v[246:247], s[18:19]
	s_and_saveexec_b64 s[22:23], s[42:43]
	s_cbranch_execz .LBB0_1939
	s_waitcnt lgkmcnt(1)
	v_add_f32_e32 v114, v114, v115
	s_waitcnt lgkmcnt(0)
	v_add_f32_e32 v115, v116, v117
	ds_write2_b32 v194, v114, v115 offset1:8
.LBB0_1939:
	s_or_b64 exec, exec, s[22:23]
	v_lshl_add_u64 v[206:207], s[20:21], 0, v[154:155]
	v_add_u32_e32 v114, 0x40000, v205
	v_add_u32_e32 v154, 0x50000, v205
	v_add_u32_e32 v186, 0x40080, v205
	global_load_dwordx4 v[122:125], v154, s[20:21]
	global_load_dwordx4 v[118:121], v186, s[20:21]
	v_add_u32_e32 v188, 0x50080, v205
	global_load_dwordx4 v[126:129], v114, s[20:21]
	s_waitcnt lgkmcnt(0)
	global_load_dwordx4 v[114:117], v188, s[20:21]
	ds_write_b128 v200, v[110:113]
	ds_write_b128 v200, v[106:109] offset:64
	ds_read_b128 v[106:109], v201
	ds_read_b128 v[110:113], v201 offset:1152
	v_mov_b32_e32 v185, v155
	v_mov_b32_e32 v183, v155
	v_lshl_add_u64 v[182:183], s[20:21], 0, v[182:183]
	s_waitcnt lgkmcnt(1)
	v_pk_fma_f32 v[108:109], v[176:177], v[108:109], v[144:145]
	v_add_u32_e32 v144, 0x8000, v202
	v_pk_fma_f32 v[106:107], v[180:181], v[106:107], v[142:143]
	v_lshlrev_b32_e32 v142, 2, v144
	s_waitcnt lgkmcnt(0)
	v_pk_fma_f32 v[110:111], v[180:181], v[110:111], v[138:139]
	global_store_dwordx4 v142, v[106:109], s[20:21]
	v_pk_mul_f32 v[142:143], v[178:179], v[106:107]
	v_pk_fma_f32 v[112:113], v[176:177], v[112:113], v[140:141]
	v_pk_mul_f32 v[138:139], v[178:179], v[110:111]
	v_pk_mul_f32 v[208:209], v[174:175], v[108:109]
	v_cvt_pk_bf16_f32 v142, v142, v143
	v_pk_mul_f32 v[140:141], v[174:175], v[112:113]
	v_cvt_pk_bf16_f32 v143, v208, v209
	global_store_dwordx4 v[206:207], v[110:113], off
	v_cvt_pk_bf16_f32 v138, v138, v139
	v_cvt_pk_bf16_f32 v139, v140, v141
	ds_write_b128 v200, v[102:105]
	ds_write_b128 v200, v[98:101] offset:64
	ds_read_b128 v[98:101], v201
	ds_read_b128 v[102:105], v201 offset:1152
	v_lshl_add_u64 v[140:141], s[20:21], 0, v[184:185]
	s_waitcnt lgkmcnt(1)
	v_pk_fma_f32 v[98:99], v[168:169], v[98:99], v[134:135]
	v_pk_fma_f32 v[100:101], v[166:167], v[100:101], v[136:137]
	v_pk_mul_f32 v[136:137], v[172:173], v[98:99]
	global_store_dwordx4 v[140:141], v[98:101], off
	v_pk_mul_f32 v[134:135], v[170:171], v[100:101]
	v_cvt_pk_bf16_f32 v136, v136, v137
	s_waitcnt lgkmcnt(0)
	v_pk_fma_f32 v[102:103], v[168:169], v[102:103], v[130:131]
	v_cvt_pk_bf16_f32 v137, v134, v135
	ds_bpermute_b32 v130, v203, v136
	ds_bpermute_b32 v131, v203, v137
	v_pk_fma_f32 v[104:105], v[166:167], v[104:105], v[132:133]
	v_pk_mul_f32 v[132:133], v[172:173], v[102:103]
	v_pk_mul_f32 v[134:135], v[170:171], v[104:105]
	global_store_dwordx4 v[182:183], v[102:105], off
	v_cvt_pk_bf16_f32 v132, v132, v133
	v_cvt_pk_bf16_f32 v133, v134, v135
	v_lshlrev_b32_e32 v134, 1, v144
	s_waitcnt lgkmcnt(0)
	v_add_u32_e32 v250, 0xfffff040, v134
	v_cndmask_b32_e64 v250, v134, v250, s[40:41]
	v_cndmask_b32_e64 v248, v142, v130, s[40:41]
	v_cndmask_b32_e64 v249, v143, v131, s[40:41]
	global_store_dwordx2 v250, v[248:249], s[18:19]
	v_cndmask_b32_e64 v246, v130, v142, s[40:41]
	v_cndmask_b32_e64 v247, v131, v143, s[40:41]
	s_waitcnt lgkmcnt(1)
	v_add_u32_e32 v130, 0x1040, v134
	v_cndmask_b32_e64 v130, v134, v130, s[38:39]
	global_store_dwordx2 v130, v[246:247], s[18:19]
	ds_bpermute_b32 v130, v203, v132
	s_waitcnt lgkmcnt(1)
	ds_bpermute_b32 v131, v203, v133
	v_add_u32_e32 v133, 0xc000, v202
	v_lshlrev_b32_e32 v132, 1, v133
	s_waitcnt lgkmcnt(0)
	v_add_u32_e32 v250, 0xfffff040, v132
	v_cndmask_b32_e64 v250, v132, v250, s[40:41]
	v_cndmask_b32_e64 v248, v138, v130, s[40:41]
	v_cndmask_b32_e64 v249, v139, v131, s[40:41]
	global_store_dwordx2 v250, v[248:249], s[18:19]
	v_cndmask_b32_e64 v246, v130, v138, s[40:41]
	v_cndmask_b32_e64 v247, v131, v139, s[40:41]
	v_mul_f32_e32 v99, v99, v99
	v_fmac_f32_e32 v99, v98, v98
	v_mul_f32_e32 v98, v101, v101
	v_mul_f32_e32 v109, v109, v109
	v_fmac_f32_e32 v98, v100, v100
	v_mul_f32_e32 v107, v107, v107
	v_fmac_f32_e32 v109, v108, v108
	v_mul_f32_e32 v108, v111, v111
	v_mul_f32_e32 v111, v113, v113
	v_add_f32_e32 v98, v99, v98
	v_mul_f32_e32 v99, v103, v103
	v_mul_f32_e32 v100, v105, v105
	v_fmac_f32_e32 v111, v112, v112
	v_fmac_f32_e32 v99, v102, v102
	v_fmac_f32_e32 v100, v104, v104
	v_fmac_f32_e32 v107, v106, v106
	v_fmac_f32_e32 v108, v110, v110
	v_add_f32_e32 v99, v99, v100
	v_add_f32_e32 v100, v107, v109
	v_add_f32_e32 v101, v108, v111
	v_add_f32_e32 v98, v100, v98
	v_add_f32_e32 v99, v101, v99
	ds_bpermute_b32 v100, v190, v98
	ds_bpermute_b32 v101, v190, v99
	s_waitcnt lgkmcnt(1)
	v_add_f32_e32 v98, v98, v100
	s_waitcnt lgkmcnt(0)
	v_add_f32_e32 v101, v99, v101
	ds_bpermute_b32 v100, v191, v98
	ds_bpermute_b32 v102, v191, v101
	s_waitcnt lgkmcnt(1)
	v_add_f32_e32 v98, v98, v100
	s_waitcnt lgkmcnt(0)
	v_add_f32_e32 v100, v101, v102
	ds_bpermute_b32 v99, v204, v98
	ds_bpermute_b32 v101, v204, v100
	v_add_u32_e32 v102, 0x1040, v132
	v_cndmask_b32_e64 v102, v132, v102, s[38:39]
	global_store_dwordx2 v102, v[246:247], s[18:19]
	s_and_saveexec_b64 s[22:23], s[42:43]
	s_cbranch_execz .LBB0_1949
; #define LAS __attribute__((address_space(3)))
; #define ERN_EOFF(q, m) (eb + (unsigned)((((q) & 1) * HALF + (m) * 16) * DM + ERN_COL((q) >> 1)))
;     __device__ __forceinline__ void operator()(const f32x4 (&acc)[2][2][4][2], const Unit& u, int wr, int wc, int fr, int fq) const {
;     ...
;         for (int g = 0; g < 8; ++g) { const int ai = g >> 2, m = g & 3;
;             if (g + 1 < 8) ERN_LOADX(g + 1);
;             float sq0 = 0.f, sq1 = 0.f; u32x2 hw[2][2];
; #pragma unroll
;             for (int bj = 0; bj < 2; ++bj) {
;                 *(LAS f32x4*)(st + wr_off) = acc[ai][bj][m][0]; *(LAS f32x4*)(st + wr_off + 64) = acc[ai][bj][m][1];
;                 const f32x4 a0 = *(const LAS f32x4*)(st + rd_off), a1 = *(const LAS f32x4*)(st + rd_off + 8 * 144);
;                 { const f32x4 xv = xb[g & 1][bj][0] + gv[bj] * a0; __builtin_nontemporal_store(xv, (f32x4*)((char*)xo + 4u * ERN_EOFF(g, bj, 0)));
;                   sq0 += (xv.x * xv.x + xv.y * xv.y) + (xv.z * xv.z + xv.w * xv.w);
;                   const f32x4 hv = xv * gsn[bj]; hw[bj][0].x = cvt_pk_bf16(hv.x, hv.y); hw[bj][0].y = cvt_pk_bf16(hv.z, hv.w); }
;                 { const f32x4 xv = xb[g & 1][bj][1] + gv[bj] * a1; __builtin_nontemporal_store(xv, (f32x4*)((char*)xo + 4u * ERN_EOFF(g, bj, 1)));
;                   sq1 += (xv.x * xv.x + xv.y * xv.y) + (xv.z * xv.z + xv.w * xv.w);
;                   const f32x4 hv = xv * gsn[bj]; hw[bj][1].x = cvt_pk_bf16(hv.x, hv.y); hw[bj][1].y = cvt_pk_bf16(hv.z, hv.w); }
;             }
;             if (!NOH && !PLAIN) {
; #pragma unroll
;                 for (int rh = 0; rh < 2; ++rh) { u32x2 rv; rv.x = __shfl_xor(hw[1][rh].x, 8); rv.y = __shfl_xor(hw[1][rh].y, 8);
;                     const unsigned e0 = ERN_EOFF(g, 0, rh);
;                     const unsigned ee = odd ? (e0 - DM + 32) : e0, eo2 = odd ? e0 : (e0 + DM + 32);
;                     *(u32x2*)((char*)ho + 2u * ee) = odd ? rv : hw[0][rh];
;                     *(u32x2*)((char*)ho + 2u * eo2) = odd ? hw[0][rh] : rv; }
;             }
;             if (!PLAIN) { sq0 += __shfl_xor(sq0, 1); sq0 += __shfl_xor(sq0, 2); sq0 += __shfl_xor(sq0, 4);
;             sq1 += __shfl_xor(sq1, 1); sq1 += __shfl_xor(sq1, 2); sq1 += __shfl_xor(sq1, 4); }
;             if (!PLAIN && pc == 0) { sst[g * 16 + rr] = sq0; sst[g * 16 + 8 + rr] = sq1; }
	s_waitcnt lgkmcnt(1)
	v_add_f32_e32 v98, v98, v99
	s_waitcnt lgkmcnt(0)
	v_add_f32_e32 v99, v100, v101
	ds_write2_b32 v194, v98, v99 offset0:16 offset1:24
.LBB0_1949:
	s_or_b64 exec, exec, s[22:23]
	v_lshl_add_u64 v[134:135], s[20:21], 0, v[154:155]
	v_add_u32_e32 v98, 0x60000, v205
	v_add_u32_e32 v154, 0x70000, v205
	v_add_u32_e32 v130, 0x60080, v205
	global_load_dwordx4 v[106:109], v154, s[20:21]
	global_load_dwordx4 v[102:105], v130, s[20:21]
	v_add_u32_e32 v132, 0x70080, v205
	global_load_dwordx4 v[110:113], v98, s[20:21]
	s_waitcnt lgkmcnt(0)
	global_load_dwordx4 v[98:101], v132, s[20:21]
	ds_write_b128 v200, v[94:97]
	ds_write_b128 v200, v[90:93] offset:64
	ds_read_b128 v[90:93], v201
	ds_read_b128 v[94:97], v201 offset:1152
	v_mov_b32_e32 v187, v155
	v_mov_b32_e32 v189, v155
	s_waitcnt vmcnt(11) lgkmcnt(1)
	v_pk_fma_f32 v[92:93], v[176:177], v[92:93], v[128:129]
	v_add_u32_e32 v128, 0x10000, v202
	v_pk_fma_f32 v[90:91], v[180:181], v[90:91], v[126:127]
	v_lshlrev_b32_e32 v126, 2, v128
	s_waitcnt lgkmcnt(0)
	v_pk_fma_f32 v[94:95], v[180:181], v[94:95], v[122:123]
	global_store_dwordx4 v126, v[90:93], s[20:21]
	v_pk_mul_f32 v[126:127], v[178:179], v[90:91]
	v_pk_fma_f32 v[96:97], v[176:177], v[96:97], v[124:125]
	v_pk_mul_f32 v[122:123], v[178:179], v[94:95]
	v_pk_mul_f32 v[136:137], v[174:175], v[92:93]
	v_cvt_pk_bf16_f32 v126, v126, v127
	v_pk_mul_f32 v[124:125], v[174:175], v[96:97]
	v_cvt_pk_bf16_f32 v127, v136, v137
	global_store_dwordx4 v[134:135], v[94:97], off
	v_cvt_pk_bf16_f32 v122, v122, v123
	v_cvt_pk_bf16_f32 v123, v124, v125
	ds_write_b128 v200, v[86:89]
	ds_write_b128 v200, v[82:85] offset:64
	ds_read_b128 v[82:85], v201
	ds_read_b128 v[86:89], v201 offset:1152
	v_lshl_add_u64 v[124:125], s[20:21], 0, v[186:187]
	v_lshl_add_u64 v[134:135], s[20:21], 0, v[188:189]
	s_waitcnt lgkmcnt(1)
	v_pk_fma_f32 v[82:83], v[168:169], v[82:83], v[118:119]
	v_pk_fma_f32 v[84:85], v[166:167], v[84:85], v[120:121]
	v_pk_mul_f32 v[120:121], v[172:173], v[82:83]
	global_store_dwordx4 v[124:125], v[82:85], off
	v_pk_mul_f32 v[118:119], v[170:171], v[84:85]
	v_cvt_pk_bf16_f32 v120, v120, v121
	s_waitcnt vmcnt(13) lgkmcnt(0)
	v_pk_fma_f32 v[86:87], v[168:169], v[86:87], v[114:115]
	v_cvt_pk_bf16_f32 v121, v118, v119
	ds_bpermute_b32 v114, v203, v120
	ds_bpermute_b32 v115, v203, v121
	v_pk_fma_f32 v[88:89], v[166:167], v[88:89], v[116:117]
	v_pk_mul_f32 v[116:117], v[172:173], v[86:87]
	v_pk_mul_f32 v[118:119], v[170:171], v[88:89]
	global_store_dwordx4 v[134:135], v[86:89], off
	v_cvt_pk_bf16_f32 v116, v116, v117
	v_cvt_pk_bf16_f32 v117, v118, v119
	v_lshlrev_b32_e32 v118, 1, v128
	s_waitcnt lgkmcnt(0)
	v_add_u32_e32 v250, 0xfffff040, v118
	v_cndmask_b32_e64 v250, v118, v250, s[40:41]
	v_cndmask_b32_e64 v248, v126, v114, s[40:41]
	v_cndmask_b32_e64 v249, v127, v115, s[40:41]
	global_store_dwordx2 v250, v[248:249], s[18:19]
	v_cndmask_b32_e64 v246, v114, v126, s[40:41]
	v_cndmask_b32_e64 v247, v115, v127, s[40:41]
	s_waitcnt lgkmcnt(1)
	v_add_u32_e32 v114, 0x1040, v118
	v_cndmask_b32_e64 v114, v118, v114, s[38:39]
	global_store_dwordx2 v114, v[246:247], s[18:19]
	ds_bpermute_b32 v114, v203, v116
	s_waitcnt lgkmcnt(1)
	ds_bpermute_b32 v115, v203, v117
	v_add_u32_e32 v117, 0x14000, v202
	v_lshlrev_b32_e32 v116, 1, v117
	s_waitcnt lgkmcnt(0)
	v_add_u32_e32 v250, 0xfffff040, v116
	v_cndmask_b32_e64 v250, v116, v250, s[40:41]
	v_cndmask_b32_e64 v248, v122, v114, s[40:41]
	v_cndmask_b32_e64 v249, v123, v115, s[40:41]
	global_store_dwordx2 v250, v[248:249], s[18:19]
	v_cndmask_b32_e64 v246, v114, v122, s[40:41]
	v_cndmask_b32_e64 v247, v115, v123, s[40:41]
	v_mul_f32_e32 v83, v83, v83
	v_fmac_f32_e32 v83, v82, v82
	v_mul_f32_e32 v82, v85, v85
	v_mul_f32_e32 v93, v93, v93
	v_fmac_f32_e32 v82, v84, v84
	v_mul_f32_e32 v91, v91, v91
	v_fmac_f32_e32 v93, v92, v92
	v_mul_f32_e32 v92, v95, v95
	v_mul_f32_e32 v95, v97, v97
	v_add_f32_e32 v82, v83, v82
	v_mul_f32_e32 v83, v87, v87
	v_mul_f32_e32 v84, v89, v89
	v_fmac_f32_e32 v95, v96, v96
	v_fmac_f32_e32 v83, v86, v86
	v_fmac_f32_e32 v84, v88, v88
	v_fmac_f32_e32 v91, v90, v90
	v_fmac_f32_e32 v92, v94, v94
	v_add_f32_e32 v83, v83, v84
	v_add_f32_e32 v84, v91, v93
	v_add_f32_e32 v85, v92, v95
	v_add_f32_e32 v82, v84, v82
	v_add_f32_e32 v83, v85, v83
	ds_bpermute_b32 v84, v190, v82
	ds_bpermute_b32 v85, v190, v83
	s_waitcnt lgkmcnt(1)
	v_add_f32_e32 v82, v82, v84
	s_waitcnt lgkmcnt(0)
	v_add_f32_e32 v85, v83, v85
	ds_bpermute_b32 v84, v191, v82
	ds_bpermute_b32 v86, v191, v85
	s_waitcnt lgkmcnt(1)
	v_add_f32_e32 v82, v82, v84
	s_waitcnt lgkmcnt(0)
	v_add_f32_e32 v84, v85, v86
	ds_bpermute_b32 v83, v204, v82
	ds_bpermute_b32 v85, v204, v84
	v_add_u32_e32 v86, 0x1040, v116
	v_cndmask_b32_e64 v86, v116, v86, s[38:39]
	global_store_dwordx2 v86, v[246:247], s[18:19]
	s_and_saveexec_b64 s[22:23], s[42:43]
	s_cbranch_execz .LBB0_1959
	s_waitcnt lgkmcnt(1)
	v_add_f32_e32 v82, v82, v83
	s_waitcnt lgkmcnt(0)
	v_add_f32_e32 v83, v84, v85
	ds_write2_b32 v194, v82, v83 offset0:32 offset1:40
; #define LAS __attribute__((address_space(3)))
; #define ERN_EOFF(q, m) (eb + (unsigned)((((q) & 1) * HALF + (m) * 16) * DM + ERN_COL((q) >> 1)))
;     __device__ __forceinline__ void operator()(const f32x4 (&acc)[2][2][4][2], const Unit& u, int wr, int wc, int fr, int fq) const {
;     ...
;         for (int g = 0; g < 8; ++g) { const int ai = g >> 2, m = g & 3;
;             if (g + 1 < 8) ERN_LOADX(g + 1);
;             float sq0 = 0.f, sq1 = 0.f; u32x2 hw[2][2];
; #pragma unroll
;             for (int bj = 0; bj < 2; ++bj) {
;                 *(LAS f32x4*)(st + wr_off) = acc[ai][bj][m][0]; *(LAS f32x4*)(st + wr_off + 64) = acc[ai][bj][m][1];
;                 const f32x4 a0 = *(const LAS f32x4*)(st + rd_off), a1 = *(const LAS f32x4*)(st + rd_off + 8 * 144);
;                 { const f32x4 xv = xb[g & 1][bj][0] + gv[bj] * a0; __builtin_nontemporal_store(xv, (f32x4*)((char*)xo + 4u * ERN_EOFF(g, bj, 0)));
;                   sq0 += (xv.x * xv.x + xv.y * xv.y) + (xv.z * xv.z + xv.w * xv.w);
;                   const f32x4 hv = xv * gsn[bj]; hw[bj][0].x = cvt_pk_bf16(hv.x, hv.y); hw[bj][0].y = cvt_pk_bf16(hv.z, hv.w); }
;                 { const f32x4 xv = xb[g & 1][bj][1] + gv[bj] * a1; __builtin_nontemporal_store(xv, (f32x4*)((char*)xo + 4u * ERN_EOFF(g, bj, 1)));
;                   sq1 += (xv.x * xv.x + xv.y * xv.y) + (xv.z * xv.z + xv.w * xv.w);
;                   const f32x4 hv = xv * gsn[bj]; hw[bj][1].x = cvt_pk_bf16(hv.x, hv.y); hw[bj][1].y = cvt_pk_bf16(hv.z, hv.w); }
;             }
;             if (!NOH && !PLAIN) {
; #pragma unroll
;                 for (int rh = 0; rh < 2; ++rh) { u32x2 rv; rv.x = __shfl_xor(hw[1][rh].x, 8); rv.y = __shfl_xor(hw[1][rh].y, 8);
;                     const unsigned e0 = ERN_EOFF(g, 0, rh);
;                     const unsigned ee = odd ? (e0 - DM + 32) : e0, eo2 = odd ? e0 : (e0 + DM + 32);
;                     *(u32x2*)((char*)ho + 2u * ee) = odd ? rv : hw[0][rh];
;                     *(u32x2*)((char*)ho + 2u * eo2) = odd ? hw[0][rh] : rv; }
;             }
;             if (!PLAIN) { sq0 += __shfl_xor(sq0, 1); sq0 += __shfl_xor(sq0, 2); sq0 += __shfl_xor(sq0, 4);
;             sq1 += __shfl_xor(sq1, 1); sq1 += __shfl_xor(sq1, 2); sq1 += __shfl_xor(sq1, 4); }
;             if (!PLAIN && pc == 0) { sst[g * 16 + rr] = sq0; sst[g * 16 + 8 + rr] = sq1; }
.LBB0_1959:
	s_or_b64 exec, exec, s[22:23]
	v_lshl_add_u64 v[116:117], s[20:21], 0, v[154:155]
	v_add_u32_e32 v82, 0x100000, v205
	s_waitcnt lgkmcnt(1)
	v_add_u32_e32 v83, 0x110000, v205
	v_add_u32_e32 v154, 0x100080, v205
	global_load_dwordx4 v[94:97], v82, s[20:21]
	global_load_dwordx4 v[90:93], v83, s[20:21]
	v_add_u32_e32 v114, 0x110080, v205
	global_load_dwordx4 v[86:89], v154, s[20:21]
	s_waitcnt lgkmcnt(0)
	global_load_dwordx4 v[82:85], v114, s[20:21]
	ds_write_b128 v200, v[78:81]
	ds_write_b128 v200, v[74:77] offset:64
	ds_read_b128 v[74:77], v201
	ds_read_b128 v[78:81], v201 offset:1152
	v_mov_b32_e32 v131, v155
	v_mov_b32_e32 v133, v155
	s_waitcnt vmcnt(11) lgkmcnt(1)
	v_pk_fma_f32 v[76:77], v[176:177], v[76:77], v[112:113]
	v_add_u32_e32 v112, 0x18000, v202
	v_pk_fma_f32 v[74:75], v[180:181], v[74:75], v[110:111]
	v_lshlrev_b32_e32 v110, 2, v112
	s_waitcnt lgkmcnt(0)
	v_pk_fma_f32 v[78:79], v[180:181], v[78:79], v[106:107]
	global_store_dwordx4 v110, v[74:77], s[20:21]
	v_pk_mul_f32 v[110:111], v[178:179], v[74:75]
	v_pk_fma_f32 v[80:81], v[176:177], v[80:81], v[108:109]
	v_pk_mul_f32 v[106:107], v[178:179], v[78:79]
	v_pk_mul_f32 v[118:119], v[174:175], v[76:77]
	v_cvt_pk_bf16_f32 v110, v110, v111
	v_pk_mul_f32 v[108:109], v[174:175], v[80:81]
	v_cvt_pk_bf16_f32 v111, v118, v119
	global_store_dwordx4 v[116:117], v[78:81], off
	v_cvt_pk_bf16_f32 v106, v106, v107
	v_cvt_pk_bf16_f32 v107, v108, v109
	ds_write_b128 v200, v[70:73]
	ds_write_b128 v200, v[66:69] offset:64
	ds_read_b128 v[66:69], v201
	ds_read_b128 v[70:73], v201 offset:1152
	v_lshl_add_u64 v[108:109], s[20:21], 0, v[130:131]
	v_lshl_add_u64 v[116:117], s[20:21], 0, v[132:133]
	s_waitcnt lgkmcnt(1)
	v_pk_fma_f32 v[66:67], v[168:169], v[66:67], v[102:103]
	v_pk_fma_f32 v[68:69], v[166:167], v[68:69], v[104:105]
	v_pk_mul_f32 v[104:105], v[172:173], v[66:67]
	global_store_dwordx4 v[108:109], v[66:69], off
	v_pk_mul_f32 v[102:103], v[170:171], v[68:69]
	v_cvt_pk_bf16_f32 v104, v104, v105
	s_waitcnt vmcnt(13) lgkmcnt(0)
	v_pk_fma_f32 v[70:71], v[168:169], v[70:71], v[98:99]
	v_cvt_pk_bf16_f32 v105, v102, v103
	ds_bpermute_b32 v98, v203, v104
	ds_bpermute_b32 v99, v203, v105
	v_pk_fma_f32 v[72:73], v[166:167], v[72:73], v[100:101]
	v_pk_mul_f32 v[100:101], v[172:173], v[70:71]
	v_pk_mul_f32 v[102:103], v[170:171], v[72:73]
	global_store_dwordx4 v[116:117], v[70:73], off
	v_cvt_pk_bf16_f32 v100, v100, v101
	v_cvt_pk_bf16_f32 v101, v102, v103
	v_lshlrev_b32_e32 v102, 1, v112
	s_waitcnt lgkmcnt(0)
	v_add_u32_e32 v250, 0xfffff040, v102
	v_cndmask_b32_e64 v250, v102, v250, s[40:41]
	v_cndmask_b32_e64 v248, v110, v98, s[40:41]
	v_cndmask_b32_e64 v249, v111, v99, s[40:41]
	global_store_dwordx2 v250, v[248:249], s[18:19]
	v_cndmask_b32_e64 v246, v98, v110, s[40:41]
	v_cndmask_b32_e64 v247, v99, v111, s[40:41]
	s_waitcnt lgkmcnt(1)
	v_add_u32_e32 v98, 0x1040, v102
	v_cndmask_b32_e64 v98, v102, v98, s[38:39]
	global_store_dwordx2 v98, v[246:247], s[18:19]
	ds_bpermute_b32 v98, v203, v100
	s_waitcnt lgkmcnt(1)
	ds_bpermute_b32 v99, v203, v101
	v_add_u32_e32 v101, 0x1c000, v202
	v_lshlrev_b32_e32 v100, 1, v101
	s_waitcnt lgkmcnt(0)
	v_add_u32_e32 v250, 0xfffff040, v100
	v_cndmask_b32_e64 v250, v100, v250, s[40:41]
	v_cndmask_b32_e64 v248, v106, v98, s[40:41]
	v_cndmask_b32_e64 v249, v107, v99, s[40:41]
	global_store_dwordx2 v250, v[248:249], s[18:19]
	v_cndmask_b32_e64 v246, v98, v106, s[40:41]
	v_cndmask_b32_e64 v247, v99, v107, s[40:41]
	v_mul_f32_e32 v67, v67, v67
	v_fmac_f32_e32 v67, v66, v66
	v_mul_f32_e32 v66, v69, v69
	v_mul_f32_e32 v77, v77, v77
	v_fmac_f32_e32 v66, v68, v68
	v_mul_f32_e32 v75, v75, v75
	v_fmac_f32_e32 v77, v76, v76
	v_mul_f32_e32 v76, v79, v79
	v_mul_f32_e32 v79, v81, v81
	v_add_f32_e32 v66, v67, v66
	v_mul_f32_e32 v67, v71, v71
	v_mul_f32_e32 v68, v73, v73
	v_fmac_f32_e32 v79, v80, v80
	v_fmac_f32_e32 v67, v70, v70
	v_fmac_f32_e32 v68, v72, v72
	v_fmac_f32_e32 v75, v74, v74
	v_fmac_f32_e32 v76, v78, v78
	v_add_f32_e32 v67, v67, v68
	v_add_f32_e32 v68, v75, v77
	v_add_f32_e32 v69, v76, v79
	v_add_f32_e32 v66, v68, v66
	v_add_f32_e32 v67, v69, v67
	ds_bpermute_b32 v68, v190, v66
	ds_bpermute_b32 v69, v190, v67
	s_waitcnt lgkmcnt(1)
	v_add_f32_e32 v66, v66, v68
	s_waitcnt lgkmcnt(0)
	v_add_f32_e32 v69, v67, v69
	ds_bpermute_b32 v68, v191, v66
	ds_bpermute_b32 v70, v191, v69
	s_waitcnt lgkmcnt(1)
	v_add_f32_e32 v66, v66, v68
	s_waitcnt lgkmcnt(0)
	v_add_f32_e32 v68, v69, v70
	ds_bpermute_b32 v67, v204, v66
	ds_bpermute_b32 v69, v204, v68
	v_add_u32_e32 v70, 0x1040, v100
	v_cndmask_b32_e64 v70, v100, v70, s[38:39]
	global_store_dwordx2 v70, v[246:247], s[18:19]
	s_and_saveexec_b64 s[22:23], s[42:43]
	s_cbranch_execz .LBB0_1969
	s_waitcnt lgkmcnt(1)
	v_add_f32_e32 v66, v66, v67
	s_waitcnt lgkmcnt(0)
	v_add_f32_e32 v67, v68, v69
	ds_write2_b32 v194, v66, v67 offset0:48 offset1:56
; #define LAS __attribute__((address_space(3)))
; #define ERN_EOFF(q, m) (eb + (unsigned)((((q) & 1) * HALF + (m) * 16) * DM + ERN_COL((q) >> 1)))
;     __device__ __forceinline__ void operator()(const f32x4 (&acc)[2][2][4][2], const Unit& u, int wr, int wc, int fr, int fq) const {
;     ...
;         for (int g = 0; g < 8; ++g) { const int ai = g >> 2, m = g & 3;
;             if (g + 1 < 8) ERN_LOADX(g + 1);
;             float sq0 = 0.f, sq1 = 0.f; u32x2 hw[2][2];
; #pragma unroll
;             for (int bj = 0; bj < 2; ++bj) {
;                 *(LAS f32x4*)(st + wr_off) = acc[ai][bj][m][0]; *(LAS f32x4*)(st + wr_off + 64) = acc[ai][bj][m][1];
;                 const f32x4 a0 = *(const LAS f32x4*)(st + rd_off), a1 = *(const LAS f32x4*)(st + rd_off + 8 * 144);
;                 { const f32x4 xv = xb[g & 1][bj][0] + gv[bj] * a0; __builtin_nontemporal_store(xv, (f32x4*)((char*)xo + 4u * ERN_EOFF(g, bj, 0)));
;                   sq0 += (xv.x * xv.x + xv.y * xv.y) + (xv.z * xv.z + xv.w * xv.w);
;                   const f32x4 hv = xv * gsn[bj]; hw[bj][0].x = cvt_pk_bf16(hv.x, hv.y); hw[bj][0].y = cvt_pk_bf16(hv.z, hv.w); }
;                 { const f32x4 xv = xb[g & 1][bj][1] + gv[bj] * a1; __builtin_nontemporal_store(xv, (f32x4*)((char*)xo + 4u * ERN_EOFF(g, bj, 1)));
;                   sq1 += (xv.x * xv.x + xv.y * xv.y) + (xv.z * xv.z + xv.w * xv.w);
;                   const f32x4 hv = xv * gsn[bj]; hw[bj][1].x = cvt_pk_bf16(hv.x, hv.y); hw[bj][1].y = cvt_pk_bf16(hv.z, hv.w); }
;             }
;             if (!NOH && !PLAIN) {
; #pragma unroll
;                 for (int rh = 0; rh < 2; ++rh) { u32x2 rv; rv.x = __shfl_xor(hw[1][rh].x, 8); rv.y = __shfl_xor(hw[1][rh].y, 8);
;                     const unsigned e0 = ERN_EOFF(g, 0, rh);
;                     const unsigned ee = odd ? (e0 - DM + 32) : e0, eo2 = odd ? e0 : (e0 + DM + 32);
;                     *(u32x2*)((char*)ho + 2u * ee) = odd ? rv : hw[0][rh];
;                     *(u32x2*)((char*)ho + 2u * eo2) = odd ? hw[0][rh] : rv; }
;             }
;             if (!PLAIN) { sq0 += __shfl_xor(sq0, 1); sq0 += __shfl_xor(sq0, 2); sq0 += __shfl_xor(sq0, 4);
;             sq1 += __shfl_xor(sq1, 1); sq1 += __shfl_xor(sq1, 2); sq1 += __shfl_xor(sq1, 4); }
;             if (!PLAIN && pc == 0) { sst[g * 16 + rr] = sq0; sst[g * 16 + 8 + rr] = sq1; }
.LBB0_1969:
	s_or_b64 exec, exec, s[22:23]
	v_lshl_add_u64 v[104:105], s[20:21], 0, v[154:155]
	v_add_u32_e32 v154, 0x120000, v205
	v_add_u32_e32 v100, 0x120080, v205
	v_add_u32_e32 v102, 0x130000, v205
	global_load_dwordx4 v[78:81], v154, s[20:21]
	global_load_dwordx4 v[74:77], v102, s[20:21]
	v_add_u32_e32 v98, 0x130080, v205
	global_load_dwordx4 v[70:73], v100, s[20:21]
	s_waitcnt lgkmcnt(0)
	global_load_dwordx4 v[66:69], v98, s[20:21]
	ds_write_b128 v200, v[62:65]
	ds_write_b128 v200, v[58:61] offset:64
	ds_read_b128 v[58:61], v201
	ds_read_b128 v[62:65], v201 offset:1152
	v_mov_b32_e32 v115, v155
	s_waitcnt vmcnt(13) lgkmcnt(1)
	v_pk_fma_f32 v[60:61], v[176:177], v[60:61], v[96:97]
	v_add_u32_e32 v96, 0x40000, v202
	v_pk_fma_f32 v[58:59], v[180:181], v[58:59], v[94:95]
	v_lshlrev_b32_e32 v94, 2, v96
	s_waitcnt vmcnt(12) lgkmcnt(0)
	v_pk_fma_f32 v[64:65], v[176:177], v[64:65], v[92:93]
	v_add_u32_e32 v92, 0x44000, v202
	global_store_dwordx4 v94, v[58:61], s[20:21]
	v_pk_mul_f32 v[94:95], v[178:179], v[58:59]
	v_pk_fma_f32 v[62:63], v[180:181], v[62:63], v[90:91]
	v_lshlrev_b32_e32 v90, 2, v92
	v_pk_mul_f32 v[106:107], v[174:175], v[60:61]
	v_cvt_pk_bf16_f32 v94, v94, v95
	s_nop 0
	v_cvt_pk_bf16_f32 v95, v106, v107
	global_store_dwordx4 v90, v[62:65], s[20:21]
	v_pk_mul_f32 v[90:91], v[178:179], v[62:63]
	v_pk_mul_f32 v[106:107], v[174:175], v[64:65]
	v_cvt_pk_bf16_f32 v90, v90, v91
	s_nop 0
	v_cvt_pk_bf16_f32 v91, v106, v107
	ds_write_b128 v200, v[54:57]
	ds_write_b128 v200, v[50:53] offset:64
	ds_read_b128 v[50:53], v201
	ds_read_b128 v[54:57], v201 offset:1152
	v_lshl_add_u64 v[106:107], s[20:21], 0, v[114:115]
	s_waitcnt vmcnt(13) lgkmcnt(1)
	v_pk_fma_f32 v[50:51], v[168:169], v[50:51], v[86:87]
	v_pk_fma_f32 v[52:53], v[166:167], v[52:53], v[88:89]
	v_pk_mul_f32 v[88:89], v[172:173], v[50:51]
	global_store_dwordx4 v[104:105], v[50:53], off
	v_pk_mul_f32 v[86:87], v[170:171], v[52:53]
	v_cvt_pk_bf16_f32 v88, v88, v89
	s_waitcnt vmcnt(13) lgkmcnt(0)
	v_pk_fma_f32 v[54:55], v[168:169], v[54:55], v[82:83]
	v_cvt_pk_bf16_f32 v89, v86, v87
	ds_bpermute_b32 v82, v203, v88
	ds_bpermute_b32 v83, v203, v89
	v_pk_fma_f32 v[56:57], v[166:167], v[56:57], v[84:85]
	v_pk_mul_f32 v[84:85], v[172:173], v[54:55]
	v_pk_mul_f32 v[86:87], v[170:171], v[56:57]
	global_store_dwordx4 v[106:107], v[54:57], off
	v_cvt_pk_bf16_f32 v84, v84, v85
	v_cvt_pk_bf16_f32 v85, v86, v87
	v_lshlrev_b32_e32 v86, 1, v96
	s_waitcnt lgkmcnt(0)
	v_add_u32_e32 v250, 0xfffff040, v86
	v_cndmask_b32_e64 v250, v86, v250, s[40:41]
	v_cndmask_b32_e64 v248, v94, v82, s[40:41]
	v_cndmask_b32_e64 v249, v95, v83, s[40:41]
	global_store_dwordx2 v250, v[248:249], s[18:19]
	v_cndmask_b32_e64 v246, v82, v94, s[40:41]
	v_cndmask_b32_e64 v247, v83, v95, s[40:41]
	s_waitcnt lgkmcnt(1)
	v_add_u32_e32 v82, 0x1040, v86
	v_cndmask_b32_e64 v82, v86, v82, s[38:39]
	global_store_dwordx2 v82, v[246:247], s[18:19]
	ds_bpermute_b32 v82, v203, v84
	s_waitcnt lgkmcnt(1)
	ds_bpermute_b32 v83, v203, v85
	v_lshlrev_b32_e32 v84, 1, v92
	s_waitcnt lgkmcnt(0)
	v_add_u32_e32 v250, 0xfffff040, v84
	v_cndmask_b32_e64 v250, v84, v250, s[40:41]
	v_cndmask_b32_e64 v248, v90, v82, s[40:41]
	v_cndmask_b32_e64 v249, v91, v83, s[40:41]
	global_store_dwordx2 v250, v[248:249], s[18:19]
	v_cndmask_b32_e64 v246, v82, v90, s[40:41]
	v_cndmask_b32_e64 v247, v83, v91, s[40:41]
	v_mul_f32_e32 v51, v51, v51
	v_fmac_f32_e32 v51, v50, v50
	v_mul_f32_e32 v50, v53, v53
	v_mul_f32_e32 v61, v61, v61
	v_fmac_f32_e32 v50, v52, v52
	v_mul_f32_e32 v59, v59, v59
	v_fmac_f32_e32 v61, v60, v60
	v_mul_f32_e32 v60, v63, v63
	v_mul_f32_e32 v63, v65, v65
	v_add_f32_e32 v50, v51, v50
	v_mul_f32_e32 v51, v55, v55
	v_mul_f32_e32 v52, v57, v57
	v_fmac_f32_e32 v63, v64, v64
	v_fmac_f32_e32 v51, v54, v54
	v_fmac_f32_e32 v52, v56, v56
	v_fmac_f32_e32 v59, v58, v58
	v_fmac_f32_e32 v60, v62, v62
	v_add_f32_e32 v51, v51, v52
	v_add_f32_e32 v52, v59, v61
	v_add_f32_e32 v53, v60, v63
	v_add_f32_e32 v50, v52, v50
	v_add_f32_e32 v51, v53, v51
	ds_bpermute_b32 v52, v190, v50
	ds_bpermute_b32 v53, v190, v51
	s_waitcnt lgkmcnt(1)
	v_add_f32_e32 v50, v50, v52
	s_waitcnt lgkmcnt(0)
	v_add_f32_e32 v53, v51, v53
	ds_bpermute_b32 v52, v191, v50
	ds_bpermute_b32 v54, v191, v53
	s_waitcnt lgkmcnt(1)
	v_add_f32_e32 v50, v50, v52
	s_waitcnt lgkmcnt(0)
	v_add_f32_e32 v52, v53, v54
	ds_bpermute_b32 v51, v204, v50
	ds_bpermute_b32 v53, v204, v52
	v_add_u32_e32 v54, 0x1040, v84
	v_cndmask_b32_e64 v54, v84, v54, s[38:39]
	global_store_dwordx2 v54, v[246:247], s[18:19]
	s_and_saveexec_b64 s[22:23], s[42:43]
	s_cbranch_execz .LBB0_1979
	s_waitcnt lgkmcnt(1)
	v_add_f32_e32 v50, v50, v51
	s_waitcnt lgkmcnt(0)
	v_add_f32_e32 v51, v52, v53
	ds_write2_b32 v194, v50, v51 offset0:64 offset1:72
; #define LAS __attribute__((address_space(3)))
; #define ERN_EOFF(q, m) (eb + (unsigned)((((q) & 1) * HALF + (m) * 16) * DM + ERN_COL((q) >> 1)))
;     __device__ __forceinline__ void operator()(const f32x4 (&acc)[2][2][4][2], const Unit& u, int wr, int wc, int fr, int fq) const {
;     ...
;         for (int g = 0; g < 8; ++g) { const int ai = g >> 2, m = g & 3;
;             if (g + 1 < 8) ERN_LOADX(g + 1);
;             float sq0 = 0.f, sq1 = 0.f; u32x2 hw[2][2];
; #pragma unroll
;             for (int bj = 0; bj < 2; ++bj) {
;                 *(LAS f32x4*)(st + wr_off) = acc[ai][bj][m][0]; *(LAS f32x4*)(st + wr_off + 64) = acc[ai][bj][m][1];
;                 const f32x4 a0 = *(const LAS f32x4*)(st + rd_off), a1 = *(const LAS f32x4*)(st + rd_off + 8 * 144);
;                 { const f32x4 xv = xb[g & 1][bj][0] + gv[bj] * a0; __builtin_nontemporal_store(xv, (f32x4*)((char*)xo + 4u * ERN_EOFF(g, bj, 0)));
;                   sq0 += (xv.x * xv.x + xv.y * xv.y) + (xv.z * xv.z + xv.w * xv.w);
;                   const f32x4 hv = xv * gsn[bj]; hw[bj][0].x = cvt_pk_bf16(hv.x, hv.y); hw[bj][0].y = cvt_pk_bf16(hv.z, hv.w); }
;                 { const f32x4 xv = xb[g & 1][bj][1] + gv[bj] * a1; __builtin_nontemporal_store(xv, (f32x4*)((char*)xo + 4u * ERN_EOFF(g, bj, 1)));
;                   sq1 += (xv.x * xv.x + xv.y * xv.y) + (xv.z * xv.z + xv.w * xv.w);
;                   const f32x4 hv = xv * gsn[bj]; hw[bj][1].x = cvt_pk_bf16(hv.x, hv.y); hw[bj][1].y = cvt_pk_bf16(hv.z, hv.w); }
;             }
;             if (!NOH && !PLAIN) {
; #pragma unroll
;                 for (int rh = 0; rh < 2; ++rh) { u32x2 rv; rv.x = __shfl_xor(hw[1][rh].x, 8); rv.y = __shfl_xor(hw[1][rh].y, 8);
;                     const unsigned e0 = ERN_EOFF(g, 0, rh);
;                     const unsigned ee = odd ? (e0 - DM + 32) : e0, eo2 = odd ? e0 : (e0 + DM + 32);
;                     *(u32x2*)((char*)ho + 2u * ee) = odd ? rv : hw[0][rh];
;                     *(u32x2*)((char*)ho + 2u * eo2) = odd ? hw[0][rh] : rv; }
;             }
;             if (!PLAIN) { sq0 += __shfl_xor(sq0, 1); sq0 += __shfl_xor(sq0, 2); sq0 += __shfl_xor(sq0, 4);
;             sq1 += __shfl_xor(sq1, 1); sq1 += __shfl_xor(sq1, 2); sq1 += __shfl_xor(sq1, 4); }
;             if (!PLAIN && pc == 0) { sst[g * 16 + rr] = sq0; sst[g * 16 + 8 + rr] = sq1; }
.LBB0_1979:
	s_or_b64 exec, exec, s[22:23]
	v_lshl_add_u64 v[88:89], s[20:21], 0, v[154:155]
	v_add_u32_e32 v154, 0x140000, v205
	v_add_u32_e32 v84, 0x140080, v205
	v_add_u32_e32 v86, 0x150000, v205
	global_load_dwordx4 v[62:65], v154, s[20:21]
	global_load_dwordx4 v[58:61], v86, s[20:21]
	v_add_u32_e32 v82, 0x150080, v205
	global_load_dwordx4 v[54:57], v84, s[20:21]
	s_waitcnt lgkmcnt(0)
	global_load_dwordx4 v[50:53], v82, s[20:21]
	ds_write_b128 v200, v[46:49]
	ds_write_b128 v200, v[42:45] offset:64
	ds_read_b128 v[42:45], v201
	ds_read_b128 v[46:49], v201 offset:1152
	v_mov_b32_e32 v103, v155
	v_lshl_add_u64 v[90:91], s[20:21], 0, v[102:103]
	v_mov_b32_e32 v101, v155
	s_waitcnt vmcnt(13) lgkmcnt(1)
	v_pk_fma_f32 v[42:43], v[180:181], v[42:43], v[78:79]
	s_waitcnt vmcnt(12) lgkmcnt(0)
	v_pk_fma_f32 v[46:47], v[180:181], v[46:47], v[74:75]
	v_pk_fma_f32 v[44:45], v[176:177], v[44:45], v[80:81]
	v_pk_mul_f32 v[78:79], v[178:179], v[42:43]
	v_pk_fma_f32 v[48:49], v[176:177], v[48:49], v[76:77]
	v_pk_mul_f32 v[74:75], v[178:179], v[46:47]
	global_store_dwordx4 v[88:89], v[42:45], off
	v_pk_mul_f32 v[80:81], v[174:175], v[44:45]
	v_cvt_pk_bf16_f32 v78, v78, v79
	v_pk_mul_f32 v[76:77], v[174:175], v[48:49]
	v_cvt_pk_bf16_f32 v79, v80, v81
	global_store_dwordx4 v[90:91], v[46:49], off
	v_cvt_pk_bf16_f32 v74, v74, v75
	v_cvt_pk_bf16_f32 v75, v76, v77
	ds_write_b128 v200, v[38:41]
	ds_write_b128 v200, v[34:37] offset:64
	ds_read_b128 v[34:37], v201
	ds_read_b128 v[38:41], v201 offset:1152
	v_lshl_add_u64 v[76:77], s[20:21], 0, v[100:101]
	v_mov_b32_e32 v99, v155
	v_lshl_add_u64 v[80:81], s[20:21], 0, v[98:99]
	s_waitcnt vmcnt(13) lgkmcnt(1)
	v_pk_fma_f32 v[34:35], v[168:169], v[34:35], v[70:71]
	v_pk_fma_f32 v[36:37], v[166:167], v[36:37], v[72:73]
	v_pk_mul_f32 v[72:73], v[172:173], v[34:35]
	global_store_dwordx4 v[76:77], v[34:37], off
	v_pk_mul_f32 v[70:71], v[170:171], v[36:37]
	v_cvt_pk_bf16_f32 v72, v72, v73
	s_waitcnt vmcnt(13) lgkmcnt(0)
	v_pk_fma_f32 v[38:39], v[168:169], v[38:39], v[66:67]
	v_cvt_pk_bf16_f32 v73, v70, v71
	ds_bpermute_b32 v66, v203, v72
	ds_bpermute_b32 v67, v203, v73
	v_pk_fma_f32 v[40:41], v[166:167], v[40:41], v[68:69]
	v_pk_mul_f32 v[68:69], v[172:173], v[38:39]
	v_pk_mul_f32 v[70:71], v[170:171], v[40:41]
	global_store_dwordx4 v[80:81], v[38:41], off
	v_cvt_pk_bf16_f32 v68, v68, v69
	v_cvt_pk_bf16_f32 v69, v70, v71
	v_add_u32_e32 v71, 0x48000, v202
	v_lshlrev_b32_e32 v70, 1, v71
	s_waitcnt lgkmcnt(0)
	v_add_u32_e32 v250, 0xfffff040, v70
	v_cndmask_b32_e64 v250, v70, v250, s[40:41]
	v_cndmask_b32_e64 v248, v78, v66, s[40:41]
	v_cndmask_b32_e64 v249, v79, v67, s[40:41]
	global_store_dwordx2 v250, v[248:249], s[18:19]
	v_cndmask_b32_e64 v246, v66, v78, s[40:41]
	v_cndmask_b32_e64 v247, v67, v79, s[40:41]
	s_waitcnt lgkmcnt(1)
	v_add_u32_e32 v66, 0x1040, v70
	v_cndmask_b32_e64 v66, v70, v66, s[38:39]
	global_store_dwordx2 v66, v[246:247], s[18:19]
	ds_bpermute_b32 v66, v203, v68
	s_waitcnt lgkmcnt(1)
	ds_bpermute_b32 v67, v203, v69
	v_add_u32_e32 v69, 0x4c000, v202
	v_lshlrev_b32_e32 v68, 1, v69
	s_waitcnt lgkmcnt(0)
	v_add_u32_e32 v250, 0xfffff040, v68
	v_cndmask_b32_e64 v250, v68, v250, s[40:41]
	v_cndmask_b32_e64 v248, v74, v66, s[40:41]
	v_cndmask_b32_e64 v249, v75, v67, s[40:41]
	global_store_dwordx2 v250, v[248:249], s[18:19]
	v_cndmask_b32_e64 v246, v66, v74, s[40:41]
	v_cndmask_b32_e64 v247, v67, v75, s[40:41]
	v_mul_f32_e32 v35, v35, v35
	v_fmac_f32_e32 v35, v34, v34
	v_mul_f32_e32 v34, v37, v37
	v_mul_f32_e32 v45, v45, v45
	v_fmac_f32_e32 v34, v36, v36
	v_mul_f32_e32 v43, v43, v43
	v_fmac_f32_e32 v45, v44, v44
	v_mul_f32_e32 v44, v47, v47
	v_mul_f32_e32 v47, v49, v49
	v_add_f32_e32 v34, v35, v34
	v_mul_f32_e32 v35, v39, v39
	v_mul_f32_e32 v36, v41, v41
	v_fmac_f32_e32 v47, v48, v48
	v_fmac_f32_e32 v35, v38, v38
	v_fmac_f32_e32 v36, v40, v40
	v_fmac_f32_e32 v43, v42, v42
	v_fmac_f32_e32 v44, v46, v46
	v_add_f32_e32 v35, v35, v36
	v_add_f32_e32 v36, v43, v45
	v_add_f32_e32 v37, v44, v47
	v_add_f32_e32 v34, v36, v34
	v_add_f32_e32 v35, v37, v35
	ds_bpermute_b32 v36, v190, v34
	ds_bpermute_b32 v37, v190, v35
	s_waitcnt lgkmcnt(1)
	v_add_f32_e32 v34, v34, v36
	s_waitcnt lgkmcnt(0)
	v_add_f32_e32 v37, v35, v37
	ds_bpermute_b32 v36, v191, v34
	ds_bpermute_b32 v38, v191, v37
	s_waitcnt lgkmcnt(1)
	v_add_f32_e32 v34, v34, v36
	s_waitcnt lgkmcnt(0)
	v_add_f32_e32 v36, v37, v38
	ds_bpermute_b32 v35, v204, v34
	ds_bpermute_b32 v37, v204, v36
	v_add_u32_e32 v38, 0x1040, v68
	v_cndmask_b32_e64 v38, v68, v38, s[38:39]
	global_store_dwordx2 v38, v[246:247], s[18:19]
	s_and_saveexec_b64 s[22:23], s[42:43]
	s_cbranch_execz .LBB0_1989
	s_waitcnt lgkmcnt(1)
	v_add_f32_e32 v34, v34, v35
	s_waitcnt lgkmcnt(0)
	v_add_f32_e32 v35, v36, v37
	ds_write2_b32 v194, v34, v35 offset0:80 offset1:88
; #define LAS __attribute__((address_space(3)))
; #define ERN_EOFF(q, m) (eb + (unsigned)((((q) & 1) * HALF + (m) * 16) * DM + ERN_COL((q) >> 1)))
;     __device__ __forceinline__ void operator()(const f32x4 (&acc)[2][2][4][2], const Unit& u, int wr, int wc, int fr, int fq) const {
;     ...
;         for (int g = 0; g < 8; ++g) { const int ai = g >> 2, m = g & 3;
;             if (g + 1 < 8) ERN_LOADX(g + 1);
;             float sq0 = 0.f, sq1 = 0.f; u32x2 hw[2][2];
; #pragma unroll
;             for (int bj = 0; bj < 2; ++bj) {
;                 *(LAS f32x4*)(st + wr_off) = acc[ai][bj][m][0]; *(LAS f32x4*)(st + wr_off + 64) = acc[ai][bj][m][1];
;                 const f32x4 a0 = *(const LAS f32x4*)(st + rd_off), a1 = *(const LAS f32x4*)(st + rd_off + 8 * 144);
;                 { const f32x4 xv = xb[g & 1][bj][0] + gv[bj] * a0; __builtin_nontemporal_store(xv, (f32x4*)((char*)xo + 4u * ERN_EOFF(g, bj, 0)));
;                   sq0 += (xv.x * xv.x + xv.y * xv.y) + (xv.z * xv.z + xv.w * xv.w);
;                   const f32x4 hv = xv * gsn[bj]; hw[bj][0].x = cvt_pk_bf16(hv.x, hv.y); hw[bj][0].y = cvt_pk_bf16(hv.z, hv.w); }
;                 { const f32x4 xv = xb[g & 1][bj][1] + gv[bj] * a1; __builtin_nontemporal_store(xv, (f32x4*)((char*)xo + 4u * ERN_EOFF(g, bj, 1)));
;                   sq1 += (xv.x * xv.x + xv.y * xv.y) + (xv.z * xv.z + xv.w * xv.w);
;                   const f32x4 hv = xv * gsn[bj]; hw[bj][1].x = cvt_pk_bf16(hv.x, hv.y); hw[bj][1].y = cvt_pk_bf16(hv.z, hv.w); }
;             }
;             if (!NOH && !PLAIN) {
; #pragma unroll
;                 for (int rh = 0; rh < 2; ++rh) { u32x2 rv; rv.x = __shfl_xor(hw[1][rh].x, 8); rv.y = __shfl_xor(hw[1][rh].y, 8);
;                     const unsigned e0 = ERN_EOFF(g, 0, rh);
;                     const unsigned ee = odd ? (e0 - DM + 32) : e0, eo2 = odd ? e0 : (e0 + DM + 32);
;                     *(u32x2*)((char*)ho + 2u * ee) = odd ? rv : hw[0][rh];
;                     *(u32x2*)((char*)ho + 2u * eo2) = odd ? hw[0][rh] : rv; }
;             }
;             if (!PLAIN) { sq0 += __shfl_xor(sq0, 1); sq0 += __shfl_xor(sq0, 2); sq0 += __shfl_xor(sq0, 4);
;             sq1 += __shfl_xor(sq1, 1); sq1 += __shfl_xor(sq1, 2); sq1 += __shfl_xor(sq1, 4); }
;             if (!PLAIN && pc == 0) { sst[g * 16 + rr] = sq0; sst[g * 16 + 8 + rr] = sq1; }
.LBB0_1989:
	s_or_b64 exec, exec, s[22:23]
	v_lshl_add_u64 v[72:73], s[20:21], 0, v[154:155]
	v_add_u32_e32 v154, 0x160000, v205
	v_add_u32_e32 v68, 0x160080, v205
	v_add_u32_e32 v70, 0x170000, v205
	global_load_dwordx4 v[46:49], v154, s[20:21]
	global_load_dwordx4 v[42:45], v70, s[20:21]
	v_add_u32_e32 v66, 0x170080, v205
	global_load_dwordx4 v[38:41], v68, s[20:21]
	s_waitcnt lgkmcnt(0)
	global_load_dwordx4 v[34:37], v66, s[20:21]
	ds_write_b128 v200, v[30:33]
	ds_write_b128 v200, v[26:29] offset:64
	ds_read_b128 v[26:29], v201
	ds_read_b128 v[30:33], v201 offset:1152
	v_mov_b32_e32 v87, v155
	v_lshl_add_u64 v[74:75], s[20:21], 0, v[86:87]
	v_mov_b32_e32 v85, v155
	s_waitcnt vmcnt(13) lgkmcnt(1)
	v_pk_fma_f32 v[26:27], v[180:181], v[26:27], v[62:63]
	s_waitcnt vmcnt(12) lgkmcnt(0)
	v_pk_fma_f32 v[30:31], v[180:181], v[30:31], v[58:59]
	v_pk_fma_f32 v[28:29], v[176:177], v[28:29], v[64:65]
	v_pk_mul_f32 v[62:63], v[178:179], v[26:27]
	v_pk_fma_f32 v[32:33], v[176:177], v[32:33], v[60:61]
	v_pk_mul_f32 v[58:59], v[178:179], v[30:31]
	global_store_dwordx4 v[72:73], v[26:29], off
	v_pk_mul_f32 v[64:65], v[174:175], v[28:29]
	v_cvt_pk_bf16_f32 v62, v62, v63
	v_pk_mul_f32 v[60:61], v[174:175], v[32:33]
	v_cvt_pk_bf16_f32 v63, v64, v65
	global_store_dwordx4 v[74:75], v[30:33], off
	v_cvt_pk_bf16_f32 v58, v58, v59
	v_cvt_pk_bf16_f32 v59, v60, v61
	ds_write_b128 v200, v[22:25]
	ds_write_b128 v200, v[18:21] offset:64
	ds_read_b128 v[18:21], v201
	ds_read_b128 v[22:25], v201 offset:1152
	v_lshl_add_u64 v[60:61], s[20:21], 0, v[84:85]
	v_mov_b32_e32 v83, v155
	v_lshl_add_u64 v[64:65], s[20:21], 0, v[82:83]
	s_waitcnt vmcnt(13) lgkmcnt(1)
	v_pk_fma_f32 v[18:19], v[168:169], v[18:19], v[54:55]
	v_pk_fma_f32 v[20:21], v[166:167], v[20:21], v[56:57]
	v_pk_mul_f32 v[56:57], v[172:173], v[18:19]
	global_store_dwordx4 v[60:61], v[18:21], off
	v_pk_mul_f32 v[54:55], v[170:171], v[20:21]
	v_cvt_pk_bf16_f32 v56, v56, v57
	s_waitcnt vmcnt(13) lgkmcnt(0)
	v_pk_fma_f32 v[22:23], v[168:169], v[22:23], v[50:51]
	v_cvt_pk_bf16_f32 v57, v54, v55
	ds_bpermute_b32 v50, v203, v56
	ds_bpermute_b32 v51, v203, v57
	v_pk_fma_f32 v[24:25], v[166:167], v[24:25], v[52:53]
	v_pk_mul_f32 v[52:53], v[172:173], v[22:23]
	v_pk_mul_f32 v[54:55], v[170:171], v[24:25]
	global_store_dwordx4 v[64:65], v[22:25], off
	v_cvt_pk_bf16_f32 v52, v52, v53
	v_cvt_pk_bf16_f32 v53, v54, v55
	v_add_u32_e32 v55, 0x50000, v202
	v_lshlrev_b32_e32 v54, 1, v55
	s_waitcnt lgkmcnt(0)
	v_add_u32_e32 v250, 0xfffff040, v54
	v_cndmask_b32_e64 v250, v54, v250, s[40:41]
	v_cndmask_b32_e64 v248, v62, v50, s[40:41]
	v_cndmask_b32_e64 v249, v63, v51, s[40:41]
	global_store_dwordx2 v250, v[248:249], s[18:19]
	v_cndmask_b32_e64 v246, v50, v62, s[40:41]
	v_cndmask_b32_e64 v247, v51, v63, s[40:41]
	s_waitcnt lgkmcnt(1)
	v_add_u32_e32 v50, 0x1040, v54
	v_cndmask_b32_e64 v50, v54, v50, s[38:39]
	global_store_dwordx2 v50, v[246:247], s[18:19]
	ds_bpermute_b32 v50, v203, v52
	s_waitcnt lgkmcnt(1)
	ds_bpermute_b32 v51, v203, v53
	v_add_u32_e32 v53, 0x54000, v202
	v_lshlrev_b32_e32 v52, 1, v53
	s_waitcnt lgkmcnt(0)
	v_add_u32_e32 v250, 0xfffff040, v52
	v_cndmask_b32_e64 v250, v52, v250, s[40:41]
	v_cndmask_b32_e64 v248, v58, v50, s[40:41]
	v_cndmask_b32_e64 v249, v59, v51, s[40:41]
	global_store_dwordx2 v250, v[248:249], s[18:19]
	v_cndmask_b32_e64 v246, v50, v58, s[40:41]
	v_cndmask_b32_e64 v247, v51, v59, s[40:41]
	v_mul_f32_e32 v19, v19, v19
	v_fmac_f32_e32 v19, v18, v18
	v_mul_f32_e32 v18, v21, v21
	v_mul_f32_e32 v29, v29, v29
	v_fmac_f32_e32 v18, v20, v20
	v_mul_f32_e32 v27, v27, v27
	v_fmac_f32_e32 v29, v28, v28
	v_mul_f32_e32 v28, v31, v31
	v_mul_f32_e32 v31, v33, v33
	v_add_f32_e32 v18, v19, v18
	v_mul_f32_e32 v19, v23, v23
	v_mul_f32_e32 v20, v25, v25
	v_fmac_f32_e32 v31, v32, v32
	v_fmac_f32_e32 v19, v22, v22
	v_fmac_f32_e32 v20, v24, v24
	v_fmac_f32_e32 v27, v26, v26
	v_fmac_f32_e32 v28, v30, v30
	v_add_f32_e32 v19, v19, v20
	v_add_f32_e32 v20, v27, v29
	v_add_f32_e32 v21, v28, v31
	v_add_f32_e32 v18, v20, v18
	v_add_f32_e32 v19, v21, v19
	ds_bpermute_b32 v20, v190, v18
	ds_bpermute_b32 v21, v190, v19
	s_waitcnt lgkmcnt(1)
	v_add_f32_e32 v18, v18, v20
	s_waitcnt lgkmcnt(0)
	v_add_f32_e32 v21, v19, v21
	ds_bpermute_b32 v20, v191, v18
	ds_bpermute_b32 v22, v191, v21
	s_waitcnt lgkmcnt(1)
	v_add_f32_e32 v18, v18, v20
	s_waitcnt lgkmcnt(0)
	v_add_f32_e32 v20, v21, v22
	ds_bpermute_b32 v19, v204, v18
	ds_bpermute_b32 v21, v204, v20
	v_add_u32_e32 v22, 0x1040, v52
	v_cndmask_b32_e64 v22, v52, v22, s[38:39]
	global_store_dwordx2 v22, v[246:247], s[18:19]
	s_and_saveexec_b64 s[22:23], s[42:43]
	s_cbranch_execz .LBB0_1999
	s_waitcnt lgkmcnt(1)
	v_add_f32_e32 v18, v18, v19
	s_waitcnt lgkmcnt(0)
	v_add_f32_e32 v19, v20, v21
	ds_write2_b32 v194, v18, v19 offset0:96 offset1:104
; #define LAS __attribute__((address_space(3)))
; #define ERN_EOFF(q, m) (eb + (unsigned)((((q) & 1) * HALF + (m) * 16) * DM + ERN_COL((q) >> 1)))
;     __device__ __forceinline__ void operator()(const f32x4 (&acc)[2][2][4][2], const Unit& u, int wr, int wc, int fr, int fq) const {
;     ...
;         for (int g = 0; g < 8; ++g) { const int ai = g >> 2, m = g & 3;
;             if (g + 1 < 8) ERN_LOADX(g + 1);
;             float sq0 = 0.f, sq1 = 0.f; u32x2 hw[2][2];
; #pragma unroll
;             for (int bj = 0; bj < 2; ++bj) {
;                 *(LAS f32x4*)(st + wr_off) = acc[ai][bj][m][0]; *(LAS f32x4*)(st + wr_off + 64) = acc[ai][bj][m][1];
;                 const f32x4 a0 = *(const LAS f32x4*)(st + rd_off), a1 = *(const LAS f32x4*)(st + rd_off + 8 * 144);
;                 { const f32x4 xv = xb[g & 1][bj][0] + gv[bj] * a0; __builtin_nontemporal_store(xv, (f32x4*)((char*)xo + 4u * ERN_EOFF(g, bj, 0)));
;                   sq0 += (xv.x * xv.x + xv.y * xv.y) + (xv.z * xv.z + xv.w * xv.w);
;                   const f32x4 hv = xv * gsn[bj]; hw[bj][0].x = cvt_pk_bf16(hv.x, hv.y); hw[bj][0].y = cvt_pk_bf16(hv.z, hv.w); }
;                 { const f32x4 xv = xb[g & 1][bj][1] + gv[bj] * a1; __builtin_nontemporal_store(xv, (f32x4*)((char*)xo + 4u * ERN_EOFF(g, bj, 1)));
;                   sq1 += (xv.x * xv.x + xv.y * xv.y) + (xv.z * xv.z + xv.w * xv.w);
;                   const f32x4 hv = xv * gsn[bj]; hw[bj][1].x = cvt_pk_bf16(hv.x, hv.y); hw[bj][1].y = cvt_pk_bf16(hv.z, hv.w); }
;             }
;             if (!NOH && !PLAIN) {
; #pragma unroll
;                 for (int rh = 0; rh < 2; ++rh) { u32x2 rv; rv.x = __shfl_xor(hw[1][rh].x, 8); rv.y = __shfl_xor(hw[1][rh].y, 8);
;                     const unsigned e0 = ERN_EOFF(g, 0, rh);
;                     const unsigned ee = odd ? (e0 - DM + 32) : e0, eo2 = odd ? e0 : (e0 + DM + 32);
;                     *(u32x2*)((char*)ho + 2u * ee) = odd ? rv : hw[0][rh];
;                     *(u32x2*)((char*)ho + 2u * eo2) = odd ? hw[0][rh] : rv; }
;             }
;             if (!PLAIN) { sq0 += __shfl_xor(sq0, 1); sq0 += __shfl_xor(sq0, 2); sq0 += __shfl_xor(sq0, 4);
;             sq1 += __shfl_xor(sq1, 1); sq1 += __shfl_xor(sq1, 2); sq1 += __shfl_xor(sq1, 4); }
;             if (!PLAIN && pc == 0) { sst[g * 16 + rr] = sq0; sst[g * 16 + 8 + rr] = sq1; }
.LBB0_1999:
	s_or_b64 exec, exec, s[22:23]
	ds_write_b128 v200, v[14:17]
	ds_write_b128 v200, v[10:13] offset:64
	ds_read_b128 v[10:13], v201
	ds_read_b128 v[14:17], v201 offset:1152
	s_waitcnt lgkmcnt(5)
	v_lshl_add_u64 v[18:19], s[20:21], 0, v[154:155]
	v_mov_b32_e32 v71, v155
	v_lshl_add_u64 v[22:23], s[20:21], 0, v[70:71]
	s_waitcnt vmcnt(9) lgkmcnt(1)
	v_pk_fma_f32 v[12:13], v[176:177], v[12:13], v[48:49]
	v_pk_fma_f32 v[10:11], v[180:181], v[10:11], v[46:47]
	global_store_dwordx4 v[18:19], v[10:13], off
	v_pk_mul_f32 v[18:19], v[174:175], v[12:13]
	v_pk_mul_f32 v[20:21], v[178:179], v[10:11]
	s_waitcnt vmcnt(9) lgkmcnt(0)
	v_pk_fma_f32 v[14:15], v[180:181], v[14:15], v[42:43]
	v_cvt_pk_bf16_f32 v20, v20, v21
	v_cvt_pk_bf16_f32 v21, v18, v19
	v_pk_fma_f32 v[16:17], v[176:177], v[16:17], v[44:45]
	v_pk_mul_f32 v[18:19], v[178:179], v[14:15]
	global_store_dwordx4 v[22:23], v[14:17], off
	v_pk_mul_f32 v[22:23], v[174:175], v[16:17]
	v_cvt_pk_bf16_f32 v18, v18, v19
	v_mov_b32_e32 v69, v155
	v_cvt_pk_bf16_f32 v19, v22, v23
	ds_write_b128 v200, v[6:9]
	ds_write_b128 v200, v[2:5] offset:64
	ds_read_b128 v[2:5], v201
	ds_read_b128 v[6:9], v201 offset:1152
	v_lshl_add_u64 v[22:23], s[20:21], 0, v[68:69]
	v_mov_b32_e32 v67, v155
	v_lshl_add_u64 v[24:25], s[20:21], 0, v[66:67]
	s_waitcnt vmcnt(9) lgkmcnt(1)
	v_pk_fma_f32 v[4:5], v[166:167], v[4:5], v[40:41]
	v_pk_fma_f32 v[2:3], v[168:169], v[2:3], v[38:39]
	global_store_dwordx4 v[22:23], v[2:5], off
	v_pk_mul_f32 v[22:23], v[170:171], v[4:5]
	v_pk_mul_f32 v[26:27], v[172:173], v[2:3]
	s_waitcnt vmcnt(9) lgkmcnt(0)
	v_pk_fma_f32 v[8:9], v[166:167], v[8:9], v[36:37]
	v_cvt_pk_bf16_f32 v28, v26, v27
	v_cvt_pk_bf16_f32 v23, v22, v23
	ds_bpermute_b32 v22, v203, v28
	ds_bpermute_b32 v23, v203, v23
	v_pk_fma_f32 v[6:7], v[168:169], v[6:7], v[34:35]
	global_store_dwordx4 v[24:25], v[6:9], off
	v_pk_mul_f32 v[26:27], v[170:171], v[8:9]
	v_pk_mul_f32 v[24:25], v[172:173], v[6:7]
	s_nop 0
	v_cvt_pk_bf16_f32 v24, v24, v25
	v_cvt_pk_bf16_f32 v25, v26, v27
	v_add_u32_e32 v27, 0x58000, v202
	v_lshlrev_b32_e32 v26, 1, v27
	s_waitcnt lgkmcnt(0)
	v_add_u32_e32 v250, 0xfffff040, v26
	v_cndmask_b32_e64 v250, v26, v250, s[40:41]
	v_cndmask_b32_e64 v248, v20, v22, s[40:41]
	v_cndmask_b32_e64 v249, v21, v23, s[40:41]
	global_store_dwordx2 v250, v[248:249], s[18:19]
	v_cndmask_b32_e64 v246, v22, v20, s[40:41]
	v_cndmask_b32_e64 v247, v23, v21, s[40:41]
	s_waitcnt lgkmcnt(1)
	v_add_u32_e32 v22, 0x1040, v26
	v_cndmask_b32_e64 v22, v26, v22, s[38:39]
	global_store_dwordx2 v22, v[246:247], s[18:19]
	ds_bpermute_b32 v20, v203, v24
	ds_bpermute_b32 v21, v203, v25
	s_waitcnt lgkmcnt(2)
	v_add_u32_e32 v23, 0x5c000, v202
	v_lshlrev_b32_e32 v22, 1, v23
	s_waitcnt lgkmcnt(0)
	v_add_u32_e32 v250, 0xfffff040, v22
	v_cndmask_b32_e64 v250, v22, v250, s[40:41]
	v_cndmask_b32_e64 v248, v18, v20, s[40:41]
	v_cndmask_b32_e64 v249, v19, v21, s[40:41]
	global_store_dwordx2 v250, v[248:249], s[18:19]
	v_cndmask_b32_e64 v246, v20, v18, s[40:41]
	v_cndmask_b32_e64 v247, v21, v19, s[40:41]
	v_mul_f32_e32 v3, v3, v3
	v_fmac_f32_e32 v3, v2, v2
	v_mul_f32_e32 v2, v5, v5
	v_mul_f32_e32 v13, v13, v13
	v_fmac_f32_e32 v2, v4, v4
	v_mul_f32_e32 v11, v11, v11
	v_fmac_f32_e32 v13, v12, v12
	v_mul_f32_e32 v12, v15, v15
	v_mul_f32_e32 v15, v17, v17
	v_add_f32_e32 v2, v3, v2
	v_mul_f32_e32 v3, v7, v7
	v_mul_f32_e32 v4, v9, v9
	v_fmac_f32_e32 v15, v16, v16
	v_fmac_f32_e32 v3, v6, v6
	v_fmac_f32_e32 v4, v8, v8
	v_fmac_f32_e32 v11, v10, v10
	v_fmac_f32_e32 v12, v14, v14
	v_add_f32_e32 v3, v3, v4
	v_add_f32_e32 v4, v11, v13
	v_add_f32_e32 v5, v12, v15
	v_add_f32_e32 v2, v4, v2
	v_add_f32_e32 v3, v5, v3
	ds_bpermute_b32 v4, v190, v2
	ds_bpermute_b32 v5, v190, v3
	s_waitcnt lgkmcnt(1)
	v_add_f32_e32 v2, v2, v4
	s_waitcnt lgkmcnt(0)
	v_add_f32_e32 v5, v3, v5
	ds_bpermute_b32 v4, v191, v2
	ds_bpermute_b32 v6, v191, v5
	s_waitcnt lgkmcnt(1)
	v_add_f32_e32 v2, v2, v4
	s_waitcnt lgkmcnt(0)
	v_add_f32_e32 v4, v5, v6
	ds_bpermute_b32 v3, v204, v2
	ds_bpermute_b32 v5, v204, v4
	v_add_u32_e32 v6, 0x1040, v22
	v_cndmask_b32_e64 v6, v22, v6, s[38:39]
	global_store_dwordx2 v6, v[246:247], s[18:19]
	s_and_saveexec_b64 s[18:19], s[42:43]
	s_cbranch_execz .LBB0_2009
	s_waitcnt lgkmcnt(1)
	v_add_f32_e32 v2, v2, v3
	s_waitcnt lgkmcnt(0)
	v_add_f32_e32 v3, v4, v5
	ds_write2_b32 v194, v2, v3 offset0:112 offset1:120

; #define LAS __attribute__((address_space(3)))
;     __device__ __forceinline__ void operator()(const f32x4 (&acc)[2][2][4][2], const Unit& u, int wr, int wc, int fr, int fq) const {
;         const int s = u.pm >> 5, lane = fq * 16 + fr, rr = lane >> 3, pc = lane & 7;
;         const float* __restrict__ xi = xin + (size_t)u.pm * BM * DM; float* __restrict__ xo = xout + (size_t)u.pm * BM * DM; bf16_t* __restrict__ ho = Hn + (size_t)u.pm * BM * DM;
;         LAS unsigned char* st = lds_epi + (wr * 4 + wc) * 2304;
;         LAS float* sst = (LAS float*)(lds_epi + 18432 + (wr * 4 + wc) * 512);
;         const int colr = u.pn * BM + wc * 64 + 4 * pc;
;         const unsigned eb = (unsigned)((wr * 64 + rr) * DM + colr);
;         f32x4 gv[2], gsn[2];
; #pragma unroll
;         for (int bj = 0; bj < 2; ++bj) { gv[bj] = *(const f32x4*)(gate + (size_t)s * MODW + colr + bj * 32) * (0.5f * GS2);
;             if (!PLAIN) gsn[bj] = *(const f32x4*)(gnext + colr + bj * 32) * (*(const f32x4*)(scnext + (size_t)s * MODW + colr + bj * 32) + 1.0f); else gsn[bj] = gv[bj]; }
;         const unsigned wr_off = (unsigned)(fr * 144 + 16 * fq), rd_off = (unsigned)(rr * 144 + pc * 16);
;         const bool odd = (rr & 1) != 0;
;         f32x4 xb[2][2][2];
;     ...
;         ERN_LOADX(0);
; #pragma unroll
;         for (int g = 0; g < 8; ++g) { const int ai = g >> 2, m = g & 3;
;             if (g + 1 < 8) ERN_LOADX(g + 1);
;             float sq0 = 0.f, sq1 = 0.f; u32x2 hw[2][2];
; #pragma unroll
;             for (int bj = 0; bj < 2; ++bj) {
;                 *(LAS f32x4*)(st + wr_off) = acc[ai][bj][m][0]; *(LAS f32x4*)(st + wr_off + 64) = acc[ai][bj][m][1];
;                 const f32x4 a0 = *(const LAS f32x4*)(st + rd_off), a1 = *(const LAS f32x4*)(st + rd_off + 8 * 144);
;                 { const f32x4 xv = xb[g & 1][bj][0] + gv[bj] * a0; __builtin_nontemporal_store(xv, (f32x4*)((char*)xo + 4u * ERN_EOFF(g, bj, 0)));
;                   sq0 += (xv.x * xv.x + xv.y * xv.y) + (xv.z * xv.z + xv.w * xv.w);
;                   const f32x4 hv = xv * gsn[bj]; hw[bj][0].x = cvt_pk_bf16(hv.x, hv.y); hw[bj][0].y = cvt_pk_bf16(hv.z, hv.w); }
;                 { const f32x4 xv = xb[g & 1][bj][1] + gv[bj] * a1; __builtin_nontemporal_store(xv, (f32x4*)((char*)xo + 4u * ERN_EOFF(g, bj, 1)));
;                   sq1 += (xv.x * xv.x + xv.y * xv.y) + (xv.z * xv.z + xv.w * xv.w);
.LBB0_2769:
	s_ashr_i32 s13, s2, 5
	s_ashr_i32 s3, s2, 31
	v_lshl_or_b32 v50, s20, 8, v192
	s_mul_hi_i32 s15, s13, 0x12000
	s_mul_i32 s13, s13, 0x12000
	s_add_u32 s20, s44, s13
	v_ashrrev_i32_e32 v51, 31, v50
	s_addc_u32 s21, s45, s15
	v_lshlrev_b64 v[52:53], 2, v[50:51]
	v_lshl_add_u64 v[138:139], s[20:21], 0, v[52:53]
	s_add_u32 s20, s46, s13
	s_addc_u32 s21, s47, s15
	v_lshl_add_u64 v[140:141], s[6:7], 0, v[52:53]
	v_lshl_add_u64 v[52:53], s[20:21], 0, v[52:53]
	s_lshl_b64 s[20:21], s[2:3], 21
	s_add_u32 s22, s90, s20
	v_add_u32_e32 v202, v50, v193
	s_addc_u32 s23, s91, s21
	v_lshlrev_b32_e32 v205, 2, v202
	global_load_dwordx4 v[54:57], v[138:139], off
	global_load_dwordx4 v[174:177], v[140:141], off
	global_load_dwordx4 v[178:181], v[52:53], off
	global_load_dwordx4 v[206:209], v[52:53], off offset:128
	global_load_dwordx4 v[186:189], v205, s[22:23]
	v_add_u32_e32 v50, 0x10000, v205
	global_load_dwordx4 v[210:213], v50, s[22:23]
	global_load_dwordx4 v[214:217], v[140:141], off offset:128
	s_nop 0
	global_load_dwordx4 v[50:53], v[138:139], off offset:128
	global_load_dwordx4 v[218:221], v205, s[22:23] offset:128
	v_add_u32_e32 v204, 0x10080, v205
	global_load_dwordx4 v[222:225], v204, s[22:23]
	v_add_u32_e32 v138, 0x20000, v205
	v_add_u32_e32 v162, 0x30000, v205
	v_add_u32_e32 v184, 0x20080, v205
	v_add_u32_e32 v182, 0x30080, v205
	global_load_dwordx4 v[150:153], v138, s[22:23]
	global_load_dwordx4 v[146:149], v162, s[22:23]
	global_load_dwordx4 v[142:145], v184, s[22:23]
	s_nop 0
	global_load_dwordx4 v[138:141], v182, s[22:23]
	ds_write_b128 v200, v[134:137]
	ds_write_b128 v200, v[130:133] offset:64
	v_and_b32_e32 v135, 64, v199
	ds_read_b128 v[130:133], v201
	ds_read_b128 v[226:229], v201 offset:1152
	v_xor_b32_e32 v134, 8, v199
	v_add_u32_e32 v183, 64, v135
	v_cmp_lt_i32_e32 vcc, v134, v183
	v_add_u32_e32 v185, 0x4000, v202
	v_lshlrev_b32_e32 v230, 2, v185
	v_cndmask_b32_e32 v134, v199, v134, vcc
	v_lshlrev_b32_e32 v203, 2, v134
	s_lshl_b64 s[20:21], s[2:3], 20
	s_add_u32 s20, s93, s20
	s_addc_u32 s21, s92, s21
	s_waitcnt vmcnt(0)
	v_pk_add_f32 v[134:135], v[180:181], 1.0 op_sel_hi:[1,0]
	v_pk_add_f32 v[136:137], v[178:179], 1.0 op_sel_hi:[1,0]
	v_pk_mul_f32 v[178:179], v[176:177], v[134:135]
	v_pk_mul_f32 v[180:181], v[174:175], v[136:137]
	s_waitcnt lgkmcnt(1)
	v_pk_fma_f32 v[134:135], v[54:55], v[130:131], v[186:187]
	s_waitcnt lgkmcnt(0)
	v_pk_fma_f32 v[130:131], v[54:55], v[226:227], v[210:211]
	v_pk_fma_f32 v[136:137], v[56:57], v[132:133], v[188:189]
	v_pk_fma_f32 v[132:133], v[56:57], v[228:229], v[212:213]
	v_pk_mul_f32 v[186:187], v[180:181], v[130:131]
	v_pk_add_f32 v[190:191], v[208:209], 1.0 op_sel_hi:[1,0]
	global_store_dwordx4 v205, v[134:137], s[22:23]
	v_pk_mul_f32 v[174:175], v[178:179], v[136:137]
	v_pk_mul_f32 v[176:177], v[180:181], v[134:135]
	v_pk_mul_f32 v[208:209], v[178:179], v[132:133]
	v_cvt_pk_bf16_f32 v188, v176, v177
	v_cvt_pk_bf16_f32 v189, v174, v175
	global_store_dwordx4 v230, v[130:133], s[22:23]
	v_cvt_pk_bf16_f32 v186, v186, v187
	v_cvt_pk_bf16_f32 v187, v208, v209
	ds_write_b128 v200, v[126:129]
	ds_write_b128 v200, v[122:125] offset:64
	ds_read_b128 v[122:125], v201
	v_pk_add_f32 v[126:127], v[206:207], 1.0 op_sel_hi:[1,0]
	ds_read_b128 v[206:209], v201 offset:1152
	v_pk_mul_f32 v[174:175], v[216:217], v[190:191]
	v_pk_mul_f32 v[176:177], v[214:215], v[126:127]
	s_waitcnt lgkmcnt(1)
	v_pk_fma_f32 v[128:129], v[52:53], v[124:125], v[220:221]
	v_pk_fma_f32 v[126:127], v[50:51], v[122:123], v[218:219]
	s_waitcnt lgkmcnt(0)
	v_pk_fma_f32 v[122:123], v[50:51], v[206:207], v[222:223]
	v_pk_mul_f32 v[190:191], v[174:175], v[128:129]
	v_pk_mul_f32 v[206:207], v[176:177], v[126:127]
	global_store_dwordx4 v205, v[126:129], s[22:23] offset:128
	v_cvt_pk_bf16_f32 v206, v206, v207
	v_cvt_pk_bf16_f32 v191, v190, v191
	ds_bpermute_b32 v190, v203, v206
	ds_bpermute_b32 v191, v203, v191
	v_pk_fma_f32 v[124:125], v[52:53], v[208:209], v[224:225]
	v_pk_mul_f32 v[206:207], v[176:177], v[122:123]
	global_store_dwordx4 v204, v[122:125], s[22:23]
	v_cvt_pk_bf16_f32 v204, v206, v207
	v_lshlrev_b32_e32 v207, 1, v202
	v_pk_mul_f32 v[208:209], v[174:175], v[124:125]
	s_nop 0
	v_cvt_pk_bf16_f32 v206, v208, v209
	s_waitcnt lgkmcnt(0)
	v_add_u32_e32 v250, 0xfffff040, v207
	v_cndmask_b32_e64 v250, v207, v250, s[38:39]
	v_cndmask_b32_e64 v248, v188, v190, s[38:39]
	v_cndmask_b32_e64 v249, v189, v191, s[38:39]
	global_store_dwordx2 v250, v[248:249], s[20:21]
	v_cndmask_b32_e64 v246, v190, v188, s[38:39]
	v_cndmask_b32_e64 v247, v191, v189, s[38:39]
	s_waitcnt lgkmcnt(1)
	v_add_u32_e32 v190, 0x1040, v207
	v_cndmask_b32_e64 v190, v207, v190, s[36:37]
	global_store_dwordx2 v190, v[246:247], s[20:21]
	ds_bpermute_b32 v188, v203, v204
	ds_bpermute_b32 v189, v203, v206
	v_lshlrev_b32_e32 v206, 1, v185
	s_and_saveexec_b64 s[24:25], s[38:39]
	s_xor_b64 s[24:25], exec, s[24:25]
	s_mov_b64 s[58:59], s[70:71]
	s_cbranch_execz .LBB0_2775
	v_lshlrev_b32_e32 v206, 1, v185
	v_add_u32_e32 v185, 0xfffff040, v206
	s_waitcnt lgkmcnt(0)
	global_store_dwordx2 v185, v[188:189], s[20:21]

; #define LAS __attribute__((address_space(3)))
; #define ERN_EOFF(q, m) (eb + (unsigned)((((q) & 1) * HALF + (m) * 16) * DM + ERN_COL((q) >> 1)))
;     __device__ __forceinline__ void operator()(const f32x4 (&acc)[2][2][4][2], const Unit& u, int wr, int wc, int fr, int fq) const {
;     ...
;         for (int g = 0; g < 8; ++g) { const int ai = g >> 2, m = g & 3;
;             if (g + 1 < 8) ERN_LOADX(g + 1);
;             float sq0 = 0.f, sq1 = 0.f; u32x2 hw[2][2];
; #pragma unroll
;             for (int bj = 0; bj < 2; ++bj) {
;                 *(LAS f32x4*)(st + wr_off) = acc[ai][bj][m][0]; *(LAS f32x4*)(st + wr_off + 64) = acc[ai][bj][m][1];
;                 const f32x4 a0 = *(const LAS f32x4*)(st + rd_off), a1 = *(const LAS f32x4*)(st + rd_off + 8 * 144);
;                 { const f32x4 xv = xb[g & 1][bj][0] + gv[bj] * a0; __builtin_nontemporal_store(xv, (f32x4*)((char*)xo + 4u * ERN_EOFF(g, bj, 0)));
;                   sq0 += (xv.x * xv.x + xv.y * xv.y) + (xv.z * xv.z + xv.w * xv.w);
;                   const f32x4 hv = xv * gsn[bj]; hw[bj][0].x = cvt_pk_bf16(hv.x, hv.y); hw[bj][0].y = cvt_pk_bf16(hv.z, hv.w); }
;                 { const f32x4 xv = xb[g & 1][bj][1] + gv[bj] * a1; __builtin_nontemporal_store(xv, (f32x4*)((char*)xo + 4u * ERN_EOFF(g, bj, 1)));
;                   sq1 += (xv.x * xv.x + xv.y * xv.y) + (xv.z * xv.z + xv.w * xv.w);
;                   const f32x4 hv = xv * gsn[bj]; hw[bj][1].x = cvt_pk_bf16(hv.x, hv.y); hw[bj][1].y = cvt_pk_bf16(hv.z, hv.w); }
;             }
;             if (!NOH && !PLAIN) {
; #pragma unroll
;                 for (int rh = 0; rh < 2; ++rh) { u32x2 rv; rv.x = __shfl_xor(hw[1][rh].x, 8); rv.y = __shfl_xor(hw[1][rh].y, 8);
;                     const unsigned e0 = ERN_EOFF(g, 0, rh);
;                     const unsigned ee = odd ? (e0 - DM + 32) : e0, eo2 = odd ? e0 : (e0 + DM + 32);
;                     *(u32x2*)((char*)ho + 2u * ee) = odd ? rv : hw[0][rh];
;                     *(u32x2*)((char*)ho + 2u * eo2) = odd ? hw[0][rh] : rv; }
;             }
;             if (!PLAIN) { sq0 += __shfl_xor(sq0, 1); sq0 += __shfl_xor(sq0, 2); sq0 += __shfl_xor(sq0, 4);
;             sq1 += __shfl_xor(sq1, 1); sq1 += __shfl_xor(sq1, 2); sq1 += __shfl_xor(sq1, 4); }
;             if (!PLAIN && pc == 0) { sst[g * 16 + rr] = sq0; sst[g * 16 + 8 + rr] = sq1; }
.LBB0_2779:
	s_or_b64 exec, exec, s[24:25]
	v_lshl_add_u64 v[206:207], s[22:23], 0, v[162:163]
	v_add_u32_e32 v122, 0x40000, v205
	v_add_u32_e32 v162, 0x50000, v205
	v_add_u32_e32 v186, 0x40080, v205
	global_load_dwordx4 v[130:133], v162, s[22:23]
	global_load_dwordx4 v[126:129], v186, s[22:23]
	v_add_u32_e32 v188, 0x50080, v205
	global_load_dwordx4 v[134:137], v122, s[22:23]
	s_waitcnt lgkmcnt(0)
	global_load_dwordx4 v[122:125], v188, s[22:23]
	ds_write_b128 v200, v[118:121]
	ds_write_b128 v200, v[114:117] offset:64
	ds_read_b128 v[114:117], v201
	ds_read_b128 v[118:121], v201 offset:1152
	v_mov_b32_e32 v185, v163
	v_mov_b32_e32 v183, v163
	v_lshl_add_u64 v[182:183], s[22:23], 0, v[182:183]
	s_waitcnt lgkmcnt(1)
	v_pk_fma_f32 v[116:117], v[56:57], v[116:117], v[152:153]
	v_add_u32_e32 v152, 0x8000, v202
	v_pk_fma_f32 v[114:115], v[54:55], v[114:115], v[150:151]
	v_lshlrev_b32_e32 v150, 2, v152
	s_waitcnt lgkmcnt(0)
	v_pk_fma_f32 v[118:119], v[54:55], v[118:119], v[146:147]
	global_store_dwordx4 v150, v[114:117], s[22:23]
	v_pk_mul_f32 v[150:151], v[180:181], v[114:115]
	v_pk_fma_f32 v[120:121], v[56:57], v[120:121], v[148:149]
	v_pk_mul_f32 v[146:147], v[180:181], v[118:119]
	v_pk_mul_f32 v[208:209], v[178:179], v[116:117]
	v_cvt_pk_bf16_f32 v150, v150, v151
	v_pk_mul_f32 v[148:149], v[178:179], v[120:121]
	v_cvt_pk_bf16_f32 v151, v208, v209
	global_store_dwordx4 v[206:207], v[118:121], off
	v_cvt_pk_bf16_f32 v146, v146, v147
	v_cvt_pk_bf16_f32 v147, v148, v149
	ds_write_b128 v200, v[110:113]
	ds_write_b128 v200, v[106:109] offset:64
	ds_read_b128 v[106:109], v201
	ds_read_b128 v[110:113], v201 offset:1152
	v_lshl_add_u64 v[148:149], s[22:23], 0, v[184:185]
	s_waitcnt lgkmcnt(1)
	v_pk_fma_f32 v[106:107], v[50:51], v[106:107], v[142:143]
	v_pk_fma_f32 v[108:109], v[52:53], v[108:109], v[144:145]
	v_pk_mul_f32 v[144:145], v[176:177], v[106:107]
	global_store_dwordx4 v[148:149], v[106:109], off
	v_pk_mul_f32 v[142:143], v[174:175], v[108:109]
	v_cvt_pk_bf16_f32 v144, v144, v145
	s_waitcnt lgkmcnt(0)
	v_pk_fma_f32 v[110:111], v[50:51], v[110:111], v[138:139]
	v_cvt_pk_bf16_f32 v145, v142, v143
	ds_bpermute_b32 v138, v203, v144
	ds_bpermute_b32 v139, v203, v145
	v_pk_fma_f32 v[112:113], v[52:53], v[112:113], v[140:141]
	v_pk_mul_f32 v[140:141], v[176:177], v[110:111]
	v_pk_mul_f32 v[142:143], v[174:175], v[112:113]
	global_store_dwordx4 v[182:183], v[110:113], off
	v_cvt_pk_bf16_f32 v140, v140, v141
	v_cvt_pk_bf16_f32 v141, v142, v143
	v_lshlrev_b32_e32 v142, 1, v152
	s_waitcnt lgkmcnt(0)
	v_add_u32_e32 v250, 0xfffff040, v142
	v_cndmask_b32_e64 v250, v142, v250, s[38:39]
	v_cndmask_b32_e64 v248, v150, v138, s[38:39]
	v_cndmask_b32_e64 v249, v151, v139, s[38:39]
	global_store_dwordx2 v250, v[248:249], s[20:21]
	v_cndmask_b32_e64 v246, v138, v150, s[38:39]
	v_cndmask_b32_e64 v247, v139, v151, s[38:39]
	s_waitcnt lgkmcnt(1)
	v_add_u32_e32 v138, 0x1040, v142
	v_cndmask_b32_e64 v138, v142, v138, s[36:37]
	global_store_dwordx2 v138, v[246:247], s[20:21]
	ds_bpermute_b32 v138, v203, v140
	s_waitcnt lgkmcnt(1)
	ds_bpermute_b32 v139, v203, v141
	v_add_u32_e32 v141, 0xc000, v202
	v_lshlrev_b32_e32 v140, 1, v141
	s_waitcnt lgkmcnt(0)
	v_add_u32_e32 v250, 0xfffff040, v140
	v_cndmask_b32_e64 v250, v140, v250, s[38:39]
	v_cndmask_b32_e64 v248, v146, v138, s[38:39]
	v_cndmask_b32_e64 v249, v147, v139, s[38:39]
	global_store_dwordx2 v250, v[248:249], s[20:21]
	v_cndmask_b32_e64 v246, v138, v146, s[38:39]
	v_cndmask_b32_e64 v247, v139, v147, s[38:39]
	v_mul_f32_e32 v107, v107, v107
	v_fmac_f32_e32 v107, v106, v106
	v_mul_f32_e32 v106, v109, v109
	v_mul_f32_e32 v117, v117, v117
	v_fmac_f32_e32 v106, v108, v108
	v_mul_f32_e32 v115, v115, v115
	v_fmac_f32_e32 v117, v116, v116
	v_mul_f32_e32 v116, v119, v119
	v_mul_f32_e32 v119, v121, v121
	v_add_f32_e32 v106, v107, v106
	v_mul_f32_e32 v107, v111, v111
	v_mul_f32_e32 v108, v113, v113
	v_fmac_f32_e32 v119, v120, v120
	v_fmac_f32_e32 v107, v110, v110
	v_fmac_f32_e32 v108, v112, v112
	v_fmac_f32_e32 v115, v114, v114
	v_fmac_f32_e32 v116, v118, v118
	v_add_f32_e32 v107, v107, v108
	v_add_f32_e32 v108, v115, v117
	v_add_f32_e32 v109, v116, v119
	v_add_f32_e32 v106, v108, v106
	v_add_f32_e32 v107, v109, v107
	ds_bpermute_b32 v108, v190, v106
	ds_bpermute_b32 v109, v190, v107
	s_waitcnt lgkmcnt(1)
	v_add_f32_e32 v106, v106, v108
	s_waitcnt lgkmcnt(0)
	v_add_f32_e32 v109, v107, v109
	ds_bpermute_b32 v108, v191, v106
	ds_bpermute_b32 v110, v191, v109
	s_waitcnt lgkmcnt(1)
	v_add_f32_e32 v106, v106, v108
	s_waitcnt lgkmcnt(0)
	v_add_f32_e32 v108, v109, v110
	ds_bpermute_b32 v107, v204, v106
	ds_bpermute_b32 v109, v204, v108
	v_add_u32_e32 v110, 0x1040, v140
	v_cndmask_b32_e64 v110, v140, v110, s[36:37]
	global_store_dwordx2 v110, v[246:247], s[20:21]
	s_and_saveexec_b64 s[24:25], s[40:41]
	s_cbranch_execz .LBB0_2789
	s_waitcnt lgkmcnt(1)
	v_add_f32_e32 v106, v106, v107
	s_waitcnt lgkmcnt(0)
	v_add_f32_e32 v107, v108, v109
	ds_write2_b32 v194, v106, v107 offset0:16 offset1:24
; #define LAS __attribute__((address_space(3)))
; #define ERN_EOFF(q, m) (eb + (unsigned)((((q) & 1) * HALF + (m) * 16) * DM + ERN_COL((q) >> 1)))
;     __device__ __forceinline__ void operator()(const f32x4 (&acc)[2][2][4][2], const Unit& u, int wr, int wc, int fr, int fq) const {
;     ...
;         for (int g = 0; g < 8; ++g) { const int ai = g >> 2, m = g & 3;
;             if (g + 1 < 8) ERN_LOADX(g + 1);
;             float sq0 = 0.f, sq1 = 0.f; u32x2 hw[2][2];
; #pragma unroll
;             for (int bj = 0; bj < 2; ++bj) {
;                 *(LAS f32x4*)(st + wr_off) = acc[ai][bj][m][0]; *(LAS f32x4*)(st + wr_off + 64) = acc[ai][bj][m][1];
;                 const f32x4 a0 = *(const LAS f32x4*)(st + rd_off), a1 = *(const LAS f32x4*)(st + rd_off + 8 * 144);
;                 { const f32x4 xv = xb[g & 1][bj][0] + gv[bj] * a0; __builtin_nontemporal_store(xv, (f32x4*)((char*)xo + 4u * ERN_EOFF(g, bj, 0)));
;                   sq0 += (xv.x * xv.x + xv.y * xv.y) + (xv.z * xv.z + xv.w * xv.w);
;                   const f32x4 hv = xv * gsn[bj]; hw[bj][0].x = cvt_pk_bf16(hv.x, hv.y); hw[bj][0].y = cvt_pk_bf16(hv.z, hv.w); }
;                 { const f32x4 xv = xb[g & 1][bj][1] + gv[bj] * a1; __builtin_nontemporal_store(xv, (f32x4*)((char*)xo + 4u * ERN_EOFF(g, bj, 1)));
;                   sq1 += (xv.x * xv.x + xv.y * xv.y) + (xv.z * xv.z + xv.w * xv.w);
;                   const f32x4 hv = xv * gsn[bj]; hw[bj][1].x = cvt_pk_bf16(hv.x, hv.y); hw[bj][1].y = cvt_pk_bf16(hv.z, hv.w); }
;             }
;             if (!NOH && !PLAIN) {
; #pragma unroll
;                 for (int rh = 0; rh < 2; ++rh) { u32x2 rv; rv.x = __shfl_xor(hw[1][rh].x, 8); rv.y = __shfl_xor(hw[1][rh].y, 8);
;                     const unsigned e0 = ERN_EOFF(g, 0, rh);
;                     const unsigned ee = odd ? (e0 - DM + 32) : e0, eo2 = odd ? e0 : (e0 + DM + 32);
;                     *(u32x2*)((char*)ho + 2u * ee) = odd ? rv : hw[0][rh];
;                     *(u32x2*)((char*)ho + 2u * eo2) = odd ? hw[0][rh] : rv; }
;             }
;             if (!PLAIN) { sq0 += __shfl_xor(sq0, 1); sq0 += __shfl_xor(sq0, 2); sq0 += __shfl_xor(sq0, 4);
;             sq1 += __shfl_xor(sq1, 1); sq1 += __shfl_xor(sq1, 2); sq1 += __shfl_xor(sq1, 4); }
;             if (!PLAIN && pc == 0) { sst[g * 16 + rr] = sq0; sst[g * 16 + 8 + rr] = sq1; }
.LBB0_2789:
	s_or_b64 exec, exec, s[24:25]
	v_lshl_add_u64 v[142:143], s[22:23], 0, v[162:163]
	v_add_u32_e32 v106, 0x60000, v205
	v_add_u32_e32 v162, 0x70000, v205
	v_add_u32_e32 v138, 0x60080, v205
	global_load_dwordx4 v[114:117], v162, s[22:23]
	global_load_dwordx4 v[110:113], v138, s[22:23]
	v_add_u32_e32 v140, 0x70080, v205
	global_load_dwordx4 v[118:121], v106, s[22:23]
	s_waitcnt lgkmcnt(0)
	global_load_dwordx4 v[106:109], v140, s[22:23]
	ds_write_b128 v200, v[102:105]
	ds_write_b128 v200, v[98:101] offset:64
	ds_read_b128 v[98:101], v201
	ds_read_b128 v[102:105], v201 offset:1152
	v_mov_b32_e32 v187, v163
	v_mov_b32_e32 v189, v163
	s_waitcnt vmcnt(11) lgkmcnt(1)
	v_pk_fma_f32 v[100:101], v[56:57], v[100:101], v[136:137]
	v_add_u32_e32 v136, 0x10000, v202
	v_pk_fma_f32 v[98:99], v[54:55], v[98:99], v[134:135]
	v_lshlrev_b32_e32 v134, 2, v136
	s_waitcnt lgkmcnt(0)
	v_pk_fma_f32 v[102:103], v[54:55], v[102:103], v[130:131]
	global_store_dwordx4 v134, v[98:101], s[22:23]
	v_pk_mul_f32 v[134:135], v[180:181], v[98:99]
	v_pk_fma_f32 v[104:105], v[56:57], v[104:105], v[132:133]
	v_pk_mul_f32 v[130:131], v[180:181], v[102:103]
	v_pk_mul_f32 v[144:145], v[178:179], v[100:101]
	v_cvt_pk_bf16_f32 v134, v134, v135
	v_pk_mul_f32 v[132:133], v[178:179], v[104:105]
	v_cvt_pk_bf16_f32 v135, v144, v145
	global_store_dwordx4 v[142:143], v[102:105], off
	v_cvt_pk_bf16_f32 v130, v130, v131
	v_cvt_pk_bf16_f32 v131, v132, v133
	ds_write_b128 v200, v[94:97]
	ds_write_b128 v200, v[90:93] offset:64
	ds_read_b128 v[90:93], v201
	ds_read_b128 v[94:97], v201 offset:1152
	v_lshl_add_u64 v[132:133], s[22:23], 0, v[186:187]
	v_lshl_add_u64 v[142:143], s[22:23], 0, v[188:189]
	s_waitcnt lgkmcnt(1)
	v_pk_fma_f32 v[90:91], v[50:51], v[90:91], v[126:127]
	v_pk_fma_f32 v[92:93], v[52:53], v[92:93], v[128:129]
	v_pk_mul_f32 v[128:129], v[176:177], v[90:91]
	global_store_dwordx4 v[132:133], v[90:93], off
	v_pk_mul_f32 v[126:127], v[174:175], v[92:93]
	v_cvt_pk_bf16_f32 v128, v128, v129
	s_waitcnt vmcnt(13) lgkmcnt(0)
	v_pk_fma_f32 v[94:95], v[50:51], v[94:95], v[122:123]
	v_cvt_pk_bf16_f32 v129, v126, v127
	ds_bpermute_b32 v122, v203, v128
	ds_bpermute_b32 v123, v203, v129
	v_pk_fma_f32 v[96:97], v[52:53], v[96:97], v[124:125]
	v_pk_mul_f32 v[124:125], v[176:177], v[94:95]
	v_pk_mul_f32 v[126:127], v[174:175], v[96:97]
	global_store_dwordx4 v[142:143], v[94:97], off
	v_cvt_pk_bf16_f32 v124, v124, v125
	v_cvt_pk_bf16_f32 v125, v126, v127
	v_lshlrev_b32_e32 v126, 1, v136
	s_waitcnt lgkmcnt(0)
	v_add_u32_e32 v250, 0xfffff040, v126
	v_cndmask_b32_e64 v250, v126, v250, s[38:39]
	v_cndmask_b32_e64 v248, v134, v122, s[38:39]
	v_cndmask_b32_e64 v249, v135, v123, s[38:39]
	global_store_dwordx2 v250, v[248:249], s[20:21]
	v_cndmask_b32_e64 v246, v122, v134, s[38:39]
	v_cndmask_b32_e64 v247, v123, v135, s[38:39]
	s_waitcnt lgkmcnt(1)
	v_add_u32_e32 v122, 0x1040, v126
	v_cndmask_b32_e64 v122, v126, v122, s[36:37]
	global_store_dwordx2 v122, v[246:247], s[20:21]
	ds_bpermute_b32 v122, v203, v124
	s_waitcnt lgkmcnt(1)
	ds_bpermute_b32 v123, v203, v125
	v_add_u32_e32 v125, 0x14000, v202
	v_lshlrev_b32_e32 v124, 1, v125
	s_waitcnt lgkmcnt(0)
	v_add_u32_e32 v250, 0xfffff040, v124
	v_cndmask_b32_e64 v250, v124, v250, s[38:39]
	v_cndmask_b32_e64 v248, v130, v122, s[38:39]
	v_cndmask_b32_e64 v249, v131, v123, s[38:39]
	global_store_dwordx2 v250, v[248:249], s[20:21]
	v_cndmask_b32_e64 v246, v122, v130, s[38:39]
	v_cndmask_b32_e64 v247, v123, v131, s[38:39]
	v_mul_f32_e32 v91, v91, v91
	v_fmac_f32_e32 v91, v90, v90
	v_mul_f32_e32 v90, v93, v93
	v_mul_f32_e32 v101, v101, v101
	v_fmac_f32_e32 v90, v92, v92
	v_mul_f32_e32 v99, v99, v99
	v_fmac_f32_e32 v101, v100, v100
	v_mul_f32_e32 v100, v103, v103
	v_mul_f32_e32 v103, v105, v105
	v_add_f32_e32 v90, v91, v90
	v_mul_f32_e32 v91, v95, v95
	v_mul_f32_e32 v92, v97, v97
	v_fmac_f32_e32 v103, v104, v104
	v_fmac_f32_e32 v91, v94, v94
	v_fmac_f32_e32 v92, v96, v96
	v_fmac_f32_e32 v99, v98, v98
	v_fmac_f32_e32 v100, v102, v102
	v_add_f32_e32 v91, v91, v92
	v_add_f32_e32 v92, v99, v101
	v_add_f32_e32 v93, v100, v103
	v_add_f32_e32 v90, v92, v90
	v_add_f32_e32 v91, v93, v91
	ds_bpermute_b32 v92, v190, v90
	ds_bpermute_b32 v93, v190, v91
	s_waitcnt lgkmcnt(1)
	v_add_f32_e32 v90, v90, v92
	s_waitcnt lgkmcnt(0)
	v_add_f32_e32 v93, v91, v93
	ds_bpermute_b32 v92, v191, v90
	ds_bpermute_b32 v94, v191, v93
	s_waitcnt lgkmcnt(1)
	v_add_f32_e32 v90, v90, v92
	s_waitcnt lgkmcnt(0)
	v_add_f32_e32 v92, v93, v94
	ds_bpermute_b32 v91, v204, v90
	ds_bpermute_b32 v93, v204, v92
	v_add_u32_e32 v94, 0x1040, v124
	v_cndmask_b32_e64 v94, v124, v94, s[36:37]
	global_store_dwordx2 v94, v[246:247], s[20:21]
	s_and_saveexec_b64 s[24:25], s[40:41]
	s_cbranch_execz .LBB0_2799
	s_waitcnt lgkmcnt(1)
	v_add_f32_e32 v90, v90, v91
	s_waitcnt lgkmcnt(0)
	v_add_f32_e32 v91, v92, v93
	ds_write2_b32 v194, v90, v91 offset0:32 offset1:40
; #define LAS __attribute__((address_space(3)))
; #define ERN_EOFF(q, m) (eb + (unsigned)((((q) & 1) * HALF + (m) * 16) * DM + ERN_COL((q) >> 1)))
;     __device__ __forceinline__ void operator()(const f32x4 (&acc)[2][2][4][2], const Unit& u, int wr, int wc, int fr, int fq) const {
;     ...
;         for (int g = 0; g < 8; ++g) { const int ai = g >> 2, m = g & 3;
;             if (g + 1 < 8) ERN_LOADX(g + 1);
;             float sq0 = 0.f, sq1 = 0.f; u32x2 hw[2][2];
; #pragma unroll
;             for (int bj = 0; bj < 2; ++bj) {
;                 *(LAS f32x4*)(st + wr_off) = acc[ai][bj][m][0]; *(LAS f32x4*)(st + wr_off + 64) = acc[ai][bj][m][1];
;                 const f32x4 a0 = *(const LAS f32x4*)(st + rd_off), a1 = *(const LAS f32x4*)(st + rd_off + 8 * 144);
;                 { const f32x4 xv = xb[g & 1][bj][0] + gv[bj] * a0; __builtin_nontemporal_store(xv, (f32x4*)((char*)xo + 4u * ERN_EOFF(g, bj, 0)));
;                   sq0 += (xv.x * xv.x + xv.y * xv.y) + (xv.z * xv.z + xv.w * xv.w);
;                   const f32x4 hv = xv * gsn[bj]; hw[bj][0].x = cvt_pk_bf16(hv.x, hv.y); hw[bj][0].y = cvt_pk_bf16(hv.z, hv.w); }
;                 { const f32x4 xv = xb[g & 1][bj][1] + gv[bj] * a1; __builtin_nontemporal_store(xv, (f32x4*)((char*)xo + 4u * ERN_EOFF(g, bj, 1)));
;                   sq1 += (xv.x * xv.x + xv.y * xv.y) + (xv.z * xv.z + xv.w * xv.w);
;                   const f32x4 hv = xv * gsn[bj]; hw[bj][1].x = cvt_pk_bf16(hv.x, hv.y); hw[bj][1].y = cvt_pk_bf16(hv.z, hv.w); }
;             }
;             if (!NOH && !PLAIN) {
; #pragma unroll
;                 for (int rh = 0; rh < 2; ++rh) { u32x2 rv; rv.x = __shfl_xor(hw[1][rh].x, 8); rv.y = __shfl_xor(hw[1][rh].y, 8);
;                     const unsigned e0 = ERN_EOFF(g, 0, rh);
;                     const unsigned ee = odd ? (e0 - DM + 32) : e0, eo2 = odd ? e0 : (e0 + DM + 32);
;                     *(u32x2*)((char*)ho + 2u * ee) = odd ? rv : hw[0][rh];
;                     *(u32x2*)((char*)ho + 2u * eo2) = odd ? hw[0][rh] : rv; }
;             }
;             if (!PLAIN) { sq0 += __shfl_xor(sq0, 1); sq0 += __shfl_xor(sq0, 2); sq0 += __shfl_xor(sq0, 4);
;             sq1 += __shfl_xor(sq1, 1); sq1 += __shfl_xor(sq1, 2); sq1 += __shfl_xor(sq1, 4); }
;             if (!PLAIN && pc == 0) { sst[g * 16 + rr] = sq0; sst[g * 16 + 8 + rr] = sq1; }
.LBB0_2799:
	s_or_b64 exec, exec, s[24:25]
	v_lshl_add_u64 v[124:125], s[22:23], 0, v[162:163]
	v_add_u32_e32 v90, 0x100000, v205
	s_waitcnt lgkmcnt(1)
	v_add_u32_e32 v91, 0x110000, v205
	v_add_u32_e32 v162, 0x100080, v205
	global_load_dwordx4 v[102:105], v90, s[22:23]
	global_load_dwordx4 v[98:101], v91, s[22:23]
	v_add_u32_e32 v122, 0x110080, v205
	global_load_dwordx4 v[94:97], v162, s[22:23]
	s_waitcnt lgkmcnt(0)
	global_load_dwordx4 v[90:93], v122, s[22:23]
	ds_write_b128 v200, v[86:89]
	ds_write_b128 v200, v[82:85] offset:64
	ds_read_b128 v[82:85], v201
	ds_read_b128 v[86:89], v201 offset:1152
	v_mov_b32_e32 v139, v163
	v_mov_b32_e32 v141, v163
	s_waitcnt vmcnt(11) lgkmcnt(1)
	v_pk_fma_f32 v[84:85], v[56:57], v[84:85], v[120:121]
	v_add_u32_e32 v120, 0x18000, v202
	v_pk_fma_f32 v[82:83], v[54:55], v[82:83], v[118:119]
	v_lshlrev_b32_e32 v118, 2, v120
	s_waitcnt lgkmcnt(0)
	v_pk_fma_f32 v[86:87], v[54:55], v[86:87], v[114:115]
	global_store_dwordx4 v118, v[82:85], s[22:23]
	v_pk_mul_f32 v[118:119], v[180:181], v[82:83]
	v_pk_fma_f32 v[88:89], v[56:57], v[88:89], v[116:117]
	v_pk_mul_f32 v[114:115], v[180:181], v[86:87]
	v_pk_mul_f32 v[126:127], v[178:179], v[84:85]
	v_cvt_pk_bf16_f32 v118, v118, v119
	v_pk_mul_f32 v[116:117], v[178:179], v[88:89]
	v_cvt_pk_bf16_f32 v119, v126, v127
	global_store_dwordx4 v[124:125], v[86:89], off
	v_cvt_pk_bf16_f32 v114, v114, v115
	v_cvt_pk_bf16_f32 v115, v116, v117
	ds_write_b128 v200, v[78:81]
	ds_write_b128 v200, v[74:77] offset:64
	ds_read_b128 v[74:77], v201
	ds_read_b128 v[78:81], v201 offset:1152
	v_lshl_add_u64 v[116:117], s[22:23], 0, v[138:139]
	v_lshl_add_u64 v[124:125], s[22:23], 0, v[140:141]
	s_waitcnt lgkmcnt(1)
	v_pk_fma_f32 v[74:75], v[50:51], v[74:75], v[110:111]
	v_pk_fma_f32 v[76:77], v[52:53], v[76:77], v[112:113]
	v_pk_mul_f32 v[112:113], v[176:177], v[74:75]
	global_store_dwordx4 v[116:117], v[74:77], off
	v_pk_mul_f32 v[110:111], v[174:175], v[76:77]
	v_cvt_pk_bf16_f32 v112, v112, v113
	s_waitcnt vmcnt(13) lgkmcnt(0)
	v_pk_fma_f32 v[78:79], v[50:51], v[78:79], v[106:107]
	v_cvt_pk_bf16_f32 v113, v110, v111
	ds_bpermute_b32 v106, v203, v112
	ds_bpermute_b32 v107, v203, v113
	v_pk_fma_f32 v[80:81], v[52:53], v[80:81], v[108:109]
	v_pk_mul_f32 v[108:109], v[176:177], v[78:79]
	v_pk_mul_f32 v[110:111], v[174:175], v[80:81]
	global_store_dwordx4 v[124:125], v[78:81], off
	v_cvt_pk_bf16_f32 v108, v108, v109
	v_cvt_pk_bf16_f32 v109, v110, v111
	v_lshlrev_b32_e32 v110, 1, v120
	s_waitcnt lgkmcnt(0)
	v_add_u32_e32 v250, 0xfffff040, v110
	v_cndmask_b32_e64 v250, v110, v250, s[38:39]
	v_cndmask_b32_e64 v248, v118, v106, s[38:39]
	v_cndmask_b32_e64 v249, v119, v107, s[38:39]
	global_store_dwordx2 v250, v[248:249], s[20:21]
	v_cndmask_b32_e64 v246, v106, v118, s[38:39]
	v_cndmask_b32_e64 v247, v107, v119, s[38:39]
	s_waitcnt lgkmcnt(1)
	v_add_u32_e32 v106, 0x1040, v110
	v_cndmask_b32_e64 v106, v110, v106, s[36:37]
	global_store_dwordx2 v106, v[246:247], s[20:21]
	ds_bpermute_b32 v106, v203, v108
	s_waitcnt lgkmcnt(1)
	ds_bpermute_b32 v107, v203, v109
	v_add_u32_e32 v109, 0x1c000, v202
	v_lshlrev_b32_e32 v108, 1, v109
	s_waitcnt lgkmcnt(0)
	v_add_u32_e32 v250, 0xfffff040, v108
	v_cndmask_b32_e64 v250, v108, v250, s[38:39]
	v_cndmask_b32_e64 v248, v114, v106, s[38:39]
	v_cndmask_b32_e64 v249, v115, v107, s[38:39]
	global_store_dwordx2 v250, v[248:249], s[20:21]
	v_cndmask_b32_e64 v246, v106, v114, s[38:39]
	v_cndmask_b32_e64 v247, v107, v115, s[38:39]
	v_mul_f32_e32 v75, v75, v75
	v_fmac_f32_e32 v75, v74, v74
	v_mul_f32_e32 v74, v77, v77
	v_mul_f32_e32 v85, v85, v85
	v_fmac_f32_e32 v74, v76, v76
	v_mul_f32_e32 v83, v83, v83
	v_fmac_f32_e32 v85, v84, v84
	v_mul_f32_e32 v84, v87, v87
	v_mul_f32_e32 v87, v89, v89
	v_add_f32_e32 v74, v75, v74
	v_mul_f32_e32 v75, v79, v79
	v_mul_f32_e32 v76, v81, v81
	v_fmac_f32_e32 v87, v88, v88
	v_fmac_f32_e32 v75, v78, v78
	v_fmac_f32_e32 v76, v80, v80
	v_fmac_f32_e32 v83, v82, v82
	v_fmac_f32_e32 v84, v86, v86
	v_add_f32_e32 v75, v75, v76
	v_add_f32_e32 v76, v83, v85
	v_add_f32_e32 v77, v84, v87
	v_add_f32_e32 v74, v76, v74
	v_add_f32_e32 v75, v77, v75
	ds_bpermute_b32 v76, v190, v74
	ds_bpermute_b32 v77, v190, v75
	s_waitcnt lgkmcnt(1)
	v_add_f32_e32 v74, v74, v76
	s_waitcnt lgkmcnt(0)
	v_add_f32_e32 v77, v75, v77
	ds_bpermute_b32 v76, v191, v74
	ds_bpermute_b32 v78, v191, v77
	s_waitcnt lgkmcnt(1)
	v_add_f32_e32 v74, v74, v76
	s_waitcnt lgkmcnt(0)
	v_add_f32_e32 v76, v77, v78
	ds_bpermute_b32 v75, v204, v74
	ds_bpermute_b32 v77, v204, v76
	v_add_u32_e32 v78, 0x1040, v108
	v_cndmask_b32_e64 v78, v108, v78, s[36:37]
	global_store_dwordx2 v78, v[246:247], s[20:21]
	s_and_saveexec_b64 s[24:25], s[40:41]
	s_cbranch_execz .LBB0_2809
	s_waitcnt lgkmcnt(1)
	v_add_f32_e32 v74, v74, v75
	s_waitcnt lgkmcnt(0)
	v_add_f32_e32 v75, v76, v77
	ds_write2_b32 v194, v74, v75 offset0:48 offset1:56
; #define LAS __attribute__((address_space(3)))
; #define ERN_EOFF(q, m) (eb + (unsigned)((((q) & 1) * HALF + (m) * 16) * DM + ERN_COL((q) >> 1)))
;     __device__ __forceinline__ void operator()(const f32x4 (&acc)[2][2][4][2], const Unit& u, int wr, int wc, int fr, int fq) const {
;     ...
;         for (int g = 0; g < 8; ++g) { const int ai = g >> 2, m = g & 3;
;             if (g + 1 < 8) ERN_LOADX(g + 1);
;             float sq0 = 0.f, sq1 = 0.f; u32x2 hw[2][2];
; #pragma unroll
;             for (int bj = 0; bj < 2; ++bj) {
;                 *(LAS f32x4*)(st + wr_off) = acc[ai][bj][m][0]; *(LAS f32x4*)(st + wr_off + 64) = acc[ai][bj][m][1];
;                 const f32x4 a0 = *(const LAS f32x4*)(st + rd_off), a1 = *(const LAS f32x4*)(st + rd_off + 8 * 144);
;                 { const f32x4 xv = xb[g & 1][bj][0] + gv[bj] * a0; __builtin_nontemporal_store(xv, (f32x4*)((char*)xo + 4u * ERN_EOFF(g, bj, 0)));
;                   sq0 += (xv.x * xv.x + xv.y * xv.y) + (xv.z * xv.z + xv.w * xv.w);
;                   const f32x4 hv = xv * gsn[bj]; hw[bj][0].x = cvt_pk_bf16(hv.x, hv.y); hw[bj][0].y = cvt_pk_bf16(hv.z, hv.w); }
;                 { const f32x4 xv = xb[g & 1][bj][1] + gv[bj] * a1; __builtin_nontemporal_store(xv, (f32x4*)((char*)xo + 4u * ERN_EOFF(g, bj, 1)));
;                   sq1 += (xv.x * xv.x + xv.y * xv.y) + (xv.z * xv.z + xv.w * xv.w);
;                   const f32x4 hv = xv * gsn[bj]; hw[bj][1].x = cvt_pk_bf16(hv.x, hv.y); hw[bj][1].y = cvt_pk_bf16(hv.z, hv.w); }
;             }
;             if (!NOH && !PLAIN) {
; #pragma unroll
;                 for (int rh = 0; rh < 2; ++rh) { u32x2 rv; rv.x = __shfl_xor(hw[1][rh].x, 8); rv.y = __shfl_xor(hw[1][rh].y, 8);
;                     const unsigned e0 = ERN_EOFF(g, 0, rh);
;                     const unsigned ee = odd ? (e0 - DM + 32) : e0, eo2 = odd ? e0 : (e0 + DM + 32);
;                     *(u32x2*)((char*)ho + 2u * ee) = odd ? rv : hw[0][rh];
;                     *(u32x2*)((char*)ho + 2u * eo2) = odd ? hw[0][rh] : rv; }
;             }
;             if (!PLAIN) { sq0 += __shfl_xor(sq0, 1); sq0 += __shfl_xor(sq0, 2); sq0 += __shfl_xor(sq0, 4);
;             sq1 += __shfl_xor(sq1, 1); sq1 += __shfl_xor(sq1, 2); sq1 += __shfl_xor(sq1, 4); }
;             if (!PLAIN && pc == 0) { sst[g * 16 + rr] = sq0; sst[g * 16 + 8 + rr] = sq1; }
.LBB0_2809:
	s_or_b64 exec, exec, s[24:25]
	v_lshl_add_u64 v[112:113], s[22:23], 0, v[162:163]
	v_add_u32_e32 v162, 0x120000, v205
	v_add_u32_e32 v108, 0x120080, v205
	v_add_u32_e32 v110, 0x130000, v205
	global_load_dwordx4 v[86:89], v162, s[22:23]
	global_load_dwordx4 v[82:85], v110, s[22:23]
	v_add_u32_e32 v106, 0x130080, v205
	global_load_dwordx4 v[78:81], v108, s[22:23]
	s_waitcnt lgkmcnt(0)
	global_load_dwordx4 v[74:77], v106, s[22:23]
	ds_write_b128 v200, v[70:73]
	ds_write_b128 v200, v[66:69] offset:64
	ds_read_b128 v[66:69], v201
	ds_read_b128 v[70:73], v201 offset:1152
	v_mov_b32_e32 v123, v163
	s_waitcnt vmcnt(13) lgkmcnt(1)
	v_pk_fma_f32 v[68:69], v[56:57], v[68:69], v[104:105]
	v_add_u32_e32 v104, 0x40000, v202
	v_pk_fma_f32 v[66:67], v[54:55], v[66:67], v[102:103]
	v_lshlrev_b32_e32 v102, 2, v104
	s_waitcnt vmcnt(12) lgkmcnt(0)
	v_pk_fma_f32 v[72:73], v[56:57], v[72:73], v[100:101]
	v_add_u32_e32 v100, 0x44000, v202
	global_store_dwordx4 v102, v[66:69], s[22:23]
	v_pk_mul_f32 v[102:103], v[180:181], v[66:67]
	v_pk_fma_f32 v[70:71], v[54:55], v[70:71], v[98:99]
	v_lshlrev_b32_e32 v98, 2, v100
	v_pk_mul_f32 v[114:115], v[178:179], v[68:69]
	v_cvt_pk_bf16_f32 v102, v102, v103
	s_nop 0
	v_cvt_pk_bf16_f32 v103, v114, v115
	global_store_dwordx4 v98, v[70:73], s[22:23]
	v_pk_mul_f32 v[98:99], v[180:181], v[70:71]
	v_pk_mul_f32 v[114:115], v[178:179], v[72:73]
	v_cvt_pk_bf16_f32 v98, v98, v99
	s_nop 0
	v_cvt_pk_bf16_f32 v99, v114, v115
	ds_write_b128 v200, v[62:65]
	ds_write_b128 v200, v[58:61] offset:64
	ds_read_b128 v[58:61], v201
	ds_read_b128 v[62:65], v201 offset:1152
	v_lshl_add_u64 v[114:115], s[22:23], 0, v[122:123]
	s_waitcnt vmcnt(13) lgkmcnt(1)
	v_pk_fma_f32 v[58:59], v[50:51], v[58:59], v[94:95]
	v_pk_fma_f32 v[60:61], v[52:53], v[60:61], v[96:97]
	v_pk_mul_f32 v[96:97], v[176:177], v[58:59]
	global_store_dwordx4 v[112:113], v[58:61], off
	v_pk_mul_f32 v[94:95], v[174:175], v[60:61]
	v_cvt_pk_bf16_f32 v96, v96, v97
	s_waitcnt vmcnt(13) lgkmcnt(0)
	v_pk_fma_f32 v[62:63], v[50:51], v[62:63], v[90:91]
	v_cvt_pk_bf16_f32 v97, v94, v95
	ds_bpermute_b32 v90, v203, v96
	ds_bpermute_b32 v91, v203, v97
	v_pk_fma_f32 v[64:65], v[52:53], v[64:65], v[92:93]
	v_pk_mul_f32 v[92:93], v[176:177], v[62:63]
	v_pk_mul_f32 v[94:95], v[174:175], v[64:65]
	global_store_dwordx4 v[114:115], v[62:65], off
	v_cvt_pk_bf16_f32 v92, v92, v93
	v_cvt_pk_bf16_f32 v93, v94, v95
	v_lshlrev_b32_e32 v94, 1, v104
	s_waitcnt lgkmcnt(0)
	v_add_u32_e32 v250, 0xfffff040, v94
	v_cndmask_b32_e64 v250, v94, v250, s[38:39]
	v_cndmask_b32_e64 v248, v102, v90, s[38:39]
	v_cndmask_b32_e64 v249, v103, v91, s[38:39]
	global_store_dwordx2 v250, v[248:249], s[20:21]
	v_cndmask_b32_e64 v246, v90, v102, s[38:39]
	v_cndmask_b32_e64 v247, v91, v103, s[38:39]
	s_waitcnt lgkmcnt(1)
	v_add_u32_e32 v90, 0x1040, v94
	v_cndmask_b32_e64 v90, v94, v90, s[36:37]
	global_store_dwordx2 v90, v[246:247], s[20:21]
	ds_bpermute_b32 v90, v203, v92
	s_waitcnt lgkmcnt(1)
	ds_bpermute_b32 v91, v203, v93
	v_lshlrev_b32_e32 v92, 1, v100
	s_waitcnt lgkmcnt(0)
	v_add_u32_e32 v250, 0xfffff040, v92
	v_cndmask_b32_e64 v250, v92, v250, s[38:39]
	v_cndmask_b32_e64 v248, v98, v90, s[38:39]
	v_cndmask_b32_e64 v249, v99, v91, s[38:39]
	global_store_dwordx2 v250, v[248:249], s[20:21]
	v_cndmask_b32_e64 v246, v90, v98, s[38:39]
	v_cndmask_b32_e64 v247, v91, v99, s[38:39]
	v_mul_f32_e32 v59, v59, v59
	v_fmac_f32_e32 v59, v58, v58
	v_mul_f32_e32 v58, v61, v61
	v_mul_f32_e32 v69, v69, v69
	v_fmac_f32_e32 v58, v60, v60
	v_mul_f32_e32 v67, v67, v67
	v_fmac_f32_e32 v69, v68, v68
	v_mul_f32_e32 v68, v71, v71
	v_mul_f32_e32 v71, v73, v73
	v_add_f32_e32 v58, v59, v58
	v_mul_f32_e32 v59, v63, v63
	v_mul_f32_e32 v60, v65, v65
	v_fmac_f32_e32 v71, v72, v72
	v_fmac_f32_e32 v59, v62, v62
	v_fmac_f32_e32 v60, v64, v64
	v_fmac_f32_e32 v67, v66, v66
	v_fmac_f32_e32 v68, v70, v70
	v_add_f32_e32 v59, v59, v60
	v_add_f32_e32 v60, v67, v69
	v_add_f32_e32 v61, v68, v71
	v_add_f32_e32 v58, v60, v58
	v_add_f32_e32 v59, v61, v59
	ds_bpermute_b32 v60, v190, v58
	ds_bpermute_b32 v61, v190, v59
	s_waitcnt lgkmcnt(1)
	v_add_f32_e32 v58, v58, v60
	s_waitcnt lgkmcnt(0)
	v_add_f32_e32 v61, v59, v61
	ds_bpermute_b32 v60, v191, v58
	ds_bpermute_b32 v62, v191, v61
	s_waitcnt lgkmcnt(1)
	v_add_f32_e32 v58, v58, v60
	s_waitcnt lgkmcnt(0)
	v_add_f32_e32 v60, v61, v62
	ds_bpermute_b32 v59, v204, v58
	ds_bpermute_b32 v61, v204, v60
	v_add_u32_e32 v62, 0x1040, v92
	v_cndmask_b32_e64 v62, v92, v62, s[36:37]
	global_store_dwordx2 v62, v[246:247], s[20:21]
	s_and_saveexec_b64 s[24:25], s[40:41]
	s_cbranch_execz .LBB0_2819
	s_waitcnt lgkmcnt(1)
	v_add_f32_e32 v58, v58, v59
	s_waitcnt lgkmcnt(0)
	v_add_f32_e32 v59, v60, v61
	ds_write2_b32 v194, v58, v59 offset0:64 offset1:72
; #define LAS __attribute__((address_space(3)))
; #define ERN_EOFF(q, m) (eb + (unsigned)((((q) & 1) * HALF + (m) * 16) * DM + ERN_COL((q) >> 1)))
;     __device__ __forceinline__ void operator()(const f32x4 (&acc)[2][2][4][2], const Unit& u, int wr, int wc, int fr, int fq) const {
;     ...
;         for (int g = 0; g < 8; ++g) { const int ai = g >> 2, m = g & 3;
;             if (g + 1 < 8) ERN_LOADX(g + 1);
;             float sq0 = 0.f, sq1 = 0.f; u32x2 hw[2][2];
; #pragma unroll
;             for (int bj = 0; bj < 2; ++bj) {
;                 *(LAS f32x4*)(st + wr_off) = acc[ai][bj][m][0]; *(LAS f32x4*)(st + wr_off + 64) = acc[ai][bj][m][1];
;                 const f32x4 a0 = *(const LAS f32x4*)(st + rd_off), a1 = *(const LAS f32x4*)(st + rd_off + 8 * 144);
;                 { const f32x4 xv = xb[g & 1][bj][0] + gv[bj] * a0; __builtin_nontemporal_store(xv, (f32x4*)((char*)xo + 4u * ERN_EOFF(g, bj, 0)));
;                   sq0 += (xv.x * xv.x + xv.y * xv.y) + (xv.z * xv.z + xv.w * xv.w);
;                   const f32x4 hv = xv * gsn[bj]; hw[bj][0].x = cvt_pk_bf16(hv.x, hv.y); hw[bj][0].y = cvt_pk_bf16(hv.z, hv.w); }
;                 { const f32x4 xv = xb[g & 1][bj][1] + gv[bj] * a1; __builtin_nontemporal_store(xv, (f32x4*)((char*)xo + 4u * ERN_EOFF(g, bj, 1)));
;                   sq1 += (xv.x * xv.x + xv.y * xv.y) + (xv.z * xv.z + xv.w * xv.w);
;                   const f32x4 hv = xv * gsn[bj]; hw[bj][1].x = cvt_pk_bf16(hv.x, hv.y); hw[bj][1].y = cvt_pk_bf16(hv.z, hv.w); }
;             }
;             if (!NOH && !PLAIN) {
; #pragma unroll
;                 for (int rh = 0; rh < 2; ++rh) { u32x2 rv; rv.x = __shfl_xor(hw[1][rh].x, 8); rv.y = __shfl_xor(hw[1][rh].y, 8);
;                     const unsigned e0 = ERN_EOFF(g, 0, rh);
;                     const unsigned ee = odd ? (e0 - DM + 32) : e0, eo2 = odd ? e0 : (e0 + DM + 32);
;                     *(u32x2*)((char*)ho + 2u * ee) = odd ? rv : hw[0][rh];
;                     *(u32x2*)((char*)ho + 2u * eo2) = odd ? hw[0][rh] : rv; }
;             }
;             if (!PLAIN) { sq0 += __shfl_xor(sq0, 1); sq0 += __shfl_xor(sq0, 2); sq0 += __shfl_xor(sq0, 4);
;             sq1 += __shfl_xor(sq1, 1); sq1 += __shfl_xor(sq1, 2); sq1 += __shfl_xor(sq1, 4); }
;             if (!PLAIN && pc == 0) { sst[g * 16 + rr] = sq0; sst[g * 16 + 8 + rr] = sq1; }
.LBB0_2819:
	s_or_b64 exec, exec, s[24:25]
	v_lshl_add_u64 v[96:97], s[22:23], 0, v[162:163]
	v_add_u32_e32 v162, 0x140000, v205
	v_add_u32_e32 v92, 0x140080, v205
	v_add_u32_e32 v94, 0x150000, v205
	global_load_dwordx4 v[70:73], v162, s[22:23]
	global_load_dwordx4 v[66:69], v94, s[22:23]
	v_add_u32_e32 v90, 0x150080, v205
	global_load_dwordx4 v[62:65], v92, s[22:23]
	s_waitcnt lgkmcnt(0)
	global_load_dwordx4 v[58:61], v90, s[22:23]
	ds_write_b128 v200, v[46:49]
	ds_write_b128 v200, v[42:45] offset:64
	ds_read_b128 v[42:45], v201
	ds_read_b128 v[46:49], v201 offset:1152
	v_mov_b32_e32 v111, v163
	v_lshl_add_u64 v[98:99], s[22:23], 0, v[110:111]
	v_mov_b32_e32 v109, v163
	s_waitcnt vmcnt(13) lgkmcnt(1)
	v_pk_fma_f32 v[42:43], v[54:55], v[42:43], v[86:87]
	s_waitcnt vmcnt(12) lgkmcnt(0)
	v_pk_fma_f32 v[46:47], v[54:55], v[46:47], v[82:83]
	v_pk_fma_f32 v[44:45], v[56:57], v[44:45], v[88:89]
	v_pk_mul_f32 v[86:87], v[180:181], v[42:43]
	v_pk_fma_f32 v[48:49], v[56:57], v[48:49], v[84:85]
	v_pk_mul_f32 v[82:83], v[180:181], v[46:47]
	global_store_dwordx4 v[96:97], v[42:45], off
	v_pk_mul_f32 v[88:89], v[178:179], v[44:45]
	v_cvt_pk_bf16_f32 v86, v86, v87
	v_pk_mul_f32 v[84:85], v[178:179], v[48:49]
	v_cvt_pk_bf16_f32 v87, v88, v89
	global_store_dwordx4 v[98:99], v[46:49], off
	v_cvt_pk_bf16_f32 v82, v82, v83
	v_cvt_pk_bf16_f32 v83, v84, v85
	ds_write_b128 v200, v[38:41]
	ds_write_b128 v200, v[34:37] offset:64
	ds_read_b128 v[34:37], v201
	ds_read_b128 v[38:41], v201 offset:1152
	v_lshl_add_u64 v[84:85], s[22:23], 0, v[108:109]
	v_mov_b32_e32 v107, v163
	v_lshl_add_u64 v[88:89], s[22:23], 0, v[106:107]
	s_waitcnt vmcnt(13) lgkmcnt(1)
	v_pk_fma_f32 v[34:35], v[50:51], v[34:35], v[78:79]
	v_pk_fma_f32 v[36:37], v[52:53], v[36:37], v[80:81]
	v_pk_mul_f32 v[80:81], v[176:177], v[34:35]
	global_store_dwordx4 v[84:85], v[34:37], off
	v_pk_mul_f32 v[78:79], v[174:175], v[36:37]
	v_cvt_pk_bf16_f32 v80, v80, v81
	s_waitcnt vmcnt(13) lgkmcnt(0)
	v_pk_fma_f32 v[38:39], v[50:51], v[38:39], v[74:75]
	v_cvt_pk_bf16_f32 v81, v78, v79
	ds_bpermute_b32 v74, v203, v80
	ds_bpermute_b32 v75, v203, v81
	v_pk_fma_f32 v[40:41], v[52:53], v[40:41], v[76:77]
	v_pk_mul_f32 v[76:77], v[176:177], v[38:39]
	v_pk_mul_f32 v[78:79], v[174:175], v[40:41]
	global_store_dwordx4 v[88:89], v[38:41], off
	v_cvt_pk_bf16_f32 v76, v76, v77
	v_cvt_pk_bf16_f32 v77, v78, v79
	v_add_u32_e32 v79, 0x48000, v202
	v_lshlrev_b32_e32 v78, 1, v79
	s_waitcnt lgkmcnt(0)
	v_add_u32_e32 v250, 0xfffff040, v78
	v_cndmask_b32_e64 v250, v78, v250, s[38:39]
	v_cndmask_b32_e64 v248, v86, v74, s[38:39]
	v_cndmask_b32_e64 v249, v87, v75, s[38:39]
	global_store_dwordx2 v250, v[248:249], s[20:21]
	v_cndmask_b32_e64 v246, v74, v86, s[38:39]
	v_cndmask_b32_e64 v247, v75, v87, s[38:39]
	s_waitcnt lgkmcnt(1)
	v_add_u32_e32 v74, 0x1040, v78
	v_cndmask_b32_e64 v74, v78, v74, s[36:37]
	global_store_dwordx2 v74, v[246:247], s[20:21]
	ds_bpermute_b32 v74, v203, v76
	s_waitcnt lgkmcnt(1)
	ds_bpermute_b32 v75, v203, v77
	v_add_u32_e32 v77, 0x4c000, v202
	v_lshlrev_b32_e32 v76, 1, v77
	s_waitcnt lgkmcnt(0)
	v_add_u32_e32 v250, 0xfffff040, v76
	v_cndmask_b32_e64 v250, v76, v250, s[38:39]
	v_cndmask_b32_e64 v248, v82, v74, s[38:39]
	v_cndmask_b32_e64 v249, v83, v75, s[38:39]
	global_store_dwordx2 v250, v[248:249], s[20:21]
	v_cndmask_b32_e64 v246, v74, v82, s[38:39]
	v_cndmask_b32_e64 v247, v75, v83, s[38:39]
	v_mul_f32_e32 v35, v35, v35
	v_fmac_f32_e32 v35, v34, v34
	v_mul_f32_e32 v34, v37, v37
	v_mul_f32_e32 v45, v45, v45
	v_fmac_f32_e32 v34, v36, v36
	v_mul_f32_e32 v43, v43, v43
	v_fmac_f32_e32 v45, v44, v44
	v_mul_f32_e32 v44, v47, v47
	v_mul_f32_e32 v47, v49, v49
	v_add_f32_e32 v34, v35, v34
	v_mul_f32_e32 v35, v39, v39
	v_mul_f32_e32 v36, v41, v41
	v_fmac_f32_e32 v47, v48, v48
	v_fmac_f32_e32 v35, v38, v38
	v_fmac_f32_e32 v36, v40, v40
	v_fmac_f32_e32 v43, v42, v42
	v_fmac_f32_e32 v44, v46, v46
	v_add_f32_e32 v35, v35, v36
	v_add_f32_e32 v36, v43, v45
	v_add_f32_e32 v37, v44, v47
	v_add_f32_e32 v34, v36, v34
	v_add_f32_e32 v35, v37, v35
	ds_bpermute_b32 v36, v190, v34
	ds_bpermute_b32 v37, v190, v35
	s_waitcnt lgkmcnt(1)
	v_add_f32_e32 v34, v34, v36
	s_waitcnt lgkmcnt(0)
	v_add_f32_e32 v37, v35, v37
	ds_bpermute_b32 v36, v191, v34
	ds_bpermute_b32 v38, v191, v37
	s_waitcnt lgkmcnt(1)
	v_add_f32_e32 v34, v34, v36
	s_waitcnt lgkmcnt(0)
	v_add_f32_e32 v36, v37, v38
	ds_bpermute_b32 v35, v204, v34
	ds_bpermute_b32 v37, v204, v36
	v_add_u32_e32 v38, 0x1040, v76
	v_cndmask_b32_e64 v38, v76, v38, s[36:37]
	global_store_dwordx2 v38, v[246:247], s[20:21]
	s_and_saveexec_b64 s[24:25], s[40:41]
	s_cbranch_execz .LBB0_2829
	s_waitcnt lgkmcnt(1)
	v_add_f32_e32 v34, v34, v35
	s_waitcnt lgkmcnt(0)
	v_add_f32_e32 v35, v36, v37
	ds_write2_b32 v194, v34, v35 offset0:80 offset1:88
; #define LAS __attribute__((address_space(3)))
; #define ERN_EOFF(q, m) (eb + (unsigned)((((q) & 1) * HALF + (m) * 16) * DM + ERN_COL((q) >> 1)))
;     __device__ __forceinline__ void operator()(const f32x4 (&acc)[2][2][4][2], const Unit& u, int wr, int wc, int fr, int fq) const {
;     ...
;         for (int g = 0; g < 8; ++g) { const int ai = g >> 2, m = g & 3;
;             if (g + 1 < 8) ERN_LOADX(g + 1);
;             float sq0 = 0.f, sq1 = 0.f; u32x2 hw[2][2];
; #pragma unroll
;             for (int bj = 0; bj < 2; ++bj) {
;                 *(LAS f32x4*)(st + wr_off) = acc[ai][bj][m][0]; *(LAS f32x4*)(st + wr_off + 64) = acc[ai][bj][m][1];
;                 const f32x4 a0 = *(const LAS f32x4*)(st + rd_off), a1 = *(const LAS f32x4*)(st + rd_off + 8 * 144);
;                 { const f32x4 xv = xb[g & 1][bj][0] + gv[bj] * a0; __builtin_nontemporal_store(xv, (f32x4*)((char*)xo + 4u * ERN_EOFF(g, bj, 0)));
;                   sq0 += (xv.x * xv.x + xv.y * xv.y) + (xv.z * xv.z + xv.w * xv.w);
;                   const f32x4 hv = xv * gsn[bj]; hw[bj][0].x = cvt_pk_bf16(hv.x, hv.y); hw[bj][0].y = cvt_pk_bf16(hv.z, hv.w); }
;                 { const f32x4 xv = xb[g & 1][bj][1] + gv[bj] * a1; __builtin_nontemporal_store(xv, (f32x4*)((char*)xo + 4u * ERN_EOFF(g, bj, 1)));
;                   sq1 += (xv.x * xv.x + xv.y * xv.y) + (xv.z * xv.z + xv.w * xv.w);
;                   const f32x4 hv = xv * gsn[bj]; hw[bj][1].x = cvt_pk_bf16(hv.x, hv.y); hw[bj][1].y = cvt_pk_bf16(hv.z, hv.w); }
;             }
;             if (!NOH && !PLAIN) {
; #pragma unroll
;                 for (int rh = 0; rh < 2; ++rh) { u32x2 rv; rv.x = __shfl_xor(hw[1][rh].x, 8); rv.y = __shfl_xor(hw[1][rh].y, 8);
;                     const unsigned e0 = ERN_EOFF(g, 0, rh);
;                     const unsigned ee = odd ? (e0 - DM + 32) : e0, eo2 = odd ? e0 : (e0 + DM + 32);
;                     *(u32x2*)((char*)ho + 2u * ee) = odd ? rv : hw[0][rh];
;                     *(u32x2*)((char*)ho + 2u * eo2) = odd ? hw[0][rh] : rv; }
;             }
;             if (!PLAIN) { sq0 += __shfl_xor(sq0, 1); sq0 += __shfl_xor(sq0, 2); sq0 += __shfl_xor(sq0, 4);
;             sq1 += __shfl_xor(sq1, 1); sq1 += __shfl_xor(sq1, 2); sq1 += __shfl_xor(sq1, 4); }
;             if (!PLAIN && pc == 0) { sst[g * 16 + rr] = sq0; sst[g * 16 + 8 + rr] = sq1; }
.LBB0_2829:
	s_or_b64 exec, exec, s[24:25]
	v_lshl_add_u64 v[80:81], s[22:23], 0, v[162:163]
	v_add_u32_e32 v162, 0x160000, v205
	v_add_u32_e32 v76, 0x160080, v205
	v_add_u32_e32 v78, 0x170000, v205
	global_load_dwordx4 v[46:49], v162, s[22:23]
	global_load_dwordx4 v[42:45], v78, s[22:23]
	v_add_u32_e32 v74, 0x170080, v205
	global_load_dwordx4 v[38:41], v76, s[22:23]
	s_waitcnt lgkmcnt(0)
	global_load_dwordx4 v[34:37], v74, s[22:23]
	ds_write_b128 v200, v[30:33]
	ds_write_b128 v200, v[26:29] offset:64
	ds_read_b128 v[26:29], v201
	ds_read_b128 v[30:33], v201 offset:1152
	v_mov_b32_e32 v95, v163
	v_lshl_add_u64 v[82:83], s[22:23], 0, v[94:95]
	v_mov_b32_e32 v93, v163
	s_waitcnt vmcnt(13) lgkmcnt(1)
	v_pk_fma_f32 v[26:27], v[54:55], v[26:27], v[70:71]
	s_waitcnt vmcnt(12) lgkmcnt(0)
	v_pk_fma_f32 v[30:31], v[54:55], v[30:31], v[66:67]
	v_pk_fma_f32 v[28:29], v[56:57], v[28:29], v[72:73]
	v_pk_mul_f32 v[70:71], v[180:181], v[26:27]
	v_pk_fma_f32 v[32:33], v[56:57], v[32:33], v[68:69]
	v_pk_mul_f32 v[66:67], v[180:181], v[30:31]
	global_store_dwordx4 v[80:81], v[26:29], off
	v_pk_mul_f32 v[72:73], v[178:179], v[28:29]
	v_cvt_pk_bf16_f32 v70, v70, v71
	v_pk_mul_f32 v[68:69], v[178:179], v[32:33]
	v_cvt_pk_bf16_f32 v71, v72, v73
	global_store_dwordx4 v[82:83], v[30:33], off
	v_cvt_pk_bf16_f32 v66, v66, v67
	v_cvt_pk_bf16_f32 v67, v68, v69
	ds_write_b128 v200, v[22:25]
	ds_write_b128 v200, v[18:21] offset:64
	ds_read_b128 v[18:21], v201
	ds_read_b128 v[22:25], v201 offset:1152
	v_lshl_add_u64 v[68:69], s[22:23], 0, v[92:93]
	v_mov_b32_e32 v91, v163
	v_lshl_add_u64 v[72:73], s[22:23], 0, v[90:91]
	s_waitcnt vmcnt(13) lgkmcnt(1)
	v_pk_fma_f32 v[18:19], v[50:51], v[18:19], v[62:63]
	v_pk_fma_f32 v[20:21], v[52:53], v[20:21], v[64:65]
	v_pk_mul_f32 v[64:65], v[176:177], v[18:19]
	global_store_dwordx4 v[68:69], v[18:21], off
	v_pk_mul_f32 v[62:63], v[174:175], v[20:21]
	v_cvt_pk_bf16_f32 v64, v64, v65
	s_waitcnt vmcnt(13) lgkmcnt(0)
	v_pk_fma_f32 v[22:23], v[50:51], v[22:23], v[58:59]
	v_cvt_pk_bf16_f32 v65, v62, v63
	ds_bpermute_b32 v58, v203, v64
	ds_bpermute_b32 v59, v203, v65
	v_pk_fma_f32 v[24:25], v[52:53], v[24:25], v[60:61]
	v_pk_mul_f32 v[60:61], v[176:177], v[22:23]
	v_pk_mul_f32 v[62:63], v[174:175], v[24:25]
	global_store_dwordx4 v[72:73], v[22:25], off
	v_cvt_pk_bf16_f32 v60, v60, v61
	v_cvt_pk_bf16_f32 v61, v62, v63
	v_add_u32_e32 v63, 0x50000, v202
	v_lshlrev_b32_e32 v62, 1, v63
	s_waitcnt lgkmcnt(0)
	v_add_u32_e32 v250, 0xfffff040, v62
	v_cndmask_b32_e64 v250, v62, v250, s[38:39]
	v_cndmask_b32_e64 v248, v70, v58, s[38:39]
	v_cndmask_b32_e64 v249, v71, v59, s[38:39]
	global_store_dwordx2 v250, v[248:249], s[20:21]
	v_cndmask_b32_e64 v246, v58, v70, s[38:39]
	v_cndmask_b32_e64 v247, v59, v71, s[38:39]
	s_waitcnt lgkmcnt(1)
	v_add_u32_e32 v58, 0x1040, v62
	v_cndmask_b32_e64 v58, v62, v58, s[36:37]
	global_store_dwordx2 v58, v[246:247], s[20:21]
	ds_bpermute_b32 v58, v203, v60
	s_waitcnt lgkmcnt(1)
	ds_bpermute_b32 v59, v203, v61
	v_add_u32_e32 v61, 0x54000, v202
	v_lshlrev_b32_e32 v60, 1, v61
	s_waitcnt lgkmcnt(0)
	v_add_u32_e32 v250, 0xfffff040, v60
	v_cndmask_b32_e64 v250, v60, v250, s[38:39]
	v_cndmask_b32_e64 v248, v66, v58, s[38:39]
	v_cndmask_b32_e64 v249, v67, v59, s[38:39]
	global_store_dwordx2 v250, v[248:249], s[20:21]
	v_cndmask_b32_e64 v246, v58, v66, s[38:39]
	v_cndmask_b32_e64 v247, v59, v67, s[38:39]
	v_mul_f32_e32 v19, v19, v19
	v_fmac_f32_e32 v19, v18, v18
	v_mul_f32_e32 v18, v21, v21
	v_mul_f32_e32 v29, v29, v29
	v_fmac_f32_e32 v18, v20, v20
	v_mul_f32_e32 v27, v27, v27
	v_fmac_f32_e32 v29, v28, v28
	v_mul_f32_e32 v28, v31, v31
	v_mul_f32_e32 v31, v33, v33
	v_add_f32_e32 v18, v19, v18
	v_mul_f32_e32 v19, v23, v23
	v_mul_f32_e32 v20, v25, v25
	v_fmac_f32_e32 v31, v32, v32
	v_fmac_f32_e32 v19, v22, v22
	v_fmac_f32_e32 v20, v24, v24
	v_fmac_f32_e32 v27, v26, v26
	v_fmac_f32_e32 v28, v30, v30
	v_add_f32_e32 v19, v19, v20
	v_add_f32_e32 v20, v27, v29
	v_add_f32_e32 v21, v28, v31
	v_add_f32_e32 v18, v20, v18
	v_add_f32_e32 v19, v21, v19
	ds_bpermute_b32 v20, v190, v18
	ds_bpermute_b32 v21, v190, v19
	s_waitcnt lgkmcnt(1)
	v_add_f32_e32 v18, v18, v20
	s_waitcnt lgkmcnt(0)
	v_add_f32_e32 v21, v19, v21
	ds_bpermute_b32 v20, v191, v18
	ds_bpermute_b32 v22, v191, v21
	s_waitcnt lgkmcnt(1)
	v_add_f32_e32 v18, v18, v20
	s_waitcnt lgkmcnt(0)
	v_add_f32_e32 v20, v21, v22
	ds_bpermute_b32 v19, v204, v18
	ds_bpermute_b32 v21, v204, v20
	v_add_u32_e32 v22, 0x1040, v60
	v_cndmask_b32_e64 v22, v60, v22, s[36:37]
	global_store_dwordx2 v22, v[246:247], s[20:21]
	s_and_saveexec_b64 s[24:25], s[40:41]
	s_cbranch_execz .LBB0_2839
	s_waitcnt lgkmcnt(1)
	v_add_f32_e32 v18, v18, v19
	s_waitcnt lgkmcnt(0)
	v_add_f32_e32 v19, v20, v21
	ds_write2_b32 v194, v18, v19 offset0:96 offset1:104
; #define LAS __attribute__((address_space(3)))
; #define ERN_EOFF(q, m) (eb + (unsigned)((((q) & 1) * HALF + (m) * 16) * DM + ERN_COL((q) >> 1)))
;     __device__ __forceinline__ void operator()(const f32x4 (&acc)[2][2][4][2], const Unit& u, int wr, int wc, int fr, int fq) const {
;     ...
;         for (int g = 0; g < 8; ++g) { const int ai = g >> 2, m = g & 3;
;             if (g + 1 < 8) ERN_LOADX(g + 1);
;             float sq0 = 0.f, sq1 = 0.f; u32x2 hw[2][2];
; #pragma unroll
;             for (int bj = 0; bj < 2; ++bj) {
;                 *(LAS f32x4*)(st + wr_off) = acc[ai][bj][m][0]; *(LAS f32x4*)(st + wr_off + 64) = acc[ai][bj][m][1];
;                 const f32x4 a0 = *(const LAS f32x4*)(st + rd_off), a1 = *(const LAS f32x4*)(st + rd_off + 8 * 144);
;                 { const f32x4 xv = xb[g & 1][bj][0] + gv[bj] * a0; __builtin_nontemporal_store(xv, (f32x4*)((char*)xo + 4u * ERN_EOFF(g, bj, 0)));
;                   sq0 += (xv.x * xv.x + xv.y * xv.y) + (xv.z * xv.z + xv.w * xv.w);
;                   const f32x4 hv = xv * gsn[bj]; hw[bj][0].x = cvt_pk_bf16(hv.x, hv.y); hw[bj][0].y = cvt_pk_bf16(hv.z, hv.w); }
;                 { const f32x4 xv = xb[g & 1][bj][1] + gv[bj] * a1; __builtin_nontemporal_store(xv, (f32x4*)((char*)xo + 4u * ERN_EOFF(g, bj, 1)));
;                   sq1 += (xv.x * xv.x + xv.y * xv.y) + (xv.z * xv.z + xv.w * xv.w);
;                   const f32x4 hv = xv * gsn[bj]; hw[bj][1].x = cvt_pk_bf16(hv.x, hv.y); hw[bj][1].y = cvt_pk_bf16(hv.z, hv.w); }
;             }
;             if (!NOH && !PLAIN) {
; #pragma unroll
;                 for (int rh = 0; rh < 2; ++rh) { u32x2 rv; rv.x = __shfl_xor(hw[1][rh].x, 8); rv.y = __shfl_xor(hw[1][rh].y, 8);
;                     const unsigned e0 = ERN_EOFF(g, 0, rh);
;                     const unsigned ee = odd ? (e0 - DM + 32) : e0, eo2 = odd ? e0 : (e0 + DM + 32);
;                     *(u32x2*)((char*)ho + 2u * ee) = odd ? rv : hw[0][rh];
;                     *(u32x2*)((char*)ho + 2u * eo2) = odd ? hw[0][rh] : rv; }
;             }
;             if (!PLAIN) { sq0 += __shfl_xor(sq0, 1); sq0 += __shfl_xor(sq0, 2); sq0 += __shfl_xor(sq0, 4);
;             sq1 += __shfl_xor(sq1, 1); sq1 += __shfl_xor(sq1, 2); sq1 += __shfl_xor(sq1, 4); }
;             if (!PLAIN && pc == 0) { sst[g * 16 + rr] = sq0; sst[g * 16 + 8 + rr] = sq1; }
.LBB0_2839:
	s_or_b64 exec, exec, s[24:25]
	ds_write_b128 v200, v[14:17]
	ds_write_b128 v200, v[10:13] offset:64
	ds_read_b128 v[10:13], v201
	ds_read_b128 v[14:17], v201 offset:1152
	s_waitcnt lgkmcnt(5)
	v_lshl_add_u64 v[18:19], s[22:23], 0, v[162:163]
	v_mov_b32_e32 v79, v163
	v_lshl_add_u64 v[22:23], s[22:23], 0, v[78:79]
	s_waitcnt vmcnt(9) lgkmcnt(1)
	v_pk_fma_f32 v[12:13], v[56:57], v[12:13], v[48:49]
	v_pk_fma_f32 v[10:11], v[54:55], v[10:11], v[46:47]
	global_store_dwordx4 v[18:19], v[10:13], off
	v_pk_mul_f32 v[18:19], v[178:179], v[12:13]
	v_pk_mul_f32 v[20:21], v[180:181], v[10:11]
	s_waitcnt vmcnt(9) lgkmcnt(0)
	v_pk_fma_f32 v[14:15], v[54:55], v[14:15], v[42:43]
	v_cvt_pk_bf16_f32 v20, v20, v21
	v_cvt_pk_bf16_f32 v21, v18, v19
	v_pk_fma_f32 v[16:17], v[56:57], v[16:17], v[44:45]
	v_pk_mul_f32 v[18:19], v[180:181], v[14:15]
	global_store_dwordx4 v[22:23], v[14:17], off
	v_pk_mul_f32 v[22:23], v[178:179], v[16:17]
	v_cvt_pk_bf16_f32 v18, v18, v19
	v_mov_b32_e32 v77, v163
	v_cvt_pk_bf16_f32 v19, v22, v23
	ds_write_b128 v200, v[6:9]
	ds_write_b128 v200, v[2:5] offset:64
	ds_read_b128 v[2:5], v201
	ds_read_b128 v[6:9], v201 offset:1152
	v_lshl_add_u64 v[22:23], s[22:23], 0, v[76:77]
	v_mov_b32_e32 v75, v163
	v_lshl_add_u64 v[24:25], s[22:23], 0, v[74:75]
	s_waitcnt vmcnt(9) lgkmcnt(1)
	v_pk_fma_f32 v[4:5], v[52:53], v[4:5], v[40:41]
	v_pk_fma_f32 v[2:3], v[50:51], v[2:3], v[38:39]
	global_store_dwordx4 v[22:23], v[2:5], off
	v_pk_mul_f32 v[22:23], v[174:175], v[4:5]
	v_pk_mul_f32 v[26:27], v[176:177], v[2:3]
	s_waitcnt vmcnt(9) lgkmcnt(0)
	v_pk_fma_f32 v[8:9], v[52:53], v[8:9], v[36:37]
	v_cvt_pk_bf16_f32 v28, v26, v27
	v_cvt_pk_bf16_f32 v23, v22, v23
	ds_bpermute_b32 v22, v203, v28
	ds_bpermute_b32 v23, v203, v23
	v_pk_fma_f32 v[6:7], v[50:51], v[6:7], v[34:35]
	global_store_dwordx4 v[24:25], v[6:9], off
	v_pk_mul_f32 v[26:27], v[174:175], v[8:9]
	v_pk_mul_f32 v[24:25], v[176:177], v[6:7]
	s_nop 0
	v_cvt_pk_bf16_f32 v24, v24, v25
	v_cvt_pk_bf16_f32 v25, v26, v27
	v_add_u32_e32 v27, 0x58000, v202
	v_lshlrev_b32_e32 v26, 1, v27
	s_waitcnt lgkmcnt(0)
	v_add_u32_e32 v250, 0xfffff040, v26
	v_cndmask_b32_e64 v250, v26, v250, s[38:39]
	v_cndmask_b32_e64 v248, v20, v22, s[38:39]
	v_cndmask_b32_e64 v249, v21, v23, s[38:39]
	global_store_dwordx2 v250, v[248:249], s[20:21]
	v_cndmask_b32_e64 v246, v22, v20, s[38:39]
	v_cndmask_b32_e64 v247, v23, v21, s[38:39]
	s_waitcnt lgkmcnt(1)
	v_add_u32_e32 v22, 0x1040, v26
	v_cndmask_b32_e64 v22, v26, v22, s[36:37]
	global_store_dwordx2 v22, v[246:247], s[20:21]
	ds_bpermute_b32 v20, v203, v24
	ds_bpermute_b32 v21, v203, v25
	s_waitcnt lgkmcnt(2)
	v_add_u32_e32 v23, 0x5c000, v202
	v_lshlrev_b32_e32 v22, 1, v23
	s_waitcnt lgkmcnt(0)
	v_add_u32_e32 v250, 0xfffff040, v22
	v_cndmask_b32_e64 v250, v22, v250, s[38:39]
	v_cndmask_b32_e64 v248, v18, v20, s[38:39]
	v_cndmask_b32_e64 v249, v19, v21, s[38:39]
	global_store_dwordx2 v250, v[248:249], s[20:21]
	v_cndmask_b32_e64 v246, v20, v18, s[38:39]
	v_cndmask_b32_e64 v247, v21, v19, s[38:39]
	v_mul_f32_e32 v3, v3, v3
	v_fmac_f32_e32 v3, v2, v2
	v_mul_f32_e32 v2, v5, v5
	v_mul_f32_e32 v13, v13, v13
	v_fmac_f32_e32 v2, v4, v4
	v_mul_f32_e32 v11, v11, v11
	v_fmac_f32_e32 v13, v12, v12
	v_mul_f32_e32 v12, v15, v15
	v_mul_f32_e32 v15, v17, v17
	v_add_f32_e32 v2, v3, v2
	v_mul_f32_e32 v3, v7, v7
	v_mul_f32_e32 v4, v9, v9
	v_fmac_f32_e32 v15, v16, v16
	v_fmac_f32_e32 v3, v6, v6
	v_fmac_f32_e32 v4, v8, v8
	v_fmac_f32_e32 v11, v10, v10
	v_fmac_f32_e32 v12, v14, v14
	v_add_f32_e32 v3, v3, v4
	v_add_f32_e32 v4, v11, v13
	v_add_f32_e32 v5, v12, v15
	v_add_f32_e32 v2, v4, v2
	v_add_f32_e32 v3, v5, v3
	ds_bpermute_b32 v4, v190, v2
	ds_bpermute_b32 v5, v190, v3
	s_waitcnt lgkmcnt(1)
	v_add_f32_e32 v2, v2, v4
	s_waitcnt lgkmcnt(0)
	v_add_f32_e32 v5, v3, v5
	ds_bpermute_b32 v4, v191, v2
	ds_bpermute_b32 v6, v191, v5
	s_waitcnt lgkmcnt(1)
	v_add_f32_e32 v2, v2, v4
	s_waitcnt lgkmcnt(0)
	v_add_f32_e32 v4, v5, v6
	ds_bpermute_b32 v3, v204, v2
	ds_bpermute_b32 v5, v204, v4
	v_add_u32_e32 v6, 0x1040, v22
	v_cndmask_b32_e64 v6, v22, v6, s[36:37]
	global_store_dwordx2 v6, v[246:247], s[20:21]
	s_and_saveexec_b64 s[20:21], s[40:41]
	s_cbranch_execz .LBB0_2849
	s_waitcnt lgkmcnt(1)
	v_add_f32_e32 v2, v2, v3
	s_waitcnt lgkmcnt(0)
	v_add_f32_e32 v3, v4, v5
	ds_write2_b32 v194, v2, v3 offset0:112 offset1:120

; #define LAS __attribute__((address_space(3)))
; __device__ __forceinline__ unsigned cvt_pk_bf16(float lo, float hi) { unsigned r; asm volatile("v_cvt_pk_bf16_f32 %0, %1, %2" : "=v"(r) : "v"(lo), "v"(hi)); return r; }
; #define ERN_EOFF(q, m) (eb + (unsigned)((((q) & 1) * HALF + (m) * 16) * DM + ERN_COL((q) >> 1)))
; #define ERN_LOADX(q) do { _Pragma("unroll") for (int m = 0; m < 4; ++m) xb[(q) & 1][m] = *(const f32x4*)((const char*)xi + 4u * ERN_EOFF(q, m)); } while (0)
;     __device__ __forceinline__ void operator()(const f32x4 (&acc)[2][2][4][2], const Unit& u, int wr, int wc, int fr, int fq) const {
;     ...
;         for (int bj = 0; bj < 2; ++bj) { gv[bj] = *(const f32x4*)(gate + (size_t)s * MODW + colr + bj * 32) * (0.5f * GS2);
;             if (!PLAIN) gsn[bj] = *(const f32x4*)(gnext + colr + bj * 32) * (*(const f32x4*)(scnext + (size_t)s * MODW + colr + bj * 32) + 1.0f); else gsn[bj] = gv[bj]; }
;         const unsigned wr_off = (unsigned)(fr * 144 + 16 * fq), rd_off = (unsigned)(rr * 144 + pc * 16);
;         const bool odd = (rr & 1) != 0;
;         f32x4 xb[2][2][2];
;     ...
;         ERN_LOADX(0);
; #pragma unroll
;         for (int g = 0; g < 8; ++g) { const int ai = g >> 2, m = g & 3;
;             if (g + 1 < 8) ERN_LOADX(g + 1);
;             float sq0 = 0.f, sq1 = 0.f; u32x2 hw[2][2];
; #pragma unroll
;             for (int bj = 0; bj < 2; ++bj) {
;                 *(LAS f32x4*)(st + wr_off) = acc[ai][bj][m][0]; *(LAS f32x4*)(st + wr_off + 64) = acc[ai][bj][m][1];
;                 const f32x4 a0 = *(const LAS f32x4*)(st + rd_off), a1 = *(const LAS f32x4*)(st + rd_off + 8 * 144);
;                 { const f32x4 xv = xb[g & 1][bj][0] + gv[bj] * a0; __builtin_nontemporal_store(xv, (f32x4*)((char*)xo + 4u * ERN_EOFF(g, bj, 0)));
;                   sq0 += (xv.x * xv.x + xv.y * xv.y) + (xv.z * xv.z + xv.w * xv.w);
;                   const f32x4 hv = xv * gsn[bj]; hw[bj][0].x = cvt_pk_bf16(hv.x, hv.y); hw[bj][0].y = cvt_pk_bf16(hv.z, hv.w); }
;                 { const f32x4 xv = xb[g & 1][bj][1] + gv[bj] * a1; __builtin_nontemporal_store(xv, (f32x4*)((char*)xo + 4u * ERN_EOFF(g, bj, 1)));
;                   sq1 += (xv.x * xv.x + xv.y * xv.y) + (xv.z * xv.z + xv.w * xv.w);
;                   const f32x4 hv = xv * gsn[bj]; hw[bj][1].x = cvt_pk_bf16(hv.x, hv.y); hw[bj][1].y = cvt_pk_bf16(hv.z, hv.w); }
;             }
.LBB0_3005:
	s_ashr_i32 s14, s12, 5
	s_ashr_i32 s13, s12, 31
	s_mul_hi_i32 s15, s14, 0x12000
	s_mul_i32 s14, s14, 0x12000
	v_lshl_or_b32 v152, s38, 8, v145
	s_add_u32 s14, s29, s14
	s_addc_u32 s15, s30, s15
	v_ashrrev_i32_e32 v153, 31, v152
	s_lshl_b64 s[12:13], s[12:13], 21
	v_lshl_add_u64 v[166:167], v[152:153], 2, s[14:15]
	s_add_u32 s12, s90, s12
	global_load_dwordx4 v[154:157], v[166:167], off
	s_addc_u32 s13, s91, s13
	v_lshl_add_u32 v152, v152, 2, v146
	global_load_dwordx4 v[158:161], v152, s[12:13]
	v_add_u32_e32 v153, 0x10000, v152
	global_load_dwordx4 v[162:165], v153, s[12:13]
	s_nop 0
	global_load_dwordx4 v[166:169], v[166:167], off offset:128
	s_nop 0
	global_load_dwordx4 v[170:173], v152, s[12:13] offset:128
	v_add_u32_e32 v198, 0x10080, v152
	global_load_dwordx4 v[174:177], v198, s[12:13]
	v_add_u32_e32 v199, 0x20000, v152
	global_load_dwordx4 v[178:181], v199, s[12:13]
	v_add_u32_e32 v200, 0x30000, v152
	global_load_dwordx4 v[182:185], v200, s[12:13]
	v_add_u32_e32 v201, 0x20080, v152
	global_load_dwordx4 v[186:189], v201, s[12:13]
	v_add_u32_e32 v202, 0x30080, v152
	global_load_dwordx4 v[190:193], v202, s[12:13]
	ds_write_b128 v150, v[124:127]
	ds_write_b128 v150, v[120:123] offset:64
	ds_read_b128 v[124:127], v151
	ds_read_b128 v[194:197], v151 offset:1152
	v_add_u32_e32 v203, 0x40000, v152
	v_add_u32_e32 v204, 0x50000, v152
	s_mov_b64 s[14:15], -1
	s_and_b64 vcc, exec, s[0:1]
	s_waitcnt vmcnt(0)
	v_pk_mul_f32 v[120:121], v[156:157], 0.5 op_sel_hi:[1,0]
	v_pk_mul_f32 v[122:123], v[154:155], 0.5 op_sel_hi:[1,0]
	s_waitcnt lgkmcnt(1)
	v_pk_fma_f32 v[126:127], v[120:121], v[126:127], v[160:161]
	v_pk_fma_f32 v[124:125], v[122:123], v[124:125], v[158:159]
	s_waitcnt lgkmcnt(0)
	v_pk_fma_f32 v[156:157], v[120:121], v[196:197], v[164:165]
	v_pk_fma_f32 v[154:155], v[122:123], v[194:195], v[162:163]
	global_store_dwordx4 v152, v[124:127], s[12:13]
	v_pk_mul_f32 v[158:159], v[120:121], v[156:157]
	v_pk_mul_f32 v[160:161], v[122:123], v[154:155]
	v_pk_mul_f32 v[124:125], v[122:123], v[124:125]
	v_pk_mul_f32 v[126:127], v[120:121], v[126:127]
	v_cvt_pk_bf16_f32 v124, v124, v125
	s_nop 0
	v_cvt_pk_bf16_f32 v124, v126, v127
	global_store_dwordx4 v153, v[154:157], s[12:13]
	v_cvt_pk_bf16_f32 v124, v160, v161
	v_add_u32_e32 v153, 0x40080, v152
	v_cvt_pk_bf16_f32 v124, v158, v159
	ds_write_b128 v150, v[116:119]
	ds_write_b128 v150, v[108:111] offset:64
	ds_read_b128 v[116:119], v151
	ds_read_b128 v[124:127], v151 offset:1152
	v_pk_mul_f32 v[108:109], v[168:169], 0.5 op_sel_hi:[1,0]
	v_pk_mul_f32 v[110:111], v[166:167], 0.5 op_sel_hi:[1,0]
	v_add_u32_e32 v166, 0x50080, v152
	s_waitcnt lgkmcnt(1)
	v_pk_fma_f32 v[118:119], v[108:109], v[118:119], v[172:173]
	v_pk_fma_f32 v[116:117], v[110:111], v[116:117], v[170:171]
	s_waitcnt lgkmcnt(0)
	v_pk_fma_f32 v[126:127], v[108:109], v[126:127], v[176:177]
	v_pk_fma_f32 v[124:125], v[110:111], v[124:125], v[174:175]
	global_store_dwordx4 v152, v[116:119], s[12:13] offset:128
	v_pk_mul_f32 v[154:155], v[108:109], v[126:127]
	v_pk_mul_f32 v[156:157], v[110:111], v[124:125]
	v_pk_mul_f32 v[116:117], v[110:111], v[116:117]
	v_pk_mul_f32 v[118:119], v[108:109], v[118:119]
	v_cvt_pk_bf16_f32 v116, v116, v117
	s_nop 0
	v_cvt_pk_bf16_f32 v116, v118, v119
	global_store_dwordx4 v198, v[124:127], s[12:13]
	v_cvt_pk_bf16_f32 v116, v156, v157
	s_nop 0
	v_cvt_pk_bf16_f32 v116, v154, v155
	global_load_dwordx4 v[116:119], v203, s[12:13]
	global_load_dwordx4 v[124:127], v204, s[12:13]
	ds_write_b128 v150, v[112:115]
	ds_write_b128 v150, v[104:107] offset:64
	ds_read_b128 v[104:107], v151
	ds_read_b128 v[112:115], v151 offset:1152
	global_load_dwordx4 v[154:157], v153, s[12:13]
	global_load_dwordx4 v[158:161], v166, s[12:13]
	s_waitcnt lgkmcnt(1)
	v_pk_fma_f32 v[106:107], v[120:121], v[106:107], v[180:181]
	v_pk_fma_f32 v[104:105], v[122:123], v[104:105], v[178:179]
	s_waitcnt lgkmcnt(0)
	v_pk_fma_f32 v[114:115], v[120:121], v[114:115], v[184:185]
	v_pk_fma_f32 v[112:113], v[122:123], v[112:113], v[182:183]
	global_store_dwordx4 v199, v[104:107], s[12:13]
	v_pk_mul_f32 v[162:163], v[120:121], v[114:115]
	v_pk_mul_f32 v[164:165], v[122:123], v[112:113]
	v_pk_mul_f32 v[104:105], v[122:123], v[104:105]
	v_pk_mul_f32 v[106:107], v[120:121], v[106:107]
	v_cvt_pk_bf16_f32 v104, v104, v105
	s_nop 0
	v_cvt_pk_bf16_f32 v104, v106, v107
	global_store_dwordx4 v200, v[112:115], s[12:13]
	v_cvt_pk_bf16_f32 v104, v164, v165
	v_add_u32_e32 v164, 0x60080, v152
	v_cvt_pk_bf16_f32 v104, v162, v163
	ds_write_b128 v150, v[100:103]
	ds_write_b128 v150, v[96:99] offset:64
	ds_read_b128 v[96:99], v151
	ds_read_b128 v[100:103], v151 offset:1152
	v_add_u32_e32 v162, 0x60000, v152
	v_add_u32_e32 v163, 0x70000, v152
	v_add_u32_e32 v165, 0x70080, v152
	s_waitcnt lgkmcnt(1)
	v_pk_fma_f32 v[98:99], v[108:109], v[98:99], v[188:189]
	v_pk_fma_f32 v[96:97], v[110:111], v[96:97], v[186:187]
	s_waitcnt lgkmcnt(0)
	v_pk_fma_f32 v[102:103], v[108:109], v[102:103], v[192:193]
	v_pk_fma_f32 v[100:101], v[110:111], v[100:101], v[190:191]
	global_store_dwordx4 v201, v[96:99], s[12:13]
	v_pk_mul_f32 v[104:105], v[108:109], v[102:103]
	v_pk_mul_f32 v[106:107], v[110:111], v[100:101]
	v_pk_mul_f32 v[96:97], v[110:111], v[96:97]
	v_pk_mul_f32 v[98:99], v[108:109], v[98:99]
	v_cvt_pk_bf16_f32 v96, v96, v97
	s_nop 0
	v_cvt_pk_bf16_f32 v96, v98, v99
	global_store_dwordx4 v202, v[100:103], s[12:13]
	v_cvt_pk_bf16_f32 v96, v106, v107
	s_nop 0
	v_cvt_pk_bf16_f32 v96, v104, v105
	global_load_dwordx4 v[96:99], v162, s[12:13]
	global_load_dwordx4 v[100:103], v163, s[12:13]
	global_load_dwordx4 v[104:107], v164, s[12:13]
	global_load_dwordx4 v[112:115], v165, s[12:13]
	ds_write_b128 v150, v[92:95]
	ds_write_b128 v150, v[88:91] offset:64
	ds_read_b128 v[88:91], v151
	ds_read_b128 v[92:95], v151 offset:1152
	s_waitcnt vmcnt(11) lgkmcnt(1)
; #define LAS __attribute__((address_space(3)))
; __device__ __forceinline__ unsigned cvt_pk_bf16(float lo, float hi) { unsigned r; asm volatile("v_cvt_pk_bf16_f32 %0, %1, %2" : "=v"(r) : "v"(lo), "v"(hi)); return r; }
; #define ERN_EOFF(q, m) (eb + (unsigned)((((q) & 1) * HALF + (m) * 16) * DM + ERN_COL((q) >> 1)))
; #define ERN_LOADX(q) do { _Pragma("unroll") for (int m = 0; m < 4; ++m) xb[(q) & 1][m] = *(const f32x4*)((const char*)xi + 4u * ERN_EOFF(q, m)); } while (0)
; #define ERN_LOADX(g) do { _Pragma("unroll") for (int bj_ = 0; bj_ < 2; ++bj_) _Pragma("unroll") for (int rh_ = 0; rh_ < 2; ++rh_) xb[(g) & 1][bj_][rh_] = *(const f32x4*)((const char*)xi + 4u * ERN_EOFF(g, bj_, rh_)); } while (0)
;     __device__ __forceinline__ void operator()(const f32x4 (&acc)[2][2][4][2], const Unit& u, int wr, int wc, int fr, int fq) const {
;     ...
;         for (int g = 0; g < 8; ++g) { const int ai = g >> 2, m = g & 3;
;             if (g + 1 < 8) ERN_LOADX(g + 1);
;             float sq0 = 0.f, sq1 = 0.f; u32x2 hw[2][2];
; #pragma unroll
;             for (int bj = 0; bj < 2; ++bj) {
;                 *(LAS f32x4*)(st + wr_off) = acc[ai][bj][m][0]; *(LAS f32x4*)(st + wr_off + 64) = acc[ai][bj][m][1];
;                 const f32x4 a0 = *(const LAS f32x4*)(st + rd_off), a1 = *(const LAS f32x4*)(st + rd_off + 8 * 144);
;                 { const f32x4 xv = xb[g & 1][bj][0] + gv[bj] * a0; __builtin_nontemporal_store(xv, (f32x4*)((char*)xo + 4u * ERN_EOFF(g, bj, 0)));
;                   sq0 += (xv.x * xv.x + xv.y * xv.y) + (xv.z * xv.z + xv.w * xv.w);
;                   const f32x4 hv = xv * gsn[bj]; hw[bj][0].x = cvt_pk_bf16(hv.x, hv.y); hw[bj][0].y = cvt_pk_bf16(hv.z, hv.w); }
;                 { const f32x4 xv = xb[g & 1][bj][1] + gv[bj] * a1; __builtin_nontemporal_store(xv, (f32x4*)((char*)xo + 4u * ERN_EOFF(g, bj, 1)));
;                   sq1 += (xv.x * xv.x + xv.y * xv.y) + (xv.z * xv.z + xv.w * xv.w);
;                   const f32x4 hv = xv * gsn[bj]; hw[bj][1].x = cvt_pk_bf16(hv.x, hv.y); hw[bj][1].y = cvt_pk_bf16(hv.z, hv.w); }
;             }
	v_pk_fma_f32 v[90:91], v[120:121], v[90:91], v[118:119]
	v_pk_fma_f32 v[88:89], v[122:123], v[88:89], v[116:117]
	s_waitcnt vmcnt(10) lgkmcnt(0)
	v_pk_fma_f32 v[94:95], v[120:121], v[94:95], v[126:127]
	v_pk_fma_f32 v[92:93], v[122:123], v[92:93], v[124:125]
	global_store_dwordx4 v203, v[88:91], s[12:13]
	v_pk_mul_f32 v[116:117], v[120:121], v[94:95]
	v_pk_mul_f32 v[118:119], v[122:123], v[92:93]
	v_pk_mul_f32 v[88:89], v[122:123], v[88:89]
	v_pk_mul_f32 v[90:91], v[120:121], v[90:91]
	v_cvt_pk_bf16_f32 v88, v88, v89
	s_nop 0
	v_cvt_pk_bf16_f32 v88, v90, v91
	global_store_dwordx4 v204, v[92:95], s[12:13]
	v_cvt_pk_bf16_f32 v88, v118, v119
	v_add_u32_e32 v118, 0x100080, v152
	v_cvt_pk_bf16_f32 v88, v116, v117
	ds_write_b128 v150, v[84:87]
	ds_write_b128 v150, v[80:83] offset:64
	ds_read_b128 v[80:83], v151
	ds_read_b128 v[84:87], v151 offset:1152
	v_add_u32_e32 v116, 0x100000, v152
	v_add_u32_e32 v117, 0x110000, v152
	v_add_u32_e32 v119, 0x110080, v152
	s_waitcnt vmcnt(11) lgkmcnt(1)
	v_pk_fma_f32 v[82:83], v[108:109], v[82:83], v[156:157]
	v_pk_fma_f32 v[80:81], v[110:111], v[80:81], v[154:155]
	s_waitcnt vmcnt(10) lgkmcnt(0)
	v_pk_fma_f32 v[86:87], v[108:109], v[86:87], v[160:161]
	v_pk_fma_f32 v[84:85], v[110:111], v[84:85], v[158:159]
	global_store_dwordx4 v153, v[80:83], s[12:13]
	v_pk_mul_f32 v[88:89], v[108:109], v[86:87]
	v_pk_mul_f32 v[90:91], v[110:111], v[84:85]
	v_pk_mul_f32 v[80:81], v[110:111], v[80:81]
	v_pk_mul_f32 v[82:83], v[108:109], v[82:83]
	v_cvt_pk_bf16_f32 v80, v80, v81
	s_nop 0
	v_cvt_pk_bf16_f32 v80, v82, v83
	global_store_dwordx4 v166, v[84:87], s[12:13]
	v_cvt_pk_bf16_f32 v80, v90, v91
	s_nop 0
	v_cvt_pk_bf16_f32 v80, v88, v89
	global_load_dwordx4 v[80:83], v116, s[12:13]
	global_load_dwordx4 v[84:87], v117, s[12:13]
	ds_write_b128 v150, v[76:79]
	ds_write_b128 v150, v[72:75] offset:64
	ds_read_b128 v[72:75], v151
	ds_read_b128 v[76:79], v151 offset:1152
	global_load_dwordx4 v[88:91], v118, s[12:13]
	global_load_dwordx4 v[92:95], v119, s[12:13]
	s_waitcnt vmcnt(11) lgkmcnt(1)
	v_pk_fma_f32 v[74:75], v[120:121], v[74:75], v[98:99]
	v_pk_fma_f32 v[72:73], v[122:123], v[72:73], v[96:97]
	s_waitcnt vmcnt(10) lgkmcnt(0)
	v_pk_fma_f32 v[78:79], v[120:121], v[78:79], v[102:103]
	v_pk_fma_f32 v[76:77], v[122:123], v[76:77], v[100:101]
	global_store_dwordx4 v162, v[72:75], s[12:13]
	v_pk_mul_f32 v[96:97], v[120:121], v[78:79]
	v_pk_mul_f32 v[98:99], v[122:123], v[76:77]
	v_pk_mul_f32 v[72:73], v[122:123], v[72:73]
	v_pk_mul_f32 v[74:75], v[120:121], v[74:75]
	v_cvt_pk_bf16_f32 v72, v72, v73
	s_nop 0
	v_cvt_pk_bf16_f32 v72, v74, v75
	global_store_dwordx4 v163, v[76:79], s[12:13]
	v_cvt_pk_bf16_f32 v72, v98, v99
	v_add_u32_e32 v98, 0x120080, v152
	v_cvt_pk_bf16_f32 v72, v96, v97
	ds_write_b128 v150, v[68:71]
	ds_write_b128 v150, v[64:67] offset:64
	ds_read_b128 v[64:67], v151
	ds_read_b128 v[68:71], v151 offset:1152
	v_add_u32_e32 v96, 0x120000, v152
	v_add_u32_e32 v97, 0x130000, v152
	v_add_u32_e32 v99, 0x130080, v152
	s_waitcnt vmcnt(11) lgkmcnt(1)
	v_pk_fma_f32 v[66:67], v[108:109], v[66:67], v[106:107]
	v_pk_fma_f32 v[64:65], v[110:111], v[64:65], v[104:105]
	s_waitcnt vmcnt(10) lgkmcnt(0)
	v_pk_fma_f32 v[70:71], v[108:109], v[70:71], v[114:115]
	v_pk_fma_f32 v[68:69], v[110:111], v[68:69], v[112:113]
	global_store_dwordx4 v164, v[64:67], s[12:13]
	v_pk_mul_f32 v[72:73], v[108:109], v[70:71]
	v_pk_mul_f32 v[74:75], v[110:111], v[68:69]
	v_pk_mul_f32 v[64:65], v[110:111], v[64:65]
	v_pk_mul_f32 v[66:67], v[108:109], v[66:67]
	v_cvt_pk_bf16_f32 v64, v64, v65
	s_nop 0
	v_cvt_pk_bf16_f32 v64, v66, v67
	global_store_dwordx4 v165, v[68:71], s[12:13]
	v_cvt_pk_bf16_f32 v64, v74, v75
	s_nop 0
	v_cvt_pk_bf16_f32 v64, v72, v73
	global_load_dwordx4 v[64:67], v96, s[12:13]
	global_load_dwordx4 v[68:71], v97, s[12:13]
	global_load_dwordx4 v[72:75], v98, s[12:13]
	global_load_dwordx4 v[76:79], v99, s[12:13]
	ds_write_b128 v150, v[60:63]
	ds_write_b128 v150, v[56:59] offset:64
	ds_read_b128 v[56:59], v151
	ds_read_b128 v[60:63], v151 offset:1152
	s_waitcnt vmcnt(11) lgkmcnt(1)
	v_pk_fma_f32 v[58:59], v[120:121], v[58:59], v[82:83]
	v_pk_fma_f32 v[56:57], v[122:123], v[56:57], v[80:81]
	s_waitcnt vmcnt(10) lgkmcnt(0)
	v_pk_fma_f32 v[62:63], v[120:121], v[62:63], v[86:87]
	v_pk_fma_f32 v[60:61], v[122:123], v[60:61], v[84:85]
	global_store_dwordx4 v116, v[56:59], s[12:13]
	v_pk_mul_f32 v[80:81], v[120:121], v[62:63]
	v_pk_mul_f32 v[82:83], v[122:123], v[60:61]
	v_pk_mul_f32 v[56:57], v[122:123], v[56:57]
	v_pk_mul_f32 v[58:59], v[120:121], v[58:59]
	v_cvt_pk_bf16_f32 v56, v56, v57
	s_nop 0
	v_cvt_pk_bf16_f32 v56, v58, v59
	global_store_dwordx4 v117, v[60:63], s[12:13]
	v_cvt_pk_bf16_f32 v56, v82, v83
	v_add_u32_e32 v82, 0x140080, v152
	v_cvt_pk_bf16_f32 v56, v80, v81
	ds_write_b128 v150, v[52:55]
	ds_write_b128 v150, v[48:51] offset:64
	ds_read_b128 v[48:51], v151
	ds_read_b128 v[52:55], v151 offset:1152
	v_add_u32_e32 v80, 0x140000, v152
	v_add_u32_e32 v81, 0x150000, v152
	v_add_u32_e32 v83, 0x150080, v152
	s_waitcnt vmcnt(11) lgkmcnt(1)
	v_pk_fma_f32 v[50:51], v[108:109], v[50:51], v[90:91]
	v_pk_fma_f32 v[48:49], v[110:111], v[48:49], v[88:89]
	s_waitcnt vmcnt(10) lgkmcnt(0)
	v_pk_fma_f32 v[54:55], v[108:109], v[54:55], v[94:95]
	v_pk_fma_f32 v[52:53], v[110:111], v[52:53], v[92:93]
	global_store_dwordx4 v118, v[48:51], s[12:13]
	v_pk_mul_f32 v[56:57], v[108:109], v[54:55]
	v_pk_mul_f32 v[58:59], v[110:111], v[52:53]
	v_pk_mul_f32 v[48:49], v[110:111], v[48:49]
	v_pk_mul_f32 v[50:51], v[108:109], v[50:51]
	v_cvt_pk_bf16_f32 v48, v48, v49
	s_nop 0
	v_cvt_pk_bf16_f32 v48, v50, v51
	global_store_dwordx4 v119, v[52:55], s[12:13]
	v_cvt_pk_bf16_f32 v48, v58, v59
	s_nop 0
	v_cvt_pk_bf16_f32 v48, v56, v57
	global_load_dwordx4 v[48:51], v80, s[12:13]
	global_load_dwordx4 v[52:55], v81, s[12:13]
	ds_write_b128 v150, v[44:47]
	ds_write_b128 v150, v[40:43] offset:64
	ds_read_b128 v[40:43], v151
	ds_read_b128 v[44:47], v151 offset:1152
	global_load_dwordx4 v[56:59], v82, s[12:13]
	global_load_dwordx4 v[60:63], v83, s[12:13]
	s_waitcnt vmcnt(11) lgkmcnt(1)
; #define LAS __attribute__((address_space(3)))
; __device__ __forceinline__ unsigned cvt_pk_bf16(float lo, float hi) { unsigned r; asm volatile("v_cvt_pk_bf16_f32 %0, %1, %2" : "=v"(r) : "v"(lo), "v"(hi)); return r; }
; #define ERN_EOFF(q, m) (eb + (unsigned)((((q) & 1) * HALF + (m) * 16) * DM + ERN_COL((q) >> 1)))
; #define ERN_LOADX(q) do { _Pragma("unroll") for (int m = 0; m < 4; ++m) xb[(q) & 1][m] = *(const f32x4*)((const char*)xi + 4u * ERN_EOFF(q, m)); } while (0)
; #define ERN_LOADX(g) do { _Pragma("unroll") for (int bj_ = 0; bj_ < 2; ++bj_) _Pragma("unroll") for (int rh_ = 0; rh_ < 2; ++rh_) xb[(g) & 1][bj_][rh_] = *(const f32x4*)((const char*)xi + 4u * ERN_EOFF(g, bj_, rh_)); } while (0)
;     __device__ __forceinline__ void operator()(const f32x4 (&acc)[2][2][4][2], const Unit& u, int wr, int wc, int fr, int fq) const {
;     ...
;         for (int g = 0; g < 8; ++g) { const int ai = g >> 2, m = g & 3;
;             if (g + 1 < 8) ERN_LOADX(g + 1);
;             float sq0 = 0.f, sq1 = 0.f; u32x2 hw[2][2];
; #pragma unroll
;             for (int bj = 0; bj < 2; ++bj) {
;                 *(LAS f32x4*)(st + wr_off) = acc[ai][bj][m][0]; *(LAS f32x4*)(st + wr_off + 64) = acc[ai][bj][m][1];
;                 const f32x4 a0 = *(const LAS f32x4*)(st + rd_off), a1 = *(const LAS f32x4*)(st + rd_off + 8 * 144);
;                 { const f32x4 xv = xb[g & 1][bj][0] + gv[bj] * a0; __builtin_nontemporal_store(xv, (f32x4*)((char*)xo + 4u * ERN_EOFF(g, bj, 0)));
;                   sq0 += (xv.x * xv.x + xv.y * xv.y) + (xv.z * xv.z + xv.w * xv.w);
;                   const f32x4 hv = xv * gsn[bj]; hw[bj][0].x = cvt_pk_bf16(hv.x, hv.y); hw[bj][0].y = cvt_pk_bf16(hv.z, hv.w); }
;                 { const f32x4 xv = xb[g & 1][bj][1] + gv[bj] * a1; __builtin_nontemporal_store(xv, (f32x4*)((char*)xo + 4u * ERN_EOFF(g, bj, 1)));
;                   sq1 += (xv.x * xv.x + xv.y * xv.y) + (xv.z * xv.z + xv.w * xv.w);
;                   const f32x4 hv = xv * gsn[bj]; hw[bj][1].x = cvt_pk_bf16(hv.x, hv.y); hw[bj][1].y = cvt_pk_bf16(hv.z, hv.w); }
;             }
	v_pk_fma_f32 v[42:43], v[120:121], v[42:43], v[66:67]
	v_pk_fma_f32 v[40:41], v[122:123], v[40:41], v[64:65]
	s_waitcnt vmcnt(10) lgkmcnt(0)
	v_pk_fma_f32 v[46:47], v[120:121], v[46:47], v[70:71]
	v_pk_fma_f32 v[44:45], v[122:123], v[44:45], v[68:69]
	global_store_dwordx4 v96, v[40:43], s[12:13]
	v_pk_mul_f32 v[64:65], v[120:121], v[46:47]
	v_pk_mul_f32 v[66:67], v[122:123], v[44:45]
	v_pk_mul_f32 v[40:41], v[122:123], v[40:41]
	v_pk_mul_f32 v[42:43], v[120:121], v[42:43]
	v_cvt_pk_bf16_f32 v40, v40, v41
	s_nop 0
	v_cvt_pk_bf16_f32 v40, v42, v43
	global_store_dwordx4 v97, v[44:47], s[12:13]
	v_cvt_pk_bf16_f32 v40, v66, v67
	v_add_u32_e32 v66, 0x160080, v152
	v_cvt_pk_bf16_f32 v40, v64, v65
	ds_write_b128 v150, v[36:39]
	ds_write_b128 v150, v[32:35] offset:64
	ds_read_b128 v[32:35], v151
	ds_read_b128 v[36:39], v151 offset:1152
	v_add_u32_e32 v64, 0x160000, v152
	v_add_u32_e32 v65, 0x170000, v152
	v_add_u32_e32 v67, 0x170080, v152
	s_waitcnt vmcnt(11) lgkmcnt(1)
	v_pk_fma_f32 v[34:35], v[108:109], v[34:35], v[74:75]
	v_pk_fma_f32 v[32:33], v[110:111], v[32:33], v[72:73]
	s_waitcnt vmcnt(10) lgkmcnt(0)
	v_pk_fma_f32 v[38:39], v[108:109], v[38:39], v[78:79]
	v_pk_fma_f32 v[36:37], v[110:111], v[36:37], v[76:77]
	global_store_dwordx4 v98, v[32:35], s[12:13]
	v_pk_mul_f32 v[40:41], v[108:109], v[38:39]
	v_pk_mul_f32 v[42:43], v[110:111], v[36:37]
	v_pk_mul_f32 v[32:33], v[110:111], v[32:33]
	v_pk_mul_f32 v[34:35], v[108:109], v[34:35]
	v_cvt_pk_bf16_f32 v32, v32, v33
	s_nop 0
	v_cvt_pk_bf16_f32 v32, v34, v35
	global_store_dwordx4 v99, v[36:39], s[12:13]
	v_cvt_pk_bf16_f32 v32, v42, v43
	s_nop 0
	v_cvt_pk_bf16_f32 v32, v40, v41
	global_load_dwordx4 v[32:35], v64, s[12:13]
	global_load_dwordx4 v[36:39], v65, s[12:13]
	global_load_dwordx4 v[40:43], v66, s[12:13]
	global_load_dwordx4 v[44:47], v67, s[12:13]
	ds_write_b128 v150, v[28:31]
	ds_write_b128 v150, v[24:27] offset:64
	ds_read_b128 v[24:27], v151
	ds_read_b128 v[28:31], v151 offset:1152
	s_waitcnt vmcnt(11) lgkmcnt(1)
	v_pk_fma_f32 v[26:27], v[120:121], v[26:27], v[50:51]
	v_pk_fma_f32 v[24:25], v[122:123], v[24:25], v[48:49]
	s_waitcnt vmcnt(10) lgkmcnt(0)
	v_pk_fma_f32 v[30:31], v[120:121], v[30:31], v[54:55]
	v_pk_fma_f32 v[28:29], v[122:123], v[28:29], v[52:53]
	global_store_dwordx4 v80, v[24:27], s[12:13]
	v_pk_mul_f32 v[48:49], v[120:121], v[30:31]
	v_pk_mul_f32 v[50:51], v[122:123], v[28:29]
	v_pk_mul_f32 v[24:25], v[122:123], v[24:25]
	v_pk_mul_f32 v[26:27], v[120:121], v[26:27]
	v_cvt_pk_bf16_f32 v24, v24, v25
	s_nop 0
	v_cvt_pk_bf16_f32 v24, v26, v27
	global_store_dwordx4 v81, v[28:31], s[12:13]
	v_cvt_pk_bf16_f32 v24, v50, v51
	s_nop 0
	v_cvt_pk_bf16_f32 v24, v48, v49
	ds_write_b128 v150, v[20:23]
	ds_write_b128 v150, v[16:19] offset:64
	ds_read_b128 v[16:19], v151
	ds_read_b128 v[20:23], v151 offset:1152
	s_waitcnt vmcnt(11) lgkmcnt(1)
	v_pk_fma_f32 v[18:19], v[108:109], v[18:19], v[58:59]
	v_pk_fma_f32 v[16:17], v[110:111], v[16:17], v[56:57]
	s_waitcnt vmcnt(10) lgkmcnt(0)
	v_pk_fma_f32 v[22:23], v[108:109], v[22:23], v[62:63]
	v_pk_fma_f32 v[20:21], v[110:111], v[20:21], v[60:61]
	global_store_dwordx4 v82, v[16:19], s[12:13]
	v_pk_mul_f32 v[24:25], v[108:109], v[22:23]
	v_pk_mul_f32 v[26:27], v[110:111], v[20:21]
	v_pk_mul_f32 v[16:17], v[110:111], v[16:17]
	v_pk_mul_f32 v[18:19], v[108:109], v[18:19]
	v_cvt_pk_bf16_f32 v16, v16, v17
	s_nop 0
	v_cvt_pk_bf16_f32 v16, v18, v19
	global_store_dwordx4 v83, v[20:23], s[12:13]
	v_cvt_pk_bf16_f32 v16, v26, v27
	s_nop 0
	v_cvt_pk_bf16_f32 v16, v24, v25
	ds_write_b128 v150, v[12:15]
	ds_write_b128 v150, v[8:11] offset:64
	ds_read_b128 v[8:11], v151
	ds_read_b128 v[12:15], v151 offset:1152
	s_waitcnt vmcnt(7) lgkmcnt(1)
	v_pk_fma_f32 v[10:11], v[120:121], v[10:11], v[34:35]
	v_pk_fma_f32 v[8:9], v[122:123], v[8:9], v[32:33]
	s_waitcnt vmcnt(6) lgkmcnt(0)
	v_pk_fma_f32 v[14:15], v[120:121], v[14:15], v[38:39]
	v_pk_fma_f32 v[12:13], v[122:123], v[12:13], v[36:37]
	global_store_dwordx4 v64, v[8:11], s[12:13]
	v_pk_mul_f32 v[16:17], v[120:121], v[14:15]
	v_pk_mul_f32 v[18:19], v[122:123], v[12:13]
	v_pk_mul_f32 v[8:9], v[122:123], v[8:9]
	v_pk_mul_f32 v[10:11], v[120:121], v[10:11]
	v_cvt_pk_bf16_f32 v8, v8, v9
	s_nop 0
	v_cvt_pk_bf16_f32 v8, v10, v11
	global_store_dwordx4 v65, v[12:15], s[12:13]
	v_cvt_pk_bf16_f32 v8, v18, v19
	s_nop 0
	v_cvt_pk_bf16_f32 v8, v16, v17
	ds_write_b128 v150, v[4:7]
	ds_write_b128 v150, v[0:3] offset:64
	ds_read_b128 v[0:3], v151
	ds_read_b128 v[4:7], v151 offset:1152
	s_waitcnt vmcnt(7) lgkmcnt(1)
	v_pk_fma_f32 v[2:3], v[108:109], v[2:3], v[42:43]
	v_pk_fma_f32 v[0:1], v[110:111], v[0:1], v[40:41]
	s_waitcnt vmcnt(6) lgkmcnt(0)
	v_pk_fma_f32 v[6:7], v[108:109], v[6:7], v[46:47]
	v_pk_fma_f32 v[4:5], v[110:111], v[4:5], v[44:45]
	global_store_dwordx4 v66, v[0:3], s[12:13]
	v_pk_mul_f32 v[8:9], v[108:109], v[6:7]
	v_pk_mul_f32 v[10:11], v[110:111], v[4:5]
	v_pk_mul_f32 v[0:1], v[110:111], v[0:1]
	v_pk_mul_f32 v[2:3], v[108:109], v[2:3]
	v_cvt_pk_bf16_f32 v0, v0, v1
	s_nop 0
	v_cvt_pk_bf16_f32 v0, v2, v3
	global_store_dwordx4 v67, v[4:7], s[12:13]
	v_cvt_pk_bf16_f32 v0, v10, v11
	s_nop 0
	v_cvt_pk_bf16_f32 v0, v8, v9
	s_cbranch_vccz .LBB0_2990
	s_andn2_b64 vcc, exec, s[4:5]
	s_cbranch_vccnz .LBB0_2989
	s_barrier
	s_branch .LBB0_2989
